# nt hint also on the once-read f32 weight loads of the tail / P4 quantisation loops (P1, P3, P7 tails, P4); on top of v019
# baseline (speedup 1.0000x reference)
; #define LAS __attribute__((address_space(3)))
; __device__ __forceinline__ void gu_load(f32x4 (&v)[16], float& gA, float& gB, const GUDesc& d, int lane) {
;     const int kr = lane >> 3, nq = lane & 7;
;     const float* __restrict__ src = d.W + (size_t)(d.k0 + 4 * kr) * d.N + d.n0 + 4 * nq;
;     gA = d.gain ? d.gain[d.k0 + lane] : 1.0f; gB = d.gain ? d.gain[d.k0 + 64 + lane] : 1.0f;
; #pragma unroll
;     for (int i = 0; i < 16; ++i) v[i] = *(const f32x4*)(src + (size_t)(32 * (i >> 2) + (i & 3)) * d.N);
; }
; template <int ROT>
; __device__ __forceinline__ void rot32_tile(f32x4 (&v)[16], int lane) {
; #pragma unroll
;     for (int jq = 0; jq < 4; ++jq) {
;         const f32x4 a = v[4 * jq], b = v[4 * jq + 1], c = v[4 * jq + 2], d = v[4 * jq + 3];
;         const f32x4 a1 = a + b, b1 = a - b, c1 = c + d, d1 = c - d;
;         if (ROT >= 2) { v[4 * jq] = a1 + c1; v[4 * jq + 2] = a1 - c1; v[4 * jq + 1] = b1 + d1; v[4 * jq + 3] = b1 - d1; }
;         else { v[4 * jq] = a1; v[4 * jq + 1] = b1; v[4 * jq + 2] = c1; v[4 * jq + 3] = d1; }
;     }
;     const int lane = (F.tid & 63), stride = nworkers * 8;
;     LAS unsigned* T = (LAS unsigned*)(F.lds + F.wave * 16384);
;     for (int it = lo + worker * 8 + F.wave; it < hi; it += stride) { f32x4 va[16]; float gA, gB; GUDesc da; gu_decode(F, it, da); gu_load(va, gA, gB, da, lane); gu_finish<ROT>(va, gA, gB, da, T, lane); }
.LBB0_1192:
	s_add_u32 s12, s78, s10
	s_addc_u32 s13, s79, s11
	v_or_b32_e32 v2, s40, v49
	s_add_u32 s10, s20, s16
	v_mul_hi_i32_i24_e32 v3, s14, v2
	v_mul_i32_i24_e32 v2, s14, v2
	s_addc_u32 s11, s21, s17
	s_waitcnt lgkmcnt(0)
	v_lshl_add_u64 v[2:3], v[2:3], 2, v[4:5]
	s_ashr_i32 s7, s6, 31
	v_lshl_add_u64 v[2:3], s[6:7], 2, v[2:3]
	v_lshl_add_u64 v[2:3], v[2:3], 0, v[38:39]
	s_lshl_b32 s0, s14, 2
	v_lshl_add_u64 v[4:5], v[2:3], 0, s[0:1]
	global_load_dwordx4 v[40:43], v[2:3], off nt
	global_load_dwordx4 v[44:47], v[4:5], off nt
	v_lshl_add_u64 v[2:3], v[4:5], 0, s[0:1]
	v_lshl_add_u64 v[4:5], v[2:3], 0, s[0:1]
	s_mulk_i32 s14, 0x74
	s_mov_b32 s15, s1
	global_load_dwordx4 v[72:75], v[2:3], off nt
	global_load_dwordx4 v[76:79], v[4:5], off nt
	v_lshl_add_u64 v[2:3], v[4:5], 0, s[14:15]
	v_lshl_add_u64 v[4:5], v[2:3], 0, s[0:1]
	global_load_dwordx4 v[80:83], v[2:3], off nt
	global_load_dwordx4 v[84:87], v[4:5], off nt
	v_lshl_add_u64 v[2:3], v[4:5], 0, s[0:1]
	v_lshl_add_u64 v[4:5], v[2:3], 0, s[0:1]
	global_load_dwordx4 v[88:91], v[2:3], off nt
	global_load_dwordx4 v[92:95], v[4:5], off nt
	v_lshl_add_u64 v[2:3], v[4:5], 0, s[14:15]
	global_load_dwordx4 v[10:13], v[2:3], off nt
	v_lshl_add_u64 v[2:3], v[2:3], 0, s[0:1]
	v_lshl_add_u64 v[6:7], v[2:3], 0, s[0:1]
	global_load_dwordx4 v[26:29], v[2:3], off nt
	s_lshl_b32 s7, s6, 1
	global_load_dwordx4 v[2:5], v[6:7], off nt
	v_lshl_add_u64 v[6:7], v[6:7], 0, s[0:1]
	global_load_dwordx4 v[14:17], v[6:7], off nt
	s_waitcnt vmcnt(12)
	v_bitop3_b32 v9, s6, v64, v52 bitop3:0xc8
	s_and_b32 s7, s7, 0xffffff00
	v_lshl_add_u64 v[6:7], v[6:7], 0, s[14:15]
	v_or_b32_e32 v9, s7, v9
	global_load_dwordx4 v[18:21], v[6:7], off nt
	v_lshl_add_u64 v[6:7], v[6:7], 0, s[0:1]
	v_or_b32_e32 v8, s6, v52
	v_or_b32_e32 v9, s9, v9
	v_lshl_add_u64 v[22:23], v[6:7], 0, s[0:1]
	v_cndmask_b32_e64 v96, v9, v8, s[2:3]
	global_load_dwordx4 v[30:33], v[6:7], off nt
	v_ashrrev_i32_e32 v97, 31, v96
	global_load_dwordx4 v[6:9], v[22:23], off nt
	v_lshl_add_u64 v[22:23], v[22:23], 0, s[0:1]
	global_load_dwordx4 v[22:25], v[22:23], off nt
	s_ashr_i32 s0, s40, 7
	s_waitcnt vmcnt(14)
	v_pk_add_f32 v[98:99], v[42:43], v[46:47]
	v_pk_add_f32 v[100:101], v[40:41], v[44:45]
	v_sub_f32_e32 v103, v43, v47
	v_sub_f32_e32 v102, v42, v46
	v_sub_f32_e32 v105, v41, v45
	v_sub_f32_e32 v104, v40, v44
	s_waitcnt vmcnt(12)
	v_pk_add_f32 v[40:41], v[74:75], v[78:79]
	v_pk_add_f32 v[42:43], v[72:73], v[76:77]
	v_sub_f32_e32 v75, v75, v79
	v_sub_f32_e32 v74, v74, v78
	v_sub_f32_e32 v73, v73, v77
	v_sub_f32_e32 v72, v72, v76
	v_pk_add_f32 v[44:45], v[98:99], v[40:41]
	v_pk_add_f32 v[46:47], v[100:101], v[42:43]
	v_sub_f32_e32 v41, v99, v41
	v_sub_f32_e32 v40, v98, v40
	v_sub_f32_e32 v43, v101, v43
	v_sub_f32_e32 v42, v100, v42
	v_pk_add_f32 v[76:77], v[104:105], v[72:73]
	v_pk_add_f32 v[78:79], v[102:103], v[74:75]
	v_sub_f32_e32 v99, v105, v73
	v_sub_f32_e32 v98, v104, v72
	v_sub_f32_e32 v101, v103, v75
	v_sub_f32_e32 v100, v102, v74
	s_waitcnt vmcnt(10)
	v_pk_add_f32 v[72:73], v[82:83], v[86:87]
	v_pk_add_f32 v[74:75], v[80:81], v[84:85]
	v_sub_f32_e32 v81, v81, v85
	v_sub_f32_e32 v80, v80, v84
	s_waitcnt vmcnt(8)
	v_pk_add_f32 v[84:85], v[90:91], v[94:95]
	v_sub_f32_e32 v83, v83, v87
	v_sub_f32_e32 v82, v82, v86
	v_pk_add_f32 v[86:87], v[88:89], v[92:93]
	v_sub_f32_e32 v89, v89, v93
	v_sub_f32_e32 v88, v88, v92
	v_pk_add_f32 v[92:93], v[72:73], v[84:85]
	v_sub_f32_e32 v85, v73, v85
	v_sub_f32_e32 v84, v72, v84
	v_lshl_add_u64 v[72:73], v[96:97], 2, s[4:5]
	v_sub_f32_e32 v91, v91, v95
	v_sub_f32_e32 v90, v90, v94
	v_pk_add_f32 v[94:95], v[74:75], v[86:87]
	v_sub_f32_e32 v87, v75, v87
	v_sub_f32_e32 v86, v74, v86
	global_load_dwordx4 v[72:75], v[72:73], off nt
	v_pk_add_f32 v[102:103], v[80:81], v[88:89]
	v_pk_add_f32 v[104:105], v[82:83], v[90:91]
	v_sub_f32_e32 v81, v81, v89
	v_sub_f32_e32 v80, v80, v88
	v_sub_f32_e32 v83, v83, v91
	v_sub_f32_e32 v82, v82, v90
	s_waitcnt vmcnt(7)
	v_pk_add_f32 v[88:89], v[12:13], v[28:29]
	v_pk_add_f32 v[90:91], v[10:11], v[26:27]
	v_sub_f32_e32 v13, v13, v29
	v_sub_f32_e32 v12, v12, v28
	v_sub_f32_e32 v11, v11, v27
	v_sub_f32_e32 v10, v10, v26
	s_waitcnt vmcnt(5)
	v_pk_add_f32 v[26:27], v[4:5], v[16:17]
	v_pk_add_f32 v[28:29], v[2:3], v[14:15]
	v_sub_f32_e32 v5, v5, v17
	v_sub_f32_e32 v4, v4, v16
	v_sub_f32_e32 v3, v3, v15
	v_sub_f32_e32 v2, v2, v14
	v_pk_add_f32 v[14:15], v[88:89], v[26:27]
	v_pk_add_f32 v[16:17], v[90:91], v[28:29]
	v_sub_f32_e32 v27, v89, v27
	v_sub_f32_e32 v26, v88, v26
	v_sub_f32_e32 v29, v91, v29
	v_sub_f32_e32 v28, v90, v28
	v_pk_add_f32 v[88:89], v[10:11], v[2:3]
	v_pk_add_f32 v[90:91], v[12:13], v[4:5]
	v_sub_f32_e32 v3, v11, v3
	v_sub_f32_e32 v2, v10, v2
	v_sub_f32_e32 v5, v13, v5
	v_sub_f32_e32 v4, v12, v4
	s_waitcnt vmcnt(3)
	v_pk_add_f32 v[10:11], v[20:21], v[32:33]
	v_pk_add_f32 v[12:13], v[18:19], v[30:31]
	v_sub_f32_e32 v19, v19, v31
	v_sub_f32_e32 v18, v18, v30
	s_waitcnt vmcnt(1)
; #define LAS __attribute__((address_space(3)))
; __device__ __forceinline__ float bfly8(float x, bool up) { const float p = __uint_as_float(__builtin_amdgcn_update_dpp(0u, __float_as_uint(x), 0x128, 0xf, 0xf, false)); return up ? p - x : x + p; }
; __device__ __forceinline__ float bfly16(float x, bool up) { const auto r = __builtin_amdgcn_permlane16_swap(__float_as_uint(x), __float_as_uint(x), false, false); const float a = __uint_as_float(r[0]), b = __uint_as_float(r[1]); return up ? a - b : a + b; }
; template <int ROT>
; __device__ __forceinline__ void rot32_tile(f32x4 (&v)[16], int lane) {
;     ...
;     }
;     { const bool s8 = (lane & 8) != 0, s16 = (lane & 16) != 0, s32 = (lane & 32) != 0;
; #pragma unroll
;       for (int i = 0; i < 16; ++i)
; #pragma unroll
;           for (int e = 0; e < 4; ++e) { float x = v[i][e]; if (ROT >= 3) x = bfly8(x, s8); if (ROT >= 4) x = bfly16(x, s16); if (ROT >= 5) x = bfly32(x, s32); v[i][e] = x; } }
; #pragma unroll
;     for (int i = 0; i < 16; ++i) v[i] *= (ROT == 1 ? 0.70710678118654752f : ROT == 2 ? 0.5f : ROT == 3 ? 0.35355339059327373f : ROT == 4 ? 0.25f : 0.17677669529663687f);
; }
; template <bool STRIP, int ROT>
; __device__ __forceinline__ void gu_finish_t(f32x4 (&v)[16], float gA, float gB, const GUDesc& d, LAS unsigned* T, int lane, const float (&sinv)[4]) {
;     const int kr = lane >> 3, nq = lane & 7;
;     const int dq0 = d.il ? gu_dest(d.n0 + 4 * nq, d.bj) : d.n0 + 4 * nq;
;     if (ROT) rot32_tile<ROT>(v, lane);
;     float inv[4];
; #pragma unroll
;     for (int e = 0; e < 4; ++e) { if (STRIP) inv[e] = sinv[e]; else { const float cm = __uint_as_float(d.cmax[dq0 + e]); inv[e] = cm > 0.f ? 127.0f / cm : 0.f; } }
; #pragma unroll
;     for (int jq = 0; jq < 4; ++jq) {
;         float g[4];
; #pragma unroll
;         for (int e2 = 0; e2 < 4; ++e2) g[e2] = jq < 2 ? __shfl(gA, 32 * jq + 4 * kr + e2) : __shfl(gB, 32 * (jq - 2) + 4 * kr + e2);
; #pragma unroll
;         for (int e = 0; e < 4; ++e)
;             T[(4 * nq + e) * 33 + 8 * jq + kr] = pack4_i8(v[4 * jq + 0][e] * g[0] * inv[e], v[4 * jq + 1][e] * g[1] * inv[e], v[4 * jq + 2][e] * g[2] * inv[e], v[4 * jq + 3][e] * g[3] * inv[e]);
	v_pk_add_f32 v[30:31], v[8:9], v[24:25]
	v_sub_f32_e32 v21, v21, v33
	v_sub_f32_e32 v20, v20, v32
	v_pk_add_f32 v[32:33], v[6:7], v[22:23]
	v_sub_f32_e32 v7, v7, v23
	v_sub_f32_e32 v6, v6, v22
	v_pk_add_f32 v[22:23], v[10:11], v[30:31]
	v_pk_mul_f32 v[110:111], v[2:3], 0.5 op_sel_hi:[1,0]
	v_pk_mul_f32 v[2:3], v[22:23], 0.5 op_sel_hi:[1,0]
	v_sub_f32_e32 v9, v9, v25
	v_sub_f32_e32 v8, v8, v24
	v_pk_add_f32 v[24:25], v[12:13], v[32:33]
	v_sub_f32_e32 v33, v13, v33
	v_sub_f32_e32 v32, v12, v32
	v_pk_add_f32 v[12:13], v[18:19], v[6:7]
	v_sub_f32_e32 v19, v19, v7
	v_sub_f32_e32 v18, v18, v6
	v_pk_mul_f32 v[106:107], v[16:17], 0.5 op_sel_hi:[1,0]
	v_pk_mul_f32 v[16:17], v[18:19], 0.5 op_sel_hi:[1,0]
	v_sub_f32_e32 v31, v11, v31
	v_sub_f32_e32 v30, v10, v30
	v_pk_mul_f32 v[10:11], v[24:25], 0.5 op_sel_hi:[1,0]
	v_pk_mul_f32 v[6:7], v[30:31], 0.5 op_sel_hi:[1,0]
	v_pk_add_f32 v[96:97], v[20:21], v[8:9]
	v_sub_f32_e32 v9, v21, v9
	v_sub_f32_e32 v8, v20, v8
	v_pk_mul_f32 v[20:21], v[44:45], 0.5 op_sel_hi:[1,0]
	v_pk_mul_f32 v[44:45], v[46:47], 0.5 op_sel_hi:[1,0]
	v_pk_mul_f32 v[46:47], v[78:79], 0.5 op_sel_hi:[1,0]
	v_pk_mul_f32 v[76:77], v[76:77], 0.5 op_sel_hi:[1,0]
	v_pk_mul_f32 v[78:79], v[100:101], 0.5 op_sel_hi:[1,0]
	v_pk_mul_f32 v[100:101], v[104:105], 0.5 op_sel_hi:[1,0]
	v_pk_mul_f32 v[104:105], v[14:15], 0.5 op_sel_hi:[1,0]
	v_pk_mul_f32 v[14:15], v[32:33], 0.5 op_sel_hi:[1,0]
	v_pk_mul_f32 v[42:43], v[42:43], 0.5 op_sel_hi:[1,0]
	v_pk_mul_f32 v[98:99], v[98:99], 0.5 op_sel_hi:[1,0]
	v_pk_mul_f32 v[40:41], v[40:41], 0.5 op_sel_hi:[1,0]
	v_pk_mul_f32 v[94:95], v[94:95], 0.5 op_sel_hi:[1,0]
	v_pk_mul_f32 v[102:103], v[102:103], 0.5 op_sel_hi:[1,0]
	v_pk_mul_f32 v[86:87], v[86:87], 0.5 op_sel_hi:[1,0]
	v_pk_mul_f32 v[80:81], v[80:81], 0.5 op_sel_hi:[1,0]
	v_pk_mul_f32 v[92:93], v[92:93], 0.5 op_sel_hi:[1,0]
	v_pk_mul_f32 v[84:85], v[84:85], 0.5 op_sel_hi:[1,0]
	v_pk_mul_f32 v[82:83], v[82:83], 0.5 op_sel_hi:[1,0]
	v_pk_mul_f32 v[88:89], v[88:89], 0.5 op_sel_hi:[1,0]
	s_waitcnt vmcnt(0)
	v_div_scale_f32 v22, s[14:15], v72, v72, s38
	v_rcp_f32_e32 v23, v22
	v_pk_mul_f32 v[28:29], v[28:29], 0.5 op_sel_hi:[1,0]
	v_pk_mul_f32 v[90:91], v[90:91], 0.5 op_sel_hi:[1,0]
	v_pk_mul_f32 v[26:27], v[26:27], 0.5 op_sel_hi:[1,0]
	v_fma_f32 v18, -v22, v23, 1.0
	v_fmac_f32_e32 v23, v18, v23
	v_div_scale_f32 v18, vcc, s38, v72, s38
	v_mul_f32_e32 v19, v18, v23
	v_fma_f32 v24, -v22, v19, v18
	v_fmac_f32_e32 v19, v24, v23
	v_fma_f32 v18, -v22, v19, v18
	v_div_fmas_f32 v18, v18, v23, v19
	v_div_scale_f32 v19, s[14:15], v73, v73, s38
	v_rcp_f32_e32 v22, v19
	v_div_fixup_f32 v18, v18, v72, s38
	v_cmp_lt_f32_e32 vcc, 0, v72
	v_pk_mul_f32 v[108:109], v[4:5], 0.5 op_sel_hi:[1,0]
	v_fma_f32 v23, -v19, v22, 1.0
	v_cndmask_b32_e32 v18, 0, v18, vcc
	v_fmac_f32_e32 v22, v23, v22
	v_div_scale_f32 v23, vcc, s38, v73, s38
	v_mul_f32_e32 v24, v23, v22
	v_fma_f32 v25, -v19, v24, v23
	v_fmac_f32_e32 v24, v25, v22
	v_fma_f32 v19, -v19, v24, v23
	v_div_fmas_f32 v19, v19, v22, v24
	v_div_scale_f32 v22, s[14:15], v74, v74, s38
	v_rcp_f32_e32 v23, v22
	v_div_fixup_f32 v19, v19, v73, s38
	v_cmp_lt_f32_e32 vcc, 0, v73
	v_pk_mul_f32 v[4:5], v[96:97], 0.5 op_sel_hi:[1,0]
	v_fma_f32 v24, -v22, v23, 1.0
	v_cndmask_b32_e32 v19, 0, v19, vcc
	v_fmac_f32_e32 v23, v24, v23
	v_div_scale_f32 v24, vcc, s38, v74, s38
	v_mul_f32_e32 v25, v24, v23
	v_fma_f32 v30, -v22, v25, v24
	v_fmac_f32_e32 v25, v30, v23
	v_fma_f32 v22, -v22, v25, v24
	v_div_fmas_f32 v22, v22, v23, v25
	v_div_scale_f32 v23, s[14:15], v75, v75, s38
	v_rcp_f32_e32 v24, v23
	v_div_fixup_f32 v22, v22, v74, s38
	v_cmp_lt_f32_e32 vcc, 0, v74
	v_pk_mul_f32 v[12:13], v[12:13], 0.5 op_sel_hi:[1,0]
	v_fma_f32 v25, -v23, v24, 1.0
	v_cndmask_b32_e32 v22, 0, v22, vcc
	v_fmac_f32_e32 v24, v25, v24
	v_div_scale_f32 v25, vcc, s38, v75, s38
	v_mul_f32_e32 v30, v25, v24
	v_fma_f32 v31, -v23, v30, v25
	v_fmac_f32_e32 v30, v31, v24
	v_fma_f32 v23, -v23, v30, v25
	v_div_fmas_f32 v23, v23, v24, v30
	ds_bpermute_b32 v24, v53, v71
	ds_bpermute_b32 v25, v54, v71
	ds_bpermute_b32 v30, v55, v71
	ds_bpermute_b32 v31, v56, v71
	v_div_fixup_f32 v23, v23, v75, s38
	s_waitcnt lgkmcnt(3)
	v_mul_f32_e32 v32, v44, v24
	s_waitcnt lgkmcnt(2)
	v_mul_f32_e32 v33, v76, v25
	v_fmaak_f32 v32, v18, v32, 0x43000000
	s_waitcnt lgkmcnt(1)
	v_mul_f32_e32 v42, v42, v30
	v_cvt_pk_u8_f32 v32, v32, 0, 0
	v_fmaak_f32 v33, v18, v33, 0x43000000
	s_waitcnt lgkmcnt(0)
	v_mul_f32_e32 v44, v98, v31
	v_cvt_pk_u8_f32 v32, v33, 1, v32
	v_fmaak_f32 v33, v18, v42, 0x43000000
	v_cvt_pk_u8_f32 v32, v33, 2, v32
	v_fmaak_f32 v33, v18, v44, 0x43000000
	v_cvt_pk_u8_f32 v32, v33, 3, v32
	v_mul_f32_e32 v33, v45, v24
	v_mul_f32_e32 v42, v77, v25
	v_fmaak_f32 v33, v19, v33, 0x43000000
	v_cmp_lt_f32_e32 vcc, 0, v75
	v_mul_f32_e32 v43, v43, v30
	v_cvt_pk_u8_f32 v33, v33, 0, 0
	v_fmaak_f32 v42, v19, v42, 0x43000000
	v_cndmask_b32_e32 v23, 0, v23, vcc
	v_mul_f32_e32 v44, v99, v31
	v_cvt_pk_u8_f32 v33, v42, 1, v33
	v_fmaak_f32 v42, v19, v43, 0x43000000
	v_mul_f32_e32 v21, v21, v24
	v_cvt_pk_u8_f32 v33, v42, 2, v33
	v_fmaak_f32 v42, v19, v44, 0x43000000
	v_mul_f32_e32 v20, v20, v24
	v_mul_f32_e32 v24, v47, v25
	v_fmaak_f32 v21, v23, v21, 0x43000000
	v_cvt_pk_u8_f32 v33, v42, 3, v33
	v_mul_f32_e32 v42, v46, v25
	v_mul_f32_e32 v25, v41, v30
	v_cvt_pk_u8_f32 v21, v21, 0, 0
	v_fmaak_f32 v24, v23, v24, 0x43000000
	v_mul_f32_e32 v40, v40, v30
	v_mul_f32_e32 v30, v79, v31
	v_cvt_pk_u8_f32 v21, v24, 1, v21
	v_fmaak_f32 v24, v23, v25, 0x43000000
	v_cvt_pk_u8_f32 v21, v24, 2, v21
	v_fmaak_f32 v24, v23, v30, 0x43000000
	v_cvt_pk_u8_f32 v21, v24, 3, v21
	ds_bpermute_b32 v24, v57, v71
	v_fmaak_f32 v20, v22, v20, 0x43000000
	ds_bpermute_b32 v25, v58, v71
	v_cvt_pk_u8_f32 v20, v20, 0, 0
	v_fmaak_f32 v42, v22, v42, 0x43000000
	ds_bpermute_b32 v30, v59, v71
	v_mul_f32_e32 v43, v78, v31
	v_cvt_pk_u8_f32 v20, v42, 1, v20
	v_fmaak_f32 v40, v22, v40, 0x43000000
	ds_bpermute_b32 v31, v60, v71
	v_cvt_pk_u8_f32 v20, v40, 2, v20
	v_fmaak_f32 v40, v22, v43, 0x43000000
	v_cvt_pk_u8_f32 v20, v40, 3, v20
	s_waitcnt lgkmcnt(3)
; template <bool STRIP, int ROT>
; __device__ __forceinline__ void gu_finish_t(f32x4 (&v)[16], float gA, float gB, const GUDesc& d, LAS unsigned* T, int lane, const float (&sinv)[4]) {
;     ...
;     for (int jq = 0; jq < 4; ++jq) {
;         float g[4];
; #pragma unroll
;         for (int e2 = 0; e2 < 4; ++e2) g[e2] = jq < 2 ? __shfl(gA, 32 * jq + 4 * kr + e2) : __shfl(gB, 32 * (jq - 2) + 4 * kr + e2);
; #pragma unroll
;         for (int e = 0; e < 4; ++e)
;             T[(4 * nq + e) * 33 + 8 * jq + kr] = pack4_i8(v[4 * jq + 0][e] * g[0] * inv[e], v[4 * jq + 1][e] * g[1] * inv[e], v[4 * jq + 2][e] * g[2] * inv[e], v[4 * jq + 3][e] * g[3] * inv[e]);
;     }
	v_mul_f32_e32 v40, v94, v24
	s_waitcnt lgkmcnt(2)
	v_mul_f32_e32 v41, v102, v25
	v_fmaak_f32 v40, v18, v40, 0x43000000
	s_waitcnt lgkmcnt(1)
	v_mul_f32_e32 v42, v86, v30
	v_cvt_pk_u8_f32 v40, v40, 0, 0
	v_fmaak_f32 v41, v18, v41, 0x43000000
	s_waitcnt lgkmcnt(0)
	v_mul_f32_e32 v43, v80, v31
	v_cvt_pk_u8_f32 v40, v41, 1, v40
	v_fmaak_f32 v41, v18, v42, 0x43000000
	v_cvt_pk_u8_f32 v40, v41, 2, v40
	v_fmaak_f32 v41, v18, v43, 0x43000000
	v_cvt_pk_u8_f32 v40, v41, 3, v40
	v_xor_b32_e32 v32, 0x80808080, v32
	v_xor_b32_e32 v40, 0x80808080, v40
	ds_write2_b32 v65, v32, v40 offset1:8
	v_mul_f32_e32 v32, v95, v24
	v_mul_f32_e32 v40, v103, v25
	v_fmaak_f32 v32, v19, v32, 0x43000000
	v_mul_f32_e32 v41, v87, v30
	v_cvt_pk_u8_f32 v32, v32, 0, 0
	v_fmaak_f32 v40, v19, v40, 0x43000000
	v_mul_f32_e32 v42, v81, v31
	v_cvt_pk_u8_f32 v32, v40, 1, v32
	v_fmaak_f32 v40, v19, v41, 0x43000000
	v_cvt_pk_u8_f32 v32, v40, 2, v32
	v_fmaak_f32 v40, v19, v42, 0x43000000
	v_cvt_pk_u8_f32 v32, v40, 3, v32
	v_xor_b32_e32 v33, 0x80808080, v33
	v_xor_b32_e32 v32, 0x80808080, v32
	ds_write2_b32 v65, v33, v32 offset0:33 offset1:41
	v_mul_f32_e32 v32, v92, v24
	v_mul_f32_e32 v33, v100, v25
	v_fmaak_f32 v32, v22, v32, 0x43000000
	v_mul_f32_e32 v40, v84, v30
	v_cvt_pk_u8_f32 v32, v32, 0, 0
	v_fmaak_f32 v33, v22, v33, 0x43000000
	v_mul_f32_e32 v41, v82, v31
	v_cvt_pk_u8_f32 v32, v33, 1, v32
	v_fmaak_f32 v33, v22, v40, 0x43000000
	v_cvt_pk_u8_f32 v32, v33, 2, v32
	v_fmaak_f32 v33, v22, v41, 0x43000000
	v_cvt_pk_u8_f32 v32, v33, 3, v32
	v_xor_b32_e32 v20, 0x80808080, v20
	v_xor_b32_e32 v32, 0x80808080, v32
	ds_write2_b32 v65, v20, v32 offset0:66 offset1:74
	v_mul_f32_e32 v20, v93, v24
	v_mul_f32_e32 v24, v101, v25
	v_fmaak_f32 v20, v23, v20, 0x43000000
	v_mul_f32_e32 v25, v85, v30
	v_cvt_pk_u8_f32 v20, v20, 0, 0
	v_fmaak_f32 v24, v23, v24, 0x43000000
	v_mul_f32_e32 v30, v83, v31
	v_cvt_pk_u8_f32 v20, v24, 1, v20
	v_fmaak_f32 v24, v23, v25, 0x43000000
	v_cvt_pk_u8_f32 v20, v24, 2, v20
	v_fmaak_f32 v24, v23, v30, 0x43000000
	v_cvt_pk_u8_f32 v20, v24, 3, v20
	ds_bpermute_b32 v24, v53, v34
	ds_bpermute_b32 v25, v54, v34
	ds_bpermute_b32 v30, v55, v34
	ds_bpermute_b32 v31, v56, v34
	v_xor_b32_e32 v21, 0x80808080, v21
	v_xor_b32_e32 v20, 0x80808080, v20
	ds_write2_b32 v65, v21, v20 offset0:99 offset1:107
	s_waitcnt lgkmcnt(4)
	v_mul_f32_e32 v20, v106, v24
	s_waitcnt lgkmcnt(3)
	v_mul_f32_e32 v21, v88, v25
	v_fmaak_f32 v20, v18, v20, 0x43000000
	s_waitcnt lgkmcnt(2)
	v_mul_f32_e32 v28, v28, v30
	v_cvt_pk_u8_f32 v20, v20, 0, 0
	v_fmaak_f32 v21, v18, v21, 0x43000000
	s_waitcnt lgkmcnt(1)
	v_mul_f32_e32 v32, v110, v31
	v_cvt_pk_u8_f32 v20, v21, 1, v20
	v_fmaak_f32 v21, v18, v28, 0x43000000
	v_cvt_pk_u8_f32 v20, v21, 2, v20
	v_fmaak_f32 v21, v18, v32, 0x43000000
	v_cvt_pk_u8_f32 v20, v21, 3, v20
	v_mul_f32_e32 v21, v107, v24
	v_mul_f32_e32 v28, v89, v25
	v_fmaak_f32 v21, v19, v21, 0x43000000
	v_mul_f32_e32 v29, v29, v30
	v_cvt_pk_u8_f32 v21, v21, 0, 0
	v_fmaak_f32 v28, v19, v28, 0x43000000
	v_mul_f32_e32 v32, v111, v31
	v_cvt_pk_u8_f32 v21, v28, 1, v21
	v_fmaak_f32 v28, v19, v29, 0x43000000
	v_cvt_pk_u8_f32 v21, v28, 2, v21
	v_fmaak_f32 v28, v19, v32, 0x43000000
	v_cvt_pk_u8_f32 v21, v28, 3, v21
	v_mul_f32_e32 v28, v104, v24
	v_mul_f32_e32 v29, v90, v25
	v_fmaak_f32 v28, v22, v28, 0x43000000
	v_mul_f32_e32 v26, v26, v30
	v_cvt_pk_u8_f32 v28, v28, 0, 0
	v_fmaak_f32 v29, v22, v29, 0x43000000
	v_mul_f32_e32 v24, v105, v24
	v_mul_f32_e32 v32, v108, v31
	v_cvt_pk_u8_f32 v28, v29, 1, v28
	v_fmaak_f32 v26, v22, v26, 0x43000000
	v_mul_f32_e32 v25, v91, v25
	v_fmaak_f32 v24, v23, v24, 0x43000000
	v_cvt_pk_u8_f32 v26, v26, 2, v28
	v_fmaak_f32 v28, v22, v32, 0x43000000
	v_mul_f32_e32 v27, v27, v30
	v_cvt_pk_u8_f32 v24, v24, 0, 0
	v_fmaak_f32 v25, v23, v25, 0x43000000
	v_cvt_pk_u8_f32 v26, v28, 3, v26
	v_mul_f32_e32 v28, v109, v31
	v_cvt_pk_u8_f32 v24, v25, 1, v24
	v_fmaak_f32 v25, v23, v27, 0x43000000
	v_cvt_pk_u8_f32 v24, v25, 2, v24
	v_fmaak_f32 v25, v23, v28, 0x43000000
	v_cvt_pk_u8_f32 v24, v25, 3, v24
	ds_bpermute_b32 v25, v57, v34
	ds_bpermute_b32 v27, v58, v34
	ds_bpermute_b32 v28, v59, v34
	ds_bpermute_b32 v29, v60, v34
	v_pk_mul_f32 v[8:9], v[8:9], 0.5 op_sel_hi:[1,0]
	s_waitcnt lgkmcnt(3)
; #define LAS __attribute__((address_space(3)))
; __host__ __device__ __forceinline__ size_t blk8_off(int r, int k, int KT8_) { return ((size_t)((r >> 8) * KT8_ + (k >> 7)) * 256 + (size_t)(r & 255)) * 128 + (size_t)(k & 127); }
; #define LDS_WAIT() asm volatile("s_waitcnt lgkmcnt(0)" ::: "memory")
; template <bool STRIP, int ROT>
; __device__ __forceinline__ void gu_finish_t(f32x4 (&v)[16], float gA, float gB, const GUDesc& d, LAS unsigned* T, int lane, const float (&sinv)[4]) {
;     ...
;     for (int jq = 0; jq < 4; ++jq) {
;         float g[4];
; #pragma unroll
;         for (int e2 = 0; e2 < 4; ++e2) g[e2] = jq < 2 ? __shfl(gA, 32 * jq + 4 * kr + e2) : __shfl(gB, 32 * (jq - 2) + 4 * kr + e2);
; #pragma unroll
;         for (int e = 0; e < 4; ++e)
;             T[(4 * nq + e) * 33 + 8 * jq + kr] = pack4_i8(v[4 * jq + 0][e] * g[0] * inv[e], v[4 * jq + 1][e] * g[1] * inv[e], v[4 * jq + 2][e] * g[2] * inv[e], v[4 * jq + 3][e] * g[3] * inv[e]);
;     }
;     LDS_WAIT(); asm volatile("" ::: "memory");
;     const int nl = lane >> 3, c = lane & 7;
; #pragma unroll
;     for (int g4 = 0; g4 < 4; ++g4) {
;         const int nloc = 8 * g4 + nl, dr = d.il ? gu_dest(d.n0 + nloc, d.bj) : d.n0 + nloc;
;         const LAS unsigned* t = T + nloc * 33 + 4 * c;
;         u32x4 o; o.x = t[0]; o.y = t[1]; o.z = t[2]; o.w = t[3];
;         *(u32x4*)(d.WQ + blk8_off(dr, d.k0 + 16 * c, d.kt8)) = o;
;         if (!STRIP) if (d.k0 == 0 && c == 0) d.sb[dr] = __uint_as_float(d.cmax[dr]) * (1.0f / 127.0f);
	v_mul_f32_e32 v2, v2, v25
	v_mul_f32_e32 v10, v10, v25
	s_waitcnt lgkmcnt(2)
	v_mul_f32_e32 v4, v4, v27
	v_fmaak_f32 v2, v22, v2, 0x43000000
	v_mul_f32_e32 v12, v12, v27
	v_fmaak_f32 v10, v18, v10, 0x43000000
	s_waitcnt lgkmcnt(1)
	v_mul_f32_e32 v6, v6, v28
	v_cvt_pk_u8_f32 v2, v2, 0, 0
	v_fmaak_f32 v4, v22, v4, 0x43000000
	v_mul_f32_e32 v14, v14, v28
	v_cvt_pk_u8_f32 v10, v10, 0, 0
	v_fmaak_f32 v12, v18, v12, 0x43000000
	s_waitcnt lgkmcnt(0)
	v_mul_f32_e32 v8, v8, v29
	v_cvt_pk_u8_f32 v2, v4, 1, v2
	v_fmaak_f32 v4, v22, v6, 0x43000000
	v_mul_f32_e32 v16, v16, v29
	v_cvt_pk_u8_f32 v10, v12, 1, v10
	v_fmaak_f32 v12, v18, v14, 0x43000000
	v_cvt_pk_u8_f32 v2, v4, 2, v2
	v_fmaak_f32 v4, v22, v8, 0x43000000
	v_cvt_pk_u8_f32 v10, v12, 2, v10
	v_fmaak_f32 v12, v18, v16, 0x43000000
	v_cvt_pk_u8_f32 v2, v4, 3, v2
	v_xor_b32_e32 v26, 0x80808080, v26
	v_cvt_pk_u8_f32 v10, v12, 3, v10
	v_xor_b32_e32 v2, 0x80808080, v2
	v_xor_b32_e32 v20, 0x80808080, v20
	v_xor_b32_e32 v10, 0x80808080, v10
	ds_write2_b32 v65, v26, v2 offset0:82 offset1:90
	v_mul_f32_e32 v2, v3, v25
	ds_write2_b32 v65, v20, v10 offset0:16 offset1:24
	v_mul_f32_e32 v10, v11, v25
	v_mul_f32_e32 v3, v5, v27
	v_fmaak_f32 v2, v23, v2, 0x43000000
	v_mul_f32_e32 v11, v13, v27
	v_fmaak_f32 v10, v19, v10, 0x43000000
	v_mul_f32_e32 v4, v7, v28
	v_cvt_pk_u8_f32 v2, v2, 0, 0
	v_fmaak_f32 v3, v23, v3, 0x43000000
	v_mul_f32_e32 v12, v15, v28
	v_cvt_pk_u8_f32 v10, v10, 0, 0
	v_fmaak_f32 v11, v19, v11, 0x43000000
	v_mul_f32_e32 v5, v9, v29
	v_cvt_pk_u8_f32 v2, v3, 1, v2
	v_fmaak_f32 v3, v23, v4, 0x43000000
	v_mul_f32_e32 v13, v17, v29
	v_cvt_pk_u8_f32 v10, v11, 1, v10
	v_fmaak_f32 v11, v19, v12, 0x43000000
	v_cvt_pk_u8_f32 v2, v3, 2, v2
	v_fmaak_f32 v3, v23, v5, 0x43000000
	v_cvt_pk_u8_f32 v10, v11, 2, v10
	v_fmaak_f32 v11, v19, v13, 0x43000000
	v_cvt_pk_u8_f32 v2, v3, 3, v2
	v_bitop3_b32 v3, s6, v66, v50 bitop3:0xc8
	v_xor_b32_e32 v24, 0x80808080, v24
	v_cvt_pk_u8_f32 v10, v11, 3, v10
	v_xor_b32_e32 v2, 0x80808080, v2
	v_or_b32_e32 v3, s7, v3
	v_xor_b32_e32 v21, 0x80808080, v21
	v_xor_b32_e32 v10, 0x80808080, v10
	ds_write2_b32 v65, v24, v2 offset0:115 offset1:123
	v_or_b32_e32 v2, s6, v50
	v_or_b32_e32 v3, s9, v3
	ds_write2_b32 v65, v21, v10 offset0:49 offset1:57
	v_cndmask_b32_e64 v2, v3, v2, s[2:3]
	s_waitcnt lgkmcnt(0)
	v_lshrrev_b32_e32 v3, 8, v2
	v_mov_b32_e32 v8, s0
	v_mad_i32_i24 v8, v3, s39, v8
	ds_read2_b32 v[4:5], v67 offset1:1
	ds_read2_b32 v[6:7], v67 offset0:2 offset1:3
	v_ashrrev_i32_e32 v9, 31, v8
	v_lshlrev_b64 v[8:9], 15, v[8:9]
	v_lshlrev_b32_e32 v3, 7, v2
	v_and_b32_e32 v34, 0x7380, v3
	v_lshl_add_u64 v[8:9], s[12:13], 0, v[8:9]
	v_lshl_add_u64 v[8:9], v[8:9], 0, v[34:35]
	v_or_b32_e32 v3, s40, v51
	v_lshl_add_u64 v[8:9], v[8:9], 0, v[36:37]
	v_cmp_eq_u32_e32 vcc, 0, v3
	s_waitcnt lgkmcnt(0)
	global_store_dwordx4 v[8:9], v[4:7], off
	s_and_saveexec_b64 s[14:15], vcc
	s_cbranch_execz .LBB0_1194
	v_ashrrev_i32_e32 v3, 31, v2
	v_lshlrev_b64 v[2:3], 2, v[2:3]
	v_lshl_add_u64 v[4:5], s[4:5], 0, v[2:3]
	global_load_dword v4, v[4:5], off
	v_lshl_add_u64 v[2:3], s[10:11], 0, v[2:3]
	s_waitcnt vmcnt(0)
	v_mul_f32_e32 v4, 0x3c010204, v4
	global_store_dword v[2:3], v4, off

; #define LAS __attribute__((address_space(3)))
; __device__ __forceinline__ void gu_load(f32x4 (&v)[16], float& gA, float& gB, const GUDesc& d, int lane) {
;     const int kr = lane >> 3, nq = lane & 7;
;     const float* __restrict__ src = d.W + (size_t)(d.k0 + 4 * kr) * d.N + d.n0 + 4 * nq;
;     gA = d.gain ? d.gain[d.k0 + lane] : 1.0f; gB = d.gain ? d.gain[d.k0 + 64 + lane] : 1.0f;
; #pragma unroll
;     for (int i = 0; i < 16; ++i) v[i] = *(const f32x4*)(src + (size_t)(32 * (i >> 2) + (i & 3)) * d.N);
; }
;     const int lane = (F.tid & 63), stride = nworkers * 8, first = lo + worker * 8 + F.wave;
;     LAS unsigned* T = (LAS unsigned*)(F.lds + F.wave * 16384);
;     if (first >= hi) return;
;     const int n_my = (hi - first + stride - 1) / stride;
;     f32x4 va[16], vb[16]; float gaA, gaB, gbA, gbB; GUDesc da, db;
;     gu_decode(F, first, da); gu_load(va, gaA, gaB, da, lane);
.LBB0_1211:
	s_xor_b32 s3, s3, s9
	s_mul_i32 s9, s10, s1
	s_sub_i32 s8, s8, s9
	s_add_i32 s9, s10, 1
	s_sub_i32 s11, s8, s1
	s_cmp_ge_u32 s8, s1
	s_cselect_b32 s9, s9, s10
	s_cselect_b32 s8, s11, s8
	s_add_i32 s10, s9, 1
	s_cmp_ge_u32 s8, s1
	s_cselect_b32 s1, s10, s9
	s_xor_b32 s1, s1, s3
	s_sub_i32 s28, s1, s3
	s_cmp_lt_i32 s28, 1
	s_cbranch_scc1 .LBB0_1256
	v_lshrrev_b32_e32 v2, 1, v0
	v_and_b32_e32 v137, 28, v2
	v_and_b32_e32 v34, 28, v1
	s_add_u32 s29, s78, 0x26000000
	v_or_b32_e32 v1, s31, v137
	s_addc_u32 s30, s79, 0
	s_lshl_b32 s1, s68, 14
	v_mul_hi_i32_i24_e32 v3, s2, v1
	v_mul_i32_i24_e32 v2, s2, v1
	s_add_i32 s14, s1, 0
	s_waitcnt lgkmcnt(0)
	v_lshl_add_u64 v[2:3], v[2:3], 2, v[4:5]
	s_ashr_i32 s1, s0, 31
	v_mov_b32_e32 v131, 0
	v_lshl_add_u64 v[2:3], s[0:1], 2, v[2:3]
	v_lshlrev_b32_e32 v130, 2, v34
	s_lshl_b32 s1, s2, 2
	s_mov_b32 s9, 0
	v_lshl_add_u64 v[36:37], v[2:3], 0, v[130:131]
	s_mul_i32 s8, s2, 0x18c
	s_sub_u32 s10, 0, s1
	v_lshl_add_u64 v[38:39], v[36:37], 0, s[8:9]
	s_subb_u32 s11, 0, 0
	s_waitcnt vmcnt(2)
	v_lshl_add_u64 v[10:11], v[38:39], 0, s[10:11]
	v_lshl_add_u64 v[12:13], v[10:11], 0, s[10:11]
	v_lshl_add_u64 v[18:19], v[12:13], 0, s[10:11]
	v_mov_b32_e32 v1, 0xffffff8c
	v_mad_i64_i32 v[20:21], s[12:13], s2, v1, v[18:19]
	v_lshl_add_u64 v[22:23], v[20:21], 0, s[10:11]
	v_lshl_add_u64 v[24:25], v[22:23], 0, s[10:11]
	global_load_dwordx4 v[2:5], v[10:11], off nt
	global_load_dwordx4 v[6:9], v[12:13], off nt
	s_nop 0
	global_load_dwordx4 v[10:13], v[18:19], off nt
	global_load_dwordx4 v[14:17], v[20:21], off nt
	s_nop 0
	global_load_dwordx4 v[18:21], v[22:23], off nt
	global_load_dwordx4 v[26:29], v[24:25], off nt
	v_lshl_add_u64 v[22:23], v[24:25], 0, s[10:11]
	global_load_dwordx4 v[30:33], v[22:23], off nt
	v_mad_i64_i32 v[22:23], s[12:13], s2, v1, v[22:23]
	global_load_dwordx4 v[66:69], v[22:23], off nt
	v_lshl_add_u64 v[22:23], v[22:23], 0, s[10:11]
	global_load_dwordx4 v[70:73], v[22:23], off nt
	v_lshl_add_u64 v[22:23], v[22:23], 0, s[10:11]
	global_load_dwordx4 v[74:77], v[22:23], off nt
	v_lshl_add_u64 v[22:23], v[22:23], 0, s[10:11]
	global_load_dwordx4 v[78:81], v[22:23], off nt
	v_mad_i64_i32 v[22:23], s[2:3], s2, v1, v[22:23]
	global_load_dwordx4 v[82:85], v[22:23], off nt
	v_lshl_add_u64 v[22:23], v[22:23], 0, s[10:11]
	v_lshl_add_u64 v[40:41], v[22:23], 0, s[10:11]
	global_load_dwordx4 v[86:89], v[22:23], off nt
	global_load_dwordx4 v[90:93], v[40:41], off nt
	s_nop 0
	global_load_dwordx4 v[22:25], v[38:39], off nt
	global_load_dwordx4 v[94:97], v[36:37], off nt
	s_add_i32 s33, s28, -1
	v_mbcnt_lo_u32_b32 v36, -1, 0
	v_lshrrev_b32_e32 v1, 3, v136
	v_and_b32_e32 v138, 7, v0
	v_mbcnt_hi_u32_b32 v36, -1, v36
	s_add_u32 s35, s78, 0x80000
	v_lshlrev_b32_e32 v37, 4, v1
	v_lshlrev_b32_e32 v36, 2, v36
	s_movk_i32 s1, 0x100
	v_lshlrev_b32_e32 v132, 4, v138
	s_addc_u32 s36, s79, 0
	v_lshl_add_u32 v35, v1, 2, s14
	v_and_or_b32 v140, v36, s1, v37
	v_mul_u32_u24_e32 v36, 0x210, v138
	v_add_u32_e32 v37, s14, v132
	v_mul_u32_u24_e32 v38, 0x84, v1
	s_add_u32 s37, s78, 0xab000
	v_lshlrev_b32_e32 v139, 2, v138
	v_or_b32_e32 v141, 4, v140
	v_or_b32_e32 v142, 8, v140
	v_or_b32_e32 v143, 12, v140
	v_or_b32_e32 v144, 0x80, v140
	v_or_b32_e32 v145, 0x84, v140
	v_or_b32_e32 v146, 0x88, v140
	v_or_b32_e32 v147, 0x8c, v140
	v_or_b32_e32 v148, 8, v1
	v_or_b32_e32 v149, 16, v1
	v_or_b32_e32 v150, 24, v1
	v_mov_b32_e32 v133, v131
	s_addc_u32 s38, s79, 0
	s_add_i32 s39, 0, 0x27c10
	s_add_i32 s40, 0, 0x27c18
	s_mov_b32 s41, 0x27c90
	s_mov_b32 s42, 0x600000
	s_mov_b32 s43, 0x200000
	s_mov_b32 s44, 0x27c08
	s_mov_b32 s45, 0x27ca0
	s_mov_b32 s46, 0x660000
	s_mov_b32 s47, 0x20a00000
	v_lshlrev_b32_e32 v134, 2, v34
	s_movk_i32 s48, 0x7f
	s_mov_b32 s49, 0x42fe0000
	v_add_u32_e32 v151, v35, v36
	v_add_u32_e32 v152, v37, v38
	v_mov_b32_e32 v153, 0x7c
	v_mov_b32_e32 v154, 0x67
	v_mov_b32_e32 v155, 0x6f
	v_mov_b32_e32 v156, 0x77
	v_mov_b32_e32 v157, 0x7f
	s_mov_b32 s50, 0
	s_branch .LBB0_1215

; __device__ __forceinline__ void gu_load(f32x4 (&v)[16], float& gA, float& gB, const GUDesc& d, int lane) {
;     const int kr = lane >> 3, nq = lane & 7;
;     const float* __restrict__ src = d.W + (size_t)(d.k0 + 4 * kr) * d.N + d.n0 + 4 * nq;
;     gA = d.gain ? d.gain[d.k0 + lane] : 1.0f; gB = d.gain ? d.gain[d.k0 + 64 + lane] : 1.0f;
; #pragma unroll
;     for (int i = 0; i < 16; ++i) v[i] = *(const f32x4*)(src + (size_t)(32 * (i >> 2) + (i & 3)) * d.N);
; }
; template <int ROT>
; __device__ __forceinline__ void rot32_tile(f32x4 (&v)[16], int lane) {
; #pragma unroll
;     for (int jq = 0; jq < 4; ++jq) {
;         const f32x4 a = v[4 * jq], b = v[4 * jq + 1], c = v[4 * jq + 2], d = v[4 * jq + 3];
;         const f32x4 a1 = a + b, b1 = a - b, c1 = c + d, d1 = c - d;
;         if (ROT >= 2) { v[4 * jq] = a1 + c1; v[4 * jq + 2] = a1 - c1; v[4 * jq + 1] = b1 + d1; v[4 * jq + 3] = b1 - d1; }
;         else { v[4 * jq] = a1; v[4 * jq + 1] = b1; v[4 * jq + 2] = c1; v[4 * jq + 3] = d1; }
;     }
;     ...
;     for (int i = 0; i < n_my; i += 2) {
;         { const int j = i + 1 < n_my ? i + 1 : n_my - 1; gu_decode(F, first + j * stride, db); gu_load(vb, gbA, gbB, db, lane); }
;         gu_finish<ROT>(va, gaA, gaB, da, T, lane);
;         { const int j = i + 2 < n_my ? i + 2 : n_my - 1; gu_decode(F, first + j * stride, da); gu_load(va, gaA, gaB, da, lane); }
.LBB0_1226:
	s_add_u32 s22, s78, s4
	s_addc_u32 s23, s79, s5
	v_or_b32_e32 v34, s52, v137
	s_add_u32 s16, s29, s16
	v_mul_hi_i32_i24_e32 v35, s24, v34
	v_mul_i32_i24_e32 v34, s24, v34
	s_addc_u32 s17, s30, s17
	s_waitcnt lgkmcnt(0)
	v_lshl_add_u64 v[34:35], v[34:35], 2, v[36:37]
	s_ashr_i32 s13, s12, 31
	v_lshl_add_u64 v[34:35], s[12:13], 2, v[34:35]
	v_mov_b32_e32 v135, v131
	v_lshl_add_u64 v[34:35], v[34:35], 0, v[134:135]
	s_lshl_b32 s8, s24, 2
	v_lshl_add_u64 v[36:37], v[34:35], 0, s[8:9]
	global_load_dwordx4 v[122:125], v[34:35], off nt
	global_load_dwordx4 v[126:129], v[36:37], off nt
	v_lshl_add_u64 v[34:35], v[36:37], 0, s[8:9]
	v_lshl_add_u64 v[36:37], v[34:35], 0, s[8:9]
	s_mul_i32 s4, s24, 0x74
	s_mov_b32 s5, s9
	global_load_dwordx4 v[114:117], v[34:35], off nt
	global_load_dwordx4 v[118:121], v[36:37], off nt
	v_lshl_add_u64 v[34:35], v[36:37], 0, s[4:5]
	v_lshl_add_u64 v[36:37], v[34:35], 0, s[8:9]
	global_load_dwordx4 v[106:109], v[34:35], off nt
	global_load_dwordx4 v[110:113], v[36:37], off nt
	v_lshl_add_u64 v[34:35], v[36:37], 0, s[8:9]
	v_lshl_add_u64 v[36:37], v[34:35], 0, s[8:9]
	global_load_dwordx4 v[98:101], v[34:35], off nt
	global_load_dwordx4 v[102:105], v[36:37], off nt
	v_lshl_add_u64 v[34:35], v[36:37], 0, s[4:5]
	global_load_dwordx4 v[54:57], v[34:35], off nt
	v_lshl_add_u64 v[34:35], v[34:35], 0, s[8:9]
	global_load_dwordx4 v[62:65], v[34:35], off nt
	v_lshl_add_u64 v[34:35], v[34:35], 0, s[8:9]
	v_add_u32_e32 v130, s0, v139
	global_load_dwordx4 v[50:53], v[34:35], off nt
	v_lshl_add_u64 v[34:35], v[34:35], 0, s[8:9]
	s_cmp_eq_u32 s53, 0
	v_lshlrev_b32_e32 v135, 1, v130
	global_load_dwordx4 v[58:61], v[34:35], off nt
	v_lshl_add_u64 v[34:35], v[34:35], 0, s[4:5]
	s_cselect_b64 s[4:5], -1, 0
	v_and_b32_e32 v135, 0xffffff00, v135
	s_lshl_b32 s1, s54, 7
	v_add_u32_e32 v135, s1, v135
	v_and_or_b32 v135, v130, s48, v135
	v_cndmask_b32_e64 v162, v135, v130, s[4:5]
	s_waitcnt vmcnt(12)
	v_pk_add_f32 v[164:165], v[96:97], v[92:93]
	v_pk_add_f32 v[166:167], v[94:95], v[90:91]
	v_sub_f32_e32 v93, v97, v93
	v_sub_f32_e32 v92, v96, v92
	v_sub_f32_e32 v91, v95, v91
	v_sub_f32_e32 v90, v94, v90
	v_pk_add_f32 v[94:95], v[88:89], v[84:85]
	v_pk_add_f32 v[96:97], v[86:87], v[82:83]
	v_sub_f32_e32 v169, v89, v85
	v_sub_f32_e32 v168, v88, v84
	v_sub_f32_e32 v171, v87, v83
	v_sub_f32_e32 v170, v86, v82
	v_pk_add_f32 v[86:87], v[164:165], v[94:95]
	v_pk_add_f32 v[88:89], v[166:167], v[96:97]
	v_sub_f32_e32 v83, v165, v95
	v_sub_f32_e32 v82, v164, v94
	v_sub_f32_e32 v85, v167, v97
	v_sub_f32_e32 v84, v166, v96
	v_pk_add_f32 v[164:165], v[80:81], v[76:77]
	v_pk_add_f32 v[166:167], v[78:79], v[74:75]
	v_sub_f32_e32 v77, v81, v77
	v_sub_f32_e32 v76, v80, v76
	v_sub_f32_e32 v75, v79, v75
	v_sub_f32_e32 v74, v78, v74
	v_pk_add_f32 v[78:79], v[72:73], v[68:69]
	v_pk_add_f32 v[80:81], v[70:71], v[66:67]
	v_sub_f32_e32 v67, v71, v67
	v_sub_f32_e32 v66, v70, v66
	v_ashrrev_i32_e32 v163, 31, v162
	v_pk_add_f32 v[70:71], v[164:165], v[78:79]
	v_sub_f32_e32 v79, v165, v79
	v_sub_f32_e32 v78, v164, v78
	v_pk_add_f32 v[164:165], v[74:75], v[66:67]
	v_sub_f32_e32 v75, v75, v67
	v_sub_f32_e32 v74, v74, v66
	v_lshl_add_u64 v[66:67], v[162:163], 2, s[6:7]
	v_sub_f32_e32 v73, v73, v69
	v_sub_f32_e32 v72, v72, v68
	global_load_dwordx4 v[66:69], v[66:67], off nt
	v_pk_add_f32 v[96:97], v[92:93], v[168:169]
	v_sub_f32_e32 v93, v93, v169
	v_sub_f32_e32 v92, v92, v168
	v_pk_add_f32 v[168:169], v[166:167], v[80:81]
	v_sub_f32_e32 v81, v167, v81
	v_sub_f32_e32 v80, v166, v80
	v_pk_add_f32 v[166:167], v[76:77], v[72:73]
	v_sub_f32_e32 v73, v77, v73
	v_sub_f32_e32 v72, v76, v72
	v_pk_add_f32 v[76:77], v[32:33], v[28:29]
	v_pk_add_f32 v[162:163], v[30:31], v[26:27]
	v_sub_f32_e32 v29, v33, v29
	v_sub_f32_e32 v28, v32, v28
	v_sub_f32_e32 v27, v31, v27
	v_sub_f32_e32 v26, v30, v26
	v_pk_add_f32 v[30:31], v[20:21], v[16:17]
	v_pk_add_f32 v[32:33], v[18:19], v[14:15]
	v_sub_f32_e32 v17, v21, v17
	v_sub_f32_e32 v16, v20, v16
	v_sub_f32_e32 v15, v19, v15
	v_sub_f32_e32 v14, v18, v14
	v_pk_add_f32 v[18:19], v[76:77], v[30:31]
	v_pk_add_f32 v[20:21], v[162:163], v[32:33]
	v_sub_f32_e32 v31, v77, v31
	v_sub_f32_e32 v30, v76, v30
	v_sub_f32_e32 v33, v163, v33
	v_sub_f32_e32 v32, v162, v32
	v_pk_add_f32 v[76:77], v[26:27], v[14:15]
	v_pk_add_f32 v[162:163], v[28:29], v[16:17]
	v_sub_f32_e32 v15, v27, v15
	v_sub_f32_e32 v14, v26, v14
	v_sub_f32_e32 v17, v29, v17
	v_sub_f32_e32 v16, v28, v16
	v_pk_add_f32 v[26:27], v[8:9], v[12:13]
	v_pk_add_f32 v[28:29], v[6:7], v[10:11]
	v_sub_f32_e32 v7, v11, v7
	v_sub_f32_e32 v6, v10, v6
	v_pk_add_f32 v[10:11], v[24:25], v[4:5]
	v_sub_f32_e32 v9, v13, v9
	v_sub_f32_e32 v8, v12, v8
	v_pk_add_f32 v[12:13], v[22:23], v[2:3]
	v_sub_f32_e32 v3, v3, v23
	v_sub_f32_e32 v2, v2, v22
	v_pk_add_f32 v[22:23], v[10:11], v[26:27]
	v_sub_f32_e32 v5, v5, v25
	v_sub_f32_e32 v4, v4, v24
	v_pk_add_f32 v[24:25], v[12:13], v[28:29]
	v_sub_f32_e32 v29, v29, v13
	v_sub_f32_e32 v28, v28, v12
	v_pk_add_f32 v[12:13], v[2:3], v[6:7]
	v_sub_f32_e32 v173, v7, v3
	v_sub_f32_e32 v172, v6, v2
	v_pk_mul_f32 v[2:3], v[22:23], 0.5 op_sel_hi:[1,0]
	v_sub_f32_e32 v27, v27, v11
	v_sub_f32_e32 v26, v26, v10
	v_pk_mul_f32 v[10:11], v[24:25], 0.5 op_sel_hi:[1,0]
	v_pk_mul_f32 v[6:7], v[26:27], 0.5 op_sel_hi:[1,0]
	v_pk_mul_f32 v[176:177], v[14:15], 0.5 op_sel_hi:[1,0]
	v_pk_mul_f32 v[14:15], v[28:29], 0.5 op_sel_hi:[1,0]
	v_pk_add_f32 v[94:95], v[90:91], v[170:171]
	v_pk_mul_f32 v[88:89], v[88:89], 0.5 op_sel_hi:[1,0]
	v_pk_mul_f32 v[94:95], v[94:95], 0.5 op_sel_hi:[1,0]
	v_sub_f32_e32 v91, v91, v171
	v_sub_f32_e32 v90, v90, v170
	v_pk_mul_f32 v[84:85], v[84:85], 0.5 op_sel_hi:[1,0]
	v_pk_mul_f32 v[90:91], v[90:91], 0.5 op_sel_hi:[1,0]
	v_pk_mul_f32 v[86:87], v[86:87], 0.5 op_sel_hi:[1,0]
	v_pk_mul_f32 v[96:97], v[96:97], 0.5 op_sel_hi:[1,0]
	v_pk_mul_f32 v[82:83], v[82:83], 0.5 op_sel_hi:[1,0]
	v_pk_mul_f32 v[92:93], v[92:93], 0.5 op_sel_hi:[1,0]
	global_load_dwordx4 v[38:41], v[34:35], off nt
	v_lshl_add_u64 v[34:35], v[34:35], 0, s[8:9]
	v_lshl_add_u64 v[42:43], v[34:35], 0, s[8:9]
	global_load_dwordx4 v[46:49], v[34:35], off nt
	v_pk_mul_f32 v[168:169], v[168:169], 0.5 op_sel_hi:[1,0]
	global_load_dwordx4 v[34:37], v[42:43], off nt
	v_lshl_add_u64 v[42:43], v[42:43], 0, s[8:9]
	global_load_dwordx4 v[42:45], v[42:43], off nt
	v_pk_mul_f32 v[164:165], v[164:165], 0.5 op_sel_hi:[1,0]
	s_waitcnt vmcnt(4)
; #define LAS __attribute__((address_space(3)))
; template <int ROT>
; __device__ __forceinline__ void rot32_tile(f32x4 (&v)[16], int lane) {
;     ...
;     for (int i = 0; i < 16; ++i) v[i] *= (ROT == 1 ? 0.70710678118654752f : ROT == 2 ? 0.5f : ROT == 3 ? 0.35355339059327373f : ROT == 4 ? 0.25f : 0.17677669529663687f);
; }
; template <bool STRIP, int ROT>
; __device__ __forceinline__ void gu_finish_t(f32x4 (&v)[16], float gA, float gB, const GUDesc& d, LAS unsigned* T, int lane, const float (&sinv)[4]) {
;     const int kr = lane >> 3, nq = lane & 7;
;     const int dq0 = d.il ? gu_dest(d.n0 + 4 * nq, d.bj) : d.n0 + 4 * nq;
;     if (ROT) rot32_tile<ROT>(v, lane);
;     float inv[4];
; #pragma unroll
;     for (int e = 0; e < 4; ++e) { if (STRIP) inv[e] = sinv[e]; else { const float cm = __uint_as_float(d.cmax[dq0 + e]); inv[e] = cm > 0.f ? 127.0f / cm : 0.f; } }
; #pragma unroll
;     for (int jq = 0; jq < 4; ++jq) {
;         float g[4];
; #pragma unroll
;         for (int e2 = 0; e2 < 4; ++e2) g[e2] = jq < 2 ? __shfl(gA, 32 * jq + 4 * kr + e2) : __shfl(gB, 32 * (jq - 2) + 4 * kr + e2);
; #pragma unroll
;         for (int e = 0; e < 4; ++e)
;             T[(4 * nq + e) * 33 + 8 * jq + kr] = pack4_i8(v[4 * jq + 0][e] * g[0] * inv[e], v[4 * jq + 1][e] * g[1] * inv[e], v[4 * jq + 2][e] * g[2] * inv[e], v[4 * jq + 3][e] * g[3] * inv[e]);
;     }
	v_div_scale_f32 v22, s[24:25], v66, v66, s49
	v_rcp_f32_e32 v23, v22
	v_pk_mul_f32 v[80:81], v[80:81], 0.5 op_sel_hi:[1,0]
	v_pk_mul_f32 v[74:75], v[74:75], 0.5 op_sel_hi:[1,0]
	v_pk_mul_f32 v[70:71], v[70:71], 0.5 op_sel_hi:[1,0]
	v_fma_f32 v24, -v22, v23, 1.0
	v_fmac_f32_e32 v23, v24, v23
	v_div_scale_f32 v24, vcc, s49, v66, s49
	v_mul_f32_e32 v25, v24, v23
	v_fma_f32 v26, -v22, v25, v24
	v_fmac_f32_e32 v25, v26, v23
	v_fma_f32 v22, -v22, v25, v24
	v_div_fmas_f32 v22, v22, v23, v25
	v_div_scale_f32 v23, s[24:25], v67, v67, s49
	v_rcp_f32_e32 v24, v23
	v_div_fixup_f32 v22, v22, v66, s49
	v_cmp_lt_f32_e32 vcc, 0, v66
	v_pk_mul_f32 v[166:167], v[166:167], 0.5 op_sel_hi:[1,0]
	v_fma_f32 v25, -v23, v24, 1.0
	v_cndmask_b32_e32 v22, 0, v22, vcc
	v_fmac_f32_e32 v24, v25, v24
	v_div_scale_f32 v25, vcc, s49, v67, s49
	v_mul_f32_e32 v26, v25, v24
	v_fma_f32 v27, -v23, v26, v25
	v_fmac_f32_e32 v26, v27, v24
	v_fma_f32 v23, -v23, v26, v25
	v_div_fmas_f32 v23, v23, v24, v26
	v_div_scale_f32 v24, s[24:25], v68, v68, s49
	v_rcp_f32_e32 v25, v24
	v_div_fixup_f32 v23, v23, v67, s49
	v_cmp_lt_f32_e32 vcc, 0, v67
	v_pk_mul_f32 v[78:79], v[78:79], 0.5 op_sel_hi:[1,0]
	v_fma_f32 v26, -v24, v25, 1.0
	v_cndmask_b32_e32 v23, 0, v23, vcc
	v_fmac_f32_e32 v25, v26, v25
	v_div_scale_f32 v26, vcc, s49, v68, s49
	v_mul_f32_e32 v27, v26, v25
	v_fma_f32 v28, -v24, v27, v26
	v_fmac_f32_e32 v27, v28, v25
	v_fma_f32 v24, -v24, v27, v26
	v_div_fmas_f32 v24, v24, v25, v27
	v_div_scale_f32 v25, s[24:25], v69, v69, s49
	v_rcp_f32_e32 v26, v25
	v_div_fixup_f32 v24, v24, v68, s49
	v_cmp_lt_f32_e32 vcc, 0, v68
	v_pk_mul_f32 v[72:73], v[72:73], 0.5 op_sel_hi:[1,0]
	v_fma_f32 v27, -v25, v26, 1.0
	v_cndmask_b32_e32 v24, 0, v24, vcc
	v_fmac_f32_e32 v26, v27, v26
	v_div_scale_f32 v27, vcc, s49, v69, s49
	v_mul_f32_e32 v28, v27, v26
	v_fma_f32 v29, -v25, v28, v27
	v_fmac_f32_e32 v28, v29, v26
	v_fma_f32 v25, -v25, v28, v27
	v_div_fmas_f32 v25, v25, v26, v28
	ds_bpermute_b32 v26, v140, v159
	ds_bpermute_b32 v27, v141, v159
	ds_bpermute_b32 v28, v142, v159
	ds_bpermute_b32 v29, v143, v159
	v_div_fixup_f32 v25, v25, v69, s49
	s_waitcnt lgkmcnt(3)
	v_mul_f32_e32 v66, v88, v26
	s_waitcnt lgkmcnt(2)
	v_mul_f32_e32 v67, v94, v27
	v_fmaak_f32 v66, v22, v66, 0x43000000
	s_waitcnt lgkmcnt(1)
	v_mul_f32_e32 v68, v84, v28
	v_cvt_pk_u8_f32 v66, v66, 0, 0
	v_fmaak_f32 v67, v22, v67, 0x43000000
	v_cmp_lt_f32_e32 vcc, 0, v69
	s_waitcnt lgkmcnt(0)
	v_mul_f32_e32 v69, v90, v29
	v_cvt_pk_u8_f32 v66, v67, 1, v66
	v_fmaak_f32 v67, v22, v68, 0x43000000
	v_cvt_pk_u8_f32 v66, v67, 2, v66
	v_fmaak_f32 v67, v22, v69, 0x43000000
	v_cvt_pk_u8_f32 v66, v67, 3, v66
	v_mul_f32_e32 v67, v89, v26
	v_mul_f32_e32 v68, v95, v27
	v_fmaak_f32 v67, v23, v67, 0x43000000
	v_mul_f32_e32 v69, v85, v28
	v_cvt_pk_u8_f32 v67, v67, 0, 0
	v_fmaak_f32 v68, v23, v68, 0x43000000
	v_mul_f32_e32 v84, v91, v29
	v_cvt_pk_u8_f32 v67, v68, 1, v67
	v_fmaak_f32 v68, v23, v69, 0x43000000
	v_cvt_pk_u8_f32 v67, v68, 2, v67
	v_fmaak_f32 v68, v23, v84, 0x43000000
	v_cndmask_b32_e32 v25, 0, v25, vcc
	v_cvt_pk_u8_f32 v67, v68, 3, v67
	v_mul_f32_e32 v68, v86, v26
	v_mul_f32_e32 v26, v87, v26
	v_mul_f32_e32 v69, v96, v27
	v_mul_f32_e32 v27, v97, v27
	v_fmaak_f32 v26, v25, v26, 0x43000000
	v_mul_f32_e32 v82, v82, v28
	v_mul_f32_e32 v28, v83, v28
	v_cvt_pk_u8_f32 v26, v26, 0, 0
	v_fmaak_f32 v27, v25, v27, 0x43000000
	v_mul_f32_e32 v84, v92, v29
	v_mul_f32_e32 v29, v93, v29
	v_cvt_pk_u8_f32 v26, v27, 1, v26
	v_fmaak_f32 v27, v25, v28, 0x43000000
	v_fmaak_f32 v68, v24, v68, 0x43000000
	v_cvt_pk_u8_f32 v26, v27, 2, v26
	v_fmaak_f32 v27, v25, v29, 0x43000000
	v_cvt_pk_u8_f32 v68, v68, 0, 0
	v_fmaak_f32 v69, v24, v69, 0x43000000
	v_cvt_pk_u8_f32 v26, v27, 3, v26
	ds_bpermute_b32 v27, v144, v159
	v_cvt_pk_u8_f32 v68, v69, 1, v68
	v_fmaak_f32 v69, v24, v82, 0x43000000
	ds_bpermute_b32 v28, v145, v159
	v_cvt_pk_u8_f32 v68, v69, 2, v68
	v_fmaak_f32 v69, v24, v84, 0x43000000
	ds_bpermute_b32 v29, v146, v159
	v_cvt_pk_u8_f32 v68, v69, 3, v68
	ds_bpermute_b32 v69, v147, v159
	s_waitcnt lgkmcnt(3)
	v_mul_f32_e32 v82, v168, v27
	s_waitcnt lgkmcnt(2)
	v_mul_f32_e32 v83, v164, v28
	v_fmaak_f32 v82, v22, v82, 0x43000000
	s_waitcnt lgkmcnt(1)
	v_mul_f32_e32 v80, v80, v29
	v_cvt_pk_u8_f32 v82, v82, 0, 0
	v_fmaak_f32 v83, v22, v83, 0x43000000
	s_waitcnt lgkmcnt(0)
	v_mul_f32_e32 v74, v74, v69
	v_cvt_pk_u8_f32 v82, v83, 1, v82
	v_fmaak_f32 v80, v22, v80, 0x43000000
	v_cvt_pk_u8_f32 v80, v80, 2, v82
	v_fmaak_f32 v74, v22, v74, 0x43000000
	v_cvt_pk_u8_f32 v74, v74, 3, v80
	v_xor_b32_e32 v66, 0x80808080, v66
	v_xor_b32_e32 v74, 0x80808080, v74
	ds_write2_b32 v151, v66, v74 offset1:8
	v_mul_f32_e32 v66, v169, v27
	v_mul_f32_e32 v74, v165, v28
	v_fmaak_f32 v66, v23, v66, 0x43000000
	v_mul_f32_e32 v80, v81, v29
	v_cvt_pk_u8_f32 v66, v66, 0, 0
	v_fmaak_f32 v74, v23, v74, 0x43000000
	v_mul_f32_e32 v75, v75, v69
	v_cvt_pk_u8_f32 v66, v74, 1, v66
	v_fmaak_f32 v74, v23, v80, 0x43000000
	v_cvt_pk_u8_f32 v66, v74, 2, v66
	v_fmaak_f32 v74, v23, v75, 0x43000000
	v_cvt_pk_u8_f32 v66, v74, 3, v66
	v_xor_b32_e32 v67, 0x80808080, v67
	v_xor_b32_e32 v66, 0x80808080, v66
	ds_write2_b32 v151, v67, v66 offset0:33 offset1:41
	v_mul_f32_e32 v66, v70, v27
	v_mul_f32_e32 v67, v166, v28
	v_fmaak_f32 v66, v24, v66, 0x43000000
	v_mul_f32_e32 v70, v78, v29
	v_cvt_pk_u8_f32 v66, v66, 0, 0
	v_fmaak_f32 v67, v24, v67, 0x43000000
	v_mul_f32_e32 v72, v72, v69
	v_cvt_pk_u8_f32 v66, v67, 1, v66
	v_fmaak_f32 v67, v24, v70, 0x43000000
	v_cvt_pk_u8_f32 v66, v67, 2, v66
	v_fmaak_f32 v67, v24, v72, 0x43000000
	v_mul_f32_e32 v27, v71, v27
	v_cvt_pk_u8_f32 v66, v67, 3, v66
	v_mul_f32_e32 v28, v167, v28
	v_fmaak_f32 v27, v25, v27, 0x43000000
	v_xor_b32_e32 v68, 0x80808080, v68
	v_xor_b32_e32 v66, 0x80808080, v66
	v_mul_f32_e32 v29, v79, v29
	v_cvt_pk_u8_f32 v27, v27, 0, 0
	v_fmaak_f32 v28, v25, v28, 0x43000000
	ds_write2_b32 v151, v68, v66 offset0:66 offset1:74
	v_mul_f32_e32 v66, v73, v69
	v_cvt_pk_u8_f32 v27, v28, 1, v27
	v_fmaak_f32 v28, v25, v29, 0x43000000
	v_cvt_pk_u8_f32 v27, v28, 2, v27
	v_fmaak_f32 v28, v25, v66, 0x43000000
	v_cvt_pk_u8_f32 v27, v28, 3, v27
	ds_bpermute_b32 v28, v140, v158
	ds_bpermute_b32 v29, v141, v158
	ds_bpermute_b32 v66, v142, v158
	ds_bpermute_b32 v67, v143, v158
	v_pk_mul_f32 v[20:21], v[20:21], 0.5 op_sel_hi:[1,0]
	v_pk_mul_f32 v[76:77], v[76:77], 0.5 op_sel_hi:[1,0]
	v_xor_b32_e32 v26, 0x80808080, v26
	v_xor_b32_e32 v27, 0x80808080, v27
	s_waitcnt lgkmcnt(3)
; #define LAS __attribute__((address_space(3)))
; __host__ __device__ __forceinline__ size_t blk8_off(int r, int k, int KT8_) { return ((size_t)((r >> 8) * KT8_ + (k >> 7)) * 256 + (size_t)(r & 255)) * 128 + (size_t)(k & 127); }
; #define LDS_WAIT() asm volatile("s_waitcnt lgkmcnt(0)" ::: "memory")
; template <bool STRIP, int ROT>
; __device__ __forceinline__ void gu_finish_t(f32x4 (&v)[16], float gA, float gB, const GUDesc& d, LAS unsigned* T, int lane, const float (&sinv)[4]) {
;     ...
;     for (int jq = 0; jq < 4; ++jq) {
;         float g[4];
; #pragma unroll
;         for (int e2 = 0; e2 < 4; ++e2) g[e2] = jq < 2 ? __shfl(gA, 32 * jq + 4 * kr + e2) : __shfl(gB, 32 * (jq - 2) + 4 * kr + e2);
; #pragma unroll
;         for (int e = 0; e < 4; ++e)
;             T[(4 * nq + e) * 33 + 8 * jq + kr] = pack4_i8(v[4 * jq + 0][e] * g[0] * inv[e], v[4 * jq + 1][e] * g[1] * inv[e], v[4 * jq + 2][e] * g[2] * inv[e], v[4 * jq + 3][e] * g[3] * inv[e]);
;     }
;     LDS_WAIT(); asm volatile("" ::: "memory");
;     const int nl = lane >> 3, c = lane & 7;
; #pragma unroll
;     for (int g4 = 0; g4 < 4; ++g4) {
;         const int nloc = 8 * g4 + nl, dr = d.il ? gu_dest(d.n0 + nloc, d.bj) : d.n0 + nloc;
;         const LAS unsigned* t = T + nloc * 33 + 4 * c;
;         u32x4 o; o.x = t[0]; o.y = t[1]; o.z = t[2]; o.w = t[3];
;         *(u32x4*)(d.WQ + blk8_off(dr, d.k0 + 16 * c, d.kt8)) = o;
;         if (!STRIP) if (d.k0 == 0 && c == 0) d.sb[dr] = __uint_as_float(d.cmax[dr]) * (1.0f / 127.0f);
;     }
	v_mul_f32_e32 v20, v20, v28
	v_pk_mul_f32 v[32:33], v[32:33], 0.5 op_sel_hi:[1,0]
	ds_write2_b32 v151, v26, v27 offset0:99 offset1:107
	s_waitcnt lgkmcnt(3)
	v_mul_f32_e32 v26, v76, v29
	v_fmaak_f32 v20, v22, v20, 0x43000000
	s_waitcnt lgkmcnt(2)
	v_mul_f32_e32 v27, v32, v66
	v_cvt_pk_u8_f32 v20, v20, 0, 0
	v_fmaak_f32 v26, v22, v26, 0x43000000
	s_waitcnt lgkmcnt(1)
	v_mul_f32_e32 v32, v176, v67
	v_cvt_pk_u8_f32 v20, v26, 1, v20
	v_fmaak_f32 v26, v22, v27, 0x43000000
	v_cvt_pk_u8_f32 v20, v26, 2, v20
	v_fmaak_f32 v26, v22, v32, 0x43000000
	v_mul_f32_e32 v21, v21, v28
	v_cvt_pk_u8_f32 v20, v26, 3, v20
	v_mul_f32_e32 v26, v77, v29
	v_fmaak_f32 v21, v23, v21, 0x43000000
	v_mul_f32_e32 v27, v33, v66
	v_cvt_pk_u8_f32 v21, v21, 0, 0
	v_fmaak_f32 v26, v23, v26, 0x43000000
	v_pk_mul_f32 v[18:19], v[18:19], 0.5 op_sel_hi:[1,0]
	v_mul_f32_e32 v32, v177, v67
	v_cvt_pk_u8_f32 v21, v26, 1, v21
	v_fmaak_f32 v26, v23, v27, 0x43000000
	v_pk_mul_f32 v[162:163], v[162:163], 0.5 op_sel_hi:[1,0]
	v_cvt_pk_u8_f32 v21, v26, 2, v21
	v_fmaak_f32 v26, v23, v32, 0x43000000
	v_mul_f32_e32 v18, v18, v28
	v_pk_mul_f32 v[30:31], v[30:31], 0.5 op_sel_hi:[1,0]
	v_cvt_pk_u8_f32 v21, v26, 3, v21
	v_mul_f32_e32 v26, v162, v29
	v_fmaak_f32 v18, v24, v18, 0x43000000
	v_pk_mul_f32 v[174:175], v[16:17], 0.5 op_sel_hi:[1,0]
	v_mul_f32_e32 v27, v30, v66
	v_cvt_pk_u8_f32 v18, v18, 0, 0
	v_fmaak_f32 v26, v24, v26, 0x43000000
	v_mul_f32_e32 v30, v174, v67
	v_cvt_pk_u8_f32 v18, v26, 1, v18
	v_fmaak_f32 v26, v24, v27, 0x43000000
	v_cvt_pk_u8_f32 v18, v26, 2, v18
	v_fmaak_f32 v26, v24, v30, 0x43000000
	v_mul_f32_e32 v19, v19, v28
	v_cvt_pk_u8_f32 v18, v26, 3, v18
	v_mul_f32_e32 v26, v163, v29
	v_fmaak_f32 v19, v25, v19, 0x43000000
	v_mul_f32_e32 v27, v31, v66
	v_cvt_pk_u8_f32 v19, v19, 0, 0
	v_fmaak_f32 v26, v25, v26, 0x43000000
	v_mul_f32_e32 v28, v175, v67
	v_cvt_pk_u8_f32 v19, v26, 1, v19
	v_fmaak_f32 v26, v25, v27, 0x43000000
	v_cvt_pk_u8_f32 v19, v26, 2, v19
	v_fmaak_f32 v26, v25, v28, 0x43000000
	v_cvt_pk_u8_f32 v19, v26, 3, v19
	ds_bpermute_b32 v26, v144, v158
	ds_bpermute_b32 v27, v145, v158
	ds_bpermute_b32 v28, v146, v158
	ds_bpermute_b32 v29, v147, v158
	v_pk_add_f32 v[170:171], v[4:5], v[8:9]
	v_sub_f32_e32 v9, v9, v5
	v_sub_f32_e32 v8, v8, v4
	v_pk_mul_f32 v[4:5], v[170:171], 0.5 op_sel_hi:[1,0]
	s_waitcnt lgkmcnt(3)
	v_mul_f32_e32 v2, v2, v26
	s_waitcnt lgkmcnt(2)
	v_mul_f32_e32 v4, v4, v27
	v_fmaak_f32 v2, v24, v2, 0x43000000
	v_pk_mul_f32 v[8:9], v[8:9], 0.5 op_sel_hi:[1,0]
	s_waitcnt lgkmcnt(1)
	v_mul_f32_e32 v6, v6, v28
	v_cvt_pk_u8_f32 v2, v2, 0, 0
	v_fmaak_f32 v4, v24, v4, 0x43000000
	s_waitcnt lgkmcnt(0)
	v_mul_f32_e32 v8, v8, v29
	v_cvt_pk_u8_f32 v2, v4, 1, v2
	v_fmaak_f32 v4, v24, v6, 0x43000000
	v_cvt_pk_u8_f32 v2, v4, 2, v2
	v_fmaak_f32 v4, v24, v8, 0x43000000
	v_pk_mul_f32 v[12:13], v[12:13], 0.5 op_sel_hi:[1,0]
	v_mul_f32_e32 v10, v10, v26
	v_cvt_pk_u8_f32 v2, v4, 3, v2
	v_xor_b32_e32 v18, 0x80808080, v18
	v_mul_f32_e32 v12, v12, v27
	v_fmaak_f32 v10, v22, v10, 0x43000000
	v_xor_b32_e32 v2, 0x80808080, v2
	v_pk_mul_f32 v[16:17], v[172:173], 0.5 op_sel_hi:[1,0]
	v_mul_f32_e32 v14, v14, v28
	v_cvt_pk_u8_f32 v10, v10, 0, 0
	v_fmaak_f32 v12, v22, v12, 0x43000000
	ds_write2_b32 v151, v18, v2 offset0:82 offset1:90
	v_mul_f32_e32 v2, v3, v26
	v_mul_f32_e32 v16, v16, v29
	v_cvt_pk_u8_f32 v10, v12, 1, v10
	v_fmaak_f32 v12, v22, v14, 0x43000000
	v_mul_f32_e32 v3, v5, v27
	v_fmaak_f32 v2, v25, v2, 0x43000000
	v_cvt_pk_u8_f32 v10, v12, 2, v10
	v_fmaak_f32 v12, v22, v16, 0x43000000
	v_mul_f32_e32 v4, v7, v28
	v_cvt_pk_u8_f32 v2, v2, 0, 0
	v_fmaak_f32 v3, v25, v3, 0x43000000
	v_cvt_pk_u8_f32 v10, v12, 3, v10
	v_mul_f32_e32 v5, v9, v29
	v_cvt_pk_u8_f32 v2, v3, 1, v2
	v_fmaak_f32 v3, v25, v4, 0x43000000
	v_xor_b32_e32 v20, 0x80808080, v20
	v_xor_b32_e32 v10, 0x80808080, v10
	v_cvt_pk_u8_f32 v2, v3, 2, v2
	v_fmaak_f32 v3, v25, v5, 0x43000000
	ds_write2_b32 v151, v20, v10 offset0:16 offset1:24
	v_mul_f32_e32 v10, v11, v26
	v_cvt_pk_u8_f32 v2, v3, 3, v2
	v_xor_b32_e32 v19, 0x80808080, v19
	v_mul_f32_e32 v11, v13, v27
	v_fmaak_f32 v10, v23, v10, 0x43000000
	v_xor_b32_e32 v2, 0x80808080, v2
	v_mul_f32_e32 v12, v15, v28
	v_cvt_pk_u8_f32 v10, v10, 0, 0
	v_fmaak_f32 v11, v23, v11, 0x43000000
	ds_write2_b32 v151, v19, v2 offset0:115 offset1:123
	v_add_u32_e32 v2, s0, v1
	v_mul_f32_e32 v13, v17, v29
	v_cvt_pk_u8_f32 v10, v11, 1, v10
	v_fmaak_f32 v11, v23, v12, 0x43000000
	v_lshlrev_b32_e32 v3, 1, v2
	v_cvt_pk_u8_f32 v10, v11, 2, v10
	v_fmaak_f32 v11, v23, v13, 0x43000000
	v_and_b32_e32 v3, 0xffffff00, v3
	v_cvt_pk_u8_f32 v10, v11, 3, v10
	v_add_u32_e32 v3, s1, v3
	v_xor_b32_e32 v21, 0x80808080, v21
	v_xor_b32_e32 v10, 0x80808080, v10
	v_and_or_b32 v3, v2, s48, v3
	ds_write2_b32 v151, v21, v10 offset0:49 offset1:57
	v_cndmask_b32_e64 v2, v3, v2, s[4:5]
	v_add_u32_e32 v3, s31, v132
	s_waitcnt lgkmcnt(0)
	v_lshrrev_b32_e32 v5, 8, v2
	v_ashrrev_i32_e32 v4, 7, v3
	v_mad_i32_i24 v10, v5, s34, v4
	ds_read2_b32 v[6:7], v152 offset1:1
	ds_read2_b32 v[8:9], v152 offset0:2 offset1:3
	v_ashrrev_i32_e32 v11, 31, v10
	v_lshlrev_b64 v[10:11], 15, v[10:11]
	v_lshlrev_b32_e32 v5, 7, v2
	v_and_b32_e32 v12, 0x7f80, v5
	v_mov_b32_e32 v13, v131
	v_lshl_add_u64 v[10:11], s[22:23], 0, v[10:11]
	v_and_b32_e32 v130, 0x7f, v3
	v_lshl_add_u64 v[10:11], v[10:11], 0, v[12:13]
	v_or_b32_e32 v3, s31, v138
	v_lshl_add_u64 v[10:11], v[10:11], 0, v[130:131]
	v_cmp_eq_u32_e32 vcc, 0, v3
	s_waitcnt lgkmcnt(0)
	global_store_dwordx4 v[10:11], v[6:9], off
	s_and_saveexec_b64 s[24:25], vcc
	s_cbranch_execz .LBB0_1228
	v_ashrrev_i32_e32 v3, 31, v2
	v_lshlrev_b64 v[2:3], 2, v[2:3]
	v_lshl_add_u64 v[6:7], s[6:7], 0, v[2:3]
	global_load_dword v5, v[6:7], off
	v_lshl_add_u64 v[2:3], s[16:17], 0, v[2:3]
	s_waitcnt vmcnt(0)
	v_mul_f32_e32 v5, 0x3c010204, v5
	global_store_dword v[2:3], v5, off

; #define LAS __attribute__((address_space(3)))
; __device__ __forceinline__ float bfly8(float x, bool up) { const float p = __uint_as_float(__builtin_amdgcn_update_dpp(0u, __float_as_uint(x), 0x128, 0xf, 0xf, false)); return up ? p - x : x + p; }
; __device__ __forceinline__ void gu_load(f32x4 (&v)[16], float& gA, float& gB, const GUDesc& d, int lane) {
;     const int kr = lane >> 3, nq = lane & 7;
;     const float* __restrict__ src = d.W + (size_t)(d.k0 + 4 * kr) * d.N + d.n0 + 4 * nq;
;     gA = d.gain ? d.gain[d.k0 + lane] : 1.0f; gB = d.gain ? d.gain[d.k0 + 64 + lane] : 1.0f;
; #pragma unroll
;     for (int i = 0; i < 16; ++i) v[i] = *(const f32x4*)(src + (size_t)(32 * (i >> 2) + (i & 3)) * d.N);
; }
; template <int ROT>
; __device__ __forceinline__ void rot32_tile(f32x4 (&v)[16], int lane) {
; #pragma unroll
;     for (int jq = 0; jq < 4; ++jq) {
;         const f32x4 a = v[4 * jq], b = v[4 * jq + 1], c = v[4 * jq + 2], d = v[4 * jq + 3];
;         const f32x4 a1 = a + b, b1 = a - b, c1 = c + d, d1 = c - d;
;         if (ROT >= 2) { v[4 * jq] = a1 + c1; v[4 * jq + 2] = a1 - c1; v[4 * jq + 1] = b1 + d1; v[4 * jq + 3] = b1 - d1; }
;         else { v[4 * jq] = a1; v[4 * jq + 1] = b1; v[4 * jq + 2] = c1; v[4 * jq + 3] = d1; }
;     }
;     { const bool s8 = (lane & 8) != 0, s16 = (lane & 16) != 0, s32 = (lane & 32) != 0;
; #pragma unroll
;       for (int i = 0; i < 16; ++i)
; #pragma unroll
;           for (int e = 0; e < 4; ++e) { float x = v[i][e]; if (ROT >= 3) x = bfly8(x, s8); if (ROT >= 4) x = bfly16(x, s16); if (ROT >= 5) x = bfly32(x, s32); v[i][e] = x; } }
; #pragma unroll
;     for (int i = 0; i < 16; ++i) v[i] *= (ROT == 1 ? 0.70710678118654752f : ROT == 2 ? 0.5f : ROT == 3 ? 0.35355339059327373f : ROT == 4 ? 0.25f : 0.17677669529663687f);
; }
; template <bool STRIP, int ROT>
; __device__ __forceinline__ void gu_finish_t(f32x4 (&v)[16], float gA, float gB, const GUDesc& d, LAS unsigned* T, int lane, const float (&sinv)[4]) {
;     const int kr = lane >> 3, nq = lane & 7;
;     const int dq0 = d.il ? gu_dest(d.n0 + 4 * nq, d.bj) : d.n0 + 4 * nq;
;     if (ROT) rot32_tile<ROT>(v, lane);
;     float inv[4];
; #pragma unroll
;     for (int e = 0; e < 4; ++e) { if (STRIP) inv[e] = sinv[e]; else { const float cm = __uint_as_float(d.cmax[dq0 + e]); inv[e] = cm > 0.f ? 127.0f / cm : 0.f; } }
.LBB0_1247:
	v_or_b32_e32 v2, s31, v137
	v_mul_hi_i32_i24_e32 v3, s22, v2
	v_mul_i32_i24_e32 v2, s22, v2
	s_ashr_i32 s1, s0, 31
	s_waitcnt lgkmcnt(0)
	v_lshl_add_u64 v[2:3], v[2:3], 2, v[4:5]
	v_lshl_add_u64 v[2:3], s[0:1], 2, v[2:3]
	v_mov_b32_e32 v135, v131
	s_lshl_b32 s8, s22, 2
	v_lshl_add_u64 v[2:3], v[2:3], 0, v[134:135]
	v_lshl_add_u64 v[4:5], v[2:3], 0, s[8:9]
	global_load_dwordx4 v[94:97], v[2:3], off nt
	global_load_dwordx4 v[90:93], v[4:5], off nt
	v_lshl_add_u64 v[2:3], v[4:5], 0, s[8:9]
	v_lshl_add_u64 v[4:5], v[2:3], 0, s[8:9]
	s_mulk_i32 s22, 0x74
	s_mov_b32 s23, s9
	global_load_dwordx4 v[86:89], v[2:3], off nt
	global_load_dwordx4 v[82:85], v[4:5], off nt
	v_lshl_add_u64 v[2:3], v[4:5], 0, s[22:23]
	v_lshl_add_u64 v[4:5], v[2:3], 0, s[8:9]
	global_load_dwordx4 v[78:81], v[2:3], off nt
	global_load_dwordx4 v[74:77], v[4:5], off nt
	v_lshl_add_u64 v[2:3], v[4:5], 0, s[8:9]
	v_lshl_add_u64 v[4:5], v[2:3], 0, s[8:9]
	global_load_dwordx4 v[70:73], v[2:3], off nt
	global_load_dwordx4 v[66:69], v[4:5], off nt
	v_lshl_add_u64 v[2:3], v[4:5], 0, s[22:23]
	global_load_dwordx4 v[30:33], v[2:3], off nt
	v_lshl_add_u64 v[2:3], v[2:3], 0, s[8:9]
	global_load_dwordx4 v[26:29], v[2:3], off nt
	v_lshl_add_u64 v[2:3], v[2:3], 0, s[8:9]
	global_load_dwordx4 v[18:21], v[2:3], off nt
	v_lshl_add_u64 v[2:3], v[2:3], 0, s[8:9]
	global_load_dwordx4 v[14:17], v[2:3], off nt
	v_lshl_add_u64 v[2:3], v[2:3], 0, s[22:23]
	global_load_dwordx4 v[10:13], v[2:3], off nt
	v_lshl_add_u64 v[2:3], v[2:3], 0, s[8:9]
	v_lshl_add_u64 v[22:23], v[2:3], 0, s[8:9]
	global_load_dwordx4 v[6:9], v[2:3], off nt
	s_cmp_ge_i32 s55, s28
	global_load_dwordx4 v[2:5], v[22:23], off nt
	v_lshl_add_u64 v[22:23], v[22:23], 0, s[8:9]
	global_load_dwordx4 v[22:25], v[22:23], off nt
	s_cbranch_scc1 .LBB0_1214
	s_add_u32 s22, s78, s18
	s_addc_u32 s23, s79, s19
	s_add_u32 s18, s29, s20
	s_addc_u32 s19, s30, s21
	s_lshl_b32 s1, s12, 1
	s_and_b32 s1, s1, 0xffffff00
	v_bitop3_b32 v135, s12, v153, v139 bitop3:0xc8
	v_or_b32_e32 v135, s1, v135
	v_or_b32_e32 v130, s12, v139
	v_or_b32_e32 v135, s15, v135
	v_cndmask_b32_e64 v168, v135, v130, s[2:3]
	v_pk_add_f32 v[170:171], v[124:125], v[128:129]
	v_pk_add_f32 v[172:173], v[122:123], v[126:127]
	v_sub_f32_e32 v125, v125, v129
	v_sub_f32_e32 v124, v124, v128
	v_sub_f32_e32 v123, v123, v127
	v_sub_f32_e32 v122, v122, v126
	v_pk_add_f32 v[126:127], v[116:117], v[120:121]
	v_pk_add_f32 v[128:129], v[114:115], v[118:119]
	v_sub_f32_e32 v175, v117, v121
	v_sub_f32_e32 v174, v116, v120
	v_sub_f32_e32 v177, v115, v119
	v_sub_f32_e32 v176, v114, v118
	v_pk_add_f32 v[118:119], v[170:171], v[126:127]
	v_pk_add_f32 v[120:121], v[172:173], v[128:129]
	v_sub_f32_e32 v115, v171, v127
	v_sub_f32_e32 v114, v170, v126
	v_sub_f32_e32 v117, v173, v129
	v_sub_f32_e32 v116, v172, v128
	v_pk_add_f32 v[170:171], v[108:109], v[112:113]
	v_pk_add_f32 v[172:173], v[106:107], v[110:111]
	v_sub_f32_e32 v109, v109, v113
	v_sub_f32_e32 v108, v108, v112
	v_sub_f32_e32 v107, v107, v111
	v_sub_f32_e32 v106, v106, v110
	v_pk_add_f32 v[110:111], v[100:101], v[104:105]
	v_pk_add_f32 v[112:113], v[98:99], v[102:103]
	v_sub_f32_e32 v99, v99, v103
	v_sub_f32_e32 v98, v98, v102
	v_ashrrev_i32_e32 v169, 31, v168
	v_pk_add_f32 v[102:103], v[170:171], v[110:111]
	v_sub_f32_e32 v111, v171, v111
	v_sub_f32_e32 v110, v170, v110
	v_pk_add_f32 v[170:171], v[106:107], v[98:99]
	v_sub_f32_e32 v107, v107, v99
	v_sub_f32_e32 v106, v106, v98
	v_lshl_add_u64 v[98:99], v[168:169], 2, s[10:11]
	v_sub_f32_e32 v105, v101, v105
	v_sub_f32_e32 v104, v100, v104
	global_load_dwordx4 v[98:101], v[98:99], off nt
	v_pk_add_f32 v[128:129], v[124:125], v[174:175]
	v_sub_f32_e32 v125, v125, v175
	v_sub_f32_e32 v124, v124, v174
	v_pk_add_f32 v[174:175], v[172:173], v[112:113]
	v_sub_f32_e32 v113, v173, v113
	v_sub_f32_e32 v112, v172, v112
	v_pk_add_f32 v[172:173], v[108:109], v[104:105]
	v_sub_f32_e32 v105, v109, v105
	v_sub_f32_e32 v104, v108, v104
	v_pk_add_f32 v[108:109], v[56:57], v[64:65]
	v_pk_add_f32 v[168:169], v[54:55], v[62:63]
	v_sub_f32_e32 v57, v57, v65
	v_sub_f32_e32 v56, v56, v64
	v_sub_f32_e32 v55, v55, v63
	v_sub_f32_e32 v54, v54, v62
	v_pk_add_f32 v[62:63], v[52:53], v[60:61]
	v_pk_add_f32 v[64:65], v[50:51], v[58:59]
	v_sub_f32_e32 v53, v53, v61
	v_sub_f32_e32 v52, v52, v60
	v_sub_f32_e32 v51, v51, v59
	v_sub_f32_e32 v50, v50, v58
	v_pk_add_f32 v[58:59], v[108:109], v[62:63]
	v_pk_add_f32 v[60:61], v[168:169], v[64:65]
	v_sub_f32_e32 v63, v109, v63
	v_sub_f32_e32 v62, v108, v62
	v_sub_f32_e32 v65, v169, v65
	v_sub_f32_e32 v64, v168, v64
	v_pk_add_f32 v[108:109], v[54:55], v[50:51]
	v_pk_add_f32 v[168:169], v[56:57], v[52:53]
	v_sub_f32_e32 v51, v55, v51
	v_sub_f32_e32 v50, v54, v50
	v_sub_f32_e32 v53, v57, v53
	v_sub_f32_e32 v52, v56, v52
	s_waitcnt vmcnt(23)
	v_pk_add_f32 v[54:55], v[40:41], v[48:49]
	v_pk_add_f32 v[56:57], v[38:39], v[46:47]
	v_sub_f32_e32 v41, v41, v49
	v_sub_f32_e32 v40, v40, v48
	v_sub_f32_e32 v39, v39, v47
	v_sub_f32_e32 v38, v38, v46
	s_waitcnt vmcnt(21)
; #define LAS __attribute__((address_space(3)))
; __device__ __forceinline__ float bfly8(float x, bool up) { const float p = __uint_as_float(__builtin_amdgcn_update_dpp(0u, __float_as_uint(x), 0x128, 0xf, 0xf, false)); return up ? p - x : x + p; }
; __device__ __forceinline__ float bfly16(float x, bool up) { const auto r = __builtin_amdgcn_permlane16_swap(__float_as_uint(x), __float_as_uint(x), false, false); const float a = __uint_as_float(r[0]), b = __uint_as_float(r[1]); return up ? a - b : a + b; }
; __device__ __forceinline__ float bfly32(float x, bool up) { const auto r = __builtin_amdgcn_permlane32_swap(__float_as_uint(x), __float_as_uint(x), false, false); const float a = __uint_as_float(r[0]), b = __uint_as_float(r[1]); return up ? a - b : a + b; }
; template <int ROT>
; __device__ __forceinline__ void rot32_tile(f32x4 (&v)[16], int lane) {
;     ...
;           for (int e = 0; e < 4; ++e) { float x = v[i][e]; if (ROT >= 3) x = bfly8(x, s8); if (ROT >= 4) x = bfly16(x, s16); if (ROT >= 5) x = bfly32(x, s32); v[i][e] = x; } }
; #pragma unroll
;     for (int i = 0; i < 16; ++i) v[i] *= (ROT == 1 ? 0.70710678118654752f : ROT == 2 ? 0.5f : ROT == 3 ? 0.35355339059327373f : ROT == 4 ? 0.25f : 0.17677669529663687f);
; }
; template <bool STRIP, int ROT>
; __device__ __forceinline__ void gu_finish_t(f32x4 (&v)[16], float gA, float gB, const GUDesc& d, LAS unsigned* T, int lane, const float (&sinv)[4]) {
;     const int kr = lane >> 3, nq = lane & 7;
;     const int dq0 = d.il ? gu_dest(d.n0 + 4 * nq, d.bj) : d.n0 + 4 * nq;
;     if (ROT) rot32_tile<ROT>(v, lane);
;     float inv[4];
; #pragma unroll
;     for (int e = 0; e < 4; ++e) { if (STRIP) inv[e] = sinv[e]; else { const float cm = __uint_as_float(d.cmax[dq0 + e]); inv[e] = cm > 0.f ? 127.0f / cm : 0.f; } }
; #pragma unroll
;     for (int jq = 0; jq < 4; ++jq) {
;         float g[4];
; #pragma unroll
;         for (int e2 = 0; e2 < 4; ++e2) g[e2] = jq < 2 ? __shfl(gA, 32 * jq + 4 * kr + e2) : __shfl(gB, 32 * (jq - 2) + 4 * kr + e2);
; #pragma unroll
;         for (int e = 0; e < 4; ++e)
;             T[(4 * nq + e) * 33 + 8 * jq + kr] = pack4_i8(v[4 * jq + 0][e] * g[0] * inv[e], v[4 * jq + 1][e] * g[1] * inv[e], v[4 * jq + 2][e] * g[2] * inv[e], v[4 * jq + 3][e] * g[3] * inv[e]);
	v_pk_add_f32 v[46:47], v[36:37], v[44:45]
	v_pk_add_f32 v[48:49], v[34:35], v[42:43]
	v_sub_f32_e32 v35, v35, v43
	v_sub_f32_e32 v34, v34, v42
	v_sub_f32_e32 v37, v37, v45
	v_sub_f32_e32 v36, v36, v44
	v_pk_add_f32 v[42:43], v[54:55], v[46:47]
	v_pk_add_f32 v[44:45], v[56:57], v[48:49]
	v_sub_f32_e32 v47, v55, v47
	v_sub_f32_e32 v46, v54, v46
	v_pk_add_f32 v[54:55], v[38:39], v[34:35]
	v_pk_add_f32 v[126:127], v[122:123], v[176:177]
	v_sub_f32_e32 v123, v123, v177
	v_sub_f32_e32 v122, v122, v176
	v_sub_f32_e32 v177, v39, v35
	v_sub_f32_e32 v176, v38, v34
	v_pk_mul_f32 v[34:35], v[42:43], 0.5 op_sel_hi:[1,0]
	v_pk_mul_f32 v[42:43], v[44:45], 0.5 op_sel_hi:[1,0]
	v_pk_mul_f32 v[44:45], v[54:55], 0.5 op_sel_hi:[1,0]
	v_sub_f32_e32 v49, v57, v49
	v_sub_f32_e32 v48, v56, v48
	v_pk_add_f32 v[56:57], v[40:41], v[36:37]
	v_sub_f32_e32 v41, v41, v37
	v_sub_f32_e32 v40, v40, v36
	v_pk_mul_f32 v[36:37], v[56:57], 0.5 op_sel_hi:[1,0]
	v_pk_mul_f32 v[120:121], v[120:121], 0.5 op_sel_hi:[1,0]
	v_pk_mul_f32 v[126:127], v[126:127], 0.5 op_sel_hi:[1,0]
	v_pk_mul_f32 v[116:117], v[116:117], 0.5 op_sel_hi:[1,0]
	v_pk_mul_f32 v[122:123], v[122:123], 0.5 op_sel_hi:[1,0]
	v_pk_mul_f32 v[118:119], v[118:119], 0.5 op_sel_hi:[1,0]
	v_pk_mul_f32 v[128:129], v[128:129], 0.5 op_sel_hi:[1,0]
	v_pk_mul_f32 v[114:115], v[114:115], 0.5 op_sel_hi:[1,0]
	v_pk_mul_f32 v[124:125], v[124:125], 0.5 op_sel_hi:[1,0]
	v_pk_mul_f32 v[174:175], v[174:175], 0.5 op_sel_hi:[1,0]
	v_pk_mul_f32 v[170:171], v[170:171], 0.5 op_sel_hi:[1,0]
	v_pk_mul_f32 v[112:113], v[112:113], 0.5 op_sel_hi:[1,0]
	v_pk_mul_f32 v[106:107], v[106:107], 0.5 op_sel_hi:[1,0]
	v_pk_mul_f32 v[102:103], v[102:103], 0.5 op_sel_hi:[1,0]
	v_pk_mul_f32 v[172:173], v[172:173], 0.5 op_sel_hi:[1,0]
	v_pk_mul_f32 v[110:111], v[110:111], 0.5 op_sel_hi:[1,0]
	s_waitcnt vmcnt(0)
	v_div_scale_f32 v54, s[20:21], v98, v98, s49
	v_rcp_f32_e32 v55, v54
	v_pk_mul_f32 v[104:105], v[104:105], 0.5 op_sel_hi:[1,0]
	v_pk_mul_f32 v[60:61], v[60:61], 0.5 op_sel_hi:[1,0]
	v_pk_mul_f32 v[108:109], v[108:109], 0.5 op_sel_hi:[1,0]
	v_fma_f32 v56, -v54, v55, 1.0
	v_fmac_f32_e32 v55, v56, v55
	v_div_scale_f32 v56, vcc, s49, v98, s49
	v_mul_f32_e32 v57, v56, v55
	v_fma_f32 v130, -v54, v57, v56
	v_fmac_f32_e32 v57, v130, v55
	v_fma_f32 v54, -v54, v57, v56
	v_div_fmas_f32 v54, v54, v55, v57
	v_div_scale_f32 v55, s[20:21], v99, v99, s49
	v_rcp_f32_e32 v56, v55
	v_div_fixup_f32 v54, v54, v98, s49
	v_cmp_lt_f32_e32 vcc, 0, v98
	v_pk_mul_f32 v[64:65], v[64:65], 0.5 op_sel_hi:[1,0]
	v_fma_f32 v57, -v55, v56, 1.0
	v_cndmask_b32_e32 v54, 0, v54, vcc
	v_fmac_f32_e32 v56, v57, v56
	v_div_scale_f32 v57, vcc, s49, v99, s49
	v_mul_f32_e32 v98, v57, v56
	v_fma_f32 v130, -v55, v98, v57
	v_fmac_f32_e32 v98, v130, v56
	v_fma_f32 v55, -v55, v98, v57
	v_div_fmas_f32 v55, v55, v56, v98
	v_div_scale_f32 v56, s[20:21], v100, v100, s49
	v_rcp_f32_e32 v57, v56
	v_div_fixup_f32 v55, v55, v99, s49
	v_cmp_lt_f32_e32 vcc, 0, v99
	v_pk_mul_f32 v[50:51], v[50:51], 0.5 op_sel_hi:[1,0]
	v_fma_f32 v98, -v56, v57, 1.0
	v_cndmask_b32_e32 v55, 0, v55, vcc
	v_fmac_f32_e32 v57, v98, v57
	v_div_scale_f32 v98, vcc, s49, v100, s49
	v_mul_f32_e32 v99, v98, v57
	v_fma_f32 v130, -v56, v99, v98
	v_fmac_f32_e32 v99, v130, v57
	v_fma_f32 v56, -v56, v99, v98
	v_div_fmas_f32 v56, v56, v57, v99
	v_div_scale_f32 v57, s[20:21], v101, v101, s49
	v_rcp_f32_e32 v98, v57
	v_div_fixup_f32 v56, v56, v100, s49
	v_cmp_lt_f32_e32 vcc, 0, v100
	v_pk_mul_f32 v[58:59], v[58:59], 0.5 op_sel_hi:[1,0]
	v_fma_f32 v99, -v57, v98, 1.0
	v_cndmask_b32_e32 v56, 0, v56, vcc
	v_fmac_f32_e32 v98, v99, v98
	v_div_scale_f32 v99, vcc, s49, v101, s49
	v_mul_f32_e32 v100, v99, v98
	v_fma_f32 v130, -v57, v100, v99
	v_fmac_f32_e32 v100, v130, v98
	v_fma_f32 v57, -v57, v100, v99
	v_div_fmas_f32 v57, v57, v98, v100
	ds_bpermute_b32 v98, v140, v161
	ds_bpermute_b32 v99, v141, v161
	ds_bpermute_b32 v100, v142, v161
	ds_bpermute_b32 v130, v143, v161
	v_div_fixup_f32 v57, v57, v101, s49
	v_cmp_lt_f32_e32 vcc, 0, v101
	s_waitcnt lgkmcnt(3)
	v_mul_f32_e32 v101, v120, v98
	s_waitcnt lgkmcnt(2)
	v_mul_f32_e32 v120, v126, v99
	v_fmaak_f32 v101, v54, v101, 0x43000000
	s_waitcnt lgkmcnt(1)
	v_mul_f32_e32 v116, v116, v100
	v_cvt_pk_u8_f32 v101, v101, 0, 0
	v_fmaak_f32 v120, v54, v120, 0x43000000
	s_waitcnt lgkmcnt(0)
	v_mul_f32_e32 v122, v122, v130
	v_cvt_pk_u8_f32 v101, v120, 1, v101
	v_fmaak_f32 v116, v54, v116, 0x43000000
	v_cvt_pk_u8_f32 v101, v116, 2, v101
	v_fmaak_f32 v116, v54, v122, 0x43000000
	v_cvt_pk_u8_f32 v101, v116, 3, v101
	v_mul_f32_e32 v116, v121, v98
	v_mul_f32_e32 v120, v127, v99
	v_fmaak_f32 v116, v55, v116, 0x43000000
	v_mul_f32_e32 v117, v117, v100
	v_cvt_pk_u8_f32 v116, v116, 0, 0
	v_fmaak_f32 v120, v55, v120, 0x43000000
	v_mul_f32_e32 v121, v123, v130
	v_cvt_pk_u8_f32 v116, v120, 1, v116
	v_fmaak_f32 v117, v55, v117, 0x43000000
	v_cvt_pk_u8_f32 v116, v117, 2, v116
	v_fmaak_f32 v117, v55, v121, 0x43000000
	v_cndmask_b32_e32 v57, 0, v57, vcc
	v_cvt_pk_u8_f32 v116, v117, 3, v116
	v_mul_f32_e32 v117, v118, v98
	v_mul_f32_e32 v98, v119, v98
	v_mul_f32_e32 v118, v128, v99
	v_mul_f32_e32 v99, v129, v99
	v_fmaak_f32 v98, v57, v98, 0x43000000
	v_mul_f32_e32 v114, v114, v100
	v_mul_f32_e32 v100, v115, v100
	v_cvt_pk_u8_f32 v98, v98, 0, 0
	v_fmaak_f32 v99, v57, v99, 0x43000000
	v_mul_f32_e32 v115, v125, v130
	v_cvt_pk_u8_f32 v98, v99, 1, v98
	v_fmaak_f32 v99, v57, v100, 0x43000000
	v_fmaak_f32 v117, v56, v117, 0x43000000
	v_cvt_pk_u8_f32 v98, v99, 2, v98
	v_fmaak_f32 v99, v57, v115, 0x43000000
	v_cvt_pk_u8_f32 v117, v117, 0, 0
	v_fmaak_f32 v118, v56, v118, 0x43000000
	v_cvt_pk_u8_f32 v98, v99, 3, v98
	ds_bpermute_b32 v99, v144, v161
	v_mul_f32_e32 v120, v124, v130
	v_cvt_pk_u8_f32 v117, v118, 1, v117
	v_fmaak_f32 v114, v56, v114, 0x43000000
	ds_bpermute_b32 v100, v145, v161
	v_cvt_pk_u8_f32 v114, v114, 2, v117
	v_fmaak_f32 v117, v56, v120, 0x43000000
	ds_bpermute_b32 v115, v146, v161
	v_cvt_pk_u8_f32 v114, v117, 3, v114
	ds_bpermute_b32 v117, v147, v161
	s_waitcnt lgkmcnt(3)
; template <bool STRIP, int ROT>
; __device__ __forceinline__ void gu_finish_t(f32x4 (&v)[16], float gA, float gB, const GUDesc& d, LAS unsigned* T, int lane, const float (&sinv)[4]) {
;     ...
;     for (int jq = 0; jq < 4; ++jq) {
;         float g[4];
; #pragma unroll
;         for (int e2 = 0; e2 < 4; ++e2) g[e2] = jq < 2 ? __shfl(gA, 32 * jq + 4 * kr + e2) : __shfl(gB, 32 * (jq - 2) + 4 * kr + e2);
; #pragma unroll
;         for (int e = 0; e < 4; ++e)
;             T[(4 * nq + e) * 33 + 8 * jq + kr] = pack4_i8(v[4 * jq + 0][e] * g[0] * inv[e], v[4 * jq + 1][e] * g[1] * inv[e], v[4 * jq + 2][e] * g[2] * inv[e], v[4 * jq + 3][e] * g[3] * inv[e]);
;     }
	v_mul_f32_e32 v118, v174, v99
	s_waitcnt lgkmcnt(2)
	v_mul_f32_e32 v119, v170, v100
	v_fmaak_f32 v118, v54, v118, 0x43000000
	s_waitcnt lgkmcnt(1)
	v_mul_f32_e32 v112, v112, v115
	v_cvt_pk_u8_f32 v118, v118, 0, 0
	v_fmaak_f32 v119, v54, v119, 0x43000000
	s_waitcnt lgkmcnt(0)
	v_mul_f32_e32 v106, v106, v117
	v_cvt_pk_u8_f32 v118, v119, 1, v118
	v_fmaak_f32 v112, v54, v112, 0x43000000
	v_cvt_pk_u8_f32 v112, v112, 2, v118
	v_fmaak_f32 v106, v54, v106, 0x43000000
	v_cvt_pk_u8_f32 v106, v106, 3, v112
	v_xor_b32_e32 v101, 0x80808080, v101
	v_xor_b32_e32 v106, 0x80808080, v106
	ds_write2_b32 v151, v101, v106 offset1:8
	v_mul_f32_e32 v101, v175, v99
	v_mul_f32_e32 v106, v171, v100
	v_fmaak_f32 v101, v55, v101, 0x43000000
	v_mul_f32_e32 v112, v113, v115
	v_cvt_pk_u8_f32 v101, v101, 0, 0
	v_fmaak_f32 v106, v55, v106, 0x43000000
	v_mul_f32_e32 v107, v107, v117
	v_cvt_pk_u8_f32 v101, v106, 1, v101
	v_fmaak_f32 v106, v55, v112, 0x43000000
	v_cvt_pk_u8_f32 v101, v106, 2, v101
	v_fmaak_f32 v106, v55, v107, 0x43000000
	v_cvt_pk_u8_f32 v101, v106, 3, v101
	v_xor_b32_e32 v116, 0x80808080, v116
	v_xor_b32_e32 v101, 0x80808080, v101
	ds_write2_b32 v151, v116, v101 offset0:33 offset1:41
	v_mul_f32_e32 v101, v102, v99
	v_mul_f32_e32 v102, v172, v100
	v_fmaak_f32 v101, v56, v101, 0x43000000
	v_mul_f32_e32 v106, v110, v115
	v_cvt_pk_u8_f32 v101, v101, 0, 0
	v_fmaak_f32 v102, v56, v102, 0x43000000
	v_mul_f32_e32 v104, v104, v117
	v_cvt_pk_u8_f32 v101, v102, 1, v101
	v_fmaak_f32 v102, v56, v106, 0x43000000
	v_cvt_pk_u8_f32 v101, v102, 2, v101
	v_fmaak_f32 v102, v56, v104, 0x43000000
	v_cvt_pk_u8_f32 v101, v102, 3, v101
	v_mul_f32_e32 v99, v103, v99
	v_xor_b32_e32 v114, 0x80808080, v114
	v_xor_b32_e32 v101, 0x80808080, v101
	v_mul_f32_e32 v100, v173, v100
	v_fmaak_f32 v99, v57, v99, 0x43000000
	ds_write2_b32 v151, v114, v101 offset0:66 offset1:74
	v_mul_f32_e32 v101, v111, v115
	v_cvt_pk_u8_f32 v99, v99, 0, 0
	v_fmaak_f32 v100, v57, v100, 0x43000000
	v_mul_f32_e32 v102, v105, v117
	v_cvt_pk_u8_f32 v99, v100, 1, v99
	v_fmaak_f32 v100, v57, v101, 0x43000000
	v_cvt_pk_u8_f32 v99, v100, 2, v99
	v_fmaak_f32 v100, v57, v102, 0x43000000
	v_cvt_pk_u8_f32 v99, v100, 3, v99
	ds_bpermute_b32 v100, v140, v160
	ds_bpermute_b32 v101, v141, v160
	ds_bpermute_b32 v102, v142, v160
	ds_bpermute_b32 v103, v143, v160
	v_xor_b32_e32 v98, 0x80808080, v98
	v_xor_b32_e32 v99, 0x80808080, v99
	s_waitcnt lgkmcnt(3)
	v_mul_f32_e32 v60, v60, v100
	ds_write2_b32 v151, v98, v99 offset0:99 offset1:107
	s_waitcnt lgkmcnt(3)
	v_mul_f32_e32 v98, v108, v101
	v_fmaak_f32 v60, v54, v60, 0x43000000
	s_waitcnt lgkmcnt(2)
	v_mul_f32_e32 v64, v64, v102
	v_cvt_pk_u8_f32 v60, v60, 0, 0
	v_fmaak_f32 v98, v54, v98, 0x43000000
	s_waitcnt lgkmcnt(1)
	v_mul_f32_e32 v50, v50, v103
	v_cvt_pk_u8_f32 v60, v98, 1, v60
	v_fmaak_f32 v64, v54, v64, 0x43000000
	v_cvt_pk_u8_f32 v60, v64, 2, v60
	v_fmaak_f32 v50, v54, v50, 0x43000000
	v_cvt_pk_u8_f32 v50, v50, 3, v60
	v_mul_f32_e32 v60, v61, v100
	v_mul_f32_e32 v61, v109, v101
	v_fmaak_f32 v60, v55, v60, 0x43000000
	v_mul_f32_e32 v64, v65, v102
	v_cvt_pk_u8_f32 v60, v60, 0, 0
	v_fmaak_f32 v61, v55, v61, 0x43000000
	v_mul_f32_e32 v51, v51, v103
	v_cvt_pk_u8_f32 v60, v61, 1, v60
	v_fmaak_f32 v61, v55, v64, 0x43000000
	v_pk_mul_f32 v[168:169], v[168:169], 0.5 op_sel_hi:[1,0]
	v_cvt_pk_u8_f32 v60, v61, 2, v60
	v_fmaak_f32 v51, v55, v51, 0x43000000
	v_mul_f32_e32 v58, v58, v100
	v_pk_mul_f32 v[62:63], v[62:63], 0.5 op_sel_hi:[1,0]
	v_cvt_pk_u8_f32 v51, v51, 3, v60
	v_mul_f32_e32 v60, v168, v101
	v_fmaak_f32 v58, v56, v58, 0x43000000
	v_pk_mul_f32 v[52:53], v[52:53], 0.5 op_sel_hi:[1,0]
	v_mul_f32_e32 v61, v62, v102
	v_cvt_pk_u8_f32 v58, v58, 0, 0
	v_fmaak_f32 v60, v56, v60, 0x43000000
	v_mul_f32_e32 v52, v52, v103
	v_cvt_pk_u8_f32 v58, v60, 1, v58
	v_fmaak_f32 v60, v56, v61, 0x43000000
	v_cvt_pk_u8_f32 v58, v60, 2, v58
	v_fmaak_f32 v52, v56, v52, 0x43000000
	v_cvt_pk_u8_f32 v52, v52, 3, v58
	v_mul_f32_e32 v58, v59, v100
	v_mul_f32_e32 v59, v169, v101
	v_fmaak_f32 v58, v57, v58, 0x43000000
	v_mul_f32_e32 v60, v63, v102
	v_cvt_pk_u8_f32 v58, v58, 0, 0
	v_fmaak_f32 v59, v57, v59, 0x43000000
	v_mul_f32_e32 v53, v53, v103
	v_cvt_pk_u8_f32 v58, v59, 1, v58
	v_fmaak_f32 v59, v57, v60, 0x43000000
	v_cvt_pk_u8_f32 v58, v59, 2, v58
	v_fmaak_f32 v53, v57, v53, 0x43000000
	v_cvt_pk_u8_f32 v53, v53, 3, v58
	ds_bpermute_b32 v58, v144, v160
	ds_bpermute_b32 v59, v145, v160
	ds_bpermute_b32 v60, v146, v160
	ds_bpermute_b32 v61, v147, v160
	v_pk_mul_f32 v[38:39], v[46:47], 0.5 op_sel_hi:[1,0]
	s_waitcnt lgkmcnt(3)
; #define LAS __attribute__((address_space(3)))
; __host__ __device__ __forceinline__ size_t blk8_off(int r, int k, int KT8_) { return ((size_t)((r >> 8) * KT8_ + (k >> 7)) * 256 + (size_t)(r & 255)) * 128 + (size_t)(k & 127); }
; #define LDS_WAIT() asm volatile("s_waitcnt lgkmcnt(0)" ::: "memory")
; template <bool STRIP, int ROT>
; __device__ __forceinline__ void gu_finish_t(f32x4 (&v)[16], float gA, float gB, const GUDesc& d, LAS unsigned* T, int lane, const float (&sinv)[4]) {
;     ...
;     for (int jq = 0; jq < 4; ++jq) {
;         float g[4];
; #pragma unroll
;         for (int e2 = 0; e2 < 4; ++e2) g[e2] = jq < 2 ? __shfl(gA, 32 * jq + 4 * kr + e2) : __shfl(gB, 32 * (jq - 2) + 4 * kr + e2);
; #pragma unroll
;         for (int e = 0; e < 4; ++e)
;             T[(4 * nq + e) * 33 + 8 * jq + kr] = pack4_i8(v[4 * jq + 0][e] * g[0] * inv[e], v[4 * jq + 1][e] * g[1] * inv[e], v[4 * jq + 2][e] * g[2] * inv[e], v[4 * jq + 3][e] * g[3] * inv[e]);
;     }
;     LDS_WAIT(); asm volatile("" ::: "memory");
;     const int nl = lane >> 3, c = lane & 7;
; #pragma unroll
;     for (int g4 = 0; g4 < 4; ++g4) {
;         const int nloc = 8 * g4 + nl, dr = d.il ? gu_dest(d.n0 + nloc, d.bj) : d.n0 + nloc;
;         const LAS unsigned* t = T + nloc * 33 + 4 * c;
;         u32x4 o; o.x = t[0]; o.y = t[1]; o.z = t[2]; o.w = t[3];
;         *(u32x4*)(d.WQ + blk8_off(dr, d.k0 + 16 * c, d.kt8)) = o;
;         if (!STRIP) if (d.k0 == 0 && c == 0) d.sb[dr] = __uint_as_float(d.cmax[dr]) * (1.0f / 127.0f);
;     }
	v_mul_f32_e32 v34, v34, v58
	v_mul_f32_e32 v42, v42, v58
	s_waitcnt lgkmcnt(2)
	v_mul_f32_e32 v36, v36, v59
	v_fmaak_f32 v34, v56, v34, 0x43000000
	v_pk_mul_f32 v[46:47], v[48:49], 0.5 op_sel_hi:[1,0]
	v_pk_mul_f32 v[40:41], v[40:41], 0.5 op_sel_hi:[1,0]
	v_mul_f32_e32 v44, v44, v59
	v_fmaak_f32 v42, v54, v42, 0x43000000
	s_waitcnt lgkmcnt(1)
	v_mul_f32_e32 v38, v38, v60
	v_cvt_pk_u8_f32 v34, v34, 0, 0
	v_fmaak_f32 v36, v56, v36, 0x43000000
	v_pk_mul_f32 v[48:49], v[176:177], 0.5 op_sel_hi:[1,0]
	v_mul_f32_e32 v46, v46, v60
	v_cvt_pk_u8_f32 v42, v42, 0, 0
	v_fmaak_f32 v44, v54, v44, 0x43000000
	s_waitcnt lgkmcnt(0)
	v_mul_f32_e32 v40, v40, v61
	v_cvt_pk_u8_f32 v34, v36, 1, v34
	v_fmaak_f32 v36, v56, v38, 0x43000000
	v_mul_f32_e32 v48, v48, v61
	v_cvt_pk_u8_f32 v42, v44, 1, v42
	v_fmaak_f32 v44, v54, v46, 0x43000000
	v_cvt_pk_u8_f32 v34, v36, 2, v34
	v_fmaak_f32 v36, v56, v40, 0x43000000
	v_cvt_pk_u8_f32 v42, v44, 2, v42
	v_fmaak_f32 v44, v54, v48, 0x43000000
	v_cvt_pk_u8_f32 v34, v36, 3, v34
	v_xor_b32_e32 v52, 0x80808080, v52
	v_cvt_pk_u8_f32 v42, v44, 3, v42
	v_xor_b32_e32 v34, 0x80808080, v34
	v_xor_b32_e32 v50, 0x80808080, v50
	v_xor_b32_e32 v42, 0x80808080, v42
	ds_write2_b32 v151, v52, v34 offset0:82 offset1:90
	v_mul_f32_e32 v34, v35, v58
	ds_write2_b32 v151, v50, v42 offset0:16 offset1:24
	v_mul_f32_e32 v42, v43, v58
	v_mul_f32_e32 v35, v37, v59
	v_fmaak_f32 v34, v57, v34, 0x43000000
	v_mul_f32_e32 v43, v45, v59
	v_fmaak_f32 v42, v55, v42, 0x43000000
	v_mul_f32_e32 v36, v39, v60
	v_cvt_pk_u8_f32 v34, v34, 0, 0
	v_fmaak_f32 v35, v57, v35, 0x43000000
	v_mul_f32_e32 v44, v47, v60
	v_cvt_pk_u8_f32 v42, v42, 0, 0
	v_fmaak_f32 v43, v55, v43, 0x43000000
	v_mul_f32_e32 v37, v41, v61
	v_cvt_pk_u8_f32 v34, v35, 1, v34
	v_fmaak_f32 v35, v57, v36, 0x43000000
	v_mul_f32_e32 v45, v49, v61
	v_cvt_pk_u8_f32 v42, v43, 1, v42
	v_fmaak_f32 v43, v55, v44, 0x43000000
	v_cvt_pk_u8_f32 v34, v35, 2, v34
	v_fmaak_f32 v35, v57, v37, 0x43000000
	v_cvt_pk_u8_f32 v42, v43, 2, v42
	v_fmaak_f32 v43, v55, v45, 0x43000000
	v_cvt_pk_u8_f32 v34, v35, 3, v34
	v_bitop3_b32 v35, s12, v154, v1 bitop3:0xc8
	v_xor_b32_e32 v53, 0x80808080, v53
	v_cvt_pk_u8_f32 v42, v43, 3, v42
	v_xor_b32_e32 v34, 0x80808080, v34
	v_or_b32_e32 v35, s1, v35
	v_xor_b32_e32 v51, 0x80808080, v51
	v_xor_b32_e32 v42, 0x80808080, v42
	ds_write2_b32 v151, v53, v34 offset0:115 offset1:123
	v_or_b32_e32 v34, s12, v1
	v_or_b32_e32 v35, s15, v35
	ds_write2_b32 v151, v51, v42 offset0:49 offset1:57
	v_cndmask_b32_e64 v34, v35, v34, s[2:3]
	s_ashr_i32 s8, s52, 7
	s_waitcnt lgkmcnt(0)
	v_lshrrev_b32_e32 v35, 8, v34
	v_mov_b32_e32 v40, s8
	v_mad_i32_i24 v40, v35, s51, v40
	ds_read2_b32 v[36:37], v152 offset1:1
	ds_read2_b32 v[38:39], v152 offset0:2 offset1:3
	v_ashrrev_i32_e32 v41, 31, v40
	v_lshlrev_b64 v[40:41], 15, v[40:41]
	v_lshlrev_b32_e32 v35, 7, v34
	v_and_b32_e32 v130, 0x7380, v35
	v_lshl_add_u64 v[40:41], s[22:23], 0, v[40:41]
	v_lshl_add_u64 v[40:41], v[40:41], 0, v[130:131]
	v_or_b32_e32 v35, s52, v138
	v_lshl_add_u64 v[40:41], v[40:41], 0, v[132:133]
	v_cmp_eq_u32_e32 vcc, 0, v35
	s_waitcnt lgkmcnt(0)
	global_store_dwordx4 v[40:41], v[36:39], off
	s_and_saveexec_b64 s[20:21], vcc
	s_cbranch_execz .LBB0_1250
	v_ashrrev_i32_e32 v35, 31, v34
	v_lshlrev_b64 v[34:35], 2, v[34:35]
	v_lshl_add_u64 v[36:37], s[10:11], 0, v[34:35]
	global_load_dword v36, v[36:37], off
	v_lshl_add_u64 v[34:35], s[18:19], 0, v[34:35]
	s_waitcnt vmcnt(0)
	v_mul_f32_e32 v36, 0x3c010204, v36
	global_store_dword v[34:35], v36, off

; __device__ __forceinline__ float bfly8(float x, bool up) { const float p = __uint_as_float(__builtin_amdgcn_update_dpp(0u, __float_as_uint(x), 0x128, 0xf, 0xf, false)); return up ? p - x : x + p; }
; __device__ __forceinline__ float bfly16(float x, bool up) { const auto r = __builtin_amdgcn_permlane16_swap(__float_as_uint(x), __float_as_uint(x), false, false); const float a = __uint_as_float(r[0]), b = __uint_as_float(r[1]); return up ? a - b : a + b; }
; __device__ __forceinline__ float bfly32(float x, bool up) { const auto r = __builtin_amdgcn_permlane32_swap(__float_as_uint(x), __float_as_uint(x), false, false); const float a = __uint_as_float(r[0]), b = __uint_as_float(r[1]); return up ? a - b : a + b; }
; __device__ __forceinline__ void gu_load(f32x4 (&v)[16], float& gA, float& gB, const GUDesc& d, int lane) {
;     const int kr = lane >> 3, nq = lane & 7;
;     const float* __restrict__ src = d.W + (size_t)(d.k0 + 4 * kr) * d.N + d.n0 + 4 * nq;
;     gA = d.gain ? d.gain[d.k0 + lane] : 1.0f; gB = d.gain ? d.gain[d.k0 + 64 + lane] : 1.0f;
; #pragma unroll
;     for (int i = 0; i < 16; ++i) v[i] = *(const f32x4*)(src + (size_t)(32 * (i >> 2) + (i & 3)) * d.N);
; }
; template <int ROT>
; __device__ __forceinline__ void rot32_tile(f32x4 (&v)[16], int lane) {
; #pragma unroll
;     for (int jq = 0; jq < 4; ++jq) {
;         const f32x4 a = v[4 * jq], b = v[4 * jq + 1], c = v[4 * jq + 2], d = v[4 * jq + 3];
;         const f32x4 a1 = a + b, b1 = a - b, c1 = c + d, d1 = c - d;
;         if (ROT >= 2) { v[4 * jq] = a1 + c1; v[4 * jq + 2] = a1 - c1; v[4 * jq + 1] = b1 + d1; v[4 * jq + 3] = b1 - d1; }
;         else { v[4 * jq] = a1; v[4 * jq + 1] = b1; v[4 * jq + 2] = c1; v[4 * jq + 3] = d1; }
;     }
;     { const bool s8 = (lane & 8) != 0, s16 = (lane & 16) != 0, s32 = (lane & 32) != 0;
; #pragma unroll
;       for (int i = 0; i < 16; ++i)
; #pragma unroll
;           for (int e = 0; e < 4; ++e) { float x = v[i][e]; if (ROT >= 3) x = bfly8(x, s8); if (ROT >= 4) x = bfly16(x, s16); if (ROT >= 5) x = bfly32(x, s32); v[i][e] = x; } }
; #pragma unroll
;     for (int i = 0; i < 16; ++i) v[i] *= (ROT == 1 ? 0.70710678118654752f : ROT == 2 ? 0.5f : ROT == 3 ? 0.35355339059327373f : ROT == 4 ? 0.25f : 0.17677669529663687f);
; }
.LBB0_2235:
	v_or_b32_e32 v2, s40, v49
	s_add_u32 s16, s22, s16
	v_mul_hi_i32_i24_e32 v3, s18, v2
	v_mul_i32_i24_e32 v2, s18, v2
	s_addc_u32 s17, s23, s17
	s_waitcnt lgkmcnt(0)
	v_lshl_add_u64 v[2:3], v[2:3], 2, v[4:5]
	s_ashr_i32 s15, s14, 31
	v_lshl_add_u64 v[2:3], s[14:15], 2, v[2:3]
	v_lshl_add_u64 v[2:3], v[2:3], 0, v[38:39]
	s_lshl_b32 s0, s18, 2
	v_lshl_add_u64 v[4:5], v[2:3], 0, s[0:1]
	global_load_dwordx4 v[40:43], v[2:3], off nt
	global_load_dwordx4 v[44:47], v[4:5], off nt
	v_lshl_add_u64 v[2:3], v[4:5], 0, s[0:1]
	v_lshl_add_u64 v[4:5], v[2:3], 0, s[0:1]
	s_mulk_i32 s18, 0x74
	s_mov_b32 s19, s1
	global_load_dwordx4 v[72:75], v[2:3], off nt
	global_load_dwordx4 v[76:79], v[4:5], off nt
	v_lshl_add_u64 v[2:3], v[4:5], 0, s[18:19]
	v_lshl_add_u64 v[4:5], v[2:3], 0, s[0:1]
	global_load_dwordx4 v[80:83], v[2:3], off nt
	global_load_dwordx4 v[84:87], v[4:5], off nt
	v_lshl_add_u64 v[2:3], v[4:5], 0, s[0:1]
	v_lshl_add_u64 v[4:5], v[2:3], 0, s[0:1]
	global_load_dwordx4 v[88:91], v[2:3], off nt
	global_load_dwordx4 v[92:95], v[4:5], off nt
	v_lshl_add_u64 v[2:3], v[4:5], 0, s[18:19]
	global_load_dwordx4 v[10:13], v[2:3], off nt
	v_lshl_add_u64 v[2:3], v[2:3], 0, s[0:1]
	v_lshl_add_u64 v[6:7], v[2:3], 0, s[0:1]
	global_load_dwordx4 v[26:29], v[2:3], off nt
	s_lshl_b32 s15, s14, 1
	global_load_dwordx4 v[2:5], v[6:7], off nt
	v_lshl_add_u64 v[6:7], v[6:7], 0, s[0:1]
	global_load_dwordx4 v[14:17], v[6:7], off nt
	s_waitcnt vmcnt(12)
	v_bitop3_b32 v9, s14, v64, v52 bitop3:0xc8
	s_and_b32 s15, s15, 0xffffff00
	v_lshl_add_u64 v[6:7], v[6:7], 0, s[18:19]
	v_or_b32_e32 v9, s15, v9
	global_load_dwordx4 v[18:21], v[6:7], off nt
	v_lshl_add_u64 v[6:7], v[6:7], 0, s[0:1]
	v_or_b32_e32 v8, s14, v52
	v_or_b32_e32 v9, s38, v9
	v_lshl_add_u64 v[22:23], v[6:7], 0, s[0:1]
	v_cndmask_b32_e64 v96, v9, v8, s[2:3]
	global_load_dwordx4 v[30:33], v[6:7], off nt
	v_ashrrev_i32_e32 v97, 31, v96
	global_load_dwordx4 v[6:9], v[22:23], off nt
	v_lshl_add_u64 v[22:23], v[22:23], 0, s[0:1]
	global_load_dwordx4 v[22:25], v[22:23], off nt
	s_ashr_i32 s0, s40, 7
	s_waitcnt vmcnt(14)
	v_pk_add_f32 v[98:99], v[42:43], v[46:47]
	v_pk_add_f32 v[100:101], v[40:41], v[44:45]
	v_sub_f32_e32 v103, v43, v47
	v_sub_f32_e32 v102, v42, v46
	v_sub_f32_e32 v105, v41, v45
	v_sub_f32_e32 v104, v40, v44
	s_waitcnt vmcnt(12)
	v_pk_add_f32 v[40:41], v[74:75], v[78:79]
	v_pk_add_f32 v[42:43], v[72:73], v[76:77]
	v_sub_f32_e32 v75, v75, v79
	v_sub_f32_e32 v74, v74, v78
	v_sub_f32_e32 v73, v73, v77
	v_sub_f32_e32 v72, v72, v76
	v_pk_add_f32 v[44:45], v[98:99], v[40:41]
	v_pk_add_f32 v[46:47], v[100:101], v[42:43]
	v_sub_f32_e32 v41, v99, v41
	v_sub_f32_e32 v40, v98, v40
	v_sub_f32_e32 v43, v101, v43
	v_sub_f32_e32 v42, v100, v42
	v_pk_add_f32 v[76:77], v[104:105], v[72:73]
	v_pk_add_f32 v[78:79], v[102:103], v[74:75]
	v_sub_f32_e32 v99, v105, v73
	v_sub_f32_e32 v98, v104, v72
	v_sub_f32_e32 v101, v103, v75
	v_sub_f32_e32 v100, v102, v74
	s_waitcnt vmcnt(10)
	v_pk_add_f32 v[72:73], v[82:83], v[86:87]
	v_pk_add_f32 v[74:75], v[80:81], v[84:85]
	v_sub_f32_e32 v81, v81, v85
	v_sub_f32_e32 v80, v80, v84
	s_waitcnt vmcnt(8)
	v_pk_add_f32 v[84:85], v[90:91], v[94:95]
	v_sub_f32_e32 v83, v83, v87
	v_sub_f32_e32 v82, v82, v86
	v_pk_add_f32 v[86:87], v[88:89], v[92:93]
	v_sub_f32_e32 v89, v89, v93
	v_sub_f32_e32 v88, v88, v92
	v_pk_add_f32 v[92:93], v[72:73], v[84:85]
	v_sub_f32_e32 v85, v73, v85
	v_sub_f32_e32 v84, v72, v84
	v_lshl_add_u64 v[72:73], v[96:97], 2, s[10:11]
	v_sub_f32_e32 v91, v91, v95
	v_sub_f32_e32 v90, v90, v94
	v_pk_add_f32 v[94:95], v[74:75], v[86:87]
	v_sub_f32_e32 v87, v75, v87
	v_sub_f32_e32 v86, v74, v86
	global_load_dwordx4 v[72:75], v[72:73], off nt
	v_pk_add_f32 v[102:103], v[80:81], v[88:89]
	v_pk_add_f32 v[104:105], v[82:83], v[90:91]
	v_sub_f32_e32 v81, v81, v89
	v_sub_f32_e32 v80, v80, v88
	v_sub_f32_e32 v83, v83, v91
	v_sub_f32_e32 v82, v82, v90
	s_waitcnt vmcnt(7)
	v_pk_add_f32 v[88:89], v[12:13], v[28:29]
	v_pk_add_f32 v[90:91], v[10:11], v[26:27]
	v_sub_f32_e32 v13, v13, v29
	v_sub_f32_e32 v12, v12, v28
	v_sub_f32_e32 v11, v11, v27
	v_sub_f32_e32 v10, v10, v26
	s_waitcnt vmcnt(5)
	v_pk_add_f32 v[26:27], v[4:5], v[16:17]
	v_pk_add_f32 v[28:29], v[2:3], v[14:15]
	v_sub_f32_e32 v5, v5, v17
	v_sub_f32_e32 v4, v4, v16
	v_sub_f32_e32 v3, v3, v15
	v_sub_f32_e32 v2, v2, v14
	v_pk_add_f32 v[14:15], v[88:89], v[26:27]
	v_pk_add_f32 v[16:17], v[90:91], v[28:29]
	v_sub_f32_e32 v27, v89, v27
	v_sub_f32_e32 v26, v88, v26
	v_sub_f32_e32 v29, v91, v29
	v_sub_f32_e32 v28, v90, v28
	v_pk_add_f32 v[88:89], v[10:11], v[2:3]
	v_pk_add_f32 v[90:91], v[12:13], v[4:5]
	v_sub_f32_e32 v3, v11, v3
	v_sub_f32_e32 v2, v10, v2
	v_sub_f32_e32 v5, v13, v5
	v_sub_f32_e32 v4, v12, v4
	s_waitcnt vmcnt(3)
	v_pk_add_f32 v[10:11], v[20:21], v[32:33]
	v_pk_add_f32 v[12:13], v[18:19], v[30:31]
	v_sub_f32_e32 v19, v19, v31
	v_sub_f32_e32 v18, v18, v30
	s_waitcnt vmcnt(1)
; #define LAS __attribute__((address_space(3)))
; __device__ __forceinline__ float bfly8(float x, bool up) { const float p = __uint_as_float(__builtin_amdgcn_update_dpp(0u, __float_as_uint(x), 0x128, 0xf, 0xf, false)); return up ? p - x : x + p; }
; __device__ __forceinline__ float bfly16(float x, bool up) { const auto r = __builtin_amdgcn_permlane16_swap(__float_as_uint(x), __float_as_uint(x), false, false); const float a = __uint_as_float(r[0]), b = __uint_as_float(r[1]); return up ? a - b : a + b; }
; __device__ __forceinline__ float bfly32(float x, bool up) { const auto r = __builtin_amdgcn_permlane32_swap(__float_as_uint(x), __float_as_uint(x), false, false); const float a = __uint_as_float(r[0]), b = __uint_as_float(r[1]); return up ? a - b : a + b; }
; template <int ROT>
; __device__ __forceinline__ void rot32_tile(f32x4 (&v)[16], int lane) {
;     ...
;           for (int e = 0; e < 4; ++e) { float x = v[i][e]; if (ROT >= 3) x = bfly8(x, s8); if (ROT >= 4) x = bfly16(x, s16); if (ROT >= 5) x = bfly32(x, s32); v[i][e] = x; } }
; #pragma unroll
;     for (int i = 0; i < 16; ++i) v[i] *= (ROT == 1 ? 0.70710678118654752f : ROT == 2 ? 0.5f : ROT == 3 ? 0.35355339059327373f : ROT == 4 ? 0.25f : 0.17677669529663687f);
; }
; template <bool STRIP, int ROT>
; __device__ __forceinline__ void gu_finish_t(f32x4 (&v)[16], float gA, float gB, const GUDesc& d, LAS unsigned* T, int lane, const float (&sinv)[4]) {
;     const int kr = lane >> 3, nq = lane & 7;
;     const int dq0 = d.il ? gu_dest(d.n0 + 4 * nq, d.bj) : d.n0 + 4 * nq;
;     if (ROT) rot32_tile<ROT>(v, lane);
;     float inv[4];
; #pragma unroll
;     for (int e = 0; e < 4; ++e) { if (STRIP) inv[e] = sinv[e]; else { const float cm = __uint_as_float(d.cmax[dq0 + e]); inv[e] = cm > 0.f ? 127.0f / cm : 0.f; } }
; #pragma unroll
;     for (int jq = 0; jq < 4; ++jq) {
;         float g[4];
; #pragma unroll
;         for (int e2 = 0; e2 < 4; ++e2) g[e2] = jq < 2 ? __shfl(gA, 32 * jq + 4 * kr + e2) : __shfl(gB, 32 * (jq - 2) + 4 * kr + e2);
; #pragma unroll
;         for (int e = 0; e < 4; ++e)
;             T[(4 * nq + e) * 33 + 8 * jq + kr] = pack4_i8(v[4 * jq + 0][e] * g[0] * inv[e], v[4 * jq + 1][e] * g[1] * inv[e], v[4 * jq + 2][e] * g[2] * inv[e], v[4 * jq + 3][e] * g[3] * inv[e]);
	v_pk_add_f32 v[30:31], v[8:9], v[24:25]
	v_sub_f32_e32 v21, v21, v33
	v_sub_f32_e32 v20, v20, v32
	v_pk_add_f32 v[32:33], v[6:7], v[22:23]
	v_sub_f32_e32 v7, v7, v23
	v_sub_f32_e32 v6, v6, v22
	v_pk_add_f32 v[22:23], v[10:11], v[30:31]
	v_pk_mul_f32 v[110:111], v[2:3], 0.5 op_sel_hi:[1,0]
	v_pk_mul_f32 v[2:3], v[22:23], 0.5 op_sel_hi:[1,0]
	v_sub_f32_e32 v9, v9, v25
	v_sub_f32_e32 v8, v8, v24
	v_pk_add_f32 v[24:25], v[12:13], v[32:33]
	v_sub_f32_e32 v33, v13, v33
	v_sub_f32_e32 v32, v12, v32
	v_pk_add_f32 v[12:13], v[18:19], v[6:7]
	v_sub_f32_e32 v19, v19, v7
	v_sub_f32_e32 v18, v18, v6
	v_pk_mul_f32 v[106:107], v[16:17], 0.5 op_sel_hi:[1,0]
	v_pk_mul_f32 v[16:17], v[18:19], 0.5 op_sel_hi:[1,0]
	v_sub_f32_e32 v31, v11, v31
	v_sub_f32_e32 v30, v10, v30
	v_pk_mul_f32 v[10:11], v[24:25], 0.5 op_sel_hi:[1,0]
	v_pk_mul_f32 v[6:7], v[30:31], 0.5 op_sel_hi:[1,0]
	v_pk_add_f32 v[96:97], v[20:21], v[8:9]
	v_sub_f32_e32 v9, v21, v9
	v_sub_f32_e32 v8, v20, v8
	v_pk_mul_f32 v[20:21], v[44:45], 0.5 op_sel_hi:[1,0]
	v_pk_mul_f32 v[44:45], v[46:47], 0.5 op_sel_hi:[1,0]
	v_pk_mul_f32 v[46:47], v[78:79], 0.5 op_sel_hi:[1,0]
	v_pk_mul_f32 v[76:77], v[76:77], 0.5 op_sel_hi:[1,0]
	v_pk_mul_f32 v[78:79], v[100:101], 0.5 op_sel_hi:[1,0]
	v_pk_mul_f32 v[100:101], v[104:105], 0.5 op_sel_hi:[1,0]
	v_pk_mul_f32 v[104:105], v[14:15], 0.5 op_sel_hi:[1,0]
	v_pk_mul_f32 v[14:15], v[32:33], 0.5 op_sel_hi:[1,0]
	v_pk_mul_f32 v[42:43], v[42:43], 0.5 op_sel_hi:[1,0]
	v_pk_mul_f32 v[98:99], v[98:99], 0.5 op_sel_hi:[1,0]
	v_pk_mul_f32 v[40:41], v[40:41], 0.5 op_sel_hi:[1,0]
	v_pk_mul_f32 v[94:95], v[94:95], 0.5 op_sel_hi:[1,0]
	v_pk_mul_f32 v[102:103], v[102:103], 0.5 op_sel_hi:[1,0]
	v_pk_mul_f32 v[86:87], v[86:87], 0.5 op_sel_hi:[1,0]
	v_pk_mul_f32 v[80:81], v[80:81], 0.5 op_sel_hi:[1,0]
	v_pk_mul_f32 v[92:93], v[92:93], 0.5 op_sel_hi:[1,0]
	v_pk_mul_f32 v[84:85], v[84:85], 0.5 op_sel_hi:[1,0]
	v_pk_mul_f32 v[82:83], v[82:83], 0.5 op_sel_hi:[1,0]
	v_pk_mul_f32 v[88:89], v[88:89], 0.5 op_sel_hi:[1,0]
	s_waitcnt vmcnt(0)
	v_div_scale_f32 v22, s[18:19], v72, v72, s37
	v_rcp_f32_e32 v23, v22
	v_pk_mul_f32 v[28:29], v[28:29], 0.5 op_sel_hi:[1,0]
	v_pk_mul_f32 v[90:91], v[90:91], 0.5 op_sel_hi:[1,0]
	v_pk_mul_f32 v[26:27], v[26:27], 0.5 op_sel_hi:[1,0]
	v_fma_f32 v18, -v22, v23, 1.0
	v_fmac_f32_e32 v23, v18, v23
	v_div_scale_f32 v18, vcc, s37, v72, s37
	v_mul_f32_e32 v19, v18, v23
	v_fma_f32 v24, -v22, v19, v18
	v_fmac_f32_e32 v19, v24, v23
	v_fma_f32 v18, -v22, v19, v18
	v_div_fmas_f32 v18, v18, v23, v19
	v_div_scale_f32 v19, s[18:19], v73, v73, s37
	v_rcp_f32_e32 v22, v19
	v_div_fixup_f32 v18, v18, v72, s37
	v_cmp_lt_f32_e32 vcc, 0, v72
	v_pk_mul_f32 v[108:109], v[4:5], 0.5 op_sel_hi:[1,0]
	v_fma_f32 v23, -v19, v22, 1.0
	v_cndmask_b32_e32 v18, 0, v18, vcc
	v_fmac_f32_e32 v22, v23, v22
	v_div_scale_f32 v23, vcc, s37, v73, s37
	v_mul_f32_e32 v24, v23, v22
	v_fma_f32 v25, -v19, v24, v23
	v_fmac_f32_e32 v24, v25, v22
	v_fma_f32 v19, -v19, v24, v23
	v_div_fmas_f32 v19, v19, v22, v24
	v_div_scale_f32 v22, s[18:19], v74, v74, s37
	v_rcp_f32_e32 v23, v22
	v_div_fixup_f32 v19, v19, v73, s37
	v_cmp_lt_f32_e32 vcc, 0, v73
	v_pk_mul_f32 v[4:5], v[96:97], 0.5 op_sel_hi:[1,0]
	v_fma_f32 v24, -v22, v23, 1.0
	v_cndmask_b32_e32 v19, 0, v19, vcc
	v_fmac_f32_e32 v23, v24, v23
	v_div_scale_f32 v24, vcc, s37, v74, s37
	v_mul_f32_e32 v25, v24, v23
	v_fma_f32 v30, -v22, v25, v24
	v_fmac_f32_e32 v25, v30, v23
	v_fma_f32 v22, -v22, v25, v24
	v_div_fmas_f32 v22, v22, v23, v25
	v_div_scale_f32 v23, s[18:19], v75, v75, s37
	v_rcp_f32_e32 v24, v23
	v_div_fixup_f32 v22, v22, v74, s37
	v_cmp_lt_f32_e32 vcc, 0, v74
	v_pk_mul_f32 v[12:13], v[12:13], 0.5 op_sel_hi:[1,0]
	v_fma_f32 v25, -v23, v24, 1.0
	v_cndmask_b32_e32 v22, 0, v22, vcc
	v_fmac_f32_e32 v24, v25, v24
	v_div_scale_f32 v25, vcc, s37, v75, s37
	v_mul_f32_e32 v30, v25, v24
	v_fma_f32 v31, -v23, v30, v25
	v_fmac_f32_e32 v30, v31, v24
	v_fma_f32 v23, -v23, v30, v25
	v_div_fmas_f32 v23, v23, v24, v30
	ds_bpermute_b32 v24, v53, v71
	ds_bpermute_b32 v25, v54, v71
	ds_bpermute_b32 v30, v55, v71
	ds_bpermute_b32 v31, v56, v71
	v_div_fixup_f32 v23, v23, v75, s37
	s_waitcnt lgkmcnt(3)
	v_mul_f32_e32 v32, v44, v24
	s_waitcnt lgkmcnt(2)
	v_mul_f32_e32 v33, v76, v25
	v_fmaak_f32 v32, v18, v32, 0x43000000
	s_waitcnt lgkmcnt(1)
	v_mul_f32_e32 v42, v42, v30
	v_cvt_pk_u8_f32 v32, v32, 0, 0
	v_fmaak_f32 v33, v18, v33, 0x43000000
	s_waitcnt lgkmcnt(0)
	v_mul_f32_e32 v44, v98, v31
	v_cvt_pk_u8_f32 v32, v33, 1, v32
	v_fmaak_f32 v33, v18, v42, 0x43000000
	v_cvt_pk_u8_f32 v32, v33, 2, v32
	v_fmaak_f32 v33, v18, v44, 0x43000000
	v_cvt_pk_u8_f32 v32, v33, 3, v32
	v_mul_f32_e32 v33, v45, v24
	v_mul_f32_e32 v42, v77, v25
	v_fmaak_f32 v33, v19, v33, 0x43000000
	v_cmp_lt_f32_e32 vcc, 0, v75
	v_mul_f32_e32 v43, v43, v30
	v_cvt_pk_u8_f32 v33, v33, 0, 0
	v_fmaak_f32 v42, v19, v42, 0x43000000
	v_cndmask_b32_e32 v23, 0, v23, vcc
	v_mul_f32_e32 v44, v99, v31
	v_cvt_pk_u8_f32 v33, v42, 1, v33
	v_fmaak_f32 v42, v19, v43, 0x43000000
	v_mul_f32_e32 v21, v21, v24
	v_cvt_pk_u8_f32 v33, v42, 2, v33
	v_fmaak_f32 v42, v19, v44, 0x43000000
	v_mul_f32_e32 v20, v20, v24
	v_mul_f32_e32 v24, v47, v25
	v_fmaak_f32 v21, v23, v21, 0x43000000
	v_cvt_pk_u8_f32 v33, v42, 3, v33
	v_mul_f32_e32 v42, v46, v25
	v_mul_f32_e32 v25, v41, v30
	v_cvt_pk_u8_f32 v21, v21, 0, 0
	v_fmaak_f32 v24, v23, v24, 0x43000000
	v_mul_f32_e32 v40, v40, v30
	v_mul_f32_e32 v30, v79, v31
	v_cvt_pk_u8_f32 v21, v24, 1, v21
	v_fmaak_f32 v24, v23, v25, 0x43000000
	v_cvt_pk_u8_f32 v21, v24, 2, v21
	v_fmaak_f32 v24, v23, v30, 0x43000000
	v_cvt_pk_u8_f32 v21, v24, 3, v21
	ds_bpermute_b32 v24, v57, v71
	v_fmaak_f32 v20, v22, v20, 0x43000000
	ds_bpermute_b32 v25, v58, v71
	v_cvt_pk_u8_f32 v20, v20, 0, 0
	v_fmaak_f32 v42, v22, v42, 0x43000000
	ds_bpermute_b32 v30, v59, v71
	v_mul_f32_e32 v43, v78, v31
	v_cvt_pk_u8_f32 v20, v42, 1, v20
	v_fmaak_f32 v40, v22, v40, 0x43000000
	ds_bpermute_b32 v31, v60, v71
	v_cvt_pk_u8_f32 v20, v40, 2, v20
	v_fmaak_f32 v40, v22, v43, 0x43000000
	v_cvt_pk_u8_f32 v20, v40, 3, v20
	s_waitcnt lgkmcnt(3)
; template <bool STRIP, int ROT>
; __device__ __forceinline__ void gu_finish_t(f32x4 (&v)[16], float gA, float gB, const GUDesc& d, LAS unsigned* T, int lane, const float (&sinv)[4]) {
;     ...
;     for (int jq = 0; jq < 4; ++jq) {
;         float g[4];
; #pragma unroll
;         for (int e2 = 0; e2 < 4; ++e2) g[e2] = jq < 2 ? __shfl(gA, 32 * jq + 4 * kr + e2) : __shfl(gB, 32 * (jq - 2) + 4 * kr + e2);
; #pragma unroll
;         for (int e = 0; e < 4; ++e)
;             T[(4 * nq + e) * 33 + 8 * jq + kr] = pack4_i8(v[4 * jq + 0][e] * g[0] * inv[e], v[4 * jq + 1][e] * g[1] * inv[e], v[4 * jq + 2][e] * g[2] * inv[e], v[4 * jq + 3][e] * g[3] * inv[e]);
;     }
	v_mul_f32_e32 v40, v94, v24
	s_waitcnt lgkmcnt(2)
	v_mul_f32_e32 v41, v102, v25
	v_fmaak_f32 v40, v18, v40, 0x43000000
	s_waitcnt lgkmcnt(1)
	v_mul_f32_e32 v42, v86, v30
	v_cvt_pk_u8_f32 v40, v40, 0, 0
	v_fmaak_f32 v41, v18, v41, 0x43000000
	s_waitcnt lgkmcnt(0)
	v_mul_f32_e32 v43, v80, v31
	v_cvt_pk_u8_f32 v40, v41, 1, v40
	v_fmaak_f32 v41, v18, v42, 0x43000000
	v_cvt_pk_u8_f32 v40, v41, 2, v40
	v_fmaak_f32 v41, v18, v43, 0x43000000
	v_cvt_pk_u8_f32 v40, v41, 3, v40
	v_xor_b32_e32 v32, 0x80808080, v32
	v_xor_b32_e32 v40, 0x80808080, v40
	ds_write2_b32 v65, v32, v40 offset1:8
	v_mul_f32_e32 v32, v95, v24
	v_mul_f32_e32 v40, v103, v25
	v_fmaak_f32 v32, v19, v32, 0x43000000
	v_mul_f32_e32 v41, v87, v30
	v_cvt_pk_u8_f32 v32, v32, 0, 0
	v_fmaak_f32 v40, v19, v40, 0x43000000
	v_mul_f32_e32 v42, v81, v31
	v_cvt_pk_u8_f32 v32, v40, 1, v32
	v_fmaak_f32 v40, v19, v41, 0x43000000
	v_cvt_pk_u8_f32 v32, v40, 2, v32
	v_fmaak_f32 v40, v19, v42, 0x43000000
	v_cvt_pk_u8_f32 v32, v40, 3, v32
	v_xor_b32_e32 v33, 0x80808080, v33
	v_xor_b32_e32 v32, 0x80808080, v32
	ds_write2_b32 v65, v33, v32 offset0:33 offset1:41
	v_mul_f32_e32 v32, v92, v24
	v_mul_f32_e32 v33, v100, v25
	v_fmaak_f32 v32, v22, v32, 0x43000000
	v_mul_f32_e32 v40, v84, v30
	v_cvt_pk_u8_f32 v32, v32, 0, 0
	v_fmaak_f32 v33, v22, v33, 0x43000000
	v_mul_f32_e32 v41, v82, v31
	v_cvt_pk_u8_f32 v32, v33, 1, v32
	v_fmaak_f32 v33, v22, v40, 0x43000000
	v_cvt_pk_u8_f32 v32, v33, 2, v32
	v_fmaak_f32 v33, v22, v41, 0x43000000
	v_cvt_pk_u8_f32 v32, v33, 3, v32
	v_xor_b32_e32 v20, 0x80808080, v20
	v_xor_b32_e32 v32, 0x80808080, v32
	ds_write2_b32 v65, v20, v32 offset0:66 offset1:74
	v_mul_f32_e32 v20, v93, v24
	v_mul_f32_e32 v24, v101, v25
	v_fmaak_f32 v20, v23, v20, 0x43000000
	v_mul_f32_e32 v25, v85, v30
	v_cvt_pk_u8_f32 v20, v20, 0, 0
	v_fmaak_f32 v24, v23, v24, 0x43000000
	v_mul_f32_e32 v30, v83, v31
	v_cvt_pk_u8_f32 v20, v24, 1, v20
	v_fmaak_f32 v24, v23, v25, 0x43000000
	v_cvt_pk_u8_f32 v20, v24, 2, v20
	v_fmaak_f32 v24, v23, v30, 0x43000000
	v_cvt_pk_u8_f32 v20, v24, 3, v20
	ds_bpermute_b32 v24, v53, v34
	ds_bpermute_b32 v25, v54, v34
	ds_bpermute_b32 v30, v55, v34
	ds_bpermute_b32 v31, v56, v34
	v_xor_b32_e32 v21, 0x80808080, v21
	v_xor_b32_e32 v20, 0x80808080, v20
	ds_write2_b32 v65, v21, v20 offset0:99 offset1:107
	s_waitcnt lgkmcnt(4)
	v_mul_f32_e32 v20, v106, v24
	s_waitcnt lgkmcnt(3)
	v_mul_f32_e32 v21, v88, v25
	v_fmaak_f32 v20, v18, v20, 0x43000000
	s_waitcnt lgkmcnt(2)
	v_mul_f32_e32 v28, v28, v30
	v_cvt_pk_u8_f32 v20, v20, 0, 0
	v_fmaak_f32 v21, v18, v21, 0x43000000
	s_waitcnt lgkmcnt(1)
	v_mul_f32_e32 v32, v110, v31
	v_cvt_pk_u8_f32 v20, v21, 1, v20
	v_fmaak_f32 v21, v18, v28, 0x43000000
	v_cvt_pk_u8_f32 v20, v21, 2, v20
	v_fmaak_f32 v21, v18, v32, 0x43000000
	v_cvt_pk_u8_f32 v20, v21, 3, v20
	v_mul_f32_e32 v21, v107, v24
	v_mul_f32_e32 v28, v89, v25
	v_fmaak_f32 v21, v19, v21, 0x43000000
	v_mul_f32_e32 v29, v29, v30
	v_cvt_pk_u8_f32 v21, v21, 0, 0
	v_fmaak_f32 v28, v19, v28, 0x43000000
	v_mul_f32_e32 v32, v111, v31
	v_cvt_pk_u8_f32 v21, v28, 1, v21
	v_fmaak_f32 v28, v19, v29, 0x43000000
	v_cvt_pk_u8_f32 v21, v28, 2, v21
	v_fmaak_f32 v28, v19, v32, 0x43000000
	v_cvt_pk_u8_f32 v21, v28, 3, v21
	v_mul_f32_e32 v28, v104, v24
	v_mul_f32_e32 v29, v90, v25
	v_fmaak_f32 v28, v22, v28, 0x43000000
	v_mul_f32_e32 v26, v26, v30
	v_cvt_pk_u8_f32 v28, v28, 0, 0
	v_fmaak_f32 v29, v22, v29, 0x43000000
	v_mul_f32_e32 v24, v105, v24
	v_mul_f32_e32 v32, v108, v31
	v_cvt_pk_u8_f32 v28, v29, 1, v28
	v_fmaak_f32 v26, v22, v26, 0x43000000
	v_mul_f32_e32 v25, v91, v25
	v_fmaak_f32 v24, v23, v24, 0x43000000
	v_cvt_pk_u8_f32 v26, v26, 2, v28
	v_fmaak_f32 v28, v22, v32, 0x43000000
	v_mul_f32_e32 v27, v27, v30
	v_cvt_pk_u8_f32 v24, v24, 0, 0
	v_fmaak_f32 v25, v23, v25, 0x43000000
	v_cvt_pk_u8_f32 v26, v28, 3, v26
	v_mul_f32_e32 v28, v109, v31
	v_cvt_pk_u8_f32 v24, v25, 1, v24
	v_fmaak_f32 v25, v23, v27, 0x43000000
	v_cvt_pk_u8_f32 v24, v25, 2, v24
	v_fmaak_f32 v25, v23, v28, 0x43000000
	v_cvt_pk_u8_f32 v24, v25, 3, v24
	ds_bpermute_b32 v25, v57, v34
	ds_bpermute_b32 v27, v58, v34
	ds_bpermute_b32 v28, v59, v34
	ds_bpermute_b32 v29, v60, v34
	v_pk_mul_f32 v[8:9], v[8:9], 0.5 op_sel_hi:[1,0]
	s_waitcnt lgkmcnt(3)
; #define LAS __attribute__((address_space(3)))
; __host__ __device__ __forceinline__ size_t blk8_off(int r, int k, int KT8_) { return ((size_t)((r >> 8) * KT8_ + (k >> 7)) * 256 + (size_t)(r & 255)) * 128 + (size_t)(k & 127); }
; #define LDS_WAIT() asm volatile("s_waitcnt lgkmcnt(0)" ::: "memory")
; template <bool STRIP, int ROT>
; __device__ __forceinline__ void gu_finish_t(f32x4 (&v)[16], float gA, float gB, const GUDesc& d, LAS unsigned* T, int lane, const float (&sinv)[4]) {
;     ...
;     for (int jq = 0; jq < 4; ++jq) {
;         float g[4];
; #pragma unroll
;         for (int e2 = 0; e2 < 4; ++e2) g[e2] = jq < 2 ? __shfl(gA, 32 * jq + 4 * kr + e2) : __shfl(gB, 32 * (jq - 2) + 4 * kr + e2);
; #pragma unroll
;         for (int e = 0; e < 4; ++e)
;             T[(4 * nq + e) * 33 + 8 * jq + kr] = pack4_i8(v[4 * jq + 0][e] * g[0] * inv[e], v[4 * jq + 1][e] * g[1] * inv[e], v[4 * jq + 2][e] * g[2] * inv[e], v[4 * jq + 3][e] * g[3] * inv[e]);
;     }
;     LDS_WAIT(); asm volatile("" ::: "memory");
;     const int nl = lane >> 3, c = lane & 7;
; #pragma unroll
;     for (int g4 = 0; g4 < 4; ++g4) {
;         const int nloc = 8 * g4 + nl, dr = d.il ? gu_dest(d.n0 + nloc, d.bj) : d.n0 + nloc;
;         const LAS unsigned* t = T + nloc * 33 + 4 * c;
;         u32x4 o; o.x = t[0]; o.y = t[1]; o.z = t[2]; o.w = t[3];
;         *(u32x4*)(d.WQ + blk8_off(dr, d.k0 + 16 * c, d.kt8)) = o;
;         if (!STRIP) if (d.k0 == 0 && c == 0) d.sb[dr] = __uint_as_float(d.cmax[dr]) * (1.0f / 127.0f);
;     }
	v_mul_f32_e32 v2, v2, v25
	v_mul_f32_e32 v10, v10, v25
	s_waitcnt lgkmcnt(2)
	v_mul_f32_e32 v4, v4, v27
	v_fmaak_f32 v2, v22, v2, 0x43000000
	v_mul_f32_e32 v12, v12, v27
	v_fmaak_f32 v10, v18, v10, 0x43000000
	s_waitcnt lgkmcnt(1)
	v_mul_f32_e32 v6, v6, v28
	v_cvt_pk_u8_f32 v2, v2, 0, 0
	v_fmaak_f32 v4, v22, v4, 0x43000000
	v_mul_f32_e32 v14, v14, v28
	v_cvt_pk_u8_f32 v10, v10, 0, 0
	v_fmaak_f32 v12, v18, v12, 0x43000000
	s_waitcnt lgkmcnt(0)
	v_mul_f32_e32 v8, v8, v29
	v_cvt_pk_u8_f32 v2, v4, 1, v2
	v_fmaak_f32 v4, v22, v6, 0x43000000
	v_mul_f32_e32 v16, v16, v29
	v_cvt_pk_u8_f32 v10, v12, 1, v10
	v_fmaak_f32 v12, v18, v14, 0x43000000
	v_cvt_pk_u8_f32 v2, v4, 2, v2
	v_fmaak_f32 v4, v22, v8, 0x43000000
	v_cvt_pk_u8_f32 v10, v12, 2, v10
	v_fmaak_f32 v12, v18, v16, 0x43000000
	v_cvt_pk_u8_f32 v2, v4, 3, v2
	v_xor_b32_e32 v26, 0x80808080, v26
	v_cvt_pk_u8_f32 v10, v12, 3, v10
	v_xor_b32_e32 v2, 0x80808080, v2
	v_xor_b32_e32 v20, 0x80808080, v20
	v_xor_b32_e32 v10, 0x80808080, v10
	ds_write2_b32 v65, v26, v2 offset0:82 offset1:90
	v_mul_f32_e32 v2, v3, v25
	ds_write2_b32 v65, v20, v10 offset0:16 offset1:24
	v_mul_f32_e32 v10, v11, v25
	v_mul_f32_e32 v3, v5, v27
	v_fmaak_f32 v2, v23, v2, 0x43000000
	v_mul_f32_e32 v11, v13, v27
	v_fmaak_f32 v10, v19, v10, 0x43000000
	v_mul_f32_e32 v4, v7, v28
	v_cvt_pk_u8_f32 v2, v2, 0, 0
	v_fmaak_f32 v3, v23, v3, 0x43000000
	v_mul_f32_e32 v12, v15, v28
	v_cvt_pk_u8_f32 v10, v10, 0, 0
	v_fmaak_f32 v11, v19, v11, 0x43000000
	v_mul_f32_e32 v5, v9, v29
	v_cvt_pk_u8_f32 v2, v3, 1, v2
	v_fmaak_f32 v3, v23, v4, 0x43000000
	v_mul_f32_e32 v13, v17, v29
	v_cvt_pk_u8_f32 v10, v11, 1, v10
	v_fmaak_f32 v11, v19, v12, 0x43000000
	v_cvt_pk_u8_f32 v2, v3, 2, v2
	v_fmaak_f32 v3, v23, v5, 0x43000000
	v_cvt_pk_u8_f32 v10, v11, 2, v10
	v_fmaak_f32 v11, v19, v13, 0x43000000
	v_cvt_pk_u8_f32 v2, v3, 3, v2
	v_bitop3_b32 v3, s14, v66, v50 bitop3:0xc8
	v_xor_b32_e32 v24, 0x80808080, v24
	v_cvt_pk_u8_f32 v10, v11, 3, v10
	v_xor_b32_e32 v2, 0x80808080, v2
	v_or_b32_e32 v3, s15, v3
	v_xor_b32_e32 v21, 0x80808080, v21
	v_xor_b32_e32 v10, 0x80808080, v10
	ds_write2_b32 v65, v24, v2 offset0:115 offset1:123
	v_or_b32_e32 v2, s14, v50
	v_or_b32_e32 v3, s38, v3
	ds_write2_b32 v65, v21, v10 offset0:49 offset1:57
	v_cndmask_b32_e64 v2, v3, v2, s[2:3]
	s_waitcnt lgkmcnt(0)
	v_lshrrev_b32_e32 v3, 8, v2
	v_mov_b32_e32 v8, s0
	v_mad_i32_i24 v8, v3, s39, v8
	ds_read2_b32 v[4:5], v67 offset1:1
	ds_read2_b32 v[6:7], v67 offset0:2 offset1:3
	v_ashrrev_i32_e32 v9, 31, v8
	v_lshlrev_b64 v[8:9], 15, v[8:9]
	v_lshlrev_b32_e32 v3, 7, v2
	v_and_b32_e32 v34, 0x7380, v3
	v_lshl_add_u64 v[8:9], s[12:13], 0, v[8:9]
	v_lshl_add_u64 v[8:9], v[8:9], 0, v[34:35]
	v_or_b32_e32 v3, s40, v51
	v_lshl_add_u64 v[8:9], v[8:9], 0, v[36:37]
	v_cmp_eq_u32_e32 vcc, 0, v3
	s_waitcnt lgkmcnt(0)
	global_store_dwordx4 v[8:9], v[4:7], off
	s_and_saveexec_b64 s[18:19], vcc
	s_cbranch_execz .LBB0_2237
	v_ashrrev_i32_e32 v3, 31, v2
	v_lshlrev_b64 v[2:3], 2, v[2:3]
	v_lshl_add_u64 v[4:5], s[10:11], 0, v[2:3]
	global_load_dword v4, v[4:5], off
	v_lshl_add_u64 v[2:3], s[16:17], 0, v[2:3]
	s_waitcnt vmcnt(0)
	v_mul_f32_e32 v4, 0x3c010204, v4
	global_store_dword v[2:3], v4, off

; #define LAS __attribute__((address_space(3)))
; __device__ __forceinline__ void gu_decode(Frame& F, int it, GUDesc& d) {
;     const int q = it / P0_I_GU, r = it % P0_I_GU;
;     if (q < 4) { d.k0 = 128 * (r / 344); d.n0 = 32 * (r % 344); d.bj = q & 1; d.N = FF; d.kt8 = KT8; d.il = 1;
;         d.W = q == 0 ? INP(2) : q == 1 ? INP(3) : q == 2 ? INP(18) : INP(19); d.gain = q < 2 ? INP(1) : INP(17);
;         d.WQ = F.ws + (q < 2 ? WS_WGU1 : WS_WGU2); d.cmax = (const unsigned*)(F.ws + WS_CTL + CTL_CMAX) + (q >> 1) * NGU; d.sb = (float*)(F.ws + WS_SMALL + (q < 2 ? SM_SB1 : SM_SB2)); }
;     else { d.k0 = 128 * (r / 128); d.n0 = 32 * (r % 128); d.bj = 0; d.N = DM; d.kt8 = FF / 128; d.il = 0; d.W = q == 4 ? INP(20) : INP(4); d.gain = nullptr;
;         d.WQ = F.ws + (q == 4 ? WS_WD2 : WS_WD1); d.cmax = (const unsigned*)(F.ws + WS_CTL + CTL_CMAX) + 2 * NGU + (q == 4 ? 0 : DM); d.sb = (float*)(F.ws + WS_SMALL + (q == 4 ? SM_SB3 : SM_SB4)); }
; }
; __device__ __forceinline__ void gu_load(f32x4 (&v)[16], float& gA, float& gB, const GUDesc& d, int lane) {
;     const int kr = lane >> 3, nq = lane & 7;
;     const float* __restrict__ src = d.W + (size_t)(d.k0 + 4 * kr) * d.N + d.n0 + 4 * nq;
;     gA = d.gain ? d.gain[d.k0 + lane] : 1.0f; gB = d.gain ? d.gain[d.k0 + 64 + lane] : 1.0f;
; #pragma unroll
;     for (int i = 0; i < 16; ++i) v[i] = *(const f32x4*)(src + (size_t)(32 * (i >> 2) + (i & 3)) * d.N);
; }
;     const int lane = (F.tid & 63), stride = nworkers * 8, first = lo + worker * 8 + F.wave;
;     LAS unsigned* T = (LAS unsigned*)(F.lds + F.wave * 16384);
;     if (first >= hi) return;
;     const int n_my = (hi - first + stride - 1) / stride;
;     f32x4 va[16], vb[16]; float gaA, gaB, gbA, gbB; GUDesc da, db;
;     gu_decode(F, first, da); gu_load(va, gaA, gaB, da, lane);
.LBB0_2254:
	s_xor_b32 s3, s3, s11
	s_mul_i32 s11, s12, s1
	s_sub_i32 s10, s10, s11
	s_add_i32 s11, s12, 1
	s_sub_i32 s13, s10, s1
	s_cmp_ge_u32 s10, s1
	s_cselect_b32 s11, s11, s12
	s_cselect_b32 s10, s13, s10
	s_add_i32 s12, s11, 1
	s_cmp_ge_u32 s10, s1
	s_cselect_b32 s1, s12, s11
	s_xor_b32 s1, s1, s3
	s_sub_i32 s31, s1, s3
	s_cmp_lt_i32 s31, 1
	s_cbranch_scc1 .LBB0_2299
	v_and_b32_e32 v137, 28, v1
	s_add_u32 s33, s78, 0x26000000
	v_or_b32_e32 v2, s35, v137
	s_addc_u32 s34, s79, 0
	s_lshl_b32 s1, s68, 14
	v_mul_hi_i32_i24_e32 v3, s2, v2
	v_mul_i32_i24_e32 v2, s2, v2
	v_and_b32_e32 v34, 28, v141
	s_add_i32 s16, s1, 0
	s_waitcnt lgkmcnt(0)
	v_lshl_add_u64 v[2:3], v[2:3], 2, v[4:5]
	s_ashr_i32 s1, s0, 31
	v_mov_b32_e32 v131, 0
	v_lshl_add_u64 v[2:3], s[0:1], 2, v[2:3]
	v_lshlrev_b32_e32 v130, 2, v34
	s_lshl_b32 s1, s2, 2
	s_mov_b32 s11, 0
	v_lshl_add_u64 v[36:37], v[2:3], 0, v[130:131]
	s_mul_i32 s10, s2, 0x18c
	s_sub_u32 s12, 0, s1
	v_lshl_add_u64 v[38:39], v[36:37], 0, s[10:11]
	s_subb_u32 s13, 0, 0
	s_waitcnt vmcnt(0)
	v_lshl_add_u64 v[10:11], v[38:39], 0, s[12:13]
	v_lshl_add_u64 v[12:13], v[10:11], 0, s[12:13]
	v_lshl_add_u64 v[18:19], v[12:13], 0, s[12:13]
	v_mov_b32_e32 v35, 0xffffff8c
	v_mad_i64_i32 v[20:21], s[14:15], s2, v35, v[18:19]
	v_lshl_add_u64 v[22:23], v[20:21], 0, s[12:13]
	v_lshl_add_u64 v[24:25], v[22:23], 0, s[12:13]
	global_load_dwordx4 v[2:5], v[10:11], off nt
	global_load_dwordx4 v[6:9], v[12:13], off nt
	s_nop 0
	global_load_dwordx4 v[10:13], v[18:19], off nt
	global_load_dwordx4 v[14:17], v[20:21], off nt
	s_nop 0
	global_load_dwordx4 v[18:21], v[22:23], off nt
	global_load_dwordx4 v[26:29], v[24:25], off nt
	v_lshl_add_u64 v[22:23], v[24:25], 0, s[12:13]
	global_load_dwordx4 v[30:33], v[22:23], off nt
	v_mad_i64_i32 v[22:23], s[14:15], s2, v35, v[22:23]
	global_load_dwordx4 v[66:69], v[22:23], off nt
	v_lshl_add_u64 v[22:23], v[22:23], 0, s[12:13]
	global_load_dwordx4 v[70:73], v[22:23], off nt
	v_lshl_add_u64 v[22:23], v[22:23], 0, s[12:13]
	global_load_dwordx4 v[74:77], v[22:23], off nt
	v_lshl_add_u64 v[22:23], v[22:23], 0, s[12:13]
	global_load_dwordx4 v[78:81], v[22:23], off nt
	v_mad_i64_i32 v[22:23], s[2:3], s2, v35, v[22:23]
	global_load_dwordx4 v[82:85], v[22:23], off nt
	v_lshl_add_u64 v[22:23], v[22:23], 0, s[12:13]
	v_lshl_add_u64 v[40:41], v[22:23], 0, s[12:13]
	global_load_dwordx4 v[86:89], v[22:23], off nt
	global_load_dwordx4 v[90:93], v[40:41], off nt
	s_nop 0
	global_load_dwordx4 v[22:25], v[38:39], off nt
	global_load_dwordx4 v[94:97], v[36:37], off nt
	s_add_i32 s36, s31, -1
	v_mbcnt_lo_u32_b32 v36, -1, 0
	v_lshrrev_b32_e32 v138, 3, v136
	v_and_b32_e32 v139, 7, v0
	v_mbcnt_hi_u32_b32 v36, -1, v36
	s_add_u32 s38, s78, 0x80000
	v_lshlrev_b32_e32 v37, 4, v138
	v_lshlrev_b32_e32 v36, 2, v36
	s_movk_i32 s1, 0x100
	v_lshlrev_b32_e32 v132, 4, v139
	s_addc_u32 s39, s79, 0
	v_lshl_add_u32 v35, v138, 2, s16
	v_and_or_b32 v142, v36, s1, v37
	v_mul_u32_u24_e32 v36, 0x210, v139
	v_add_u32_e32 v37, s16, v132
	v_mul_u32_u24_e32 v38, 0x84, v138
	s_add_u32 s40, s78, 0xab000
	v_lshlrev_b32_e32 v140, 2, v139
	v_or_b32_e32 v143, 4, v142
	v_or_b32_e32 v144, 8, v142
	v_or_b32_e32 v145, 12, v142
	v_or_b32_e32 v146, 0x80, v142
	v_or_b32_e32 v147, 0x84, v142
	v_or_b32_e32 v148, 0x88, v142
	v_or_b32_e32 v149, 0x8c, v142
	v_or_b32_e32 v150, 8, v138
	v_or_b32_e32 v151, 16, v138
	v_or_b32_e32 v152, 24, v138
	v_mov_b32_e32 v133, v131
	s_addc_u32 s41, s79, 0
	s_add_i32 s42, 0, 0x27c10
	s_add_i32 s43, 0, 0x27c18
	s_mov_b32 s44, 0x27c90
	s_mov_b32 s45, 0x600000
	s_mov_b32 s46, 0x200000
	s_mov_b32 s47, 0x27c08
	s_mov_b32 s48, 0x27ca0
	s_mov_b32 s49, 0x660000
	s_mov_b32 s50, 0x20a00000
	v_lshlrev_b32_e32 v134, 2, v34
	s_movk_i32 s51, 0x7f
	s_mov_b32 s52, 0x42fe0000
	v_add_u32_e32 v153, v35, v36
	v_add_u32_e32 v154, v37, v38
	v_mov_b32_e32 v155, 0x7c
	v_mov_b32_e32 v156, 0x67
	v_mov_b32_e32 v157, 0x6f
	v_mov_b32_e32 v158, 0x77
	v_mov_b32_e32 v159, 0x7f
	s_mov_b32 s53, 0
	s_branch .LBB0_2258

; #define LAS __attribute__((address_space(3)))
; __device__ __forceinline__ float bfly8(float x, bool up) { const float p = __uint_as_float(__builtin_amdgcn_update_dpp(0u, __float_as_uint(x), 0x128, 0xf, 0xf, false)); return up ? p - x : x + p; }
; __device__ __forceinline__ void gu_load(f32x4 (&v)[16], float& gA, float& gB, const GUDesc& d, int lane) {
;     const int kr = lane >> 3, nq = lane & 7;
;     const float* __restrict__ src = d.W + (size_t)(d.k0 + 4 * kr) * d.N + d.n0 + 4 * nq;
;     gA = d.gain ? d.gain[d.k0 + lane] : 1.0f; gB = d.gain ? d.gain[d.k0 + 64 + lane] : 1.0f;
; #pragma unroll
;     for (int i = 0; i < 16; ++i) v[i] = *(const f32x4*)(src + (size_t)(32 * (i >> 2) + (i & 3)) * d.N);
; }
; template <int ROT>
; __device__ __forceinline__ void rot32_tile(f32x4 (&v)[16], int lane) {
; #pragma unroll
;     for (int jq = 0; jq < 4; ++jq) {
;         const f32x4 a = v[4 * jq], b = v[4 * jq + 1], c = v[4 * jq + 2], d = v[4 * jq + 3];
;         const f32x4 a1 = a + b, b1 = a - b, c1 = c + d, d1 = c - d;
;         if (ROT >= 2) { v[4 * jq] = a1 + c1; v[4 * jq + 2] = a1 - c1; v[4 * jq + 1] = b1 + d1; v[4 * jq + 3] = b1 - d1; }
;         else { v[4 * jq] = a1; v[4 * jq + 1] = b1; v[4 * jq + 2] = c1; v[4 * jq + 3] = d1; }
;     }
;     { const bool s8 = (lane & 8) != 0, s16 = (lane & 16) != 0, s32 = (lane & 32) != 0;
; #pragma unroll
;       for (int i = 0; i < 16; ++i)
; #pragma unroll
;           for (int e = 0; e < 4; ++e) { float x = v[i][e]; if (ROT >= 3) x = bfly8(x, s8); if (ROT >= 4) x = bfly16(x, s16); if (ROT >= 5) x = bfly32(x, s32); v[i][e] = x; } }
; #pragma unroll
;     for (int i = 0; i < 16; ++i) v[i] *= (ROT == 1 ? 0.70710678118654752f : ROT == 2 ? 0.5f : ROT == 3 ? 0.35355339059327373f : ROT == 4 ? 0.25f : 0.17677669529663687f);
; }
; template <bool STRIP, int ROT>
; __device__ __forceinline__ void gu_finish_t(f32x4 (&v)[16], float gA, float gB, const GUDesc& d, LAS unsigned* T, int lane, const float (&sinv)[4]) {
;     const int kr = lane >> 3, nq = lane & 7;
;     const int dq0 = d.il ? gu_dest(d.n0 + 4 * nq, d.bj) : d.n0 + 4 * nq;
;     if (ROT) rot32_tile<ROT>(v, lane);
;     float inv[4];
; #pragma unroll
;     for (int e = 0; e < 4; ++e) { if (STRIP) inv[e] = sinv[e]; else { const float cm = __uint_as_float(d.cmax[dq0 + e]); inv[e] = cm > 0.f ? 127.0f / cm : 0.f; } }
.LBB0_2269:
	v_or_b32_e32 v34, s55, v137
	s_add_u32 s24, s33, s4
	v_mul_hi_i32_i24_e32 v35, s26, v34
	v_mul_i32_i24_e32 v34, s26, v34
	s_addc_u32 s25, s34, s5
	s_waitcnt lgkmcnt(0)
	v_lshl_add_u64 v[34:35], v[34:35], 2, v[36:37]
	s_ashr_i32 s15, s14, 31
	v_lshl_add_u64 v[34:35], s[14:15], 2, v[34:35]
	v_mov_b32_e32 v135, v131
	v_lshl_add_u64 v[34:35], v[34:35], 0, v[134:135]
	s_lshl_b32 s10, s26, 2
	v_lshl_add_u64 v[36:37], v[34:35], 0, s[10:11]
	global_load_dwordx4 v[122:125], v[34:35], off nt
	global_load_dwordx4 v[126:129], v[36:37], off nt
	v_lshl_add_u64 v[34:35], v[36:37], 0, s[10:11]
	v_lshl_add_u64 v[36:37], v[34:35], 0, s[10:11]
	s_mul_i32 s4, s26, 0x74
	s_mov_b32 s5, s11
	global_load_dwordx4 v[114:117], v[34:35], off nt
	global_load_dwordx4 v[118:121], v[36:37], off nt
	v_lshl_add_u64 v[34:35], v[36:37], 0, s[4:5]
	v_lshl_add_u64 v[36:37], v[34:35], 0, s[10:11]
	global_load_dwordx4 v[106:109], v[34:35], off nt
	global_load_dwordx4 v[110:113], v[36:37], off nt
	v_lshl_add_u64 v[34:35], v[36:37], 0, s[10:11]
	v_lshl_add_u64 v[36:37], v[34:35], 0, s[10:11]
	global_load_dwordx4 v[98:101], v[34:35], off nt
	global_load_dwordx4 v[102:105], v[36:37], off nt
	v_lshl_add_u64 v[34:35], v[36:37], 0, s[4:5]
	global_load_dwordx4 v[54:57], v[34:35], off nt
	v_lshl_add_u64 v[34:35], v[34:35], 0, s[10:11]
	global_load_dwordx4 v[62:65], v[34:35], off nt
	v_lshl_add_u64 v[34:35], v[34:35], 0, s[10:11]
	v_add_u32_e32 v130, s0, v140
	global_load_dwordx4 v[50:53], v[34:35], off nt
	v_lshl_add_u64 v[34:35], v[34:35], 0, s[10:11]
	s_cmp_eq_u32 s57, 0
	v_lshlrev_b32_e32 v135, 1, v130
	global_load_dwordx4 v[58:61], v[34:35], off nt
	v_lshl_add_u64 v[34:35], v[34:35], 0, s[4:5]
	s_cselect_b64 s[4:5], -1, 0
	v_and_b32_e32 v135, 0xffffff00, v135
	s_lshl_b32 s1, s56, 7
	v_add_u32_e32 v135, s1, v135
	v_and_or_b32 v135, v130, s51, v135
	v_cndmask_b32_e64 v164, v135, v130, s[4:5]
	s_waitcnt vmcnt(12)
	v_pk_add_f32 v[166:167], v[96:97], v[92:93]
	v_pk_add_f32 v[168:169], v[94:95], v[90:91]
	v_sub_f32_e32 v93, v97, v93
	v_sub_f32_e32 v92, v96, v92
	v_sub_f32_e32 v91, v95, v91
	v_sub_f32_e32 v90, v94, v90
	v_pk_add_f32 v[94:95], v[88:89], v[84:85]
	v_pk_add_f32 v[96:97], v[86:87], v[82:83]
	v_sub_f32_e32 v171, v89, v85
	v_sub_f32_e32 v170, v88, v84
	v_sub_f32_e32 v173, v87, v83
	v_sub_f32_e32 v172, v86, v82
	v_pk_add_f32 v[86:87], v[166:167], v[94:95]
	v_pk_add_f32 v[88:89], v[168:169], v[96:97]
	v_sub_f32_e32 v83, v167, v95
	v_sub_f32_e32 v82, v166, v94
	v_sub_f32_e32 v85, v169, v97
	v_sub_f32_e32 v84, v168, v96
	v_pk_add_f32 v[166:167], v[80:81], v[76:77]
	v_pk_add_f32 v[168:169], v[78:79], v[74:75]
	v_sub_f32_e32 v77, v81, v77
	v_sub_f32_e32 v76, v80, v76
	v_sub_f32_e32 v75, v79, v75
	v_sub_f32_e32 v74, v78, v74
	v_pk_add_f32 v[78:79], v[72:73], v[68:69]
	v_pk_add_f32 v[80:81], v[70:71], v[66:67]
	v_sub_f32_e32 v67, v71, v67
	v_sub_f32_e32 v66, v70, v66
	v_ashrrev_i32_e32 v165, 31, v164
	v_pk_add_f32 v[70:71], v[166:167], v[78:79]
	v_sub_f32_e32 v79, v167, v79
	v_sub_f32_e32 v78, v166, v78
	v_pk_add_f32 v[166:167], v[74:75], v[66:67]
	v_sub_f32_e32 v75, v75, v67
	v_sub_f32_e32 v74, v74, v66
	v_lshl_add_u64 v[66:67], v[164:165], 2, s[8:9]
	v_sub_f32_e32 v73, v73, v69
	v_sub_f32_e32 v72, v72, v68
	global_load_dwordx4 v[66:69], v[66:67], off nt
	v_pk_add_f32 v[96:97], v[92:93], v[170:171]
	v_sub_f32_e32 v93, v93, v171
	v_sub_f32_e32 v92, v92, v170
	v_pk_add_f32 v[170:171], v[168:169], v[80:81]
	v_sub_f32_e32 v81, v169, v81
	v_sub_f32_e32 v80, v168, v80
	v_pk_add_f32 v[168:169], v[76:77], v[72:73]
	v_sub_f32_e32 v73, v77, v73
	v_sub_f32_e32 v72, v76, v72
	v_pk_add_f32 v[76:77], v[32:33], v[28:29]
	v_pk_add_f32 v[164:165], v[30:31], v[26:27]
	v_sub_f32_e32 v29, v33, v29
	v_sub_f32_e32 v28, v32, v28
	v_sub_f32_e32 v27, v31, v27
	v_sub_f32_e32 v26, v30, v26
	v_pk_add_f32 v[30:31], v[20:21], v[16:17]
	v_pk_add_f32 v[32:33], v[18:19], v[14:15]
	v_sub_f32_e32 v17, v21, v17
	v_sub_f32_e32 v16, v20, v16
	v_sub_f32_e32 v15, v19, v15
	v_sub_f32_e32 v14, v18, v14
	v_pk_add_f32 v[18:19], v[76:77], v[30:31]
	v_pk_add_f32 v[20:21], v[164:165], v[32:33]
	v_sub_f32_e32 v31, v77, v31
	v_sub_f32_e32 v30, v76, v30
	v_sub_f32_e32 v33, v165, v33
	v_sub_f32_e32 v32, v164, v32
	v_pk_add_f32 v[76:77], v[26:27], v[14:15]
	v_pk_add_f32 v[164:165], v[28:29], v[16:17]
	v_sub_f32_e32 v15, v27, v15
	v_sub_f32_e32 v14, v26, v14
	v_sub_f32_e32 v17, v29, v17
	v_sub_f32_e32 v16, v28, v16
	v_pk_add_f32 v[26:27], v[8:9], v[12:13]
	v_pk_add_f32 v[28:29], v[6:7], v[10:11]
	v_sub_f32_e32 v7, v11, v7
	v_sub_f32_e32 v6, v10, v6
	v_pk_add_f32 v[10:11], v[24:25], v[4:5]
	v_sub_f32_e32 v9, v13, v9
	v_sub_f32_e32 v8, v12, v8
	v_pk_add_f32 v[12:13], v[22:23], v[2:3]
	v_sub_f32_e32 v3, v3, v23
	v_sub_f32_e32 v2, v2, v22
	v_pk_add_f32 v[22:23], v[10:11], v[26:27]
	v_sub_f32_e32 v5, v5, v25
	v_sub_f32_e32 v4, v4, v24
	v_pk_add_f32 v[24:25], v[12:13], v[28:29]
	v_sub_f32_e32 v29, v29, v13
	v_sub_f32_e32 v28, v28, v12
	v_pk_add_f32 v[12:13], v[2:3], v[6:7]
	v_sub_f32_e32 v175, v7, v3
	v_sub_f32_e32 v174, v6, v2
	v_pk_mul_f32 v[2:3], v[22:23], 0.5 op_sel_hi:[1,0]
	v_sub_f32_e32 v27, v27, v11
	v_sub_f32_e32 v26, v26, v10
	v_pk_mul_f32 v[10:11], v[24:25], 0.5 op_sel_hi:[1,0]
	v_pk_mul_f32 v[6:7], v[26:27], 0.5 op_sel_hi:[1,0]
	v_pk_mul_f32 v[178:179], v[14:15], 0.5 op_sel_hi:[1,0]
	v_pk_mul_f32 v[14:15], v[28:29], 0.5 op_sel_hi:[1,0]
	v_pk_add_f32 v[94:95], v[90:91], v[172:173]
	v_pk_mul_f32 v[88:89], v[88:89], 0.5 op_sel_hi:[1,0]
	v_pk_mul_f32 v[94:95], v[94:95], 0.5 op_sel_hi:[1,0]
	v_sub_f32_e32 v91, v91, v173
	v_sub_f32_e32 v90, v90, v172
	v_pk_mul_f32 v[84:85], v[84:85], 0.5 op_sel_hi:[1,0]
	v_pk_mul_f32 v[90:91], v[90:91], 0.5 op_sel_hi:[1,0]
	v_pk_mul_f32 v[86:87], v[86:87], 0.5 op_sel_hi:[1,0]
	v_pk_mul_f32 v[96:97], v[96:97], 0.5 op_sel_hi:[1,0]
	v_pk_mul_f32 v[82:83], v[82:83], 0.5 op_sel_hi:[1,0]
	v_pk_mul_f32 v[92:93], v[92:93], 0.5 op_sel_hi:[1,0]
	global_load_dwordx4 v[38:41], v[34:35], off nt
	v_lshl_add_u64 v[34:35], v[34:35], 0, s[10:11]
	v_lshl_add_u64 v[42:43], v[34:35], 0, s[10:11]
	global_load_dwordx4 v[46:49], v[34:35], off nt
	v_pk_mul_f32 v[170:171], v[170:171], 0.5 op_sel_hi:[1,0]
	global_load_dwordx4 v[34:37], v[42:43], off nt
	v_lshl_add_u64 v[42:43], v[42:43], 0, s[10:11]
	global_load_dwordx4 v[42:45], v[42:43], off nt
	v_pk_mul_f32 v[166:167], v[166:167], 0.5 op_sel_hi:[1,0]
	s_waitcnt vmcnt(4)
; #define LAS __attribute__((address_space(3)))
; __device__ __forceinline__ float bfly8(float x, bool up) { const float p = __uint_as_float(__builtin_amdgcn_update_dpp(0u, __float_as_uint(x), 0x128, 0xf, 0xf, false)); return up ? p - x : x + p; }
; __device__ __forceinline__ float bfly16(float x, bool up) { const auto r = __builtin_amdgcn_permlane16_swap(__float_as_uint(x), __float_as_uint(x), false, false); const float a = __uint_as_float(r[0]), b = __uint_as_float(r[1]); return up ? a - b : a + b; }
; __device__ __forceinline__ float bfly32(float x, bool up) { const auto r = __builtin_amdgcn_permlane32_swap(__float_as_uint(x), __float_as_uint(x), false, false); const float a = __uint_as_float(r[0]), b = __uint_as_float(r[1]); return up ? a - b : a + b; }
; template <int ROT>
; __device__ __forceinline__ void rot32_tile(f32x4 (&v)[16], int lane) {
;     ...
;           for (int e = 0; e < 4; ++e) { float x = v[i][e]; if (ROT >= 3) x = bfly8(x, s8); if (ROT >= 4) x = bfly16(x, s16); if (ROT >= 5) x = bfly32(x, s32); v[i][e] = x; } }
; #pragma unroll
;     for (int i = 0; i < 16; ++i) v[i] *= (ROT == 1 ? 0.70710678118654752f : ROT == 2 ? 0.5f : ROT == 3 ? 0.35355339059327373f : ROT == 4 ? 0.25f : 0.17677669529663687f);
; }
; template <bool STRIP, int ROT>
; __device__ __forceinline__ void gu_finish_t(f32x4 (&v)[16], float gA, float gB, const GUDesc& d, LAS unsigned* T, int lane, const float (&sinv)[4]) {
;     const int kr = lane >> 3, nq = lane & 7;
;     const int dq0 = d.il ? gu_dest(d.n0 + 4 * nq, d.bj) : d.n0 + 4 * nq;
;     if (ROT) rot32_tile<ROT>(v, lane);
;     float inv[4];
; #pragma unroll
;     for (int e = 0; e < 4; ++e) { if (STRIP) inv[e] = sinv[e]; else { const float cm = __uint_as_float(d.cmax[dq0 + e]); inv[e] = cm > 0.f ? 127.0f / cm : 0.f; } }
; #pragma unroll
;     for (int jq = 0; jq < 4; ++jq) {
;         float g[4];
; #pragma unroll
;         for (int e2 = 0; e2 < 4; ++e2) g[e2] = jq < 2 ? __shfl(gA, 32 * jq + 4 * kr + e2) : __shfl(gB, 32 * (jq - 2) + 4 * kr + e2);
; #pragma unroll
;         for (int e = 0; e < 4; ++e)
;             T[(4 * nq + e) * 33 + 8 * jq + kr] = pack4_i8(v[4 * jq + 0][e] * g[0] * inv[e], v[4 * jq + 1][e] * g[1] * inv[e], v[4 * jq + 2][e] * g[2] * inv[e], v[4 * jq + 3][e] * g[3] * inv[e]);
;     }
	v_div_scale_f32 v22, s[26:27], v66, v66, s52
	v_rcp_f32_e32 v23, v22
	v_pk_mul_f32 v[80:81], v[80:81], 0.5 op_sel_hi:[1,0]
	v_pk_mul_f32 v[74:75], v[74:75], 0.5 op_sel_hi:[1,0]
	v_pk_mul_f32 v[70:71], v[70:71], 0.5 op_sel_hi:[1,0]
	v_fma_f32 v24, -v22, v23, 1.0
	v_fmac_f32_e32 v23, v24, v23
	v_div_scale_f32 v24, vcc, s52, v66, s52
	v_mul_f32_e32 v25, v24, v23
	v_fma_f32 v26, -v22, v25, v24
	v_fmac_f32_e32 v25, v26, v23
	v_fma_f32 v22, -v22, v25, v24
	v_div_fmas_f32 v22, v22, v23, v25
	v_div_scale_f32 v23, s[26:27], v67, v67, s52
	v_rcp_f32_e32 v24, v23
	v_div_fixup_f32 v22, v22, v66, s52
	v_cmp_lt_f32_e32 vcc, 0, v66
	v_pk_mul_f32 v[168:169], v[168:169], 0.5 op_sel_hi:[1,0]
	v_fma_f32 v25, -v23, v24, 1.0
	v_cndmask_b32_e32 v22, 0, v22, vcc
	v_fmac_f32_e32 v24, v25, v24
	v_div_scale_f32 v25, vcc, s52, v67, s52
	v_mul_f32_e32 v26, v25, v24
	v_fma_f32 v27, -v23, v26, v25
	v_fmac_f32_e32 v26, v27, v24
	v_fma_f32 v23, -v23, v26, v25
	v_div_fmas_f32 v23, v23, v24, v26
	v_div_scale_f32 v24, s[26:27], v68, v68, s52
	v_rcp_f32_e32 v25, v24
	v_div_fixup_f32 v23, v23, v67, s52
	v_cmp_lt_f32_e32 vcc, 0, v67
	v_pk_mul_f32 v[78:79], v[78:79], 0.5 op_sel_hi:[1,0]
	v_fma_f32 v26, -v24, v25, 1.0
	v_cndmask_b32_e32 v23, 0, v23, vcc
	v_fmac_f32_e32 v25, v26, v25
	v_div_scale_f32 v26, vcc, s52, v68, s52
	v_mul_f32_e32 v27, v26, v25
	v_fma_f32 v28, -v24, v27, v26
	v_fmac_f32_e32 v27, v28, v25
	v_fma_f32 v24, -v24, v27, v26
	v_div_fmas_f32 v24, v24, v25, v27
	v_div_scale_f32 v25, s[26:27], v69, v69, s52
	v_rcp_f32_e32 v26, v25
	v_div_fixup_f32 v24, v24, v68, s52
	v_cmp_lt_f32_e32 vcc, 0, v68
	v_pk_mul_f32 v[72:73], v[72:73], 0.5 op_sel_hi:[1,0]
	v_fma_f32 v27, -v25, v26, 1.0
	v_cndmask_b32_e32 v24, 0, v24, vcc
	v_fmac_f32_e32 v26, v27, v26
	v_div_scale_f32 v27, vcc, s52, v69, s52
	v_mul_f32_e32 v28, v27, v26
	v_fma_f32 v29, -v25, v28, v27
	v_fmac_f32_e32 v28, v29, v26
	v_fma_f32 v25, -v25, v28, v27
	v_div_fmas_f32 v25, v25, v26, v28
	ds_bpermute_b32 v26, v142, v161
	ds_bpermute_b32 v27, v143, v161
	ds_bpermute_b32 v28, v144, v161
	ds_bpermute_b32 v29, v145, v161
	v_div_fixup_f32 v25, v25, v69, s52
	s_waitcnt lgkmcnt(3)
	v_mul_f32_e32 v66, v88, v26
	s_waitcnt lgkmcnt(2)
	v_mul_f32_e32 v67, v94, v27
	v_fmaak_f32 v66, v22, v66, 0x43000000
	s_waitcnt lgkmcnt(1)
	v_mul_f32_e32 v68, v84, v28
	v_cvt_pk_u8_f32 v66, v66, 0, 0
	v_fmaak_f32 v67, v22, v67, 0x43000000
	v_cmp_lt_f32_e32 vcc, 0, v69
	s_waitcnt lgkmcnt(0)
	v_mul_f32_e32 v69, v90, v29
	v_cvt_pk_u8_f32 v66, v67, 1, v66
	v_fmaak_f32 v67, v22, v68, 0x43000000
	v_cvt_pk_u8_f32 v66, v67, 2, v66
	v_fmaak_f32 v67, v22, v69, 0x43000000
	v_cvt_pk_u8_f32 v66, v67, 3, v66
	v_mul_f32_e32 v67, v89, v26
	v_mul_f32_e32 v68, v95, v27
	v_fmaak_f32 v67, v23, v67, 0x43000000
	v_mul_f32_e32 v69, v85, v28
	v_cvt_pk_u8_f32 v67, v67, 0, 0
	v_fmaak_f32 v68, v23, v68, 0x43000000
	v_mul_f32_e32 v84, v91, v29
	v_cvt_pk_u8_f32 v67, v68, 1, v67
	v_fmaak_f32 v68, v23, v69, 0x43000000
	v_cvt_pk_u8_f32 v67, v68, 2, v67
	v_fmaak_f32 v68, v23, v84, 0x43000000
	v_cndmask_b32_e32 v25, 0, v25, vcc
	v_cvt_pk_u8_f32 v67, v68, 3, v67
	v_mul_f32_e32 v68, v86, v26
	v_mul_f32_e32 v26, v87, v26
	v_mul_f32_e32 v69, v96, v27
	v_mul_f32_e32 v27, v97, v27
	v_fmaak_f32 v26, v25, v26, 0x43000000
	v_mul_f32_e32 v82, v82, v28
	v_mul_f32_e32 v28, v83, v28
	v_cvt_pk_u8_f32 v26, v26, 0, 0
	v_fmaak_f32 v27, v25, v27, 0x43000000
	v_mul_f32_e32 v84, v92, v29
	v_mul_f32_e32 v29, v93, v29
	v_cvt_pk_u8_f32 v26, v27, 1, v26
	v_fmaak_f32 v27, v25, v28, 0x43000000
	v_fmaak_f32 v68, v24, v68, 0x43000000
	v_cvt_pk_u8_f32 v26, v27, 2, v26
	v_fmaak_f32 v27, v25, v29, 0x43000000
	v_cvt_pk_u8_f32 v68, v68, 0, 0
	v_fmaak_f32 v69, v24, v69, 0x43000000
	v_cvt_pk_u8_f32 v26, v27, 3, v26
	ds_bpermute_b32 v27, v146, v161
	v_cvt_pk_u8_f32 v68, v69, 1, v68
	v_fmaak_f32 v69, v24, v82, 0x43000000
	ds_bpermute_b32 v28, v147, v161
	v_cvt_pk_u8_f32 v68, v69, 2, v68
	v_fmaak_f32 v69, v24, v84, 0x43000000
	ds_bpermute_b32 v29, v148, v161
	v_cvt_pk_u8_f32 v68, v69, 3, v68
	ds_bpermute_b32 v69, v149, v161
	s_waitcnt lgkmcnt(3)
	v_mul_f32_e32 v82, v170, v27
	s_waitcnt lgkmcnt(2)
	v_mul_f32_e32 v83, v166, v28
	v_fmaak_f32 v82, v22, v82, 0x43000000
	s_waitcnt lgkmcnt(1)
	v_mul_f32_e32 v80, v80, v29
	v_cvt_pk_u8_f32 v82, v82, 0, 0
	v_fmaak_f32 v83, v22, v83, 0x43000000
	s_waitcnt lgkmcnt(0)
	v_mul_f32_e32 v74, v74, v69
	v_cvt_pk_u8_f32 v82, v83, 1, v82
	v_fmaak_f32 v80, v22, v80, 0x43000000
	v_cvt_pk_u8_f32 v80, v80, 2, v82
	v_fmaak_f32 v74, v22, v74, 0x43000000
	v_cvt_pk_u8_f32 v74, v74, 3, v80
	v_xor_b32_e32 v66, 0x80808080, v66
	v_xor_b32_e32 v74, 0x80808080, v74
	ds_write2_b32 v153, v66, v74 offset1:8
	v_mul_f32_e32 v66, v171, v27
	v_mul_f32_e32 v74, v167, v28
	v_fmaak_f32 v66, v23, v66, 0x43000000
	v_mul_f32_e32 v80, v81, v29
	v_cvt_pk_u8_f32 v66, v66, 0, 0
	v_fmaak_f32 v74, v23, v74, 0x43000000
	v_mul_f32_e32 v75, v75, v69
	v_cvt_pk_u8_f32 v66, v74, 1, v66
	v_fmaak_f32 v74, v23, v80, 0x43000000
	v_cvt_pk_u8_f32 v66, v74, 2, v66
	v_fmaak_f32 v74, v23, v75, 0x43000000
	v_cvt_pk_u8_f32 v66, v74, 3, v66
	v_xor_b32_e32 v67, 0x80808080, v67
	v_xor_b32_e32 v66, 0x80808080, v66
	ds_write2_b32 v153, v67, v66 offset0:33 offset1:41
	v_mul_f32_e32 v66, v70, v27
	v_mul_f32_e32 v67, v168, v28
	v_fmaak_f32 v66, v24, v66, 0x43000000
	v_mul_f32_e32 v70, v78, v29
	v_cvt_pk_u8_f32 v66, v66, 0, 0
	v_fmaak_f32 v67, v24, v67, 0x43000000
	v_mul_f32_e32 v72, v72, v69
	v_cvt_pk_u8_f32 v66, v67, 1, v66
	v_fmaak_f32 v67, v24, v70, 0x43000000
	v_cvt_pk_u8_f32 v66, v67, 2, v66
	v_fmaak_f32 v67, v24, v72, 0x43000000
	v_mul_f32_e32 v27, v71, v27
	v_cvt_pk_u8_f32 v66, v67, 3, v66
	v_mul_f32_e32 v28, v169, v28
	v_fmaak_f32 v27, v25, v27, 0x43000000
	v_xor_b32_e32 v68, 0x80808080, v68
	v_xor_b32_e32 v66, 0x80808080, v66
	v_mul_f32_e32 v29, v79, v29
	v_cvt_pk_u8_f32 v27, v27, 0, 0
	v_fmaak_f32 v28, v25, v28, 0x43000000
	ds_write2_b32 v153, v68, v66 offset0:66 offset1:74
	v_mul_f32_e32 v66, v73, v69
	v_cvt_pk_u8_f32 v27, v28, 1, v27
	v_fmaak_f32 v28, v25, v29, 0x43000000
	v_cvt_pk_u8_f32 v27, v28, 2, v27
	v_fmaak_f32 v28, v25, v66, 0x43000000
	v_cvt_pk_u8_f32 v27, v28, 3, v27
	ds_bpermute_b32 v28, v142, v160
	ds_bpermute_b32 v29, v143, v160
	ds_bpermute_b32 v66, v144, v160
	ds_bpermute_b32 v67, v145, v160
	v_pk_mul_f32 v[20:21], v[20:21], 0.5 op_sel_hi:[1,0]
	v_pk_mul_f32 v[76:77], v[76:77], 0.5 op_sel_hi:[1,0]
	v_xor_b32_e32 v26, 0x80808080, v26
	v_xor_b32_e32 v27, 0x80808080, v27
	s_waitcnt lgkmcnt(3)
; #define LAS __attribute__((address_space(3)))
; __host__ __device__ __forceinline__ size_t blk8_off(int r, int k, int KT8_) { return ((size_t)((r >> 8) * KT8_ + (k >> 7)) * 256 + (size_t)(r & 255)) * 128 + (size_t)(k & 127); }
; #define LDS_WAIT() asm volatile("s_waitcnt lgkmcnt(0)" ::: "memory")
; template <bool STRIP, int ROT>
; __device__ __forceinline__ void gu_finish_t(f32x4 (&v)[16], float gA, float gB, const GUDesc& d, LAS unsigned* T, int lane, const float (&sinv)[4]) {
;     ...
;     for (int jq = 0; jq < 4; ++jq) {
;         float g[4];
; #pragma unroll
;         for (int e2 = 0; e2 < 4; ++e2) g[e2] = jq < 2 ? __shfl(gA, 32 * jq + 4 * kr + e2) : __shfl(gB, 32 * (jq - 2) + 4 * kr + e2);
; #pragma unroll
;         for (int e = 0; e < 4; ++e)
;             T[(4 * nq + e) * 33 + 8 * jq + kr] = pack4_i8(v[4 * jq + 0][e] * g[0] * inv[e], v[4 * jq + 1][e] * g[1] * inv[e], v[4 * jq + 2][e] * g[2] * inv[e], v[4 * jq + 3][e] * g[3] * inv[e]);
;     }
;     LDS_WAIT(); asm volatile("" ::: "memory");
;     const int nl = lane >> 3, c = lane & 7;
; #pragma unroll
;     for (int g4 = 0; g4 < 4; ++g4) {
;         const int nloc = 8 * g4 + nl, dr = d.il ? gu_dest(d.n0 + nloc, d.bj) : d.n0 + nloc;
;         const LAS unsigned* t = T + nloc * 33 + 4 * c;
;         u32x4 o; o.x = t[0]; o.y = t[1]; o.z = t[2]; o.w = t[3];
;         *(u32x4*)(d.WQ + blk8_off(dr, d.k0 + 16 * c, d.kt8)) = o;
;         if (!STRIP) if (d.k0 == 0 && c == 0) d.sb[dr] = __uint_as_float(d.cmax[dr]) * (1.0f / 127.0f);
;     }
	v_mul_f32_e32 v20, v20, v28
	v_pk_mul_f32 v[32:33], v[32:33], 0.5 op_sel_hi:[1,0]
	ds_write2_b32 v153, v26, v27 offset0:99 offset1:107
	s_waitcnt lgkmcnt(3)
	v_mul_f32_e32 v26, v76, v29
	v_fmaak_f32 v20, v22, v20, 0x43000000
	s_waitcnt lgkmcnt(2)
	v_mul_f32_e32 v27, v32, v66
	v_cvt_pk_u8_f32 v20, v20, 0, 0
	v_fmaak_f32 v26, v22, v26, 0x43000000
	s_waitcnt lgkmcnt(1)
	v_mul_f32_e32 v32, v178, v67
	v_cvt_pk_u8_f32 v20, v26, 1, v20
	v_fmaak_f32 v26, v22, v27, 0x43000000
	v_cvt_pk_u8_f32 v20, v26, 2, v20
	v_fmaak_f32 v26, v22, v32, 0x43000000
	v_mul_f32_e32 v21, v21, v28
	v_cvt_pk_u8_f32 v20, v26, 3, v20
	v_mul_f32_e32 v26, v77, v29
	v_fmaak_f32 v21, v23, v21, 0x43000000
	v_mul_f32_e32 v27, v33, v66
	v_cvt_pk_u8_f32 v21, v21, 0, 0
	v_fmaak_f32 v26, v23, v26, 0x43000000
	v_pk_mul_f32 v[18:19], v[18:19], 0.5 op_sel_hi:[1,0]
	v_mul_f32_e32 v32, v179, v67
	v_cvt_pk_u8_f32 v21, v26, 1, v21
	v_fmaak_f32 v26, v23, v27, 0x43000000
	v_pk_mul_f32 v[164:165], v[164:165], 0.5 op_sel_hi:[1,0]
	v_cvt_pk_u8_f32 v21, v26, 2, v21
	v_fmaak_f32 v26, v23, v32, 0x43000000
	v_mul_f32_e32 v18, v18, v28
	v_pk_mul_f32 v[30:31], v[30:31], 0.5 op_sel_hi:[1,0]
	v_cvt_pk_u8_f32 v21, v26, 3, v21
	v_mul_f32_e32 v26, v164, v29
	v_fmaak_f32 v18, v24, v18, 0x43000000
	v_pk_mul_f32 v[176:177], v[16:17], 0.5 op_sel_hi:[1,0]
	v_mul_f32_e32 v27, v30, v66
	v_cvt_pk_u8_f32 v18, v18, 0, 0
	v_fmaak_f32 v26, v24, v26, 0x43000000
	v_mul_f32_e32 v30, v176, v67
	v_cvt_pk_u8_f32 v18, v26, 1, v18
	v_fmaak_f32 v26, v24, v27, 0x43000000
	v_cvt_pk_u8_f32 v18, v26, 2, v18
	v_fmaak_f32 v26, v24, v30, 0x43000000
	v_mul_f32_e32 v19, v19, v28
	v_cvt_pk_u8_f32 v18, v26, 3, v18
	v_mul_f32_e32 v26, v165, v29
	v_fmaak_f32 v19, v25, v19, 0x43000000
	v_mul_f32_e32 v27, v31, v66
	v_cvt_pk_u8_f32 v19, v19, 0, 0
	v_fmaak_f32 v26, v25, v26, 0x43000000
	v_mul_f32_e32 v28, v177, v67
	v_cvt_pk_u8_f32 v19, v26, 1, v19
	v_fmaak_f32 v26, v25, v27, 0x43000000
	v_cvt_pk_u8_f32 v19, v26, 2, v19
	v_fmaak_f32 v26, v25, v28, 0x43000000
	v_cvt_pk_u8_f32 v19, v26, 3, v19
	ds_bpermute_b32 v26, v146, v160
	ds_bpermute_b32 v27, v147, v160
	ds_bpermute_b32 v28, v148, v160
	ds_bpermute_b32 v29, v149, v160
	v_pk_add_f32 v[172:173], v[4:5], v[8:9]
	v_sub_f32_e32 v9, v9, v5
	v_sub_f32_e32 v8, v8, v4
	v_pk_mul_f32 v[4:5], v[172:173], 0.5 op_sel_hi:[1,0]
	s_waitcnt lgkmcnt(3)
	v_mul_f32_e32 v2, v2, v26
	s_waitcnt lgkmcnt(2)
	v_mul_f32_e32 v4, v4, v27
	v_fmaak_f32 v2, v24, v2, 0x43000000
	v_pk_mul_f32 v[8:9], v[8:9], 0.5 op_sel_hi:[1,0]
	s_waitcnt lgkmcnt(1)
	v_mul_f32_e32 v6, v6, v28
	v_cvt_pk_u8_f32 v2, v2, 0, 0
	v_fmaak_f32 v4, v24, v4, 0x43000000
	s_waitcnt lgkmcnt(0)
	v_mul_f32_e32 v8, v8, v29
	v_cvt_pk_u8_f32 v2, v4, 1, v2
	v_fmaak_f32 v4, v24, v6, 0x43000000
	v_cvt_pk_u8_f32 v2, v4, 2, v2
	v_fmaak_f32 v4, v24, v8, 0x43000000
	v_pk_mul_f32 v[12:13], v[12:13], 0.5 op_sel_hi:[1,0]
	v_mul_f32_e32 v10, v10, v26
	v_cvt_pk_u8_f32 v2, v4, 3, v2
	v_xor_b32_e32 v18, 0x80808080, v18
	v_mul_f32_e32 v12, v12, v27
	v_fmaak_f32 v10, v22, v10, 0x43000000
	v_xor_b32_e32 v2, 0x80808080, v2
	v_pk_mul_f32 v[16:17], v[174:175], 0.5 op_sel_hi:[1,0]
	v_mul_f32_e32 v14, v14, v28
	v_cvt_pk_u8_f32 v10, v10, 0, 0
	v_fmaak_f32 v12, v22, v12, 0x43000000
	ds_write2_b32 v153, v18, v2 offset0:82 offset1:90
	v_mul_f32_e32 v2, v3, v26
	v_mul_f32_e32 v16, v16, v29
	v_cvt_pk_u8_f32 v10, v12, 1, v10
	v_fmaak_f32 v12, v22, v14, 0x43000000
	v_mul_f32_e32 v3, v5, v27
	v_fmaak_f32 v2, v25, v2, 0x43000000
	v_cvt_pk_u8_f32 v10, v12, 2, v10
	v_fmaak_f32 v12, v22, v16, 0x43000000
	v_mul_f32_e32 v4, v7, v28
	v_cvt_pk_u8_f32 v2, v2, 0, 0
	v_fmaak_f32 v3, v25, v3, 0x43000000
	v_cvt_pk_u8_f32 v10, v12, 3, v10
	v_mul_f32_e32 v5, v9, v29
	v_cvt_pk_u8_f32 v2, v3, 1, v2
	v_fmaak_f32 v3, v25, v4, 0x43000000
	v_xor_b32_e32 v20, 0x80808080, v20
	v_xor_b32_e32 v10, 0x80808080, v10
	v_cvt_pk_u8_f32 v2, v3, 2, v2
	v_fmaak_f32 v3, v25, v5, 0x43000000
	ds_write2_b32 v153, v20, v10 offset0:16 offset1:24
	v_mul_f32_e32 v10, v11, v26
	v_cvt_pk_u8_f32 v2, v3, 3, v2
	v_xor_b32_e32 v19, 0x80808080, v19
	v_mul_f32_e32 v11, v13, v27
	v_fmaak_f32 v10, v23, v10, 0x43000000
	v_xor_b32_e32 v2, 0x80808080, v2
	v_mul_f32_e32 v12, v15, v28
	v_cvt_pk_u8_f32 v10, v10, 0, 0
	v_fmaak_f32 v11, v23, v11, 0x43000000
	ds_write2_b32 v153, v19, v2 offset0:115 offset1:123
	v_add_u32_e32 v2, s0, v138
	v_mul_f32_e32 v13, v17, v29
	v_cvt_pk_u8_f32 v10, v11, 1, v10
	v_fmaak_f32 v11, v23, v12, 0x43000000
	v_lshlrev_b32_e32 v3, 1, v2
	v_cvt_pk_u8_f32 v10, v11, 2, v10
	v_fmaak_f32 v11, v23, v13, 0x43000000
	v_and_b32_e32 v3, 0xffffff00, v3
	v_cvt_pk_u8_f32 v10, v11, 3, v10
	v_add_u32_e32 v3, s1, v3
	v_xor_b32_e32 v21, 0x80808080, v21
	v_xor_b32_e32 v10, 0x80808080, v10
	v_and_or_b32 v3, v2, s51, v3
	ds_write2_b32 v153, v21, v10 offset0:49 offset1:57
	v_cndmask_b32_e64 v2, v3, v2, s[4:5]
	v_add_u32_e32 v3, s35, v132
	s_waitcnt lgkmcnt(0)
	v_lshrrev_b32_e32 v5, 8, v2
	v_ashrrev_i32_e32 v4, 7, v3
	v_mad_i32_i24 v10, v5, s37, v4
	ds_read2_b32 v[6:7], v154 offset1:1
	ds_read2_b32 v[8:9], v154 offset0:2 offset1:3
	v_ashrrev_i32_e32 v11, 31, v10
	v_lshlrev_b64 v[10:11], 15, v[10:11]
	v_lshlrev_b32_e32 v5, 7, v2
	v_and_b32_e32 v12, 0x7f80, v5
	v_mov_b32_e32 v13, v131
	v_lshl_add_u64 v[10:11], s[18:19], 0, v[10:11]
	v_and_b32_e32 v130, 0x7f, v3
	v_lshl_add_u64 v[10:11], v[10:11], 0, v[12:13]
	v_or_b32_e32 v3, s35, v139
	v_lshl_add_u64 v[10:11], v[10:11], 0, v[130:131]
	v_cmp_eq_u32_e32 vcc, 0, v3
	s_waitcnt lgkmcnt(0)
	global_store_dwordx4 v[10:11], v[6:9], off
	s_and_saveexec_b64 s[26:27], vcc
	s_cbranch_execz .LBB0_2271
	v_ashrrev_i32_e32 v3, 31, v2
	v_lshlrev_b64 v[2:3], 2, v[2:3]
	v_lshl_add_u64 v[6:7], s[8:9], 0, v[2:3]
	global_load_dword v5, v[6:7], off
	v_lshl_add_u64 v[2:3], s[24:25], 0, v[2:3]
	s_waitcnt vmcnt(0)
	v_mul_f32_e32 v5, 0x3c010204, v5
	global_store_dword v[2:3], v5, off

; #define LAS __attribute__((address_space(3)))
; __device__ __forceinline__ float bfly8(float x, bool up) { const float p = __uint_as_float(__builtin_amdgcn_update_dpp(0u, __float_as_uint(x), 0x128, 0xf, 0xf, false)); return up ? p - x : x + p; }
; __device__ __forceinline__ void gu_load(f32x4 (&v)[16], float& gA, float& gB, const GUDesc& d, int lane) {
;     const int kr = lane >> 3, nq = lane & 7;
;     const float* __restrict__ src = d.W + (size_t)(d.k0 + 4 * kr) * d.N + d.n0 + 4 * nq;
;     gA = d.gain ? d.gain[d.k0 + lane] : 1.0f; gB = d.gain ? d.gain[d.k0 + 64 + lane] : 1.0f;
; #pragma unroll
;     for (int i = 0; i < 16; ++i) v[i] = *(const f32x4*)(src + (size_t)(32 * (i >> 2) + (i & 3)) * d.N);
; }
; template <int ROT>
; __device__ __forceinline__ void rot32_tile(f32x4 (&v)[16], int lane) {
; #pragma unroll
;     for (int jq = 0; jq < 4; ++jq) {
;         const f32x4 a = v[4 * jq], b = v[4 * jq + 1], c = v[4 * jq + 2], d = v[4 * jq + 3];
;         const f32x4 a1 = a + b, b1 = a - b, c1 = c + d, d1 = c - d;
;         if (ROT >= 2) { v[4 * jq] = a1 + c1; v[4 * jq + 2] = a1 - c1; v[4 * jq + 1] = b1 + d1; v[4 * jq + 3] = b1 - d1; }
;         else { v[4 * jq] = a1; v[4 * jq + 1] = b1; v[4 * jq + 2] = c1; v[4 * jq + 3] = d1; }
;     }
;     { const bool s8 = (lane & 8) != 0, s16 = (lane & 16) != 0, s32 = (lane & 32) != 0;
; #pragma unroll
;       for (int i = 0; i < 16; ++i)
; #pragma unroll
;           for (int e = 0; e < 4; ++e) { float x = v[i][e]; if (ROT >= 3) x = bfly8(x, s8); if (ROT >= 4) x = bfly16(x, s16); if (ROT >= 5) x = bfly32(x, s32); v[i][e] = x; } }
; #pragma unroll
;     for (int i = 0; i < 16; ++i) v[i] *= (ROT == 1 ? 0.70710678118654752f : ROT == 2 ? 0.5f : ROT == 3 ? 0.35355339059327373f : ROT == 4 ? 0.25f : 0.17677669529663687f);
; }
; template <bool STRIP, int ROT>
; __device__ __forceinline__ void gu_finish_t(f32x4 (&v)[16], float gA, float gB, const GUDesc& d, LAS unsigned* T, int lane, const float (&sinv)[4]) {
;     const int kr = lane >> 3, nq = lane & 7;
;     const int dq0 = d.il ? gu_dest(d.n0 + 4 * nq, d.bj) : d.n0 + 4 * nq;
;     if (ROT) rot32_tile<ROT>(v, lane);
;     float inv[4];
; #pragma unroll
;     for (int e = 0; e < 4; ++e) { if (STRIP) inv[e] = sinv[e]; else { const float cm = __uint_as_float(d.cmax[dq0 + e]); inv[e] = cm > 0.f ? 127.0f / cm : 0.f; } }
.LBB0_2290:
	v_or_b32_e32 v2, s35, v137
	v_mul_hi_i32_i24_e32 v3, s24, v2
	v_mul_i32_i24_e32 v2, s24, v2
	s_ashr_i32 s1, s0, 31
	s_waitcnt lgkmcnt(0)
	v_lshl_add_u64 v[2:3], v[2:3], 2, v[4:5]
	v_lshl_add_u64 v[2:3], s[0:1], 2, v[2:3]
	v_mov_b32_e32 v135, v131
	s_lshl_b32 s10, s24, 2
	v_lshl_add_u64 v[2:3], v[2:3], 0, v[134:135]
	v_lshl_add_u64 v[4:5], v[2:3], 0, s[10:11]
	global_load_dwordx4 v[94:97], v[2:3], off nt
	global_load_dwordx4 v[90:93], v[4:5], off nt
	v_lshl_add_u64 v[2:3], v[4:5], 0, s[10:11]
	v_lshl_add_u64 v[4:5], v[2:3], 0, s[10:11]
	s_mulk_i32 s24, 0x74
	s_mov_b32 s25, s11
	global_load_dwordx4 v[86:89], v[2:3], off nt
	global_load_dwordx4 v[82:85], v[4:5], off nt
	v_lshl_add_u64 v[2:3], v[4:5], 0, s[24:25]
	v_lshl_add_u64 v[4:5], v[2:3], 0, s[10:11]
	global_load_dwordx4 v[78:81], v[2:3], off nt
	global_load_dwordx4 v[74:77], v[4:5], off nt
	v_lshl_add_u64 v[2:3], v[4:5], 0, s[10:11]
	v_lshl_add_u64 v[4:5], v[2:3], 0, s[10:11]
	global_load_dwordx4 v[70:73], v[2:3], off nt
	global_load_dwordx4 v[66:69], v[4:5], off nt
	v_lshl_add_u64 v[2:3], v[4:5], 0, s[24:25]
	global_load_dwordx4 v[30:33], v[2:3], off nt
	v_lshl_add_u64 v[2:3], v[2:3], 0, s[10:11]
	global_load_dwordx4 v[26:29], v[2:3], off nt
	v_lshl_add_u64 v[2:3], v[2:3], 0, s[10:11]
	global_load_dwordx4 v[18:21], v[2:3], off nt
	v_lshl_add_u64 v[2:3], v[2:3], 0, s[10:11]
	global_load_dwordx4 v[14:17], v[2:3], off nt
	v_lshl_add_u64 v[2:3], v[2:3], 0, s[24:25]
	global_load_dwordx4 v[10:13], v[2:3], off nt
	v_lshl_add_u64 v[2:3], v[2:3], 0, s[10:11]
	v_lshl_add_u64 v[22:23], v[2:3], 0, s[10:11]
	global_load_dwordx4 v[6:9], v[2:3], off nt
	s_cmp_ge_i32 s58, s31
	global_load_dwordx4 v[2:5], v[22:23], off nt
	v_lshl_add_u64 v[22:23], v[22:23], 0, s[10:11]
	global_load_dwordx4 v[22:25], v[22:23], off nt
	s_cbranch_scc1 .LBB0_2257
	s_add_u32 s24, s78, s20
	s_addc_u32 s25, s79, s21
	s_add_u32 s20, s33, s22
	s_addc_u32 s21, s34, s23
	s_lshl_b32 s1, s14, 1
	s_and_b32 s1, s1, 0xffffff00
	v_bitop3_b32 v135, s14, v155, v140 bitop3:0xc8
	v_or_b32_e32 v135, s1, v135
	v_or_b32_e32 v130, s14, v140
	v_or_b32_e32 v135, s17, v135
	v_cndmask_b32_e64 v170, v135, v130, s[2:3]
	v_pk_add_f32 v[172:173], v[124:125], v[128:129]
	v_pk_add_f32 v[174:175], v[122:123], v[126:127]
	v_sub_f32_e32 v125, v125, v129
	v_sub_f32_e32 v124, v124, v128
	v_sub_f32_e32 v123, v123, v127
	v_sub_f32_e32 v122, v122, v126
	v_pk_add_f32 v[126:127], v[116:117], v[120:121]
	v_pk_add_f32 v[128:129], v[114:115], v[118:119]
	v_sub_f32_e32 v177, v117, v121
	v_sub_f32_e32 v176, v116, v120
	v_sub_f32_e32 v179, v115, v119
	v_sub_f32_e32 v178, v114, v118
	v_pk_add_f32 v[118:119], v[172:173], v[126:127]
	v_pk_add_f32 v[120:121], v[174:175], v[128:129]
	v_sub_f32_e32 v115, v173, v127
	v_sub_f32_e32 v114, v172, v126
	v_sub_f32_e32 v117, v175, v129
	v_sub_f32_e32 v116, v174, v128
	v_pk_add_f32 v[172:173], v[108:109], v[112:113]
	v_pk_add_f32 v[174:175], v[106:107], v[110:111]
	v_sub_f32_e32 v109, v109, v113
	v_sub_f32_e32 v108, v108, v112
	v_sub_f32_e32 v107, v107, v111
	v_sub_f32_e32 v106, v106, v110
	v_pk_add_f32 v[110:111], v[100:101], v[104:105]
	v_pk_add_f32 v[112:113], v[98:99], v[102:103]
	v_sub_f32_e32 v99, v99, v103
	v_sub_f32_e32 v98, v98, v102
	v_ashrrev_i32_e32 v171, 31, v170
	v_pk_add_f32 v[102:103], v[172:173], v[110:111]
	v_sub_f32_e32 v111, v173, v111
	v_sub_f32_e32 v110, v172, v110
	v_pk_add_f32 v[172:173], v[106:107], v[98:99]
	v_sub_f32_e32 v107, v107, v99
	v_sub_f32_e32 v106, v106, v98
	v_lshl_add_u64 v[98:99], v[170:171], 2, s[12:13]
	v_sub_f32_e32 v105, v101, v105
	v_sub_f32_e32 v104, v100, v104
	global_load_dwordx4 v[98:101], v[98:99], off nt
	v_pk_add_f32 v[128:129], v[124:125], v[176:177]
	v_sub_f32_e32 v125, v125, v177
	v_sub_f32_e32 v124, v124, v176
	v_pk_add_f32 v[176:177], v[174:175], v[112:113]
	v_sub_f32_e32 v113, v175, v113
	v_sub_f32_e32 v112, v174, v112
	v_pk_add_f32 v[174:175], v[108:109], v[104:105]
	v_sub_f32_e32 v105, v109, v105
	v_sub_f32_e32 v104, v108, v104
	v_pk_add_f32 v[108:109], v[56:57], v[64:65]
	v_pk_add_f32 v[170:171], v[54:55], v[62:63]
	v_sub_f32_e32 v57, v57, v65
	v_sub_f32_e32 v56, v56, v64
	v_sub_f32_e32 v55, v55, v63
	v_sub_f32_e32 v54, v54, v62
	v_pk_add_f32 v[62:63], v[52:53], v[60:61]
	v_pk_add_f32 v[64:65], v[50:51], v[58:59]
	v_sub_f32_e32 v53, v53, v61
	v_sub_f32_e32 v52, v52, v60
	v_sub_f32_e32 v51, v51, v59
	v_sub_f32_e32 v50, v50, v58
	v_pk_add_f32 v[58:59], v[108:109], v[62:63]
	v_pk_add_f32 v[60:61], v[170:171], v[64:65]
	v_sub_f32_e32 v63, v109, v63
	v_sub_f32_e32 v62, v108, v62
	v_sub_f32_e32 v65, v171, v65
	v_sub_f32_e32 v64, v170, v64
	v_pk_add_f32 v[108:109], v[54:55], v[50:51]
	v_pk_add_f32 v[170:171], v[56:57], v[52:53]
	v_sub_f32_e32 v51, v55, v51
	v_sub_f32_e32 v50, v54, v50
	v_sub_f32_e32 v53, v57, v53
	v_sub_f32_e32 v52, v56, v52
	s_waitcnt vmcnt(23)
	v_pk_add_f32 v[54:55], v[40:41], v[48:49]
	v_pk_add_f32 v[56:57], v[38:39], v[46:47]
	v_sub_f32_e32 v41, v41, v49
	v_sub_f32_e32 v40, v40, v48
	v_sub_f32_e32 v39, v39, v47
	v_sub_f32_e32 v38, v38, v46
	s_waitcnt vmcnt(21)
; #define LAS __attribute__((address_space(3)))
; __device__ __forceinline__ float bfly8(float x, bool up) { const float p = __uint_as_float(__builtin_amdgcn_update_dpp(0u, __float_as_uint(x), 0x128, 0xf, 0xf, false)); return up ? p - x : x + p; }
; __device__ __forceinline__ float bfly16(float x, bool up) { const auto r = __builtin_amdgcn_permlane16_swap(__float_as_uint(x), __float_as_uint(x), false, false); const float a = __uint_as_float(r[0]), b = __uint_as_float(r[1]); return up ? a - b : a + b; }
; __device__ __forceinline__ float bfly32(float x, bool up) { const auto r = __builtin_amdgcn_permlane32_swap(__float_as_uint(x), __float_as_uint(x), false, false); const float a = __uint_as_float(r[0]), b = __uint_as_float(r[1]); return up ? a - b : a + b; }
; template <int ROT>
; __device__ __forceinline__ void rot32_tile(f32x4 (&v)[16], int lane) {
;     ...
;           for (int e = 0; e < 4; ++e) { float x = v[i][e]; if (ROT >= 3) x = bfly8(x, s8); if (ROT >= 4) x = bfly16(x, s16); if (ROT >= 5) x = bfly32(x, s32); v[i][e] = x; } }
; #pragma unroll
;     for (int i = 0; i < 16; ++i) v[i] *= (ROT == 1 ? 0.70710678118654752f : ROT == 2 ? 0.5f : ROT == 3 ? 0.35355339059327373f : ROT == 4 ? 0.25f : 0.17677669529663687f);
; }
; template <bool STRIP, int ROT>
; __device__ __forceinline__ void gu_finish_t(f32x4 (&v)[16], float gA, float gB, const GUDesc& d, LAS unsigned* T, int lane, const float (&sinv)[4]) {
;     const int kr = lane >> 3, nq = lane & 7;
;     const int dq0 = d.il ? gu_dest(d.n0 + 4 * nq, d.bj) : d.n0 + 4 * nq;
;     if (ROT) rot32_tile<ROT>(v, lane);
;     float inv[4];
; #pragma unroll
;     for (int e = 0; e < 4; ++e) { if (STRIP) inv[e] = sinv[e]; else { const float cm = __uint_as_float(d.cmax[dq0 + e]); inv[e] = cm > 0.f ? 127.0f / cm : 0.f; } }
; #pragma unroll
;     for (int jq = 0; jq < 4; ++jq) {
;         float g[4];
; #pragma unroll
;         for (int e2 = 0; e2 < 4; ++e2) g[e2] = jq < 2 ? __shfl(gA, 32 * jq + 4 * kr + e2) : __shfl(gB, 32 * (jq - 2) + 4 * kr + e2);
; #pragma unroll
;         for (int e = 0; e < 4; ++e)
;             T[(4 * nq + e) * 33 + 8 * jq + kr] = pack4_i8(v[4 * jq + 0][e] * g[0] * inv[e], v[4 * jq + 1][e] * g[1] * inv[e], v[4 * jq + 2][e] * g[2] * inv[e], v[4 * jq + 3][e] * g[3] * inv[e]);
	v_pk_add_f32 v[46:47], v[36:37], v[44:45]
	v_pk_add_f32 v[48:49], v[34:35], v[42:43]
	v_sub_f32_e32 v35, v35, v43
	v_sub_f32_e32 v34, v34, v42
	v_sub_f32_e32 v37, v37, v45
	v_sub_f32_e32 v36, v36, v44
	v_pk_add_f32 v[42:43], v[54:55], v[46:47]
	v_pk_add_f32 v[44:45], v[56:57], v[48:49]
	v_sub_f32_e32 v47, v55, v47
	v_sub_f32_e32 v46, v54, v46
	v_pk_add_f32 v[54:55], v[38:39], v[34:35]
	v_pk_add_f32 v[126:127], v[122:123], v[178:179]
	v_sub_f32_e32 v123, v123, v179
	v_sub_f32_e32 v122, v122, v178
	v_sub_f32_e32 v179, v39, v35
	v_sub_f32_e32 v178, v38, v34
	v_pk_mul_f32 v[34:35], v[42:43], 0.5 op_sel_hi:[1,0]
	v_pk_mul_f32 v[42:43], v[44:45], 0.5 op_sel_hi:[1,0]
	v_pk_mul_f32 v[44:45], v[54:55], 0.5 op_sel_hi:[1,0]
	v_sub_f32_e32 v49, v57, v49
	v_sub_f32_e32 v48, v56, v48
	v_pk_add_f32 v[56:57], v[40:41], v[36:37]
	v_sub_f32_e32 v41, v41, v37
	v_sub_f32_e32 v40, v40, v36
	v_pk_mul_f32 v[36:37], v[56:57], 0.5 op_sel_hi:[1,0]
	v_pk_mul_f32 v[120:121], v[120:121], 0.5 op_sel_hi:[1,0]
	v_pk_mul_f32 v[126:127], v[126:127], 0.5 op_sel_hi:[1,0]
	v_pk_mul_f32 v[116:117], v[116:117], 0.5 op_sel_hi:[1,0]
	v_pk_mul_f32 v[122:123], v[122:123], 0.5 op_sel_hi:[1,0]
	v_pk_mul_f32 v[118:119], v[118:119], 0.5 op_sel_hi:[1,0]
	v_pk_mul_f32 v[128:129], v[128:129], 0.5 op_sel_hi:[1,0]
	v_pk_mul_f32 v[114:115], v[114:115], 0.5 op_sel_hi:[1,0]
	v_pk_mul_f32 v[124:125], v[124:125], 0.5 op_sel_hi:[1,0]
	v_pk_mul_f32 v[176:177], v[176:177], 0.5 op_sel_hi:[1,0]
	v_pk_mul_f32 v[172:173], v[172:173], 0.5 op_sel_hi:[1,0]
	v_pk_mul_f32 v[112:113], v[112:113], 0.5 op_sel_hi:[1,0]
	v_pk_mul_f32 v[106:107], v[106:107], 0.5 op_sel_hi:[1,0]
	v_pk_mul_f32 v[102:103], v[102:103], 0.5 op_sel_hi:[1,0]
	v_pk_mul_f32 v[174:175], v[174:175], 0.5 op_sel_hi:[1,0]
	v_pk_mul_f32 v[110:111], v[110:111], 0.5 op_sel_hi:[1,0]
	s_waitcnt vmcnt(0)
	v_div_scale_f32 v54, s[22:23], v98, v98, s52
	v_rcp_f32_e32 v55, v54
	v_pk_mul_f32 v[104:105], v[104:105], 0.5 op_sel_hi:[1,0]
	v_pk_mul_f32 v[60:61], v[60:61], 0.5 op_sel_hi:[1,0]
	v_pk_mul_f32 v[108:109], v[108:109], 0.5 op_sel_hi:[1,0]
	v_fma_f32 v56, -v54, v55, 1.0
	v_fmac_f32_e32 v55, v56, v55
	v_div_scale_f32 v56, vcc, s52, v98, s52
	v_mul_f32_e32 v57, v56, v55
	v_fma_f32 v130, -v54, v57, v56
	v_fmac_f32_e32 v57, v130, v55
	v_fma_f32 v54, -v54, v57, v56
	v_div_fmas_f32 v54, v54, v55, v57
	v_div_scale_f32 v55, s[22:23], v99, v99, s52
	v_rcp_f32_e32 v56, v55
	v_div_fixup_f32 v54, v54, v98, s52
	v_cmp_lt_f32_e32 vcc, 0, v98
	v_pk_mul_f32 v[64:65], v[64:65], 0.5 op_sel_hi:[1,0]
	v_fma_f32 v57, -v55, v56, 1.0
	v_cndmask_b32_e32 v54, 0, v54, vcc
	v_fmac_f32_e32 v56, v57, v56
	v_div_scale_f32 v57, vcc, s52, v99, s52
	v_mul_f32_e32 v98, v57, v56
	v_fma_f32 v130, -v55, v98, v57
	v_fmac_f32_e32 v98, v130, v56
	v_fma_f32 v55, -v55, v98, v57
	v_div_fmas_f32 v55, v55, v56, v98
	v_div_scale_f32 v56, s[22:23], v100, v100, s52
	v_rcp_f32_e32 v57, v56
	v_div_fixup_f32 v55, v55, v99, s52
	v_cmp_lt_f32_e32 vcc, 0, v99
	v_pk_mul_f32 v[50:51], v[50:51], 0.5 op_sel_hi:[1,0]
	v_fma_f32 v98, -v56, v57, 1.0
	v_cndmask_b32_e32 v55, 0, v55, vcc
	v_fmac_f32_e32 v57, v98, v57
	v_div_scale_f32 v98, vcc, s52, v100, s52
	v_mul_f32_e32 v99, v98, v57
	v_fma_f32 v130, -v56, v99, v98
	v_fmac_f32_e32 v99, v130, v57
	v_fma_f32 v56, -v56, v99, v98
	v_div_fmas_f32 v56, v56, v57, v99
	v_div_scale_f32 v57, s[22:23], v101, v101, s52
	v_rcp_f32_e32 v98, v57
	v_div_fixup_f32 v56, v56, v100, s52
	v_cmp_lt_f32_e32 vcc, 0, v100
	v_pk_mul_f32 v[58:59], v[58:59], 0.5 op_sel_hi:[1,0]
	v_fma_f32 v99, -v57, v98, 1.0
	v_cndmask_b32_e32 v56, 0, v56, vcc
	v_fmac_f32_e32 v98, v99, v98
	v_div_scale_f32 v99, vcc, s52, v101, s52
	v_mul_f32_e32 v100, v99, v98
	v_fma_f32 v130, -v57, v100, v99
	v_fmac_f32_e32 v100, v130, v98
	v_fma_f32 v57, -v57, v100, v99
	v_div_fmas_f32 v57, v57, v98, v100
	ds_bpermute_b32 v98, v142, v163
	ds_bpermute_b32 v99, v143, v163
	ds_bpermute_b32 v100, v144, v163
	ds_bpermute_b32 v130, v145, v163
	v_div_fixup_f32 v57, v57, v101, s52
	v_cmp_lt_f32_e32 vcc, 0, v101
	s_waitcnt lgkmcnt(3)
	v_mul_f32_e32 v101, v120, v98
	s_waitcnt lgkmcnt(2)
	v_mul_f32_e32 v120, v126, v99
	v_fmaak_f32 v101, v54, v101, 0x43000000
	s_waitcnt lgkmcnt(1)
	v_mul_f32_e32 v116, v116, v100
	v_cvt_pk_u8_f32 v101, v101, 0, 0
	v_fmaak_f32 v120, v54, v120, 0x43000000
	s_waitcnt lgkmcnt(0)
	v_mul_f32_e32 v122, v122, v130
	v_cvt_pk_u8_f32 v101, v120, 1, v101
	v_fmaak_f32 v116, v54, v116, 0x43000000
	v_cvt_pk_u8_f32 v101, v116, 2, v101
	v_fmaak_f32 v116, v54, v122, 0x43000000
	v_cvt_pk_u8_f32 v101, v116, 3, v101
	v_mul_f32_e32 v116, v121, v98
	v_mul_f32_e32 v120, v127, v99
	v_fmaak_f32 v116, v55, v116, 0x43000000
	v_mul_f32_e32 v117, v117, v100
	v_cvt_pk_u8_f32 v116, v116, 0, 0
	v_fmaak_f32 v120, v55, v120, 0x43000000
	v_mul_f32_e32 v121, v123, v130
	v_cvt_pk_u8_f32 v116, v120, 1, v116
	v_fmaak_f32 v117, v55, v117, 0x43000000
	v_cvt_pk_u8_f32 v116, v117, 2, v116
	v_fmaak_f32 v117, v55, v121, 0x43000000
	v_cndmask_b32_e32 v57, 0, v57, vcc
	v_cvt_pk_u8_f32 v116, v117, 3, v116
	v_mul_f32_e32 v117, v118, v98
	v_mul_f32_e32 v98, v119, v98
	v_mul_f32_e32 v118, v128, v99
	v_mul_f32_e32 v99, v129, v99
	v_fmaak_f32 v98, v57, v98, 0x43000000
	v_mul_f32_e32 v114, v114, v100
	v_mul_f32_e32 v100, v115, v100
	v_cvt_pk_u8_f32 v98, v98, 0, 0
	v_fmaak_f32 v99, v57, v99, 0x43000000
	v_mul_f32_e32 v115, v125, v130
	v_cvt_pk_u8_f32 v98, v99, 1, v98
	v_fmaak_f32 v99, v57, v100, 0x43000000
	v_fmaak_f32 v117, v56, v117, 0x43000000
	v_cvt_pk_u8_f32 v98, v99, 2, v98
	v_fmaak_f32 v99, v57, v115, 0x43000000
	v_cvt_pk_u8_f32 v117, v117, 0, 0
	v_fmaak_f32 v118, v56, v118, 0x43000000
	v_cvt_pk_u8_f32 v98, v99, 3, v98
	ds_bpermute_b32 v99, v146, v163
	v_mul_f32_e32 v120, v124, v130
	v_cvt_pk_u8_f32 v117, v118, 1, v117
	v_fmaak_f32 v114, v56, v114, 0x43000000
	ds_bpermute_b32 v100, v147, v163
	v_cvt_pk_u8_f32 v114, v114, 2, v117
	v_fmaak_f32 v117, v56, v120, 0x43000000
	ds_bpermute_b32 v115, v148, v163
	v_cvt_pk_u8_f32 v114, v117, 3, v114
	ds_bpermute_b32 v117, v149, v163
	s_waitcnt lgkmcnt(3)
; template <bool STRIP, int ROT>
; __device__ __forceinline__ void gu_finish_t(f32x4 (&v)[16], float gA, float gB, const GUDesc& d, LAS unsigned* T, int lane, const float (&sinv)[4]) {
;     ...
;     for (int jq = 0; jq < 4; ++jq) {
;         float g[4];
; #pragma unroll
;         for (int e2 = 0; e2 < 4; ++e2) g[e2] = jq < 2 ? __shfl(gA, 32 * jq + 4 * kr + e2) : __shfl(gB, 32 * (jq - 2) + 4 * kr + e2);
; #pragma unroll
;         for (int e = 0; e < 4; ++e)
;             T[(4 * nq + e) * 33 + 8 * jq + kr] = pack4_i8(v[4 * jq + 0][e] * g[0] * inv[e], v[4 * jq + 1][e] * g[1] * inv[e], v[4 * jq + 2][e] * g[2] * inv[e], v[4 * jq + 3][e] * g[3] * inv[e]);
;     }
	v_mul_f32_e32 v118, v176, v99
	s_waitcnt lgkmcnt(2)
	v_mul_f32_e32 v119, v172, v100
	v_fmaak_f32 v118, v54, v118, 0x43000000
	s_waitcnt lgkmcnt(1)
	v_mul_f32_e32 v112, v112, v115
	v_cvt_pk_u8_f32 v118, v118, 0, 0
	v_fmaak_f32 v119, v54, v119, 0x43000000
	s_waitcnt lgkmcnt(0)
	v_mul_f32_e32 v106, v106, v117
	v_cvt_pk_u8_f32 v118, v119, 1, v118
	v_fmaak_f32 v112, v54, v112, 0x43000000
	v_cvt_pk_u8_f32 v112, v112, 2, v118
	v_fmaak_f32 v106, v54, v106, 0x43000000
	v_cvt_pk_u8_f32 v106, v106, 3, v112
	v_xor_b32_e32 v101, 0x80808080, v101
	v_xor_b32_e32 v106, 0x80808080, v106
	ds_write2_b32 v153, v101, v106 offset1:8
	v_mul_f32_e32 v101, v177, v99
	v_mul_f32_e32 v106, v173, v100
	v_fmaak_f32 v101, v55, v101, 0x43000000
	v_mul_f32_e32 v112, v113, v115
	v_cvt_pk_u8_f32 v101, v101, 0, 0
	v_fmaak_f32 v106, v55, v106, 0x43000000
	v_mul_f32_e32 v107, v107, v117
	v_cvt_pk_u8_f32 v101, v106, 1, v101
	v_fmaak_f32 v106, v55, v112, 0x43000000
	v_cvt_pk_u8_f32 v101, v106, 2, v101
	v_fmaak_f32 v106, v55, v107, 0x43000000
	v_cvt_pk_u8_f32 v101, v106, 3, v101
	v_xor_b32_e32 v116, 0x80808080, v116
	v_xor_b32_e32 v101, 0x80808080, v101
	ds_write2_b32 v153, v116, v101 offset0:33 offset1:41
	v_mul_f32_e32 v101, v102, v99
	v_mul_f32_e32 v102, v174, v100
	v_fmaak_f32 v101, v56, v101, 0x43000000
	v_mul_f32_e32 v106, v110, v115
	v_cvt_pk_u8_f32 v101, v101, 0, 0
	v_fmaak_f32 v102, v56, v102, 0x43000000
	v_mul_f32_e32 v104, v104, v117
	v_cvt_pk_u8_f32 v101, v102, 1, v101
	v_fmaak_f32 v102, v56, v106, 0x43000000
	v_cvt_pk_u8_f32 v101, v102, 2, v101
	v_fmaak_f32 v102, v56, v104, 0x43000000
	v_cvt_pk_u8_f32 v101, v102, 3, v101
	v_mul_f32_e32 v99, v103, v99
	v_xor_b32_e32 v114, 0x80808080, v114
	v_xor_b32_e32 v101, 0x80808080, v101
	v_mul_f32_e32 v100, v175, v100
	v_fmaak_f32 v99, v57, v99, 0x43000000
	ds_write2_b32 v153, v114, v101 offset0:66 offset1:74
	v_mul_f32_e32 v101, v111, v115
	v_cvt_pk_u8_f32 v99, v99, 0, 0
	v_fmaak_f32 v100, v57, v100, 0x43000000
	v_mul_f32_e32 v102, v105, v117
	v_cvt_pk_u8_f32 v99, v100, 1, v99
	v_fmaak_f32 v100, v57, v101, 0x43000000
	v_cvt_pk_u8_f32 v99, v100, 2, v99
	v_fmaak_f32 v100, v57, v102, 0x43000000
	v_cvt_pk_u8_f32 v99, v100, 3, v99
	ds_bpermute_b32 v100, v142, v162
	ds_bpermute_b32 v101, v143, v162
	ds_bpermute_b32 v102, v144, v162
	ds_bpermute_b32 v103, v145, v162
	v_xor_b32_e32 v98, 0x80808080, v98
	v_xor_b32_e32 v99, 0x80808080, v99
	s_waitcnt lgkmcnt(3)
	v_mul_f32_e32 v60, v60, v100
	ds_write2_b32 v153, v98, v99 offset0:99 offset1:107
	s_waitcnt lgkmcnt(3)
	v_mul_f32_e32 v98, v108, v101
	v_fmaak_f32 v60, v54, v60, 0x43000000
	s_waitcnt lgkmcnt(2)
	v_mul_f32_e32 v64, v64, v102
	v_cvt_pk_u8_f32 v60, v60, 0, 0
	v_fmaak_f32 v98, v54, v98, 0x43000000
	s_waitcnt lgkmcnt(1)
	v_mul_f32_e32 v50, v50, v103
	v_cvt_pk_u8_f32 v60, v98, 1, v60
	v_fmaak_f32 v64, v54, v64, 0x43000000
	v_cvt_pk_u8_f32 v60, v64, 2, v60
	v_fmaak_f32 v50, v54, v50, 0x43000000
	v_cvt_pk_u8_f32 v50, v50, 3, v60
	v_mul_f32_e32 v60, v61, v100
	v_mul_f32_e32 v61, v109, v101
	v_fmaak_f32 v60, v55, v60, 0x43000000
	v_mul_f32_e32 v64, v65, v102
	v_cvt_pk_u8_f32 v60, v60, 0, 0
	v_fmaak_f32 v61, v55, v61, 0x43000000
	v_mul_f32_e32 v51, v51, v103
	v_cvt_pk_u8_f32 v60, v61, 1, v60
	v_fmaak_f32 v61, v55, v64, 0x43000000
	v_pk_mul_f32 v[170:171], v[170:171], 0.5 op_sel_hi:[1,0]
	v_cvt_pk_u8_f32 v60, v61, 2, v60
	v_fmaak_f32 v51, v55, v51, 0x43000000
	v_mul_f32_e32 v58, v58, v100
	v_pk_mul_f32 v[62:63], v[62:63], 0.5 op_sel_hi:[1,0]
	v_cvt_pk_u8_f32 v51, v51, 3, v60
	v_mul_f32_e32 v60, v170, v101
	v_fmaak_f32 v58, v56, v58, 0x43000000
	v_pk_mul_f32 v[52:53], v[52:53], 0.5 op_sel_hi:[1,0]
	v_mul_f32_e32 v61, v62, v102
	v_cvt_pk_u8_f32 v58, v58, 0, 0
	v_fmaak_f32 v60, v56, v60, 0x43000000
	v_mul_f32_e32 v52, v52, v103
	v_cvt_pk_u8_f32 v58, v60, 1, v58
	v_fmaak_f32 v60, v56, v61, 0x43000000
	v_cvt_pk_u8_f32 v58, v60, 2, v58
	v_fmaak_f32 v52, v56, v52, 0x43000000
	v_cvt_pk_u8_f32 v52, v52, 3, v58
	v_mul_f32_e32 v58, v59, v100
	v_mul_f32_e32 v59, v171, v101
	v_fmaak_f32 v58, v57, v58, 0x43000000
	v_mul_f32_e32 v60, v63, v102
	v_cvt_pk_u8_f32 v58, v58, 0, 0
	v_fmaak_f32 v59, v57, v59, 0x43000000
	v_mul_f32_e32 v53, v53, v103
	v_cvt_pk_u8_f32 v58, v59, 1, v58
	v_fmaak_f32 v59, v57, v60, 0x43000000
	v_cvt_pk_u8_f32 v58, v59, 2, v58
	v_fmaak_f32 v53, v57, v53, 0x43000000
	v_cvt_pk_u8_f32 v53, v53, 3, v58
	ds_bpermute_b32 v58, v146, v162
	ds_bpermute_b32 v59, v147, v162
	ds_bpermute_b32 v60, v148, v162
	ds_bpermute_b32 v61, v149, v162
	v_pk_mul_f32 v[38:39], v[46:47], 0.5 op_sel_hi:[1,0]
	s_waitcnt lgkmcnt(3)
; #define LAS __attribute__((address_space(3)))
; __host__ __device__ __forceinline__ size_t blk8_off(int r, int k, int KT8_) { return ((size_t)((r >> 8) * KT8_ + (k >> 7)) * 256 + (size_t)(r & 255)) * 128 + (size_t)(k & 127); }
; #define LDS_WAIT() asm volatile("s_waitcnt lgkmcnt(0)" ::: "memory")
; template <bool STRIP, int ROT>
; __device__ __forceinline__ void gu_finish_t(f32x4 (&v)[16], float gA, float gB, const GUDesc& d, LAS unsigned* T, int lane, const float (&sinv)[4]) {
;     ...
;     for (int jq = 0; jq < 4; ++jq) {
;         float g[4];
; #pragma unroll
;         for (int e2 = 0; e2 < 4; ++e2) g[e2] = jq < 2 ? __shfl(gA, 32 * jq + 4 * kr + e2) : __shfl(gB, 32 * (jq - 2) + 4 * kr + e2);
; #pragma unroll
;         for (int e = 0; e < 4; ++e)
;             T[(4 * nq + e) * 33 + 8 * jq + kr] = pack4_i8(v[4 * jq + 0][e] * g[0] * inv[e], v[4 * jq + 1][e] * g[1] * inv[e], v[4 * jq + 2][e] * g[2] * inv[e], v[4 * jq + 3][e] * g[3] * inv[e]);
;     }
;     LDS_WAIT(); asm volatile("" ::: "memory");
;     const int nl = lane >> 3, c = lane & 7;
; #pragma unroll
;     for (int g4 = 0; g4 < 4; ++g4) {
;         const int nloc = 8 * g4 + nl, dr = d.il ? gu_dest(d.n0 + nloc, d.bj) : d.n0 + nloc;
;         const LAS unsigned* t = T + nloc * 33 + 4 * c;
;         u32x4 o; o.x = t[0]; o.y = t[1]; o.z = t[2]; o.w = t[3];
;         *(u32x4*)(d.WQ + blk8_off(dr, d.k0 + 16 * c, d.kt8)) = o;
;         if (!STRIP) if (d.k0 == 0 && c == 0) d.sb[dr] = __uint_as_float(d.cmax[dr]) * (1.0f / 127.0f);
;     }
	v_mul_f32_e32 v34, v34, v58
	v_mul_f32_e32 v42, v42, v58
	s_waitcnt lgkmcnt(2)
	v_mul_f32_e32 v36, v36, v59
	v_fmaak_f32 v34, v56, v34, 0x43000000
	v_pk_mul_f32 v[46:47], v[48:49], 0.5 op_sel_hi:[1,0]
	v_pk_mul_f32 v[40:41], v[40:41], 0.5 op_sel_hi:[1,0]
	v_mul_f32_e32 v44, v44, v59
	v_fmaak_f32 v42, v54, v42, 0x43000000
	s_waitcnt lgkmcnt(1)
	v_mul_f32_e32 v38, v38, v60
	v_cvt_pk_u8_f32 v34, v34, 0, 0
	v_fmaak_f32 v36, v56, v36, 0x43000000
	v_pk_mul_f32 v[48:49], v[178:179], 0.5 op_sel_hi:[1,0]
	v_mul_f32_e32 v46, v46, v60
	v_cvt_pk_u8_f32 v42, v42, 0, 0
	v_fmaak_f32 v44, v54, v44, 0x43000000
	s_waitcnt lgkmcnt(0)
	v_mul_f32_e32 v40, v40, v61
	v_cvt_pk_u8_f32 v34, v36, 1, v34
	v_fmaak_f32 v36, v56, v38, 0x43000000
	v_mul_f32_e32 v48, v48, v61
	v_cvt_pk_u8_f32 v42, v44, 1, v42
	v_fmaak_f32 v44, v54, v46, 0x43000000
	v_cvt_pk_u8_f32 v34, v36, 2, v34
	v_fmaak_f32 v36, v56, v40, 0x43000000
	v_cvt_pk_u8_f32 v42, v44, 2, v42
	v_fmaak_f32 v44, v54, v48, 0x43000000
	v_cvt_pk_u8_f32 v34, v36, 3, v34
	v_xor_b32_e32 v52, 0x80808080, v52
	v_cvt_pk_u8_f32 v42, v44, 3, v42
	v_xor_b32_e32 v34, 0x80808080, v34
	v_xor_b32_e32 v50, 0x80808080, v50
	v_xor_b32_e32 v42, 0x80808080, v42
	ds_write2_b32 v153, v52, v34 offset0:82 offset1:90
	v_mul_f32_e32 v34, v35, v58
	ds_write2_b32 v153, v50, v42 offset0:16 offset1:24
	v_mul_f32_e32 v42, v43, v58
	v_mul_f32_e32 v35, v37, v59
	v_fmaak_f32 v34, v57, v34, 0x43000000
	v_mul_f32_e32 v43, v45, v59
	v_fmaak_f32 v42, v55, v42, 0x43000000
	v_mul_f32_e32 v36, v39, v60
	v_cvt_pk_u8_f32 v34, v34, 0, 0
	v_fmaak_f32 v35, v57, v35, 0x43000000
	v_mul_f32_e32 v44, v47, v60
	v_cvt_pk_u8_f32 v42, v42, 0, 0
	v_fmaak_f32 v43, v55, v43, 0x43000000
	v_mul_f32_e32 v37, v41, v61
	v_cvt_pk_u8_f32 v34, v35, 1, v34
	v_fmaak_f32 v35, v57, v36, 0x43000000
	v_mul_f32_e32 v45, v49, v61
	v_cvt_pk_u8_f32 v42, v43, 1, v42
	v_fmaak_f32 v43, v55, v44, 0x43000000
	v_cvt_pk_u8_f32 v34, v35, 2, v34
	v_fmaak_f32 v35, v57, v37, 0x43000000
	v_cvt_pk_u8_f32 v42, v43, 2, v42
	v_fmaak_f32 v43, v55, v45, 0x43000000
	v_cvt_pk_u8_f32 v34, v35, 3, v34
	v_bitop3_b32 v35, s14, v156, v138 bitop3:0xc8
	v_xor_b32_e32 v53, 0x80808080, v53
	v_cvt_pk_u8_f32 v42, v43, 3, v42
	v_xor_b32_e32 v34, 0x80808080, v34
	v_or_b32_e32 v35, s1, v35
	v_xor_b32_e32 v51, 0x80808080, v51
	v_xor_b32_e32 v42, 0x80808080, v42
	ds_write2_b32 v153, v53, v34 offset0:115 offset1:123
	v_or_b32_e32 v34, s14, v138
	v_or_b32_e32 v35, s17, v35
	ds_write2_b32 v153, v51, v42 offset0:49 offset1:57
	v_cndmask_b32_e64 v34, v35, v34, s[2:3]
	s_ashr_i32 s10, s55, 7
	s_waitcnt lgkmcnt(0)
	v_lshrrev_b32_e32 v35, 8, v34
	v_mov_b32_e32 v40, s10
	v_mad_i32_i24 v40, v35, s54, v40
	ds_read2_b32 v[36:37], v154 offset1:1
	ds_read2_b32 v[38:39], v154 offset0:2 offset1:3
	v_ashrrev_i32_e32 v41, 31, v40
	v_lshlrev_b64 v[40:41], 15, v[40:41]
	v_lshlrev_b32_e32 v35, 7, v34
	v_and_b32_e32 v130, 0x7380, v35
	v_lshl_add_u64 v[40:41], s[24:25], 0, v[40:41]
	v_lshl_add_u64 v[40:41], v[40:41], 0, v[130:131]
	v_or_b32_e32 v35, s55, v139
	v_lshl_add_u64 v[40:41], v[40:41], 0, v[132:133]
	v_cmp_eq_u32_e32 vcc, 0, v35
	s_waitcnt lgkmcnt(0)
	global_store_dwordx4 v[40:41], v[36:39], off
	s_and_saveexec_b64 s[22:23], vcc
	s_cbranch_execz .LBB0_2293
	v_ashrrev_i32_e32 v35, 31, v34
	v_lshlrev_b64 v[34:35], 2, v[34:35]
	v_lshl_add_u64 v[36:37], s[12:13], 0, v[34:35]
	global_load_dword v36, v[36:37], off
	v_lshl_add_u64 v[34:35], s[20:21], 0, v[34:35]
	s_waitcnt vmcnt(0)
	v_mul_f32_e32 v36, 0x3c010204, v36
	global_store_dword v[34:35], v36, off

; __device__ __forceinline__ void gu_decode(Frame& F, int it, GUDesc& d) {
;     const int q = it / P0_I_GU, r = it % P0_I_GU;
;     if (q < 4) { d.k0 = 128 * (r / 344); d.n0 = 32 * (r % 344); d.bj = q & 1; d.N = FF; d.kt8 = KT8; d.il = 1;
;         d.W = q == 0 ? INP(2) : q == 1 ? INP(3) : q == 2 ? INP(18) : INP(19); d.gain = q < 2 ? INP(1) : INP(17);
;         d.WQ = F.ws + (q < 2 ? WS_WGU1 : WS_WGU2); d.cmax = (const unsigned*)(F.ws + WS_CTL + CTL_CMAX) + (q >> 1) * NGU; d.sb = (float*)(F.ws + WS_SMALL + (q < 2 ? SM_SB1 : SM_SB2)); }
;     else { d.k0 = 128 * (r / 128); d.n0 = 32 * (r % 128); d.bj = 0; d.N = DM; d.kt8 = FF / 128; d.il = 0; d.W = q == 4 ? INP(20) : INP(4); d.gain = nullptr;
;         d.WQ = F.ws + (q == 4 ? WS_WD2 : WS_WD1); d.cmax = (const unsigned*)(F.ws + WS_CTL + CTL_CMAX) + 2 * NGU + (q == 4 ? 0 : DM); d.sb = (float*)(F.ws + WS_SMALL + (q == 4 ? SM_SB3 : SM_SB4)); }
; }
; __device__ __forceinline__ void gu_load(f32x4 (&v)[16], float& gA, float& gB, const GUDesc& d, int lane) {
;     const int kr = lane >> 3, nq = lane & 7;
;     const float* __restrict__ src = d.W + (size_t)(d.k0 + 4 * kr) * d.N + d.n0 + 4 * nq;
;     gA = d.gain ? d.gain[d.k0 + lane] : 1.0f; gB = d.gain ? d.gain[d.k0 + 64 + lane] : 1.0f;
; #pragma unroll
;     for (int i = 0; i < 16; ++i) v[i] = *(const f32x4*)(src + (size_t)(32 * (i >> 2) + (i & 3)) * d.N);
; }
; template <bool STRIP, int ROT>
; __device__ __forceinline__ void gu_finish_t(f32x4 (&v)[16], float gA, float gB, const GUDesc& d, LAS unsigned* T, int lane, const float (&sinv)[4]) {
;     ...
;     for (int e = 0; e < 4; ++e) { if (STRIP) inv[e] = sinv[e]; else { const float cm = __uint_as_float(d.cmax[dq0 + e]); inv[e] = cm > 0.f ? 127.0f / cm : 0.f; } }
; #pragma unroll
;     for (int jq = 0; jq < 4; ++jq) {
;         float g[4];
; #pragma unroll
;         for (int e2 = 0; e2 < 4; ++e2) g[e2] = jq < 2 ? __shfl(gA, 32 * jq + 4 * kr + e2) : __shfl(gB, 32 * (jq - 2) + 4 * kr + e2);
; #pragma unroll
;         for (int e = 0; e < 4; ++e)
;             T[(4 * nq + e) * 33 + 8 * jq + kr] = pack4_i8(v[4 * jq + 0][e] * g[0] * inv[e], v[4 * jq + 1][e] * g[1] * inv[e], v[4 * jq + 2][e] * g[2] * inv[e], v[4 * jq + 3][e] * g[3] * inv[e]);
;     }
.LBB0_2309:
	s_and_b64 s[0:1], s[0:1], exec
	s_cselect_b32 s0, s21, 0x15e00000
	s_cselect_b32 s9, s20, 0x620000
	s_add_u32 s6, s78, s0
	s_addc_u32 s7, s79, 0
	s_lshr_b32 s0, s41, 1
	s_mulk_i32 s0, 0x5600
	s_ashr_i32 s1, s0, 31
	s_lshl_b64 s[0:1], s[0:1], 2
	s_add_u32 s2, s12, s0
	s_addc_u32 s3, s13, s1
	s_add_u32 s0, s14, s9
	s_mul_i32 s9, s8, 0x158
	s_addc_u32 s1, s15, 0
	s_sub_i32 s4, s4, s9
	s_sext_i32_i16 s9, s4
	s_lshl_b32 s4, s9, 5
	s_lshl_b32 s39, s9, 6
	s_and_b32 s40, s4, 0x60
	s_and_b32 s39, s39, 0xffffff00
	v_or_b32_e32 v4, s40, v45
	s_lshl_b32 s41, s41, 7
	s_and_b32 s41, s41, 0x80
	v_or_b32_e32 v4, s39, v4
	v_or_b32_e32 v4, s41, v4
	v_ashrrev_i32_e32 v5, 31, v4
	v_lshl_add_u64 v[4:5], v[4:5], 2, s[2:3]
	global_load_dwordx4 v[60:63], v[4:5], off nt
	v_or_b32_e32 v4, s5, v43
	v_mul_i32_i24_e32 v4, 0x2b00, v4
	v_ashrrev_i32_e32 v5, 31, v4
	s_waitcnt lgkmcnt(0)
	v_lshl_add_u64 v[2:3], v[4:5], 2, v[2:3]
	s_ashr_i32 s5, s4, 31
	v_lshl_add_u64 v[2:3], s[4:5], 2, v[2:3]
	s_waitcnt vmcnt(1)
	v_lshl_add_u64 v[10:11], v[2:3], 0, v[40:41]
	v_add_co_u32_e32 v2, vcc, s22, v10
	s_waitcnt vmcnt(0)
	v_div_scale_f32 v96, s[4:5], v60, v60, s38
	v_addc_co_u32_e32 v3, vcc, 0, v11, vcc
	global_load_dwordx4 v[64:67], v[10:11], off nt
	global_load_dwordx4 v[68:71], v[2:3], off offset:3072 nt
	v_add_co_u32_e32 v2, vcc, s23, v10
	v_rcp_f32_e32 v97, v96
	s_nop 0
	v_addc_co_u32_e32 v3, vcc, 0, v11, vcc
	v_add_co_u32_e32 v4, vcc, s24, v10
	v_fma_f32 v98, -v96, v97, 1.0
	s_nop 0
	v_addc_co_u32_e32 v5, vcc, 0, v11, vcc
	global_load_dwordx4 v[72:75], v[2:3], off offset:2048 nt
	global_load_dwordx4 v[76:79], v[4:5], off offset:1024 nt
	v_add_co_u32_e32 v2, vcc, s25, v10
	v_fmac_f32_e32 v97, v98, v97
	s_nop 0
	v_addc_co_u32_e32 v3, vcc, 0, v11, vcc
	v_add_co_u32_e32 v4, vcc, s26, v10
	s_nop 1
	v_addc_co_u32_e32 v5, vcc, 0, v11, vcc
	global_load_dwordx4 v[80:83], v[2:3], off nt
	global_load_dwordx4 v[84:87], v[4:5], off offset:3072 nt
	v_add_co_u32_e32 v2, vcc, s27, v10
	s_nop 1
	v_addc_co_u32_e32 v3, vcc, 0, v11, vcc
	v_add_co_u32_e32 v4, vcc, s28, v10
	s_nop 1
	v_addc_co_u32_e32 v5, vcc, 0, v11, vcc
	global_load_dwordx4 v[88:91], v[2:3], off offset:2048 nt
	global_load_dwordx4 v[92:95], v[4:5], off offset:1024 nt
	v_add_co_u32_e32 v2, vcc, s29, v10
	s_nop 1
	v_addc_co_u32_e32 v3, vcc, 0, v11, vcc
	v_add_co_u32_e32 v4, vcc, s30, v10
	s_nop 1
	v_addc_co_u32_e32 v5, vcc, 0, v11, vcc
	global_load_dwordx4 v[18:21], v[2:3], off nt
	global_load_dwordx4 v[22:25], v[4:5], off offset:3072 nt
	v_add_co_u32_e32 v2, vcc, s31, v10
	s_nop 1
	v_addc_co_u32_e32 v3, vcc, 0, v11, vcc
	v_add_co_u32_e32 v4, vcc, s33, v10
	s_nop 1
	v_addc_co_u32_e32 v5, vcc, 0, v11, vcc
	global_load_dwordx4 v[26:29], v[2:3], off offset:2048 nt
	global_load_dwordx4 v[30:33], v[4:5], off offset:1024 nt
	v_add_co_u32_e32 v2, vcc, s34, v10
	s_nop 1
	v_addc_co_u32_e32 v3, vcc, 0, v11, vcc
	v_add_co_u32_e32 v6, vcc, s35, v10
	s_nop 1
	v_addc_co_u32_e32 v7, vcc, 0, v11, vcc
	v_add_co_u32_e32 v12, vcc, s36, v10
	global_load_dwordx4 v[2:5], v[2:3], off nt
	s_nop 0
	global_load_dwordx4 v[6:9], v[6:7], off offset:3072 nt
	v_addc_co_u32_e32 v13, vcc, 0, v11, vcc
	v_add_co_u32_e32 v14, vcc, s37, v10
	s_nop 1
	v_addc_co_u32_e32 v15, vcc, 0, v11, vcc
	v_div_scale_f32 v98, vcc, s38, v60, s38
	v_mul_f32_e32 v99, v98, v97
	v_fma_f32 v100, -v96, v99, v98
	v_fmac_f32_e32 v99, v100, v97
	v_fma_f32 v96, -v96, v99, v98
	v_div_fmas_f32 v96, v96, v97, v99
	v_div_scale_f32 v97, s[4:5], v61, v61, s38
	v_rcp_f32_e32 v98, v97
	v_div_fixup_f32 v96, v96, v60, s38
	v_cmp_lt_f32_e32 vcc, 0, v60
	global_load_dwordx4 v[10:13], v[12:13], off offset:2048 nt
	s_nop 0
	global_load_dwordx4 v[14:17], v[14:15], off offset:1024 nt
	v_cndmask_b32_e32 v60, 0, v96, vcc
	v_fma_f32 v96, -v97, v98, 1.0
	v_fmac_f32_e32 v98, v96, v98
	v_div_scale_f32 v96, vcc, s38, v61, s38
	v_mul_f32_e32 v99, v96, v98
	v_fma_f32 v100, -v97, v99, v96
	v_fmac_f32_e32 v99, v100, v98
	v_fma_f32 v96, -v97, v99, v96
	v_div_scale_f32 v97, s[4:5], v62, v62, s38
	v_div_fmas_f32 v96, v96, v98, v99
	v_rcp_f32_e32 v98, v97
	v_div_fixup_f32 v96, v96, v61, s38
	v_cmp_lt_f32_e32 vcc, 0, v61
	s_nop 1
	v_cndmask_b32_e32 v61, 0, v96, vcc
	v_fma_f32 v96, -v97, v98, 1.0
	v_fmac_f32_e32 v98, v96, v98
	v_div_scale_f32 v96, vcc, s38, v62, s38
	v_mul_f32_e32 v99, v96, v98
	v_fma_f32 v100, -v97, v99, v96
	v_fmac_f32_e32 v99, v100, v98
	v_fma_f32 v96, -v97, v99, v96
	v_div_scale_f32 v97, s[4:5], v63, v63, s38
	v_div_fmas_f32 v96, v96, v98, v99
	v_rcp_f32_e32 v98, v97
	v_div_fixup_f32 v96, v96, v62, s38
	v_cmp_lt_f32_e32 vcc, 0, v62
	s_lshl_b32 s5, s9, 3
	s_andn2_b32 s5, s5, 31
	v_cndmask_b32_e32 v62, 0, v96, vcc
	v_fma_f32 v96, -v97, v98, 1.0
	v_fmac_f32_e32 v98, v96, v98
	v_div_scale_f32 v96, vcc, s38, v63, s38
	v_mul_f32_e32 v99, v96, v98
	v_fma_f32 v100, -v97, v99, v96
	v_fmac_f32_e32 v99, v100, v98
	v_fma_f32 v96, -v97, v99, v96
	ds_bpermute_b32 v97, v46, v59
	v_div_fmas_f32 v96, v96, v98, v99
	ds_bpermute_b32 v98, v47, v59
	ds_bpermute_b32 v99, v48, v59
	ds_bpermute_b32 v100, v49, v59
	s_waitcnt vmcnt(15) lgkmcnt(3)
	v_mul_f32_e32 v64, v64, v97
	v_fmaak_f32 v64, v60, v64, 0x43000000
	s_waitcnt vmcnt(14) lgkmcnt(2)
	v_mul_f32_e32 v68, v68, v98
	s_waitcnt vmcnt(13) lgkmcnt(1)
	v_mul_f32_e32 v72, v72, v99
	v_cvt_pk_u8_f32 v64, v64, 0, 0
	v_fmaak_f32 v68, v60, v68, 0x43000000
	s_waitcnt vmcnt(12) lgkmcnt(0)
; template <bool STRIP, int ROT>
; __device__ __forceinline__ void gu_finish_t(f32x4 (&v)[16], float gA, float gB, const GUDesc& d, LAS unsigned* T, int lane, const float (&sinv)[4]) {
;     ...
;     for (int jq = 0; jq < 4; ++jq) {
;         float g[4];
; #pragma unroll
;         for (int e2 = 0; e2 < 4; ++e2) g[e2] = jq < 2 ? __shfl(gA, 32 * jq + 4 * kr + e2) : __shfl(gB, 32 * (jq - 2) + 4 * kr + e2);
; #pragma unroll
;         for (int e = 0; e < 4; ++e)
;             T[(4 * nq + e) * 33 + 8 * jq + kr] = pack4_i8(v[4 * jq + 0][e] * g[0] * inv[e], v[4 * jq + 1][e] * g[1] * inv[e], v[4 * jq + 2][e] * g[2] * inv[e], v[4 * jq + 3][e] * g[3] * inv[e]);
;     }
	v_mul_f32_e32 v76, v76, v100
	v_cvt_pk_u8_f32 v64, v68, 1, v64
	v_fmaak_f32 v68, v60, v72, 0x43000000
	v_cvt_pk_u8_f32 v64, v68, 2, v64
	v_fmaak_f32 v68, v60, v76, 0x43000000
	v_mul_f32_e32 v65, v65, v97
	v_cvt_pk_u8_f32 v64, v68, 3, v64
	v_mul_f32_e32 v68, v69, v98
	v_fmaak_f32 v65, v61, v65, 0x43000000
	v_mul_f32_e32 v69, v73, v99
	v_cvt_pk_u8_f32 v65, v65, 0, 0
	v_fmaak_f32 v68, v61, v68, 0x43000000
	v_mul_f32_e32 v72, v77, v100
	v_cvt_pk_u8_f32 v65, v68, 1, v65
	v_fmaak_f32 v68, v61, v69, 0x43000000
	v_cvt_pk_u8_f32 v65, v68, 2, v65
	v_fmaak_f32 v68, v61, v72, 0x43000000
	v_mul_f32_e32 v66, v66, v97
	v_cvt_pk_u8_f32 v65, v68, 3, v65
	v_mul_f32_e32 v68, v70, v98
	v_fmaak_f32 v66, v62, v66, 0x43000000
	v_mul_f32_e32 v69, v74, v99
	v_cvt_pk_u8_f32 v66, v66, 0, 0
	v_fmaak_f32 v68, v62, v68, 0x43000000
	v_div_fixup_f32 v96, v96, v63, s38
	v_cmp_lt_f32_e32 vcc, 0, v63
	v_mul_f32_e32 v70, v78, v100
	v_cvt_pk_u8_f32 v66, v68, 1, v66
	v_fmaak_f32 v68, v62, v69, 0x43000000
	v_cndmask_b32_e32 v63, 0, v96, vcc
	v_cvt_pk_u8_f32 v66, v68, 2, v66
	v_fmaak_f32 v68, v62, v70, 0x43000000
	v_mul_f32_e32 v67, v67, v97
	v_cvt_pk_u8_f32 v66, v68, 3, v66
	v_mul_f32_e32 v68, v71, v98
	v_fmaak_f32 v67, v63, v67, 0x43000000
	v_mul_f32_e32 v69, v75, v99
	v_cvt_pk_u8_f32 v67, v67, 0, 0
	v_fmaak_f32 v68, v63, v68, 0x43000000
	v_mul_f32_e32 v70, v79, v100
	v_cvt_pk_u8_f32 v67, v68, 1, v67
	v_fmaak_f32 v68, v63, v69, 0x43000000
	v_cvt_pk_u8_f32 v67, v68, 2, v67
	v_fmaak_f32 v68, v63, v70, 0x43000000
	v_cvt_pk_u8_f32 v67, v68, 3, v67
	ds_bpermute_b32 v68, v50, v59
	ds_bpermute_b32 v69, v51, v59
	ds_bpermute_b32 v70, v52, v59
	ds_bpermute_b32 v59, v53, v59
	v_xor_b32_e32 v64, 0x80808080, v64
	s_waitcnt vmcnt(11) lgkmcnt(3)
	v_mul_f32_e32 v71, v80, v68
	s_waitcnt vmcnt(10) lgkmcnt(2)
	v_mul_f32_e32 v72, v84, v69
	v_fmaak_f32 v71, v60, v71, 0x43000000
	s_waitcnt vmcnt(9) lgkmcnt(1)
	v_mul_f32_e32 v73, v88, v70
	v_cvt_pk_u8_f32 v71, v71, 0, 0
	v_fmaak_f32 v72, v60, v72, 0x43000000
	s_waitcnt vmcnt(8) lgkmcnt(0)
	v_mul_f32_e32 v74, v92, v59
	v_cvt_pk_u8_f32 v71, v72, 1, v71
	v_fmaak_f32 v72, v60, v73, 0x43000000
	v_cvt_pk_u8_f32 v71, v72, 2, v71
	v_fmaak_f32 v72, v60, v74, 0x43000000
	v_cvt_pk_u8_f32 v71, v72, 3, v71
	v_xor_b32_e32 v71, 0x80808080, v71
	ds_write2_b32 v57, v64, v71 offset1:8
	v_mul_f32_e32 v64, v81, v68
	v_mul_f32_e32 v71, v85, v69
	v_fmaak_f32 v64, v61, v64, 0x43000000
	v_mul_f32_e32 v72, v89, v70
	v_cvt_pk_u8_f32 v64, v64, 0, 0
	v_fmaak_f32 v71, v61, v71, 0x43000000
	v_mul_f32_e32 v73, v93, v59
	v_cvt_pk_u8_f32 v64, v71, 1, v64
	v_fmaak_f32 v71, v61, v72, 0x43000000
	v_cvt_pk_u8_f32 v64, v71, 2, v64
	v_fmaak_f32 v71, v61, v73, 0x43000000
	v_cvt_pk_u8_f32 v64, v71, 3, v64
	v_xor_b32_e32 v65, 0x80808080, v65
	v_xor_b32_e32 v64, 0x80808080, v64
	ds_write2_b32 v57, v65, v64 offset0:33 offset1:41
	v_mul_f32_e32 v64, v82, v68
	v_mul_f32_e32 v65, v86, v69
	v_fmaak_f32 v64, v62, v64, 0x43000000
	v_mul_f32_e32 v71, v90, v70
	v_cvt_pk_u8_f32 v64, v64, 0, 0
	v_fmaak_f32 v65, v62, v65, 0x43000000
	v_mul_f32_e32 v72, v94, v59
	v_cvt_pk_u8_f32 v64, v65, 1, v64
	v_fmaak_f32 v65, v62, v71, 0x43000000
	v_cvt_pk_u8_f32 v64, v65, 2, v64
	v_fmaak_f32 v65, v62, v72, 0x43000000
	v_cvt_pk_u8_f32 v64, v65, 3, v64
	v_xor_b32_e32 v66, 0x80808080, v66
	v_xor_b32_e32 v64, 0x80808080, v64
	ds_write2_b32 v57, v66, v64 offset0:66 offset1:74
	v_mul_f32_e32 v64, v83, v68
	v_mul_f32_e32 v65, v87, v69
	v_fmaak_f32 v64, v63, v64, 0x43000000
	v_mul_f32_e32 v66, v91, v70
	v_cvt_pk_u8_f32 v64, v64, 0, 0
	v_fmaak_f32 v65, v63, v65, 0x43000000
	v_mul_f32_e32 v59, v95, v59
	v_cvt_pk_u8_f32 v64, v65, 1, v64
	v_fmaak_f32 v65, v63, v66, 0x43000000
	v_cvt_pk_u8_f32 v64, v65, 2, v64
	v_fmaak_f32 v59, v63, v59, 0x43000000
	v_cvt_pk_u8_f32 v59, v59, 3, v64
	ds_bpermute_b32 v64, v46, v34
	ds_bpermute_b32 v65, v47, v34
	ds_bpermute_b32 v66, v48, v34
	ds_bpermute_b32 v68, v49, v34
	v_xor_b32_e32 v67, 0x80808080, v67
	s_waitcnt vmcnt(7) lgkmcnt(3)
	v_mul_f32_e32 v18, v18, v64
	s_waitcnt vmcnt(6) lgkmcnt(2)
	v_mul_f32_e32 v22, v22, v65
	v_fmaak_f32 v18, v60, v18, 0x43000000
	s_waitcnt vmcnt(5) lgkmcnt(1)
	v_mul_f32_e32 v26, v26, v66
	v_cvt_pk_u8_f32 v18, v18, 0, 0
	v_fmaak_f32 v22, v60, v22, 0x43000000
	s_waitcnt vmcnt(4) lgkmcnt(0)
; #define LAS __attribute__((address_space(3)))
; __host__ __device__ __forceinline__ size_t blk8_off(int r, int k, int KT8_) { return ((size_t)((r >> 8) * KT8_ + (k >> 7)) * 256 + (size_t)(r & 255)) * 128 + (size_t)(k & 127); }
; #define LDS_WAIT() asm volatile("s_waitcnt lgkmcnt(0)" ::: "memory")
; template <bool STRIP, int ROT>
; __device__ __forceinline__ void gu_finish_t(f32x4 (&v)[16], float gA, float gB, const GUDesc& d, LAS unsigned* T, int lane, const float (&sinv)[4]) {
;     ...
;     for (int jq = 0; jq < 4; ++jq) {
;         float g[4];
; #pragma unroll
;         for (int e2 = 0; e2 < 4; ++e2) g[e2] = jq < 2 ? __shfl(gA, 32 * jq + 4 * kr + e2) : __shfl(gB, 32 * (jq - 2) + 4 * kr + e2);
; #pragma unroll
;         for (int e = 0; e < 4; ++e)
;             T[(4 * nq + e) * 33 + 8 * jq + kr] = pack4_i8(v[4 * jq + 0][e] * g[0] * inv[e], v[4 * jq + 1][e] * g[1] * inv[e], v[4 * jq + 2][e] * g[2] * inv[e], v[4 * jq + 3][e] * g[3] * inv[e]);
;     }
;     LDS_WAIT(); asm volatile("" ::: "memory");
;     const int nl = lane >> 3, c = lane & 7;
; #pragma unroll
;     for (int g4 = 0; g4 < 4; ++g4) {
;         const int nloc = 8 * g4 + nl, dr = d.il ? gu_dest(d.n0 + nloc, d.bj) : d.n0 + nloc;
;         const LAS unsigned* t = T + nloc * 33 + 4 * c;
;         u32x4 o; o.x = t[0]; o.y = t[1]; o.z = t[2]; o.w = t[3];
;         *(u32x4*)(d.WQ + blk8_off(dr, d.k0 + 16 * c, d.kt8)) = o;
;         if (!STRIP) if (d.k0 == 0 && c == 0) d.sb[dr] = __uint_as_float(d.cmax[dr]) * (1.0f / 127.0f);
;     }
	v_mul_f32_e32 v30, v30, v68
	v_cvt_pk_u8_f32 v18, v22, 1, v18
	v_fmaak_f32 v22, v60, v26, 0x43000000
	v_cvt_pk_u8_f32 v18, v22, 2, v18
	v_fmaak_f32 v22, v60, v30, 0x43000000
	v_mul_f32_e32 v19, v19, v64
	v_cvt_pk_u8_f32 v18, v22, 3, v18
	v_mul_f32_e32 v22, v23, v65
	v_fmaak_f32 v19, v61, v19, 0x43000000
	v_mul_f32_e32 v23, v27, v66
	v_cvt_pk_u8_f32 v19, v19, 0, 0
	v_fmaak_f32 v22, v61, v22, 0x43000000
	v_mul_f32_e32 v26, v31, v68
	v_cvt_pk_u8_f32 v19, v22, 1, v19
	v_fmaak_f32 v22, v61, v23, 0x43000000
	v_cvt_pk_u8_f32 v19, v22, 2, v19
	v_fmaak_f32 v22, v61, v26, 0x43000000
	v_mul_f32_e32 v20, v20, v64
	v_cvt_pk_u8_f32 v19, v22, 3, v19
	v_mul_f32_e32 v22, v24, v65
	v_fmaak_f32 v20, v62, v20, 0x43000000
	v_mul_f32_e32 v23, v28, v66
	v_cvt_pk_u8_f32 v20, v20, 0, 0
	v_fmaak_f32 v22, v62, v22, 0x43000000
	v_mul_f32_e32 v24, v32, v68
	v_cvt_pk_u8_f32 v20, v22, 1, v20
	v_fmaak_f32 v22, v62, v23, 0x43000000
	v_cvt_pk_u8_f32 v20, v22, 2, v20
	v_fmaak_f32 v22, v62, v24, 0x43000000
	v_mul_f32_e32 v21, v21, v64
	v_cvt_pk_u8_f32 v20, v22, 3, v20
	v_mul_f32_e32 v22, v25, v65
	v_fmaak_f32 v21, v63, v21, 0x43000000
	v_mul_f32_e32 v23, v29, v66
	v_cvt_pk_u8_f32 v21, v21, 0, 0
	v_fmaak_f32 v22, v63, v22, 0x43000000
	v_mul_f32_e32 v24, v33, v68
	v_cvt_pk_u8_f32 v21, v22, 1, v21
	v_fmaak_f32 v22, v63, v23, 0x43000000
	v_cvt_pk_u8_f32 v21, v22, 2, v21
	v_fmaak_f32 v22, v63, v24, 0x43000000
	v_cvt_pk_u8_f32 v21, v22, 3, v21
	ds_bpermute_b32 v22, v50, v34
	ds_bpermute_b32 v23, v51, v34
	ds_bpermute_b32 v24, v52, v34
	ds_bpermute_b32 v25, v53, v34
	v_xor_b32_e32 v18, 0x80808080, v18
	s_waitcnt vmcnt(3) lgkmcnt(3)
	v_mul_f32_e32 v2, v2, v22
	s_waitcnt vmcnt(2) lgkmcnt(2)
	v_mul_f32_e32 v6, v6, v23
	v_fmaak_f32 v2, v60, v2, 0x43000000
	s_waitcnt vmcnt(1) lgkmcnt(1)
	v_mul_f32_e32 v10, v10, v24
	v_cvt_pk_u8_f32 v2, v2, 0, 0
	v_fmaak_f32 v6, v60, v6, 0x43000000
	s_waitcnt vmcnt(0) lgkmcnt(0)
	v_mul_f32_e32 v14, v14, v25
	v_cvt_pk_u8_f32 v2, v6, 1, v2
	v_fmaak_f32 v6, v60, v10, 0x43000000
	v_cvt_pk_u8_f32 v2, v6, 2, v2
	v_fmaak_f32 v6, v60, v14, 0x43000000
	v_cvt_pk_u8_f32 v2, v6, 3, v2
	v_xor_b32_e32 v2, 0x80808080, v2
	ds_write2_b32 v57, v18, v2 offset0:16 offset1:24
	v_mul_f32_e32 v2, v3, v22
	v_mul_f32_e32 v3, v7, v23
	v_fmaak_f32 v2, v61, v2, 0x43000000
	v_mul_f32_e32 v6, v11, v24
	v_cvt_pk_u8_f32 v2, v2, 0, 0
	v_fmaak_f32 v3, v61, v3, 0x43000000
	v_mul_f32_e32 v7, v15, v25
	v_cvt_pk_u8_f32 v2, v3, 1, v2
	v_fmaak_f32 v3, v61, v6, 0x43000000
	v_cvt_pk_u8_f32 v2, v3, 2, v2
	v_fmaak_f32 v3, v61, v7, 0x43000000
	v_cvt_pk_u8_f32 v2, v3, 3, v2
	v_xor_b32_e32 v19, 0x80808080, v19
	v_xor_b32_e32 v2, 0x80808080, v2
	ds_write2_b32 v57, v19, v2 offset0:49 offset1:57
	v_mul_f32_e32 v2, v4, v22
	v_mul_f32_e32 v3, v8, v23
	v_fmaak_f32 v2, v62, v2, 0x43000000
	v_mul_f32_e32 v4, v12, v24
	v_cvt_pk_u8_f32 v2, v2, 0, 0
	v_fmaak_f32 v3, v62, v3, 0x43000000
	v_mul_f32_e32 v6, v16, v25
	v_cvt_pk_u8_f32 v2, v3, 1, v2
	v_fmaak_f32 v3, v62, v4, 0x43000000
	v_cvt_pk_u8_f32 v2, v3, 2, v2
	v_fmaak_f32 v3, v62, v6, 0x43000000
	v_cvt_pk_u8_f32 v2, v3, 3, v2
	v_xor_b32_e32 v20, 0x80808080, v20
	v_xor_b32_e32 v2, 0x80808080, v2
	ds_write2_b32 v57, v20, v2 offset0:82 offset1:90
	v_mul_f32_e32 v2, v5, v22
	v_mul_f32_e32 v3, v9, v23
	v_fmaak_f32 v2, v63, v2, 0x43000000
	v_mul_f32_e32 v4, v13, v24
	v_cvt_pk_u8_f32 v2, v2, 0, 0
	v_fmaak_f32 v3, v63, v3, 0x43000000
	v_mul_f32_e32 v5, v17, v25
	v_cvt_pk_u8_f32 v2, v3, 1, v2
	v_fmaak_f32 v3, v63, v4, 0x43000000
	v_cvt_pk_u8_f32 v2, v3, 2, v2
	v_fmaak_f32 v3, v63, v5, 0x43000000
	v_cvt_pk_u8_f32 v2, v3, 3, v2
	v_xor_b32_e32 v59, 0x80808080, v59
	v_xor_b32_e32 v21, 0x80808080, v21
	v_xor_b32_e32 v2, 0x80808080, v2
	ds_write2_b32 v57, v67, v59 offset0:99 offset1:107
	ds_write2_b32 v57, v21, v2 offset0:115 offset1:123
	s_waitcnt lgkmcnt(0)
	s_or_b32 s4, s40, s41
	s_add_i32 s40, s5, s8
	s_or_b32 s4, s4, s39
	s_ashr_i32 s41, s40, 31
	v_or_b32_e32 v2, s4, v36
	ds_read2_b32 v[4:5], v58 offset1:1
	ds_read2_b32 v[6:7], v58 offset0:2 offset1:3
	s_lshl_b64 s[40:41], s[40:41], 15
	v_lshlrev_b32_e32 v3, 7, v2
	s_add_u32 s6, s6, s40
	v_and_b32_e32 v34, 0x7380, v3
	s_addc_u32 s7, s7, s41
	v_lshl_add_u64 v[8:9], s[6:7], 0, v[34:35]
	v_or_b32_e32 v3, s8, v44
	v_lshl_add_u64 v[8:9], v[8:9], 0, v[38:39]
	v_cmp_ne_u32_e32 vcc, 0, v3
	v_or_b32_e32 v3, s4, v54
	s_waitcnt lgkmcnt(0)
	global_store_dwordx4 v[8:9], v[4:7], off
	s_nop 1
	v_add_u32_e32 v5, 0x420, v58
	v_add_u32_e32 v6, 0x428, v58
	v_lshlrev_b32_e32 v4, 7, v3
	s_and_saveexec_b64 s[8:9], vcc
	s_xor_b64 s[8:9], exec, s[8:9]
	s_cbranch_execz .LBB0_2311
	ds_read2_b32 v[8:9], v5 offset1:1
	ds_read2_b32 v[10:11], v6 offset1:1
	v_and_b32_e32 v34, 0x7780, v4
	v_lshl_add_u64 v[2:3], s[6:7], 0, v[34:35]
	v_lshl_add_u64 v[2:3], v[2:3], 0, v[38:39]
	s_waitcnt lgkmcnt(0)
	global_store_dwordx4 v[2:3], v[8:11], off

; #define LAS __attribute__((address_space(3)))
; __device__ __forceinline__ void gu_load(f32x4 (&v)[16], float& gA, float& gB, const GUDesc& d, int lane) {
;     const int kr = lane >> 3, nq = lane & 7;
;     const float* __restrict__ src = d.W + (size_t)(d.k0 + 4 * kr) * d.N + d.n0 + 4 * nq;
;     gA = d.gain ? d.gain[d.k0 + lane] : 1.0f; gB = d.gain ? d.gain[d.k0 + 64 + lane] : 1.0f;
; #pragma unroll
;     for (int i = 0; i < 16; ++i) v[i] = *(const f32x4*)(src + (size_t)(32 * (i >> 2) + (i & 3)) * d.N);
; }
;     const int lane = (F.tid & 63), stride = nworkers * 8, first = lo + worker * 8 + F.wave;
;     LAS unsigned* T = (LAS unsigned*)(F.lds + F.wave * 16384);
;     if (first >= hi) return;
;     const int n_my = (hi - first + stride - 1) / stride;
;     f32x4 va[16], vb[16]; float gaA, gaB, gbA, gbB; GUDesc da, db;
;     gu_decode(F, first, da); gu_load(va, gaA, gaB, da, lane);
.LBB0_2322:
	s_xor_b32 s6, s8, s6
	s_mul_i32 s8, s9, s3
	s_sub_i32 s7, s7, s8
	s_add_i32 s8, s9, 1
	s_sub_i32 s10, s7, s3
	s_cmp_ge_u32 s7, s3
	s_cselect_b32 s8, s8, s9
	s_cselect_b32 s7, s10, s7
	s_add_i32 s9, s8, 1
	s_cmp_ge_u32 s7, s3
	s_cselect_b32 s3, s9, s8
	s_xor_b32 s3, s3, s6
	s_sub_i32 s34, s3, s6
	s_cmp_lt_i32 s34, 1
	s_mov_b32 s59, 1
	s_cbranch_scc1 .LBB0_2368
	s_mulk_i32 s5, 0x158
	s_sub_i32 s3, s4, s5
	s_sext_i32_i16 s3, s3
	s_lshl_b32 s10, s3, 5
	s_and_b32 s58, s2, 1
	s_mov_b32 s35, 0x600000
	s_and_b64 s[0:1], s[0:1], exec
	s_mov_b32 s36, 0x200000
	s_cselect_b32 s8, s35, 0x620000
	s_cselect_b32 s20, s36, 0x15e00000
	s_add_u32 s37, s78, 0x80000
	s_addc_u32 s38, s79, 0
	s_lshr_b32 s0, s2, 1
	s_mulk_i32 s0, 0x5600
	s_ashr_i32 s1, s0, 31
	v_and_b32_e32 v1, 28, v1
	s_lshl_b64 s[0:1], s[0:1], 2
	s_add_u32 s12, s37, s0
	v_or_b32_e32 v4, s41, v1
	s_addc_u32 s13, s38, s1
	v_mul_i32_i24_e32 v4, 0x2b00, v4
	s_add_u32 s39, s78, 0x26000000
	v_ashrrev_i32_e32 v5, 31, v4
	v_and_b32_e32 v66, 28, v141
	s_addc_u32 s40, s79, 0
	s_waitcnt lgkmcnt(0)
	v_lshl_add_u64 v[2:3], v[4:5], 2, v[2:3]
	s_ashr_i32 s11, s10, 31
	v_mov_b32_e32 v131, 0
	v_lshl_add_u64 v[2:3], s[10:11], 2, v[2:3]
	v_lshlrev_b32_e32 v130, 2, v66
	v_lshl_add_u64 v[68:69], v[2:3], 0, v[130:131]
	s_mov_b32 s0, 0x428000
	v_add_co_u32_e32 v70, vcc, s0, v68
	s_mov_b32 s0, 0x41d000
	s_nop 0
	v_addc_co_u32_e32 v71, vcc, 0, v69, vcc
	v_add_co_u32_e32 v10, vcc, s0, v68
	s_mov_b32 s0, 0x412000
	s_nop 0
	v_addc_co_u32_e32 v11, vcc, 0, v69, vcc
	v_add_co_u32_e32 v12, vcc, s0, v68
	s_mov_b32 s0, 0x408000
	s_nop 0
	v_addc_co_u32_e32 v13, vcc, 0, v69, vcc
	v_add_co_u32_e32 v18, vcc, s0, v68
	s_mov_b32 s0, 0x2d0000
	s_nop 0
	v_addc_co_u32_e32 v19, vcc, 0, v69, vcc
	v_add_co_u32_e32 v20, vcc, s0, v68
	s_mov_b32 s0, 0x2c5000
	s_nop 0
	v_addc_co_u32_e32 v21, vcc, 0, v69, vcc
	v_add_co_u32_e32 v26, vcc, s0, v68
	s_mov_b32 s0, 0x2ba000
	s_nop 0
	v_addc_co_u32_e32 v27, vcc, 0, v69, vcc
	v_add_co_u32_e32 v28, vcc, s0, v68
	s_mov_b32 s0, 0x2b0000
	s_nop 0
	v_addc_co_u32_e32 v29, vcc, 0, v69, vcc
	global_load_dwordx4 v[2:5], v[10:11], off offset:2048 nt
	global_load_dwordx4 v[6:9], v[12:13], off offset:3072 nt
	s_nop 0
	global_load_dwordx4 v[10:13], v[18:19], off nt
	global_load_dwordx4 v[14:17], v[20:21], off offset:1024 nt
	s_nop 0
	global_load_dwordx4 v[18:21], v[26:27], off offset:2048 nt
	global_load_dwordx4 v[22:25], v[28:29], off offset:3072 nt
	v_add_co_u32_e32 v26, vcc, s0, v68
	s_mov_b32 s0, 0x178000
	s_nop 0
	v_addc_co_u32_e32 v27, vcc, 0, v69, vcc
	v_add_co_u32_e32 v28, vcc, s0, v68
	s_mov_b32 s0, 0x16d000
	s_nop 0
	v_addc_co_u32_e32 v29, vcc, 0, v69, vcc
	global_load_dwordx4 v[30:33], v[26:27], off nt
	global_load_dwordx4 v[34:37], v[28:29], off offset:1024 nt
	v_add_co_u32_e32 v26, vcc, s0, v68
	s_mov_b32 s0, 0x162000
	s_nop 0
	v_addc_co_u32_e32 v27, vcc, 0, v69, vcc
	v_add_co_u32_e32 v28, vcc, s0, v68
	s_mov_b32 s0, 0x158000
	s_nop 0
	v_addc_co_u32_e32 v29, vcc, 0, v69, vcc
	global_load_dwordx4 v[38:41], v[26:27], off offset:2048 nt
	global_load_dwordx4 v[42:45], v[28:29], off offset:3072 nt
	v_add_co_u32_e32 v26, vcc, s0, v68
	s_mov_b32 s0, 0x20000
	s_nop 0
	v_addc_co_u32_e32 v27, vcc, 0, v69, vcc
	v_add_co_u32_e32 v28, vcc, s0, v68
	s_mov_b32 s0, 0x15000
	s_nop 0
	v_addc_co_u32_e32 v29, vcc, 0, v69, vcc
	v_add_co_u32_e32 v72, vcc, s0, v68
	s_mov_b32 s0, 0xa000
	s_nop 0
	v_addc_co_u32_e32 v73, vcc, 0, v69, vcc
	v_add_co_u32_e32 v74, vcc, s0, v68
	global_load_dwordx4 v[46:49], v[26:27], off nt
	global_load_dwordx4 v[50:53], v[28:29], off offset:1024 nt
	v_addc_co_u32_e32 v75, vcc, 0, v69, vcc
	global_load_dwordx4 v[54:57], v[72:73], off offset:2048 nt
	global_load_dwordx4 v[58:61], v[74:75], off offset:3072 nt
	global_load_dwordx4 v[26:29], v[70:71], off offset:1024 nt
	global_load_dwordx4 v[62:65], v[68:69], off nt
	v_mbcnt_lo_u32_b32 v68, -1, 0
	s_lshl_b32 s0, s68, 14
	v_lshrrev_b32_e32 v137, 3, v136
	v_and_b32_e32 v138, 7, v0
	v_mbcnt_hi_u32_b32 v68, -1, v68
	s_add_i32 s0, s0, 0
	s_add_i32 s42, s34, -1
	v_lshlrev_b32_e32 v69, 4, v137
	v_lshlrev_b32_e32 v68, 2, v68
	s_movk_i32 s1, 0x100
	v_lshlrev_b32_e32 v132, 4, v138
	s_mov_b32 s9, 0
	v_lshl_add_u32 v67, v137, 2, s0
	v_and_or_b32 v140, v68, s1, v69
	v_mul_u32_u24_e32 v68, 0x210, v138
	v_add_u32_e32 v69, s0, v132
	v_mul_u32_u24_e32 v70, 0x84, v137
	s_add_u32 s43, s78, 0xab000
	s_mov_b32 s21, s9
	v_lshlrev_b32_e32 v139, 2, v138
	v_or_b32_e32 v141, 4, v140
	v_or_b32_e32 v142, 8, v140
	v_or_b32_e32 v143, 12, v140
	v_or_b32_e32 v144, 0x80, v140
	v_or_b32_e32 v145, 0x84, v140
	v_or_b32_e32 v146, 0x88, v140
	v_or_b32_e32 v147, 0x8c, v140
	v_or_b32_e32 v148, 8, v137
	v_or_b32_e32 v149, 16, v137
	v_or_b32_e32 v150, 24, v137
	v_mov_b32_e32 v133, v131
	s_addc_u32 s44, s79, 0
	s_mov_b32 s55, 32
	s_add_i32 s45, 0, 0x27c10
	s_add_i32 s46, 0, 0x27c18
	s_mov_b32 s47, 0x27c90
	s_mov_b32 s48, 0x27c08
	s_mov_b32 s49, 0x27ca0
	s_mov_b32 s50, 0x660000
	s_mov_b32 s51, 0x20a00000
	v_lshlrev_b32_e32 v134, 2, v66
	s_movk_i32 s52, 0x7f
	s_mov_b32 s53, 0x42fe0000
	v_add_u32_e32 v151, v67, v68
	v_add_u32_e32 v152, v69, v70
	v_mov_b32_e32 v153, 0x7c
	v_mov_b32_e32 v154, 0x67
	v_mov_b32_e32 v155, 0x6f
	v_mov_b32_e32 v156, 0x77
	v_mov_b32_e32 v157, 0x7f
	s_mov_b32 s54, 0
	s_mov_b64 s[24:25], s[8:9]
	s_branch .LBB0_2326

; __device__ __forceinline__ void gu_load(f32x4 (&v)[16], float& gA, float& gB, const GUDesc& d, int lane) {
;     const int kr = lane >> 3, nq = lane & 7;
;     const float* __restrict__ src = d.W + (size_t)(d.k0 + 4 * kr) * d.N + d.n0 + 4 * nq;
;     gA = d.gain ? d.gain[d.k0 + lane] : 1.0f; gB = d.gain ? d.gain[d.k0 + 64 + lane] : 1.0f;
; #pragma unroll
;     for (int i = 0; i < 16; ++i) v[i] = *(const f32x4*)(src + (size_t)(32 * (i >> 2) + (i & 3)) * d.N);
; }
; template <int ROT>
; __device__ __forceinline__ void rot32_tile(f32x4 (&v)[16], int lane) {
; #pragma unroll
;     for (int jq = 0; jq < 4; ++jq) {
;         const f32x4 a = v[4 * jq], b = v[4 * jq + 1], c = v[4 * jq + 2], d = v[4 * jq + 3];
;         const f32x4 a1 = a + b, b1 = a - b, c1 = c + d, d1 = c - d;
;         if (ROT >= 2) { v[4 * jq] = a1 + c1; v[4 * jq + 2] = a1 - c1; v[4 * jq + 1] = b1 + d1; v[4 * jq + 3] = b1 - d1; }
;         else { v[4 * jq] = a1; v[4 * jq + 1] = b1; v[4 * jq + 2] = c1; v[4 * jq + 3] = d1; }
;     }
;     { const bool s8 = (lane & 8) != 0, s16 = (lane & 16) != 0, s32 = (lane & 32) != 0;
; #pragma unroll
;       for (int i = 0; i < 16; ++i)
; #pragma unroll
;           for (int e = 0; e < 4; ++e) { float x = v[i][e]; if (ROT >= 3) x = bfly8(x, s8); if (ROT >= 4) x = bfly16(x, s16); if (ROT >= 5) x = bfly32(x, s32); v[i][e] = x; } }
; #pragma unroll
;     for (int i = 0; i < 16; ++i) v[i] *= (ROT == 1 ? 0.70710678118654752f : ROT == 2 ? 0.5f : ROT == 3 ? 0.35355339059327373f : ROT == 4 ? 0.25f : 0.17677669529663687f);
; }
; template <bool STRIP, int ROT>
; __device__ __forceinline__ void gu_finish_t(f32x4 (&v)[16], float gA, float gB, const GUDesc& d, LAS unsigned* T, int lane, const float (&sinv)[4]) {
;     const int kr = lane >> 3, nq = lane & 7;
;     const int dq0 = d.il ? gu_dest(d.n0 + 4 * nq, d.bj) : d.n0 + 4 * nq;
;     if (ROT) rot32_tile<ROT>(v, lane);
;     float inv[4];
; #pragma unroll
;     for (int e = 0; e < 4; ++e) { if (STRIP) inv[e] = sinv[e]; else { const float cm = __uint_as_float(d.cmax[dq0 + e]); inv[e] = cm > 0.f ? 127.0f / cm : 0.f; } }
; #pragma unroll
;     for (int jq = 0; jq < 4; ++jq) {
;         float g[4];
; #pragma unroll
;         for (int e2 = 0; e2 < 4; ++e2) g[e2] = jq < 2 ? __shfl(gA, 32 * jq + 4 * kr + e2) : __shfl(gB, 32 * (jq - 2) + 4 * kr + e2);
; #pragma unroll
;         for (int e = 0; e < 4; ++e)
.LBB0_2337:
	s_add_u32 s28, s78, s20
	s_addc_u32 s29, s79, s21
	s_add_u32 s20, s39, s24
	s_addc_u32 s21, s40, s25
	s_ashr_i32 s17, s16, 31
	s_lshl_b32 s8, s0, 2
	v_add_u32_e32 v68, s10, v139
	s_cmp_eq_u32 s59, 0
	v_lshlrev_b32_e32 v69, 1, v68
	s_cselect_b64 s[4:5], -1, 0
	v_and_b32_e32 v69, 0xffffff00, v69
	s_lshl_b32 s11, s58, 7
	v_add_u32_e32 v69, s11, v69
	v_and_or_b32 v69, v68, s52, v69
	v_cndmask_b32_e64 v68, v69, v68, s[4:5]
	v_ashrrev_i32_e32 v69, 31, v68
	v_lshl_add_u64 v[68:69], v[68:69], 2, s[12:13]
	global_load_dwordx4 v[162:165], v[68:69], off nt
	v_or_b32_e32 v68, s57, v1
	v_mul_hi_i32_i24_e32 v69, s0, v68
	v_mul_i32_i24_e32 v68, s0, v68
	s_waitcnt lgkmcnt(0)
	v_lshl_add_u64 v[66:67], v[68:69], 2, v[66:67]
	v_mov_b32_e32 v135, v131
	v_lshl_add_u64 v[66:67], s[16:17], 2, v[66:67]
	v_lshl_add_u64 v[66:67], v[66:67], 0, v[134:135]
	v_lshl_add_u64 v[68:69], v[66:67], 0, s[8:9]
	global_load_dwordx4 v[114:117], v[66:67], off nt
	global_load_dwordx4 v[118:121], v[68:69], off nt
	v_lshl_add_u64 v[66:67], v[68:69], 0, s[8:9]
	s_mul_i32 s6, s0, 0x74
	s_mov_b32 s7, s9
	v_lshl_add_u64 v[68:69], v[66:67], 0, s[8:9]
	global_load_dwordx4 v[122:125], v[66:67], off nt
	global_load_dwordx4 v[126:129], v[68:69], off nt
	v_lshl_add_u64 v[66:67], v[68:69], 0, s[6:7]
	v_lshl_add_u64 v[68:69], v[66:67], 0, s[8:9]
	global_load_dwordx4 v[98:101], v[66:67], off nt
	global_load_dwordx4 v[102:105], v[68:69], off nt
	v_lshl_add_u64 v[66:67], v[68:69], 0, s[8:9]
	v_lshl_add_u64 v[68:69], v[66:67], 0, s[8:9]
	global_load_dwordx4 v[106:109], v[66:67], off nt
	global_load_dwordx4 v[110:113], v[68:69], off nt
	v_lshl_add_u64 v[66:67], v[68:69], 0, s[6:7]
	global_load_dwordx4 v[82:85], v[66:67], off nt
	v_lshl_add_u64 v[66:67], v[66:67], 0, s[8:9]
	global_load_dwordx4 v[86:89], v[66:67], off nt
	v_lshl_add_u64 v[66:67], v[66:67], 0, s[8:9]
	global_load_dwordx4 v[90:93], v[66:67], off nt
	v_lshl_add_u64 v[66:67], v[66:67], 0, s[8:9]
	s_waitcnt vmcnt(34)
	v_lshl_add_u64 v[70:71], v[66:67], 0, s[6:7]
	s_waitcnt vmcnt(33)
	v_lshl_add_u64 v[74:75], v[70:71], 0, s[8:9]
	s_waitcnt vmcnt(32)
	v_lshl_add_u64 v[78:79], v[74:75], 0, s[8:9]
	global_load_dwordx4 v[94:97], v[66:67], off nt
	s_waitcnt vmcnt(12)
	v_div_scale_f32 v130, s[0:1], v162, v162, s53
	v_div_scale_f32 v166, s[0:1], v163, v163, s53
	v_rcp_f32_e32 v171, v130
	v_rcp_f32_e32 v172, v166
	v_div_scale_f32 v168, s[6:7], v164, v164, s53
	v_rcp_f32_e32 v173, v168
	v_fma_f32 v175, -v130, v171, 1.0
	v_div_scale_f32 v135, vcc, s53, v162, s53
	v_fma_f32 v176, -v166, v172, 1.0
	v_fmac_f32_e32 v171, v175, v171
	v_div_scale_f32 v167, s[0:1], s53, v163, s53
	v_fmac_f32_e32 v172, v176, v172
	v_mul_f32_e32 v175, v135, v171
	v_fma_f32 v177, -v168, v173, 1.0
	v_mul_f32_e32 v176, v167, v172
	v_fma_f32 v178, -v130, v175, v135
	v_div_scale_f32 v169, s[6:7], s53, v164, s53
	v_fmac_f32_e32 v173, v177, v173
	v_fma_f32 v179, -v166, v176, v167
	v_fmac_f32_e32 v175, v178, v171
	v_div_scale_f32 v170, s[24:25], v165, v165, s53
	v_mul_f32_e32 v177, v169, v173
	v_fmac_f32_e32 v176, v179, v172
	v_fma_f32 v130, -v130, v175, v135
	v_rcp_f32_e32 v174, v170
	v_fma_f32 v180, -v168, v177, v169
	v_fma_f32 v135, -v166, v176, v167
	v_div_fmas_f32 v130, v130, v171, v175
	s_mov_b64 vcc, s[0:1]
	v_fmac_f32_e32 v177, v180, v173
	v_div_fixup_f32 v130, v130, v162, s53
	v_div_fmas_f32 v135, v135, v172, v176
	v_cmp_lt_f32_e32 vcc, 0, v162
	v_fma_f32 v166, -v168, v177, v169
	v_div_fixup_f32 v135, v135, v163, s53
	v_cndmask_b32_e32 v130, 0, v130, vcc
	s_mov_b64 vcc, s[6:7]
	v_div_fmas_f32 v162, v166, v173, v177
	v_cmp_lt_f32_e32 vcc, 0, v163
	v_div_fixup_f32 v162, v162, v164, s53
	v_fma_f32 v163, -v170, v174, 1.0
	v_cndmask_b32_e32 v135, 0, v135, vcc
	v_cmp_lt_f32_e32 vcc, 0, v164
	v_fmac_f32_e32 v174, v163, v174
	ds_bpermute_b32 v167, v142, v159
	v_cndmask_b32_e32 v162, 0, v162, vcc
	v_div_scale_f32 v163, vcc, s53, v165, s53
	v_mul_f32_e32 v164, v163, v174
	v_fma_f32 v166, -v170, v164, v163
	v_fmac_f32_e32 v164, v166, v174
	v_fma_f32 v163, -v170, v164, v163
	v_div_fmas_f32 v163, v163, v174, v164
	ds_bpermute_b32 v164, v140, v159
	ds_bpermute_b32 v166, v141, v159
	ds_bpermute_b32 v168, v143, v159
	s_waitcnt lgkmcnt(3)
	v_mul_f32_e32 v54, v54, v167
	v_fmaak_f32 v54, v130, v54, 0x43000000
	s_waitcnt lgkmcnt(2)
	v_mul_f32_e32 v62, v62, v164
	s_waitcnt lgkmcnt(1)
	v_mul_f32_e32 v58, v58, v166
	v_fmaak_f32 v62, v130, v62, 0x43000000
	v_cvt_pk_u8_f32 v62, v62, 0, 0
	v_fmaak_f32 v58, v130, v58, 0x43000000
	s_waitcnt lgkmcnt(0)
	v_mul_f32_e32 v50, v50, v168
	v_cvt_pk_u8_f32 v58, v58, 1, v62
	v_cvt_pk_u8_f32 v54, v54, 2, v58
	v_fmaak_f32 v50, v130, v50, 0x43000000
	v_cvt_pk_u8_f32 v50, v50, 3, v54
	v_mul_f32_e32 v54, v63, v164
	v_mul_f32_e32 v58, v59, v166
	v_fmaak_f32 v54, v135, v54, 0x43000000
	v_mul_f32_e32 v55, v55, v167
	v_cvt_pk_u8_f32 v54, v54, 0, 0
	v_fmaak_f32 v58, v135, v58, 0x43000000
	v_mul_f32_e32 v51, v51, v168
	v_cvt_pk_u8_f32 v54, v58, 1, v54
	v_fmaak_f32 v55, v135, v55, 0x43000000
	v_cvt_pk_u8_f32 v54, v55, 2, v54
	v_fmaak_f32 v51, v135, v51, 0x43000000
	v_cvt_pk_u8_f32 v51, v51, 3, v54
	v_mul_f32_e32 v54, v64, v164
	v_mul_f32_e32 v55, v60, v166
	v_fmaak_f32 v54, v162, v54, 0x43000000
	v_mul_f32_e32 v56, v56, v167
	v_cvt_pk_u8_f32 v54, v54, 0, 0
	v_fmaak_f32 v55, v162, v55, 0x43000000
	v_mul_f32_e32 v52, v52, v168
	v_cvt_pk_u8_f32 v54, v55, 1, v54
	v_fmaak_f32 v55, v162, v56, 0x43000000
	v_div_fixup_f32 v163, v163, v165, s53
	v_cmp_lt_f32_e32 vcc, 0, v165
	v_cvt_pk_u8_f32 v54, v55, 2, v54
	v_fmaak_f32 v52, v162, v52, 0x43000000
	v_cndmask_b32_e32 v163, 0, v163, vcc
	v_cvt_pk_u8_f32 v52, v52, 3, v54
	v_mul_f32_e32 v54, v65, v164
	v_mul_f32_e32 v55, v61, v166
	v_fmaak_f32 v54, v163, v54, 0x43000000
	v_mul_f32_e32 v56, v57, v167
	v_cvt_pk_u8_f32 v54, v54, 0, 0
	v_fmaak_f32 v55, v163, v55, 0x43000000
	v_mul_f32_e32 v53, v53, v168
	v_cvt_pk_u8_f32 v54, v55, 1, v54
	v_fmaak_f32 v55, v163, v56, 0x43000000
	v_cvt_pk_u8_f32 v54, v55, 2, v54
	v_fmaak_f32 v53, v163, v53, 0x43000000
	v_cvt_pk_u8_f32 v53, v53, 3, v54
	ds_bpermute_b32 v54, v144, v159
	ds_bpermute_b32 v55, v145, v159
	ds_bpermute_b32 v56, v146, v159
	ds_bpermute_b32 v57, v147, v159
	v_xor_b32_e32 v50, 0x80808080, v50
	s_waitcnt lgkmcnt(3)
; __device__ __forceinline__ void gu_load(f32x4 (&v)[16], float& gA, float& gB, const GUDesc& d, int lane) {
;     const int kr = lane >> 3, nq = lane & 7;
;     const float* __restrict__ src = d.W + (size_t)(d.k0 + 4 * kr) * d.N + d.n0 + 4 * nq;
;     gA = d.gain ? d.gain[d.k0 + lane] : 1.0f; gB = d.gain ? d.gain[d.k0 + 64 + lane] : 1.0f;
; #pragma unroll
;     for (int i = 0; i < 16; ++i) v[i] = *(const f32x4*)(src + (size_t)(32 * (i >> 2) + (i & 3)) * d.N);
; }
; template <bool STRIP, int ROT>
; __device__ __forceinline__ void gu_finish_t(f32x4 (&v)[16], float gA, float gB, const GUDesc& d, LAS unsigned* T, int lane, const float (&sinv)[4]) {
;     ...
;     for (int jq = 0; jq < 4; ++jq) {
;         float g[4];
; #pragma unroll
;         for (int e2 = 0; e2 < 4; ++e2) g[e2] = jq < 2 ? __shfl(gA, 32 * jq + 4 * kr + e2) : __shfl(gB, 32 * (jq - 2) + 4 * kr + e2);
; #pragma unroll
;         for (int e = 0; e < 4; ++e)
;             T[(4 * nq + e) * 33 + 8 * jq + kr] = pack4_i8(v[4 * jq + 0][e] * g[0] * inv[e], v[4 * jq + 1][e] * g[1] * inv[e], v[4 * jq + 2][e] * g[2] * inv[e], v[4 * jq + 3][e] * g[3] * inv[e]);
;     }
	v_mul_f32_e32 v46, v46, v54
	s_waitcnt lgkmcnt(2)
	v_mul_f32_e32 v42, v42, v55
	v_fmaak_f32 v46, v130, v46, 0x43000000
	s_waitcnt lgkmcnt(1)
	v_mul_f32_e32 v38, v38, v56
	v_cvt_pk_u8_f32 v46, v46, 0, 0
	v_fmaak_f32 v42, v130, v42, 0x43000000
	s_waitcnt lgkmcnt(0)
	v_mul_f32_e32 v34, v34, v57
	v_cvt_pk_u8_f32 v42, v42, 1, v46
	v_fmaak_f32 v38, v130, v38, 0x43000000
	v_cvt_pk_u8_f32 v38, v38, 2, v42
	v_fmaak_f32 v34, v130, v34, 0x43000000
	v_cvt_pk_u8_f32 v34, v34, 3, v38
	v_xor_b32_e32 v34, 0x80808080, v34
	ds_write2_b32 v151, v50, v34 offset1:8
	v_mul_f32_e32 v34, v47, v54
	v_mul_f32_e32 v38, v43, v55
	v_fmaak_f32 v34, v135, v34, 0x43000000
	v_mul_f32_e32 v39, v39, v56
	v_cvt_pk_u8_f32 v34, v34, 0, 0
	v_fmaak_f32 v38, v135, v38, 0x43000000
	v_mul_f32_e32 v35, v35, v57
	v_cvt_pk_u8_f32 v34, v38, 1, v34
	v_fmaak_f32 v38, v135, v39, 0x43000000
	v_cvt_pk_u8_f32 v34, v38, 2, v34
	v_fmaak_f32 v35, v135, v35, 0x43000000
	v_cvt_pk_u8_f32 v34, v35, 3, v34
	v_xor_b32_e32 v51, 0x80808080, v51
	v_xor_b32_e32 v34, 0x80808080, v34
	ds_write2_b32 v151, v51, v34 offset0:33 offset1:41
	v_mul_f32_e32 v34, v48, v54
	v_mul_f32_e32 v35, v44, v55
	v_fmaak_f32 v34, v162, v34, 0x43000000
	global_load_dwordx4 v[66:69], v[70:71], off nt
	v_mul_f32_e32 v38, v40, v56
	global_load_dwordx4 v[70:73], v[74:75], off nt
	v_cvt_pk_u8_f32 v34, v34, 0, 0
	global_load_dwordx4 v[74:77], v[78:79], off nt
	v_lshl_add_u64 v[78:79], v[78:79], 0, s[8:9]
	v_fmaak_f32 v35, v162, v35, 0x43000000
	global_load_dwordx4 v[78:81], v[78:79], off nt
	v_mul_f32_e32 v36, v36, v57
	v_cvt_pk_u8_f32 v34, v35, 1, v34
	v_fmaak_f32 v35, v162, v38, 0x43000000
	v_cvt_pk_u8_f32 v34, v35, 2, v34
	v_fmaak_f32 v35, v162, v36, 0x43000000
	v_cvt_pk_u8_f32 v34, v35, 3, v34
	v_xor_b32_e32 v52, 0x80808080, v52
	v_xor_b32_e32 v34, 0x80808080, v34
	ds_write2_b32 v151, v52, v34 offset0:66 offset1:74
	v_mul_f32_e32 v34, v49, v54
	v_mul_f32_e32 v35, v45, v55
	v_fmaak_f32 v34, v163, v34, 0x43000000
	v_mul_f32_e32 v36, v41, v56
	v_cvt_pk_u8_f32 v34, v34, 0, 0
	v_fmaak_f32 v35, v163, v35, 0x43000000
	v_mul_f32_e32 v37, v37, v57
	v_cvt_pk_u8_f32 v34, v35, 1, v34
	v_fmaak_f32 v35, v163, v36, 0x43000000
	v_cvt_pk_u8_f32 v34, v35, 2, v34
	v_fmaak_f32 v35, v163, v37, 0x43000000
	v_cvt_pk_u8_f32 v34, v35, 3, v34
	ds_bpermute_b32 v35, v140, v158
	ds_bpermute_b32 v36, v141, v158
	ds_bpermute_b32 v37, v142, v158
	ds_bpermute_b32 v38, v143, v158
	v_xor_b32_e32 v53, 0x80808080, v53
	s_waitcnt lgkmcnt(3)
	v_mul_f32_e32 v30, v30, v35
	s_waitcnt lgkmcnt(2)
	v_mul_f32_e32 v22, v22, v36
	v_fmaak_f32 v30, v130, v30, 0x43000000
	s_waitcnt lgkmcnt(1)
	v_mul_f32_e32 v18, v18, v37
	v_cvt_pk_u8_f32 v30, v30, 0, 0
	v_fmaak_f32 v22, v130, v22, 0x43000000
	s_waitcnt lgkmcnt(0)
	v_mul_f32_e32 v14, v14, v38
	v_cvt_pk_u8_f32 v22, v22, 1, v30
	v_fmaak_f32 v18, v130, v18, 0x43000000
	v_cvt_pk_u8_f32 v18, v18, 2, v22
	v_fmaak_f32 v14, v130, v14, 0x43000000
	v_cvt_pk_u8_f32 v14, v14, 3, v18
	v_mul_f32_e32 v18, v31, v35
	v_mul_f32_e32 v22, v23, v36
	v_fmaak_f32 v18, v135, v18, 0x43000000
	v_mul_f32_e32 v19, v19, v37
	v_cvt_pk_u8_f32 v18, v18, 0, 0
	v_fmaak_f32 v22, v135, v22, 0x43000000
	v_mul_f32_e32 v15, v15, v38
	v_cvt_pk_u8_f32 v18, v22, 1, v18
	v_fmaak_f32 v19, v135, v19, 0x43000000
	v_cvt_pk_u8_f32 v18, v19, 2, v18
	v_fmaak_f32 v15, v135, v15, 0x43000000
	v_cvt_pk_u8_f32 v15, v15, 3, v18
	v_mul_f32_e32 v18, v32, v35
	v_mul_f32_e32 v19, v24, v36
	v_fmaak_f32 v18, v162, v18, 0x43000000
	v_mul_f32_e32 v20, v20, v37
	v_cvt_pk_u8_f32 v18, v18, 0, 0
	v_fmaak_f32 v19, v162, v19, 0x43000000
	v_mul_f32_e32 v16, v16, v38
	v_cvt_pk_u8_f32 v18, v19, 1, v18
	v_fmaak_f32 v19, v162, v20, 0x43000000
	v_cvt_pk_u8_f32 v18, v19, 2, v18
	v_fmaak_f32 v16, v162, v16, 0x43000000
	v_cvt_pk_u8_f32 v16, v16, 3, v18
	v_mul_f32_e32 v18, v33, v35
	v_mul_f32_e32 v19, v25, v36
	v_fmaak_f32 v18, v163, v18, 0x43000000
	v_mul_f32_e32 v20, v21, v37
	v_cvt_pk_u8_f32 v18, v18, 0, 0
	v_fmaak_f32 v19, v163, v19, 0x43000000
	v_mul_f32_e32 v17, v17, v38
	v_cvt_pk_u8_f32 v18, v19, 1, v18
	v_fmaak_f32 v19, v163, v20, 0x43000000
	v_cvt_pk_u8_f32 v18, v19, 2, v18
	v_fmaak_f32 v17, v163, v17, 0x43000000
	v_cvt_pk_u8_f32 v17, v17, 3, v18
	ds_bpermute_b32 v18, v144, v158
	ds_bpermute_b32 v19, v145, v158
	ds_bpermute_b32 v20, v146, v158
	ds_bpermute_b32 v21, v147, v158
	v_xor_b32_e32 v14, 0x80808080, v14
	s_waitcnt lgkmcnt(3)
; #define LAS __attribute__((address_space(3)))
; __host__ __device__ __forceinline__ size_t blk8_off(int r, int k, int KT8_) { return ((size_t)((r >> 8) * KT8_ + (k >> 7)) * 256 + (size_t)(r & 255)) * 128 + (size_t)(k & 127); }
; #define LDS_WAIT() asm volatile("s_waitcnt lgkmcnt(0)" ::: "memory")
; template <bool STRIP, int ROT>
; __device__ __forceinline__ void gu_finish_t(f32x4 (&v)[16], float gA, float gB, const GUDesc& d, LAS unsigned* T, int lane, const float (&sinv)[4]) {
;     ...
;     for (int jq = 0; jq < 4; ++jq) {
;         float g[4];
; #pragma unroll
;         for (int e2 = 0; e2 < 4; ++e2) g[e2] = jq < 2 ? __shfl(gA, 32 * jq + 4 * kr + e2) : __shfl(gB, 32 * (jq - 2) + 4 * kr + e2);
; #pragma unroll
;         for (int e = 0; e < 4; ++e)
;             T[(4 * nq + e) * 33 + 8 * jq + kr] = pack4_i8(v[4 * jq + 0][e] * g[0] * inv[e], v[4 * jq + 1][e] * g[1] * inv[e], v[4 * jq + 2][e] * g[2] * inv[e], v[4 * jq + 3][e] * g[3] * inv[e]);
;     }
;     LDS_WAIT(); asm volatile("" ::: "memory");
;     const int nl = lane >> 3, c = lane & 7;
; #pragma unroll
;     for (int g4 = 0; g4 < 4; ++g4) {
;         const int nloc = 8 * g4 + nl, dr = d.il ? gu_dest(d.n0 + nloc, d.bj) : d.n0 + nloc;
;         const LAS unsigned* t = T + nloc * 33 + 4 * c;
;         u32x4 o; o.x = t[0]; o.y = t[1]; o.z = t[2]; o.w = t[3];
;         *(u32x4*)(d.WQ + blk8_off(dr, d.k0 + 16 * c, d.kt8)) = o;
;         if (!STRIP) if (d.k0 == 0 && c == 0) d.sb[dr] = __uint_as_float(d.cmax[dr]) * (1.0f / 127.0f);
	v_mul_f32_e32 v10, v10, v18
	s_waitcnt lgkmcnt(2)
	v_mul_f32_e32 v6, v6, v19
	v_fmaak_f32 v10, v130, v10, 0x43000000
	s_waitcnt lgkmcnt(1)
	v_mul_f32_e32 v2, v2, v20
	v_cvt_pk_u8_f32 v10, v10, 0, 0
	v_fmaak_f32 v6, v130, v6, 0x43000000
	s_waitcnt lgkmcnt(0)
	v_mul_f32_e32 v22, v26, v21
	v_cvt_pk_u8_f32 v6, v6, 1, v10
	v_fmaak_f32 v2, v130, v2, 0x43000000
	v_cvt_pk_u8_f32 v2, v2, 2, v6
	v_fmaak_f32 v6, v130, v22, 0x43000000
	v_cvt_pk_u8_f32 v2, v6, 3, v2
	v_xor_b32_e32 v2, 0x80808080, v2
	ds_write2_b32 v151, v14, v2 offset0:16 offset1:24
	v_mul_f32_e32 v2, v11, v18
	v_mul_f32_e32 v6, v7, v19
	v_fmaak_f32 v2, v135, v2, 0x43000000
	v_mul_f32_e32 v3, v3, v20
	v_cvt_pk_u8_f32 v2, v2, 0, 0
	v_fmaak_f32 v6, v135, v6, 0x43000000
	v_mul_f32_e32 v7, v27, v21
	v_cvt_pk_u8_f32 v2, v6, 1, v2
	v_fmaak_f32 v3, v135, v3, 0x43000000
	v_cvt_pk_u8_f32 v2, v3, 2, v2
	v_fmaak_f32 v3, v135, v7, 0x43000000
	v_cvt_pk_u8_f32 v2, v3, 3, v2
	v_xor_b32_e32 v15, 0x80808080, v15
	v_xor_b32_e32 v2, 0x80808080, v2
	ds_write2_b32 v151, v15, v2 offset0:49 offset1:57
	v_mul_f32_e32 v2, v12, v18
	v_mul_f32_e32 v3, v8, v19
	v_fmaak_f32 v2, v162, v2, 0x43000000
	v_mul_f32_e32 v4, v4, v20
	v_cvt_pk_u8_f32 v2, v2, 0, 0
	v_fmaak_f32 v3, v162, v3, 0x43000000
	v_mul_f32_e32 v6, v28, v21
	v_cvt_pk_u8_f32 v2, v3, 1, v2
	v_fmaak_f32 v3, v162, v4, 0x43000000
	v_cvt_pk_u8_f32 v2, v3, 2, v2
	v_fmaak_f32 v3, v162, v6, 0x43000000
	v_cvt_pk_u8_f32 v2, v3, 3, v2
	v_xor_b32_e32 v16, 0x80808080, v16
	v_xor_b32_e32 v2, 0x80808080, v2
	ds_write2_b32 v151, v16, v2 offset0:82 offset1:90
	v_mul_f32_e32 v2, v13, v18
	v_mul_f32_e32 v3, v9, v19
	v_fmaak_f32 v2, v163, v2, 0x43000000
	v_mul_f32_e32 v4, v5, v20
	v_cvt_pk_u8_f32 v2, v2, 0, 0
	v_fmaak_f32 v3, v163, v3, 0x43000000
	v_mul_f32_e32 v5, v29, v21
	v_cvt_pk_u8_f32 v2, v3, 1, v2
	v_fmaak_f32 v3, v163, v4, 0x43000000
	v_cvt_pk_u8_f32 v2, v3, 2, v2
	v_fmaak_f32 v3, v163, v5, 0x43000000
	v_cvt_pk_u8_f32 v2, v3, 3, v2
	v_xor_b32_e32 v17, 0x80808080, v17
	v_xor_b32_e32 v2, 0x80808080, v2
	ds_write2_b32 v151, v17, v2 offset0:115 offset1:123
	v_add_u32_e32 v2, s10, v137
	v_lshlrev_b32_e32 v3, 1, v2
	v_and_b32_e32 v3, 0xffffff00, v3
	v_add_u32_e32 v3, s11, v3
	v_xor_b32_e32 v34, 0x80808080, v34
	v_and_or_b32 v3, v2, s52, v3
	ds_write2_b32 v151, v53, v34 offset0:99 offset1:107
	v_cndmask_b32_e64 v2, v3, v2, s[4:5]
	v_add_u32_e32 v3, s41, v132
	s_waitcnt lgkmcnt(0)
	v_lshrrev_b32_e32 v5, 8, v2
	v_ashrrev_i32_e32 v4, 7, v3
	v_mad_i32_i24 v10, v5, s55, v4
	ds_read2_b32 v[6:7], v152 offset1:1
	ds_read2_b32 v[8:9], v152 offset0:2 offset1:3
	v_ashrrev_i32_e32 v11, 31, v10
	v_lshlrev_b64 v[10:11], 15, v[10:11]
	v_lshlrev_b32_e32 v5, 7, v2
	v_and_b32_e32 v12, 0x7f80, v5
	v_mov_b32_e32 v13, v131
	v_lshl_add_u64 v[10:11], s[28:29], 0, v[10:11]
	v_and_b32_e32 v130, 0x7f, v3
	v_lshl_add_u64 v[10:11], v[10:11], 0, v[12:13]
	v_or_b32_e32 v3, s41, v138
	v_lshl_add_u64 v[10:11], v[10:11], 0, v[130:131]
	v_cmp_eq_u32_e32 vcc, 0, v3
	s_waitcnt lgkmcnt(0)
	global_store_dwordx4 v[10:11], v[6:9], off
	s_and_saveexec_b64 s[0:1], vcc
	s_cbranch_execz .LBB0_2339
	v_ashrrev_i32_e32 v3, 31, v2
	v_lshlrev_b64 v[2:3], 2, v[2:3]
	v_lshl_add_u64 v[6:7], s[12:13], 0, v[2:3]
	global_load_dword v5, v[6:7], off
	v_lshl_add_u64 v[2:3], s[20:21], 0, v[2:3]
	s_waitcnt vmcnt(0)
	v_mul_f32_e32 v5, 0x3c010204, v5
	global_store_dword v[2:3], v5, off

; __device__ __forceinline__ void gu_load(f32x4 (&v)[16], float& gA, float& gB, const GUDesc& d, int lane) {
;     const int kr = lane >> 3, nq = lane & 7;
;     const float* __restrict__ src = d.W + (size_t)(d.k0 + 4 * kr) * d.N + d.n0 + 4 * nq;
;     gA = d.gain ? d.gain[d.k0 + lane] : 1.0f; gB = d.gain ? d.gain[d.k0 + 64 + lane] : 1.0f;
; #pragma unroll
;     for (int i = 0; i < 16; ++i) v[i] = *(const f32x4*)(src + (size_t)(32 * (i >> 2) + (i & 3)) * d.N);
; }
; template <bool STRIP, int ROT>
; __device__ __forceinline__ void gu_finish_t(f32x4 (&v)[16], float gA, float gB, const GUDesc& d, LAS unsigned* T, int lane, const float (&sinv)[4]) {
;     ...
;     const int dq0 = d.il ? gu_dest(d.n0 + 4 * nq, d.bj) : d.n0 + 4 * nq;
;     if (ROT) rot32_tile<ROT>(v, lane);
;     float inv[4];
; #pragma unroll
;     for (int e = 0; e < 4; ++e) { if (STRIP) inv[e] = sinv[e]; else { const float cm = __uint_as_float(d.cmax[dq0 + e]); inv[e] = cm > 0.f ? 127.0f / cm : 0.f; } }
; #pragma unroll
;     for (int jq = 0; jq < 4; ++jq) {
;         float g[4];
; #pragma unroll
;         for (int e2 = 0; e2 < 4; ++e2) g[e2] = jq < 2 ? __shfl(gA, 32 * jq + 4 * kr + e2) : __shfl(gB, 32 * (jq - 2) + 4 * kr + e2);
; #pragma unroll
;         for (int e = 0; e < 4; ++e)
;             T[(4 * nq + e) * 33 + 8 * jq + kr] = pack4_i8(v[4 * jq + 0][e] * g[0] * inv[e], v[4 * jq + 1][e] * g[1] * inv[e], v[4 * jq + 2][e] * g[2] * inv[e], v[4 * jq + 3][e] * g[3] * inv[e]);
.LBB0_2358:
	v_or_b32_e32 v2, s41, v1
	v_mul_hi_i32_i24_e32 v3, s0, v2
	v_mul_i32_i24_e32 v2, s0, v2
	s_ashr_i32 s11, s10, 31
	s_waitcnt lgkmcnt(0)
	v_lshl_add_u64 v[2:3], v[2:3], 2, v[4:5]
	v_lshl_add_u64 v[2:3], s[10:11], 2, v[2:3]
	v_mov_b32_e32 v135, v131
	s_lshl_b32 s8, s0, 2
	v_lshl_add_u64 v[2:3], v[2:3], 0, v[134:135]
	v_lshl_add_u64 v[4:5], v[2:3], 0, s[8:9]
	global_load_dwordx4 v[62:65], v[2:3], off nt
	global_load_dwordx4 v[58:61], v[4:5], off nt
	v_lshl_add_u64 v[2:3], v[4:5], 0, s[8:9]
	v_lshl_add_u64 v[4:5], v[2:3], 0, s[8:9]
	s_mulk_i32 s0, 0x74
	s_mov_b32 s1, s9
	global_load_dwordx4 v[54:57], v[2:3], off nt
	global_load_dwordx4 v[50:53], v[4:5], off nt
	v_lshl_add_u64 v[2:3], v[4:5], 0, s[0:1]
	v_lshl_add_u64 v[4:5], v[2:3], 0, s[8:9]
	global_load_dwordx4 v[46:49], v[2:3], off nt
	global_load_dwordx4 v[42:45], v[4:5], off nt
	v_lshl_add_u64 v[2:3], v[4:5], 0, s[8:9]
	v_lshl_add_u64 v[4:5], v[2:3], 0, s[8:9]
	global_load_dwordx4 v[38:41], v[2:3], off nt
	global_load_dwordx4 v[34:37], v[4:5], off nt
	v_lshl_add_u64 v[2:3], v[4:5], 0, s[0:1]
	global_load_dwordx4 v[30:33], v[2:3], off nt
	v_lshl_add_u64 v[2:3], v[2:3], 0, s[8:9]
	global_load_dwordx4 v[22:25], v[2:3], off nt
	v_lshl_add_u64 v[2:3], v[2:3], 0, s[8:9]
	global_load_dwordx4 v[18:21], v[2:3], off nt
	v_lshl_add_u64 v[2:3], v[2:3], 0, s[8:9]
	global_load_dwordx4 v[14:17], v[2:3], off nt
	v_lshl_add_u64 v[2:3], v[2:3], 0, s[0:1]
	global_load_dwordx4 v[10:13], v[2:3], off nt
	v_lshl_add_u64 v[2:3], v[2:3], 0, s[8:9]
	v_lshl_add_u64 v[26:27], v[2:3], 0, s[8:9]
	global_load_dwordx4 v[6:9], v[2:3], off nt
	s_cmp_ge_i32 s60, s34
	global_load_dwordx4 v[2:5], v[26:27], off nt
	v_lshl_add_u64 v[26:27], v[26:27], 0, s[8:9]
	global_load_dwordx4 v[26:29], v[26:27], off nt
	s_cbranch_scc1 .LBB0_2325
	s_add_u32 s28, s78, s22
	s_addc_u32 s29, s79, s23
	s_add_u32 s22, s39, s26
	s_addc_u32 s23, s40, s27
	s_lshl_b32 s0, s16, 1
	s_and_b32 s8, s0, 0xffffff00
	v_bitop3_b32 v135, s16, v153, v139 bitop3:0xc8
	v_or_b32_e32 v135, s8, v135
	v_or_b32_e32 v130, s16, v139
	v_or_b32_e32 v135, s19, v135
	v_cndmask_b32_e64 v168, v135, v130, s[2:3]
	v_ashrrev_i32_e32 v169, 31, v168
	v_lshl_add_u64 v[168:169], v[168:169], 2, s[14:15]
	global_load_dwordx4 v[168:171], v[168:169], off nt
	ds_bpermute_b32 v130, v140, v161
	ds_bpermute_b32 v135, v141, v161
	ds_bpermute_b32 v172, v142, v161
	ds_bpermute_b32 v173, v143, v161
	s_waitcnt vmcnt(36) lgkmcnt(3)
	v_mul_f32_e32 v115, v115, v130
	v_mul_f32_e32 v114, v114, v130
	s_waitcnt vmcnt(35) lgkmcnt(2)
	v_mul_f32_e32 v119, v119, v135
	v_mul_f32_e32 v116, v116, v130
	v_mul_f32_e32 v118, v118, v135
	v_mul_f32_e32 v120, v120, v135
	s_waitcnt vmcnt(34) lgkmcnt(1)
	v_mul_f32_e32 v124, v124, v172
	v_mul_f32_e32 v117, v117, v130
	v_mul_f32_e32 v122, v122, v172
	s_waitcnt vmcnt(33) lgkmcnt(0)
	v_mul_f32_e32 v126, v126, v173
	v_mul_f32_e32 v123, v123, v172
	v_mul_f32_e32 v127, v127, v173
	s_waitcnt vmcnt(0)
	v_div_scale_f32 v174, s[0:1], v168, v168, s53
	v_div_scale_f32 v176, s[0:1], v169, v169, s53
	v_rcp_f32_e32 v182, v174
	v_rcp_f32_e32 v183, v176
	v_div_scale_f32 v178, s[4:5], v170, v170, s53
	v_rcp_f32_e32 v184, v178
	v_div_scale_f32 v180, s[6:7], v171, v171, s53
	v_fma_f32 v186, -v174, v182, 1.0
	v_div_scale_f32 v175, vcc, s53, v168, s53
	v_rcp_f32_e32 v185, v180
	v_fma_f32 v187, -v176, v183, 1.0
	v_fmac_f32_e32 v182, v186, v182
	v_div_scale_f32 v177, s[0:1], s53, v169, s53
	v_fmac_f32_e32 v183, v187, v183
	v_mul_f32_e32 v186, v175, v182
	v_fma_f32 v188, -v178, v184, 1.0
	v_mul_f32_e32 v187, v177, v183
	v_fma_f32 v190, -v174, v186, v175
	v_div_scale_f32 v179, s[4:5], s53, v170, s53
	v_fmac_f32_e32 v184, v188, v184
	v_fma_f32 v191, -v176, v187, v177
	v_fmac_f32_e32 v186, v190, v182
	v_fma_f32 v189, -v180, v185, 1.0
	v_mul_f32_e32 v188, v179, v184
	v_fmac_f32_e32 v187, v191, v183
	v_fma_f32 v174, -v174, v186, v175
	v_div_scale_f32 v181, s[6:7], s53, v171, s53
	v_fmac_f32_e32 v185, v189, v185
	v_fma_f32 v192, -v178, v188, v179
	v_fma_f32 v175, -v176, v187, v177
	v_div_fmas_f32 v174, v174, v182, v186
	s_mov_b64 vcc, s[0:1]
	v_mul_f32_e32 v189, v181, v185
	v_fmac_f32_e32 v188, v192, v184
	v_div_fixup_f32 v174, v174, v168, s53
	v_div_fmas_f32 v175, v175, v183, v187
	v_cmp_lt_f32_e32 vcc, 0, v168
	v_fma_f32 v193, -v180, v189, v181
	v_fma_f32 v176, -v178, v188, v179
	v_cndmask_b32_e32 v168, 0, v174, vcc
	s_mov_b64 vcc, s[4:5]
	v_fmac_f32_e32 v189, v193, v185
	v_div_fixup_f32 v174, v175, v169, s53
	v_div_fmas_f32 v175, v176, v184, v188
	v_cmp_lt_f32_e32 vcc, 0, v169
	v_fma_f32 v177, -v180, v189, v181
	v_fmaak_f32 v114, v168, v114, 0x43000000
	v_cndmask_b32_e32 v169, 0, v174, vcc
	s_mov_b64 vcc, s[6:7]
	v_div_fixup_f32 v174, v175, v170, s53
	v_div_fmas_f32 v175, v177, v185, v189
	v_cmp_lt_f32_e32 vcc, 0, v170
	v_fmaak_f32 v115, v169, v115, 0x43000000
	v_fmaak_f32 v119, v169, v119, 0x43000000
	v_cndmask_b32_e32 v170, 0, v174, vcc
	v_cvt_pk_u8_f32 v115, v115, 0, 0
	v_fmaak_f32 v116, v170, v116, 0x43000000
	v_fmaak_f32 v118, v168, v118, 0x43000000
	v_cvt_pk_u8_f32 v114, v114, 0, 0
	v_cvt_pk_u8_f32 v115, v119, 1, v115
	v_cvt_pk_u8_f32 v116, v116, 0, 0
	v_fmaak_f32 v119, v170, v120, 0x43000000
	v_div_fixup_f32 v174, v175, v171, s53
	v_cmp_lt_f32_e32 vcc, 0, v171
	v_cvt_pk_u8_f32 v114, v118, 1, v114
	v_mul_f32_e32 v118, v128, v173
	v_cvt_pk_u8_f32 v116, v119, 1, v116
	v_fmaak_f32 v119, v170, v124, 0x43000000
	v_cndmask_b32_e32 v171, 0, v174, vcc
	v_cvt_pk_u8_f32 v116, v119, 2, v116
	v_fmaak_f32 v118, v170, v118, 0x43000000
	v_cvt_pk_u8_f32 v116, v118, 3, v116
	v_mul_f32_e32 v118, v121, v135
	v_fmaak_f32 v117, v171, v117, 0x43000000
	v_mul_f32_e32 v119, v125, v172
	v_cvt_pk_u8_f32 v117, v117, 0, 0
	v_fmaak_f32 v118, v171, v118, 0x43000000
	v_mul_f32_e32 v120, v129, v173
	v_cvt_pk_u8_f32 v117, v118, 1, v117
	v_fmaak_f32 v118, v171, v119, 0x43000000
	v_cvt_pk_u8_f32 v117, v118, 2, v117
	v_fmaak_f32 v118, v171, v120, 0x43000000
	v_cvt_pk_u8_f32 v117, v118, 3, v117
	ds_bpermute_b32 v118, v144, v161
	ds_bpermute_b32 v119, v145, v161
	ds_bpermute_b32 v120, v146, v161
	ds_bpermute_b32 v121, v147, v161
	v_fmaak_f32 v122, v168, v122, 0x43000000
	s_waitcnt lgkmcnt(3)
; template <bool STRIP, int ROT>
; __device__ __forceinline__ void gu_finish_t(f32x4 (&v)[16], float gA, float gB, const GUDesc& d, LAS unsigned* T, int lane, const float (&sinv)[4]) {
;     ...
;     for (int jq = 0; jq < 4; ++jq) {
;         float g[4];
; #pragma unroll
;         for (int e2 = 0; e2 < 4; ++e2) g[e2] = jq < 2 ? __shfl(gA, 32 * jq + 4 * kr + e2) : __shfl(gB, 32 * (jq - 2) + 4 * kr + e2);
; #pragma unroll
;         for (int e = 0; e < 4; ++e)
;             T[(4 * nq + e) * 33 + 8 * jq + kr] = pack4_i8(v[4 * jq + 0][e] * g[0] * inv[e], v[4 * jq + 1][e] * g[1] * inv[e], v[4 * jq + 2][e] * g[2] * inv[e], v[4 * jq + 3][e] * g[3] * inv[e]);
;     }
	v_mul_f32_e32 v98, v98, v118
	s_waitcnt lgkmcnt(2)
	v_mul_f32_e32 v102, v102, v119
	v_fmaak_f32 v98, v168, v98, 0x43000000
	s_waitcnt lgkmcnt(1)
	v_mul_f32_e32 v106, v106, v120
	v_cvt_pk_u8_f32 v98, v98, 0, 0
	v_fmaak_f32 v102, v168, v102, 0x43000000
	s_waitcnt lgkmcnt(0)
	v_mul_f32_e32 v110, v110, v121
	v_cvt_pk_u8_f32 v98, v102, 1, v98
	v_fmaak_f32 v102, v168, v106, 0x43000000
	v_fmaak_f32 v126, v168, v126, 0x43000000
	v_cvt_pk_u8_f32 v114, v122, 2, v114
	v_cvt_pk_u8_f32 v98, v102, 2, v98
	v_fmaak_f32 v102, v168, v110, 0x43000000
	v_cvt_pk_u8_f32 v114, v126, 3, v114
	v_cvt_pk_u8_f32 v98, v102, 3, v98
	v_xor_b32_e32 v114, 0x80808080, v114
	v_xor_b32_e32 v98, 0x80808080, v98
	ds_write2_b32 v151, v114, v98 offset1:8
	v_mul_f32_e32 v98, v99, v118
	v_mul_f32_e32 v99, v103, v119
	v_fmaak_f32 v98, v169, v98, 0x43000000
	v_mul_f32_e32 v102, v107, v120
	v_cvt_pk_u8_f32 v98, v98, 0, 0
	v_fmaak_f32 v99, v169, v99, 0x43000000
	v_fmaak_f32 v123, v169, v123, 0x43000000
	v_mul_f32_e32 v103, v111, v121
	v_cvt_pk_u8_f32 v98, v99, 1, v98
	v_fmaak_f32 v99, v169, v102, 0x43000000
	v_fmaak_f32 v127, v169, v127, 0x43000000
	v_cvt_pk_u8_f32 v115, v123, 2, v115
	v_cvt_pk_u8_f32 v98, v99, 2, v98
	v_fmaak_f32 v99, v169, v103, 0x43000000
	v_cvt_pk_u8_f32 v115, v127, 3, v115
	v_cvt_pk_u8_f32 v98, v99, 3, v98
	v_xor_b32_e32 v115, 0x80808080, v115
	v_xor_b32_e32 v98, 0x80808080, v98
	ds_write2_b32 v151, v115, v98 offset0:33 offset1:41
	v_mul_f32_e32 v98, v100, v118
	v_mul_f32_e32 v99, v104, v119
	v_fmaak_f32 v98, v170, v98, 0x43000000
	v_mul_f32_e32 v100, v108, v120
	v_cvt_pk_u8_f32 v98, v98, 0, 0
	v_fmaak_f32 v99, v170, v99, 0x43000000
	v_mul_f32_e32 v102, v112, v121
	v_cvt_pk_u8_f32 v98, v99, 1, v98
	v_fmaak_f32 v99, v170, v100, 0x43000000
	v_cvt_pk_u8_f32 v98, v99, 2, v98
	v_fmaak_f32 v99, v170, v102, 0x43000000
	v_cvt_pk_u8_f32 v98, v99, 3, v98
	v_xor_b32_e32 v116, 0x80808080, v116
	v_xor_b32_e32 v98, 0x80808080, v98
	ds_write2_b32 v151, v116, v98 offset0:66 offset1:74
	v_mul_f32_e32 v98, v101, v118
	v_mul_f32_e32 v99, v105, v119
	v_fmaak_f32 v98, v171, v98, 0x43000000
	v_mul_f32_e32 v100, v109, v120
	v_cvt_pk_u8_f32 v98, v98, 0, 0
	v_fmaak_f32 v99, v171, v99, 0x43000000
	v_mul_f32_e32 v101, v113, v121
	v_cvt_pk_u8_f32 v98, v99, 1, v98
	v_fmaak_f32 v99, v171, v100, 0x43000000
	v_cvt_pk_u8_f32 v98, v99, 2, v98
	v_fmaak_f32 v99, v171, v101, 0x43000000
	v_cvt_pk_u8_f32 v98, v99, 3, v98
	ds_bpermute_b32 v99, v140, v160
	ds_bpermute_b32 v100, v141, v160
	ds_bpermute_b32 v101, v142, v160
	ds_bpermute_b32 v102, v143, v160
	v_xor_b32_e32 v117, 0x80808080, v117
	s_waitcnt lgkmcnt(3)
	v_mul_f32_e32 v82, v82, v99
	s_waitcnt lgkmcnt(2)
	v_mul_f32_e32 v86, v86, v100
	v_fmaak_f32 v82, v168, v82, 0x43000000
	s_waitcnt lgkmcnt(1)
	v_mul_f32_e32 v90, v90, v101
	v_cvt_pk_u8_f32 v82, v82, 0, 0
	v_fmaak_f32 v86, v168, v86, 0x43000000
	s_waitcnt lgkmcnt(0)
	v_mul_f32_e32 v94, v94, v102
	v_cvt_pk_u8_f32 v82, v86, 1, v82
	v_fmaak_f32 v86, v168, v90, 0x43000000
	v_cvt_pk_u8_f32 v82, v86, 2, v82
	v_fmaak_f32 v86, v168, v94, 0x43000000
	v_mul_f32_e32 v83, v83, v99
	v_cvt_pk_u8_f32 v82, v86, 3, v82
	v_mul_f32_e32 v86, v87, v100
	v_fmaak_f32 v83, v169, v83, 0x43000000
	v_mul_f32_e32 v87, v91, v101
	v_cvt_pk_u8_f32 v83, v83, 0, 0
	v_fmaak_f32 v86, v169, v86, 0x43000000
	v_mul_f32_e32 v90, v95, v102
	v_cvt_pk_u8_f32 v83, v86, 1, v83
	v_fmaak_f32 v86, v169, v87, 0x43000000
	v_cvt_pk_u8_f32 v83, v86, 2, v83
	v_fmaak_f32 v86, v169, v90, 0x43000000
	v_mul_f32_e32 v84, v84, v99
	v_cvt_pk_u8_f32 v83, v86, 3, v83
	v_mul_f32_e32 v86, v88, v100
	v_fmaak_f32 v84, v170, v84, 0x43000000
	v_mul_f32_e32 v87, v92, v101
	v_cvt_pk_u8_f32 v84, v84, 0, 0
	v_fmaak_f32 v86, v170, v86, 0x43000000
	v_mul_f32_e32 v88, v96, v102
	v_cvt_pk_u8_f32 v84, v86, 1, v84
	v_fmaak_f32 v86, v170, v87, 0x43000000
	v_cvt_pk_u8_f32 v84, v86, 2, v84
	v_fmaak_f32 v86, v170, v88, 0x43000000
	v_mul_f32_e32 v85, v85, v99
	v_cvt_pk_u8_f32 v84, v86, 3, v84
	v_mul_f32_e32 v86, v89, v100
	v_fmaak_f32 v85, v171, v85, 0x43000000
	v_mul_f32_e32 v87, v93, v101
	v_cvt_pk_u8_f32 v85, v85, 0, 0
	v_fmaak_f32 v86, v171, v86, 0x43000000
	v_mul_f32_e32 v88, v97, v102
	v_cvt_pk_u8_f32 v85, v86, 1, v85
	v_fmaak_f32 v86, v171, v87, 0x43000000
	v_cvt_pk_u8_f32 v85, v86, 2, v85
	v_fmaak_f32 v86, v171, v88, 0x43000000
	v_cvt_pk_u8_f32 v85, v86, 3, v85
	ds_bpermute_b32 v86, v144, v160
	ds_bpermute_b32 v87, v145, v160
	ds_bpermute_b32 v88, v146, v160
	ds_bpermute_b32 v89, v147, v160
	v_xor_b32_e32 v82, 0x80808080, v82
	s_waitcnt lgkmcnt(3)
; #define LAS __attribute__((address_space(3)))
; __host__ __device__ __forceinline__ size_t blk8_off(int r, int k, int KT8_) { return ((size_t)((r >> 8) * KT8_ + (k >> 7)) * 256 + (size_t)(r & 255)) * 128 + (size_t)(k & 127); }
; #define LDS_WAIT() asm volatile("s_waitcnt lgkmcnt(0)" ::: "memory")
; template <bool STRIP, int ROT>
; __device__ __forceinline__ void gu_finish_t(f32x4 (&v)[16], float gA, float gB, const GUDesc& d, LAS unsigned* T, int lane, const float (&sinv)[4]) {
;     ...
;     for (int jq = 0; jq < 4; ++jq) {
;         float g[4];
; #pragma unroll
;         for (int e2 = 0; e2 < 4; ++e2) g[e2] = jq < 2 ? __shfl(gA, 32 * jq + 4 * kr + e2) : __shfl(gB, 32 * (jq - 2) + 4 * kr + e2);
; #pragma unroll
;         for (int e = 0; e < 4; ++e)
;             T[(4 * nq + e) * 33 + 8 * jq + kr] = pack4_i8(v[4 * jq + 0][e] * g[0] * inv[e], v[4 * jq + 1][e] * g[1] * inv[e], v[4 * jq + 2][e] * g[2] * inv[e], v[4 * jq + 3][e] * g[3] * inv[e]);
;     }
;     LDS_WAIT(); asm volatile("" ::: "memory");
;     const int nl = lane >> 3, c = lane & 7;
; #pragma unroll
;     for (int g4 = 0; g4 < 4; ++g4) {
;         const int nloc = 8 * g4 + nl, dr = d.il ? gu_dest(d.n0 + nloc, d.bj) : d.n0 + nloc;
;         const LAS unsigned* t = T + nloc * 33 + 4 * c;
;         u32x4 o; o.x = t[0]; o.y = t[1]; o.z = t[2]; o.w = t[3];
;         *(u32x4*)(d.WQ + blk8_off(dr, d.k0 + 16 * c, d.kt8)) = o;
;         if (!STRIP) if (d.k0 == 0 && c == 0) d.sb[dr] = __uint_as_float(d.cmax[dr]) * (1.0f / 127.0f);
	v_mul_f32_e32 v66, v66, v86
	s_waitcnt lgkmcnt(2)
	v_mul_f32_e32 v70, v70, v87
	v_fmaak_f32 v66, v168, v66, 0x43000000
	s_waitcnt lgkmcnt(1)
	v_mul_f32_e32 v74, v74, v88
	v_cvt_pk_u8_f32 v66, v66, 0, 0
	v_fmaak_f32 v70, v168, v70, 0x43000000
	s_waitcnt lgkmcnt(0)
	v_mul_f32_e32 v78, v78, v89
	v_cvt_pk_u8_f32 v66, v70, 1, v66
	v_fmaak_f32 v70, v168, v74, 0x43000000
	v_cvt_pk_u8_f32 v66, v70, 2, v66
	v_fmaak_f32 v70, v168, v78, 0x43000000
	v_cvt_pk_u8_f32 v66, v70, 3, v66
	v_xor_b32_e32 v66, 0x80808080, v66
	ds_write2_b32 v151, v82, v66 offset0:16 offset1:24
	v_mul_f32_e32 v66, v67, v86
	v_mul_f32_e32 v67, v71, v87
	v_fmaak_f32 v66, v169, v66, 0x43000000
	v_mul_f32_e32 v70, v75, v88
	v_cvt_pk_u8_f32 v66, v66, 0, 0
	v_fmaak_f32 v67, v169, v67, 0x43000000
	v_mul_f32_e32 v71, v79, v89
	v_cvt_pk_u8_f32 v66, v67, 1, v66
	v_fmaak_f32 v67, v169, v70, 0x43000000
	v_cvt_pk_u8_f32 v66, v67, 2, v66
	v_fmaak_f32 v67, v169, v71, 0x43000000
	v_cvt_pk_u8_f32 v66, v67, 3, v66
	v_xor_b32_e32 v83, 0x80808080, v83
	v_xor_b32_e32 v66, 0x80808080, v66
	ds_write2_b32 v151, v83, v66 offset0:49 offset1:57
	v_mul_f32_e32 v66, v68, v86
	v_mul_f32_e32 v67, v72, v87
	v_fmaak_f32 v66, v170, v66, 0x43000000
	v_mul_f32_e32 v68, v76, v88
	v_cvt_pk_u8_f32 v66, v66, 0, 0
	v_fmaak_f32 v67, v170, v67, 0x43000000
	v_mul_f32_e32 v70, v80, v89
	v_cvt_pk_u8_f32 v66, v67, 1, v66
	v_fmaak_f32 v67, v170, v68, 0x43000000
	v_cvt_pk_u8_f32 v66, v67, 2, v66
	v_fmaak_f32 v67, v170, v70, 0x43000000
	v_cvt_pk_u8_f32 v66, v67, 3, v66
	v_xor_b32_e32 v84, 0x80808080, v84
	v_xor_b32_e32 v66, 0x80808080, v66
	ds_write2_b32 v151, v84, v66 offset0:82 offset1:90
	v_mul_f32_e32 v66, v69, v86
	v_mul_f32_e32 v67, v73, v87
	v_fmaak_f32 v66, v171, v66, 0x43000000
	v_mul_f32_e32 v68, v77, v88
	v_cvt_pk_u8_f32 v66, v66, 0, 0
	v_fmaak_f32 v67, v171, v67, 0x43000000
	v_mul_f32_e32 v69, v81, v89
	v_cvt_pk_u8_f32 v66, v67, 1, v66
	v_fmaak_f32 v67, v171, v68, 0x43000000
	v_cvt_pk_u8_f32 v66, v67, 2, v66
	v_fmaak_f32 v67, v171, v69, 0x43000000
	v_cvt_pk_u8_f32 v66, v67, 3, v66
	v_bitop3_b32 v67, s16, v154, v137 bitop3:0xc8
	v_xor_b32_e32 v85, 0x80808080, v85
	v_xor_b32_e32 v66, 0x80808080, v66
	v_or_b32_e32 v67, s8, v67
	v_xor_b32_e32 v98, 0x80808080, v98
	ds_write2_b32 v151, v85, v66 offset0:115 offset1:123
	v_or_b32_e32 v66, s16, v137
	v_or_b32_e32 v67, s19, v67
	ds_write2_b32 v151, v117, v98 offset0:99 offset1:107
	v_cndmask_b32_e64 v66, v67, v66, s[2:3]
	s_ashr_i32 s4, s57, 7
	s_waitcnt lgkmcnt(0)
	v_lshrrev_b32_e32 v67, 8, v66
	v_mov_b32_e32 v72, s4
	v_mad_i32_i24 v72, v67, s56, v72
	ds_read2_b32 v[68:69], v152 offset1:1
	ds_read2_b32 v[70:71], v152 offset0:2 offset1:3
	v_ashrrev_i32_e32 v73, 31, v72
	v_lshlrev_b64 v[72:73], 15, v[72:73]
	v_lshlrev_b32_e32 v67, 7, v66
	v_and_b32_e32 v130, 0x7380, v67
	v_lshl_add_u64 v[72:73], s[28:29], 0, v[72:73]
	v_lshl_add_u64 v[72:73], v[72:73], 0, v[130:131]
	v_or_b32_e32 v67, s57, v138
	v_lshl_add_u64 v[72:73], v[72:73], 0, v[132:133]
	v_cmp_eq_u32_e32 vcc, 0, v67
	s_waitcnt lgkmcnt(0)
	global_store_dwordx4 v[72:73], v[68:71], off
	s_and_saveexec_b64 s[0:1], vcc
	s_cbranch_execz .LBB0_2361
	v_ashrrev_i32_e32 v67, 31, v66
	v_lshlrev_b64 v[66:67], 2, v[66:67]
	v_lshl_add_u64 v[68:69], s[14:15], 0, v[66:67]
	global_load_dword v68, v[68:69], off
	v_lshl_add_u64 v[66:67], s[22:23], 0, v[66:67]
	s_waitcnt vmcnt(0)
	v_mul_f32_e32 v68, 0x3c010204, v68
	global_store_dword v[66:67], v68, off

; #define LAS __attribute__((address_space(3)))
; __device__ __forceinline__ void gu_decode(Frame& F, int it, GUDesc& d) {
;     const int q = it / P0_I_GU, r = it % P0_I_GU;
;     if (q < 4) { d.k0 = 128 * (r / 344); d.n0 = 32 * (r % 344); d.bj = q & 1; d.N = FF; d.kt8 = KT8; d.il = 1;
;         d.W = q == 0 ? INP(2) : q == 1 ? INP(3) : q == 2 ? INP(18) : INP(19); d.gain = q < 2 ? INP(1) : INP(17);
;         d.WQ = F.ws + (q < 2 ? WS_WGU1 : WS_WGU2); d.cmax = (const unsigned*)(F.ws + WS_CTL + CTL_CMAX) + (q >> 1) * NGU; d.sb = (float*)(F.ws + WS_SMALL + (q < 2 ? SM_SB1 : SM_SB2)); }
;     else { d.k0 = 128 * (r / 128); d.n0 = 32 * (r % 128); d.bj = 0; d.N = DM; d.kt8 = FF / 128; d.il = 0; d.W = q == 4 ? INP(20) : INP(4); d.gain = nullptr;
;         d.WQ = F.ws + (q == 4 ? WS_WD2 : WS_WD1); d.cmax = (const unsigned*)(F.ws + WS_CTL + CTL_CMAX) + 2 * NGU + (q == 4 ? 0 : DM); d.sb = (float*)(F.ws + WS_SMALL + (q == 4 ? SM_SB3 : SM_SB4)); }
; }
; __device__ __forceinline__ void gu_load(f32x4 (&v)[16], float& gA, float& gB, const GUDesc& d, int lane) {
;     const int kr = lane >> 3, nq = lane & 7;
;     const float* __restrict__ src = d.W + (size_t)(d.k0 + 4 * kr) * d.N + d.n0 + 4 * nq;
;     gA = d.gain ? d.gain[d.k0 + lane] : 1.0f; gB = d.gain ? d.gain[d.k0 + 64 + lane] : 1.0f;
; #pragma unroll
;     for (int i = 0; i < 16; ++i) v[i] = *(const f32x4*)(src + (size_t)(32 * (i >> 2) + (i & 3)) * d.N);
; }
;     const int lane = (F.tid & 63), stride = nworkers * 8, first = lo + worker * 8 + F.wave;
;     LAS unsigned* T = (LAS unsigned*)(F.lds + F.wave * 16384);
;     if (first >= hi) return;
;     const int n_my = (hi - first + stride - 1) / stride;
;     f32x4 va[16], vb[16]; float gaA, gaB, gbA, gbB; GUDesc da, db;
;     gu_decode(F, first, da); gu_load(va, gaA, gaB, da, lane);
.LBB0_2525:
	s_xor_b32 s8, s8, s9
	s_mul_i32 s9, s7, s3
	s_sub_i32 s6, s6, s9
	s_add_i32 s9, s7, 1
	s_sub_i32 s10, s6, s3
	s_cmp_ge_u32 s6, s3
	s_cselect_b32 s7, s9, s7
	s_cselect_b32 s6, s10, s6
	s_add_i32 s9, s7, 1
	s_cmp_ge_u32 s6, s3
	s_cselect_b32 s3, s9, s7
	s_xor_b32 s3, s3, s8
	s_sub_i32 s33, s3, s8
	s_cmp_lt_i32 s33, 1
	s_mov_b32 s57, 1
	s_cbranch_scc1 .LBB0_2570
	s_mov_b32 s34, 0x600000
	s_and_b64 s[0:1], s[0:1], exec
	s_mov_b32 s35, 0x200000
	s_cselect_b32 s8, s34, 0x620000
	s_cselect_b32 s20, s35, 0x15e00000
	s_add_u32 s36, s78, 0x80000
	s_addc_u32 s37, s79, 0
	s_lshr_b32 s0, s2, 1
	s_mulk_i32 s0, 0x5600
	s_ashr_i32 s1, s0, 31
	s_lshl_b64 s[0:1], s[0:1], 2
	s_add_u32 s10, s36, s0
	v_lshrrev_b32_e32 v4, 1, v0
	s_addc_u32 s11, s37, s1
	v_and_b32_e32 v136, 28, v4
	v_lshlrev_b32_e32 v4, 2, v0
	s_add_u32 s38, s78, 0x26000000
	s_mulk_i32 s5, 0x158
	v_and_b32_e32 v66, 28, v4
	s_addc_u32 s39, s79, 0
	s_sub_i32 s0, s4, s5
	v_or_b32_e32 v4, s40, v136
	s_sext_i32_i16 s0, s0
	v_mul_i32_i24_e32 v4, 0x2b00, v4
	s_lshl_b32 s12, s0, 5
	v_ashrrev_i32_e32 v5, 31, v4
	s_waitcnt lgkmcnt(0)
	v_lshl_add_u64 v[2:3], v[4:5], 2, v[2:3]
	s_ashr_i32 s13, s12, 31
	v_mov_b32_e32 v131, 0
	v_lshl_add_u64 v[2:3], s[12:13], 2, v[2:3]
	v_lshlrev_b32_e32 v130, 2, v66
	v_lshl_add_u64 v[68:69], v[2:3], 0, v[130:131]
	s_mov_b32 s0, 0x428000
	v_add_co_u32_e32 v70, vcc, s0, v68
	s_mov_b32 s0, 0x41d000
	s_nop 0
	v_addc_co_u32_e32 v71, vcc, 0, v69, vcc
	v_add_co_u32_e32 v10, vcc, s0, v68
	s_mov_b32 s0, 0x412000
	s_nop 0
	v_addc_co_u32_e32 v11, vcc, 0, v69, vcc
	v_add_co_u32_e32 v12, vcc, s0, v68
	s_mov_b32 s0, 0x408000
	s_nop 0
	v_addc_co_u32_e32 v13, vcc, 0, v69, vcc
	v_add_co_u32_e32 v18, vcc, s0, v68
	s_mov_b32 s0, 0x2d0000
	s_nop 0
	v_addc_co_u32_e32 v19, vcc, 0, v69, vcc
	v_add_co_u32_e32 v20, vcc, s0, v68
	s_mov_b32 s0, 0x2c5000
	s_nop 0
	v_addc_co_u32_e32 v21, vcc, 0, v69, vcc
	v_add_co_u32_e32 v26, vcc, s0, v68
	s_mov_b32 s0, 0x2ba000
	s_nop 0
	v_addc_co_u32_e32 v27, vcc, 0, v69, vcc
	v_add_co_u32_e32 v28, vcc, s0, v68
	s_mov_b32 s0, 0x2b0000
	s_nop 0
	v_addc_co_u32_e32 v29, vcc, 0, v69, vcc
	global_load_dwordx4 v[2:5], v[10:11], off offset:2048 nt
	global_load_dwordx4 v[6:9], v[12:13], off offset:3072 nt
	s_nop 0
	global_load_dwordx4 v[10:13], v[18:19], off nt
	global_load_dwordx4 v[14:17], v[20:21], off offset:1024 nt
	s_nop 0
	global_load_dwordx4 v[18:21], v[26:27], off offset:2048 nt
	global_load_dwordx4 v[22:25], v[28:29], off offset:3072 nt
	v_add_co_u32_e32 v26, vcc, s0, v68
	s_mov_b32 s0, 0x178000
	s_nop 0
	v_addc_co_u32_e32 v27, vcc, 0, v69, vcc
	v_add_co_u32_e32 v28, vcc, s0, v68
	s_mov_b32 s0, 0x16d000
	s_nop 0
	v_addc_co_u32_e32 v29, vcc, 0, v69, vcc
	global_load_dwordx4 v[30:33], v[26:27], off nt
	global_load_dwordx4 v[34:37], v[28:29], off offset:1024 nt
	v_add_co_u32_e32 v26, vcc, s0, v68
	s_mov_b32 s0, 0x162000
	s_nop 0
	v_addc_co_u32_e32 v27, vcc, 0, v69, vcc
	v_add_co_u32_e32 v28, vcc, s0, v68
	s_mov_b32 s0, 0x158000
	s_nop 0
	v_addc_co_u32_e32 v29, vcc, 0, v69, vcc
	global_load_dwordx4 v[38:41], v[26:27], off offset:2048 nt
	global_load_dwordx4 v[42:45], v[28:29], off offset:3072 nt
	v_add_co_u32_e32 v26, vcc, s0, v68
	s_mov_b32 s0, 0x20000
	s_nop 0
	v_addc_co_u32_e32 v27, vcc, 0, v69, vcc
	v_add_co_u32_e32 v28, vcc, s0, v68
	s_mov_b32 s0, 0x15000
	s_nop 0
	v_addc_co_u32_e32 v29, vcc, 0, v69, vcc
	v_add_co_u32_e32 v72, vcc, s0, v68
	s_mov_b32 s0, 0xa000
	s_nop 0
	v_addc_co_u32_e32 v73, vcc, 0, v69, vcc
	v_add_co_u32_e32 v74, vcc, s0, v68
	global_load_dwordx4 v[46:49], v[26:27], off nt
	global_load_dwordx4 v[50:53], v[28:29], off offset:1024 nt
	v_addc_co_u32_e32 v75, vcc, 0, v69, vcc
	global_load_dwordx4 v[54:57], v[72:73], off offset:2048 nt
	global_load_dwordx4 v[58:61], v[74:75], off offset:3072 nt
	global_load_dwordx4 v[26:29], v[70:71], off offset:1024 nt
	global_load_dwordx4 v[62:65], v[68:69], off nt
	v_mbcnt_lo_u32_b32 v68, -1, 0
	s_lshl_b32 s0, s68, 14
	v_lshrrev_b32_e32 v137, 3, v1
	v_and_b32_e32 v138, 7, v0
	v_mbcnt_hi_u32_b32 v68, -1, v68
	s_and_b32 s58, s2, 1
	s_add_i32 s0, s0, 0
	s_add_i32 s41, s33, -1
	v_lshlrev_b32_e32 v69, 4, v137
	v_lshlrev_b32_e32 v68, 2, v68
	s_movk_i32 s1, 0x100
	v_lshlrev_b32_e32 v132, 4, v138
	s_mov_b32 s9, 0
	v_lshl_add_u32 v67, v137, 2, s0
	v_and_or_b32 v140, v68, s1, v69
	v_mul_u32_u24_e32 v68, 0x210, v138
	v_add_u32_e32 v69, s0, v132
	v_mul_u32_u24_e32 v70, 0x84, v137
	s_add_u32 s42, s78, 0xab000
	s_mov_b32 s21, s9
	v_lshlrev_b32_e32 v139, 2, v138
	v_or_b32_e32 v141, 4, v140
	v_or_b32_e32 v142, 8, v140
	v_or_b32_e32 v143, 12, v140
	v_or_b32_e32 v144, 0x80, v140
	v_or_b32_e32 v145, 0x84, v140
	v_or_b32_e32 v146, 0x88, v140
	v_or_b32_e32 v147, 0x8c, v140
	v_or_b32_e32 v148, 8, v137
	v_or_b32_e32 v149, 16, v137
	v_or_b32_e32 v150, 24, v137
	v_mov_b32_e32 v133, v131
	s_addc_u32 s43, s79, 0
	s_mov_b32 s54, 32
	s_add_i32 s44, 0, 0x27c10
	s_add_i32 s45, 0, 0x27c18
	s_mov_b32 s46, 0x27c90
	s_mov_b32 s47, 0x27c08
	s_mov_b32 s48, 0x27ca0
	s_mov_b32 s49, 0x660000
	s_mov_b32 s50, 0x20a00000
	v_lshlrev_b32_e32 v134, 2, v66
	s_movk_i32 s51, 0x7f
	s_mov_b32 s52, 0x42fe0000
	v_add_u32_e32 v151, v67, v68
	v_add_u32_e32 v152, v69, v70
	v_mov_b32_e32 v153, 0x7c
	v_mov_b32_e32 v154, 0x67
	v_mov_b32_e32 v155, 0x6f
	v_mov_b32_e32 v156, 0x77
	v_mov_b32_e32 v157, 0x7f
	s_mov_b32 s53, 0
	s_mov_b64 s[24:25], s[8:9]
	s_branch .LBB0_2529

; __device__ __forceinline__ void gu_load(f32x4 (&v)[16], float& gA, float& gB, const GUDesc& d, int lane) {
;     const int kr = lane >> 3, nq = lane & 7;
;     const float* __restrict__ src = d.W + (size_t)(d.k0 + 4 * kr) * d.N + d.n0 + 4 * nq;
;     gA = d.gain ? d.gain[d.k0 + lane] : 1.0f; gB = d.gain ? d.gain[d.k0 + 64 + lane] : 1.0f;
; #pragma unroll
;     for (int i = 0; i < 16; ++i) v[i] = *(const f32x4*)(src + (size_t)(32 * (i >> 2) + (i & 3)) * d.N);
; }
; template <bool STRIP, int ROT>
; __device__ __forceinline__ void gu_finish_t(f32x4 (&v)[16], float gA, float gB, const GUDesc& d, LAS unsigned* T, int lane, const float (&sinv)[4]) {
;     ...
;     const int dq0 = d.il ? gu_dest(d.n0 + 4 * nq, d.bj) : d.n0 + 4 * nq;
;     if (ROT) rot32_tile<ROT>(v, lane);
;     float inv[4];
; #pragma unroll
;     for (int e = 0; e < 4; ++e) { if (STRIP) inv[e] = sinv[e]; else { const float cm = __uint_as_float(d.cmax[dq0 + e]); inv[e] = cm > 0.f ? 127.0f / cm : 0.f; } }
; #pragma unroll
;     for (int jq = 0; jq < 4; ++jq) {
;         float g[4];
; #pragma unroll
;         for (int e2 = 0; e2 < 4; ++e2) g[e2] = jq < 2 ? __shfl(gA, 32 * jq + 4 * kr + e2) : __shfl(gB, 32 * (jq - 2) + 4 * kr + e2);
; #pragma unroll
;         for (int e = 0; e < 4; ++e)
;             T[(4 * nq + e) * 33 + 8 * jq + kr] = pack4_i8(v[4 * jq + 0][e] * g[0] * inv[e], v[4 * jq + 1][e] * g[1] * inv[e], v[4 * jq + 2][e] * g[2] * inv[e], v[4 * jq + 3][e] * g[3] * inv[e]);
.LBB0_2540:
	s_add_u32 s28, s78, s20
	s_addc_u32 s29, s79, s21
	s_add_u32 s20, s38, s24
	s_addc_u32 s21, s39, s25
	s_ashr_i32 s17, s16, 31
	s_lshl_b32 s8, s0, 2
	v_add_u32_e32 v68, s12, v139
	s_cmp_eq_u32 s57, 0
	v_lshlrev_b32_e32 v69, 1, v68
	s_cselect_b64 s[4:5], -1, 0
	v_and_b32_e32 v69, 0xffffff00, v69
	s_lshl_b32 s13, s58, 7
	v_add_u32_e32 v69, s13, v69
	v_and_or_b32 v69, v68, s51, v69
	v_cndmask_b32_e64 v68, v69, v68, s[4:5]
	v_ashrrev_i32_e32 v69, 31, v68
	v_lshl_add_u64 v[68:69], v[68:69], 2, s[10:11]
	global_load_dwordx4 v[162:165], v[68:69], off nt
	v_or_b32_e32 v68, s56, v136
	v_mul_hi_i32_i24_e32 v69, s0, v68
	v_mul_i32_i24_e32 v68, s0, v68
	s_waitcnt lgkmcnt(0)
	v_lshl_add_u64 v[66:67], v[68:69], 2, v[66:67]
	v_mov_b32_e32 v135, v131
	v_lshl_add_u64 v[66:67], s[16:17], 2, v[66:67]
	v_lshl_add_u64 v[66:67], v[66:67], 0, v[134:135]
	v_lshl_add_u64 v[68:69], v[66:67], 0, s[8:9]
	global_load_dwordx4 v[114:117], v[66:67], off nt
	global_load_dwordx4 v[118:121], v[68:69], off nt
	v_lshl_add_u64 v[66:67], v[68:69], 0, s[8:9]
	s_mul_i32 s6, s0, 0x74
	s_mov_b32 s7, s9
	v_lshl_add_u64 v[68:69], v[66:67], 0, s[8:9]
	global_load_dwordx4 v[122:125], v[66:67], off nt
	global_load_dwordx4 v[126:129], v[68:69], off nt
	v_lshl_add_u64 v[66:67], v[68:69], 0, s[6:7]
	v_lshl_add_u64 v[68:69], v[66:67], 0, s[8:9]
	global_load_dwordx4 v[98:101], v[66:67], off nt
	global_load_dwordx4 v[102:105], v[68:69], off nt
	v_lshl_add_u64 v[66:67], v[68:69], 0, s[8:9]
	v_lshl_add_u64 v[68:69], v[66:67], 0, s[8:9]
	global_load_dwordx4 v[106:109], v[66:67], off nt
	global_load_dwordx4 v[110:113], v[68:69], off nt
	v_lshl_add_u64 v[66:67], v[68:69], 0, s[6:7]
	global_load_dwordx4 v[82:85], v[66:67], off nt
	v_lshl_add_u64 v[66:67], v[66:67], 0, s[8:9]
	global_load_dwordx4 v[86:89], v[66:67], off nt
	v_lshl_add_u64 v[66:67], v[66:67], 0, s[8:9]
	global_load_dwordx4 v[90:93], v[66:67], off nt
	v_lshl_add_u64 v[66:67], v[66:67], 0, s[8:9]
	s_waitcnt vmcnt(34)
	v_lshl_add_u64 v[70:71], v[66:67], 0, s[6:7]
	s_waitcnt vmcnt(33)
	v_lshl_add_u64 v[74:75], v[70:71], 0, s[8:9]
	s_waitcnt vmcnt(32)
	v_lshl_add_u64 v[78:79], v[74:75], 0, s[8:9]
	global_load_dwordx4 v[94:97], v[66:67], off nt
	s_waitcnt vmcnt(12)
	v_div_scale_f32 v130, s[0:1], v162, v162, s52
	v_div_scale_f32 v166, s[0:1], v163, v163, s52
	v_rcp_f32_e32 v171, v130
	v_rcp_f32_e32 v172, v166
	v_div_scale_f32 v168, s[6:7], v164, v164, s52
	v_rcp_f32_e32 v173, v168
	v_fma_f32 v175, -v130, v171, 1.0
	v_div_scale_f32 v135, vcc, s52, v162, s52
	v_fma_f32 v176, -v166, v172, 1.0
	v_fmac_f32_e32 v171, v175, v171
	v_div_scale_f32 v167, s[0:1], s52, v163, s52
	v_fmac_f32_e32 v172, v176, v172
	v_mul_f32_e32 v175, v135, v171
	v_fma_f32 v177, -v168, v173, 1.0
	v_mul_f32_e32 v176, v167, v172
	v_fma_f32 v178, -v130, v175, v135
	v_div_scale_f32 v169, s[6:7], s52, v164, s52
	v_fmac_f32_e32 v173, v177, v173
	v_fma_f32 v179, -v166, v176, v167
	v_fmac_f32_e32 v175, v178, v171
	v_div_scale_f32 v170, s[24:25], v165, v165, s52
	v_mul_f32_e32 v177, v169, v173
	v_fmac_f32_e32 v176, v179, v172
	v_fma_f32 v130, -v130, v175, v135
	v_rcp_f32_e32 v174, v170
	v_fma_f32 v180, -v168, v177, v169
	v_fma_f32 v135, -v166, v176, v167
	v_div_fmas_f32 v130, v130, v171, v175
	s_mov_b64 vcc, s[0:1]
	v_fmac_f32_e32 v177, v180, v173
	v_div_fixup_f32 v130, v130, v162, s52
	v_div_fmas_f32 v135, v135, v172, v176
	v_cmp_lt_f32_e32 vcc, 0, v162
	v_fma_f32 v166, -v168, v177, v169
	v_div_fixup_f32 v135, v135, v163, s52
	v_cndmask_b32_e32 v130, 0, v130, vcc
	s_mov_b64 vcc, s[6:7]
	v_div_fmas_f32 v162, v166, v173, v177
	v_cmp_lt_f32_e32 vcc, 0, v163
	v_div_fixup_f32 v162, v162, v164, s52
	v_fma_f32 v163, -v170, v174, 1.0
	v_cndmask_b32_e32 v135, 0, v135, vcc
	v_cmp_lt_f32_e32 vcc, 0, v164
	v_fmac_f32_e32 v174, v163, v174
	ds_bpermute_b32 v167, v142, v159
	v_cndmask_b32_e32 v162, 0, v162, vcc
	v_div_scale_f32 v163, vcc, s52, v165, s52
	v_mul_f32_e32 v164, v163, v174
	v_fma_f32 v166, -v170, v164, v163
	v_fmac_f32_e32 v164, v166, v174
	v_fma_f32 v163, -v170, v164, v163
	v_div_fmas_f32 v163, v163, v174, v164
	ds_bpermute_b32 v164, v140, v159
	ds_bpermute_b32 v166, v141, v159
	ds_bpermute_b32 v168, v143, v159
	s_waitcnt lgkmcnt(3)
	v_mul_f32_e32 v54, v54, v167
	v_fmaak_f32 v54, v130, v54, 0x43000000
	s_waitcnt lgkmcnt(2)
	v_mul_f32_e32 v62, v62, v164
	s_waitcnt lgkmcnt(1)
	v_mul_f32_e32 v58, v58, v166
	v_fmaak_f32 v62, v130, v62, 0x43000000
	v_cvt_pk_u8_f32 v62, v62, 0, 0
	v_fmaak_f32 v58, v130, v58, 0x43000000
	s_waitcnt lgkmcnt(0)
	v_mul_f32_e32 v50, v50, v168
	v_cvt_pk_u8_f32 v58, v58, 1, v62
	v_cvt_pk_u8_f32 v54, v54, 2, v58
	v_fmaak_f32 v50, v130, v50, 0x43000000
	v_cvt_pk_u8_f32 v50, v50, 3, v54
	v_mul_f32_e32 v54, v63, v164
	v_mul_f32_e32 v58, v59, v166
	v_fmaak_f32 v54, v135, v54, 0x43000000
	v_mul_f32_e32 v55, v55, v167
	v_cvt_pk_u8_f32 v54, v54, 0, 0
	v_fmaak_f32 v58, v135, v58, 0x43000000
	v_mul_f32_e32 v51, v51, v168
	v_cvt_pk_u8_f32 v54, v58, 1, v54
	v_fmaak_f32 v55, v135, v55, 0x43000000
	v_cvt_pk_u8_f32 v54, v55, 2, v54
	v_fmaak_f32 v51, v135, v51, 0x43000000
	v_cvt_pk_u8_f32 v51, v51, 3, v54
	v_mul_f32_e32 v54, v64, v164
	v_mul_f32_e32 v55, v60, v166
	v_fmaak_f32 v54, v162, v54, 0x43000000
	v_mul_f32_e32 v56, v56, v167
	v_cvt_pk_u8_f32 v54, v54, 0, 0
	v_fmaak_f32 v55, v162, v55, 0x43000000
	v_mul_f32_e32 v52, v52, v168
	v_cvt_pk_u8_f32 v54, v55, 1, v54
	v_fmaak_f32 v55, v162, v56, 0x43000000
	v_div_fixup_f32 v163, v163, v165, s52
	v_cmp_lt_f32_e32 vcc, 0, v165
	v_cvt_pk_u8_f32 v54, v55, 2, v54
	v_fmaak_f32 v52, v162, v52, 0x43000000
	v_cndmask_b32_e32 v163, 0, v163, vcc
	v_cvt_pk_u8_f32 v52, v52, 3, v54
	v_mul_f32_e32 v54, v65, v164
	v_mul_f32_e32 v55, v61, v166
	v_fmaak_f32 v54, v163, v54, 0x43000000
	v_mul_f32_e32 v56, v57, v167
	v_cvt_pk_u8_f32 v54, v54, 0, 0
	v_fmaak_f32 v55, v163, v55, 0x43000000
	v_mul_f32_e32 v53, v53, v168
	v_cvt_pk_u8_f32 v54, v55, 1, v54
	v_fmaak_f32 v55, v163, v56, 0x43000000
	v_cvt_pk_u8_f32 v54, v55, 2, v54
	v_fmaak_f32 v53, v163, v53, 0x43000000
	v_cvt_pk_u8_f32 v53, v53, 3, v54
	ds_bpermute_b32 v54, v144, v159
	ds_bpermute_b32 v55, v145, v159
	ds_bpermute_b32 v56, v146, v159
	ds_bpermute_b32 v57, v147, v159
	v_xor_b32_e32 v50, 0x80808080, v50
	s_waitcnt lgkmcnt(3)
; __device__ __forceinline__ void gu_load(f32x4 (&v)[16], float& gA, float& gB, const GUDesc& d, int lane) {
;     const int kr = lane >> 3, nq = lane & 7;
;     const float* __restrict__ src = d.W + (size_t)(d.k0 + 4 * kr) * d.N + d.n0 + 4 * nq;
;     gA = d.gain ? d.gain[d.k0 + lane] : 1.0f; gB = d.gain ? d.gain[d.k0 + 64 + lane] : 1.0f;
; #pragma unroll
;     for (int i = 0; i < 16; ++i) v[i] = *(const f32x4*)(src + (size_t)(32 * (i >> 2) + (i & 3)) * d.N);
; }
; template <bool STRIP, int ROT>
; __device__ __forceinline__ void gu_finish_t(f32x4 (&v)[16], float gA, float gB, const GUDesc& d, LAS unsigned* T, int lane, const float (&sinv)[4]) {
;     ...
;     for (int jq = 0; jq < 4; ++jq) {
;         float g[4];
; #pragma unroll
;         for (int e2 = 0; e2 < 4; ++e2) g[e2] = jq < 2 ? __shfl(gA, 32 * jq + 4 * kr + e2) : __shfl(gB, 32 * (jq - 2) + 4 * kr + e2);
; #pragma unroll
;         for (int e = 0; e < 4; ++e)
;             T[(4 * nq + e) * 33 + 8 * jq + kr] = pack4_i8(v[4 * jq + 0][e] * g[0] * inv[e], v[4 * jq + 1][e] * g[1] * inv[e], v[4 * jq + 2][e] * g[2] * inv[e], v[4 * jq + 3][e] * g[3] * inv[e]);
;     }
	v_mul_f32_e32 v46, v46, v54
	s_waitcnt lgkmcnt(2)
	v_mul_f32_e32 v42, v42, v55
	v_fmaak_f32 v46, v130, v46, 0x43000000
	s_waitcnt lgkmcnt(1)
	v_mul_f32_e32 v38, v38, v56
	v_cvt_pk_u8_f32 v46, v46, 0, 0
	v_fmaak_f32 v42, v130, v42, 0x43000000
	s_waitcnt lgkmcnt(0)
	v_mul_f32_e32 v34, v34, v57
	v_cvt_pk_u8_f32 v42, v42, 1, v46
	v_fmaak_f32 v38, v130, v38, 0x43000000
	v_cvt_pk_u8_f32 v38, v38, 2, v42
	v_fmaak_f32 v34, v130, v34, 0x43000000
	v_cvt_pk_u8_f32 v34, v34, 3, v38
	v_xor_b32_e32 v34, 0x80808080, v34
	ds_write2_b32 v151, v50, v34 offset1:8
	v_mul_f32_e32 v34, v47, v54
	v_mul_f32_e32 v38, v43, v55
	v_fmaak_f32 v34, v135, v34, 0x43000000
	v_mul_f32_e32 v39, v39, v56
	v_cvt_pk_u8_f32 v34, v34, 0, 0
	v_fmaak_f32 v38, v135, v38, 0x43000000
	v_mul_f32_e32 v35, v35, v57
	v_cvt_pk_u8_f32 v34, v38, 1, v34
	v_fmaak_f32 v38, v135, v39, 0x43000000
	v_cvt_pk_u8_f32 v34, v38, 2, v34
	v_fmaak_f32 v35, v135, v35, 0x43000000
	v_cvt_pk_u8_f32 v34, v35, 3, v34
	v_xor_b32_e32 v51, 0x80808080, v51
	v_xor_b32_e32 v34, 0x80808080, v34
	ds_write2_b32 v151, v51, v34 offset0:33 offset1:41
	v_mul_f32_e32 v34, v48, v54
	v_mul_f32_e32 v35, v44, v55
	v_fmaak_f32 v34, v162, v34, 0x43000000
	global_load_dwordx4 v[66:69], v[70:71], off nt
	v_mul_f32_e32 v38, v40, v56
	global_load_dwordx4 v[70:73], v[74:75], off nt
	v_cvt_pk_u8_f32 v34, v34, 0, 0
	global_load_dwordx4 v[74:77], v[78:79], off nt
	v_lshl_add_u64 v[78:79], v[78:79], 0, s[8:9]
	v_fmaak_f32 v35, v162, v35, 0x43000000
	global_load_dwordx4 v[78:81], v[78:79], off nt
	v_mul_f32_e32 v36, v36, v57
	v_cvt_pk_u8_f32 v34, v35, 1, v34
	v_fmaak_f32 v35, v162, v38, 0x43000000
	v_cvt_pk_u8_f32 v34, v35, 2, v34
	v_fmaak_f32 v35, v162, v36, 0x43000000
	v_cvt_pk_u8_f32 v34, v35, 3, v34
	v_xor_b32_e32 v52, 0x80808080, v52
	v_xor_b32_e32 v34, 0x80808080, v34
	ds_write2_b32 v151, v52, v34 offset0:66 offset1:74
	v_mul_f32_e32 v34, v49, v54
	v_mul_f32_e32 v35, v45, v55
	v_fmaak_f32 v34, v163, v34, 0x43000000
	v_mul_f32_e32 v36, v41, v56
	v_cvt_pk_u8_f32 v34, v34, 0, 0
	v_fmaak_f32 v35, v163, v35, 0x43000000
	v_mul_f32_e32 v37, v37, v57
	v_cvt_pk_u8_f32 v34, v35, 1, v34
	v_fmaak_f32 v35, v163, v36, 0x43000000
	v_cvt_pk_u8_f32 v34, v35, 2, v34
	v_fmaak_f32 v35, v163, v37, 0x43000000
	v_cvt_pk_u8_f32 v34, v35, 3, v34
	ds_bpermute_b32 v35, v140, v158
	ds_bpermute_b32 v36, v141, v158
	ds_bpermute_b32 v37, v142, v158
	ds_bpermute_b32 v38, v143, v158
	v_xor_b32_e32 v53, 0x80808080, v53
	s_waitcnt lgkmcnt(3)
	v_mul_f32_e32 v30, v30, v35
	s_waitcnt lgkmcnt(2)
	v_mul_f32_e32 v22, v22, v36
	v_fmaak_f32 v30, v130, v30, 0x43000000
	s_waitcnt lgkmcnt(1)
	v_mul_f32_e32 v18, v18, v37
	v_cvt_pk_u8_f32 v30, v30, 0, 0
	v_fmaak_f32 v22, v130, v22, 0x43000000
	s_waitcnt lgkmcnt(0)
	v_mul_f32_e32 v14, v14, v38
	v_cvt_pk_u8_f32 v22, v22, 1, v30
	v_fmaak_f32 v18, v130, v18, 0x43000000
	v_cvt_pk_u8_f32 v18, v18, 2, v22
	v_fmaak_f32 v14, v130, v14, 0x43000000
	v_cvt_pk_u8_f32 v14, v14, 3, v18
	v_mul_f32_e32 v18, v31, v35
	v_mul_f32_e32 v22, v23, v36
	v_fmaak_f32 v18, v135, v18, 0x43000000
	v_mul_f32_e32 v19, v19, v37
	v_cvt_pk_u8_f32 v18, v18, 0, 0
	v_fmaak_f32 v22, v135, v22, 0x43000000
	v_mul_f32_e32 v15, v15, v38
	v_cvt_pk_u8_f32 v18, v22, 1, v18
	v_fmaak_f32 v19, v135, v19, 0x43000000
	v_cvt_pk_u8_f32 v18, v19, 2, v18
	v_fmaak_f32 v15, v135, v15, 0x43000000
	v_cvt_pk_u8_f32 v15, v15, 3, v18
	v_mul_f32_e32 v18, v32, v35
	v_mul_f32_e32 v19, v24, v36
	v_fmaak_f32 v18, v162, v18, 0x43000000
	v_mul_f32_e32 v20, v20, v37
	v_cvt_pk_u8_f32 v18, v18, 0, 0
	v_fmaak_f32 v19, v162, v19, 0x43000000
	v_mul_f32_e32 v16, v16, v38
	v_cvt_pk_u8_f32 v18, v19, 1, v18
	v_fmaak_f32 v19, v162, v20, 0x43000000
	v_cvt_pk_u8_f32 v18, v19, 2, v18
	v_fmaak_f32 v16, v162, v16, 0x43000000
	v_cvt_pk_u8_f32 v16, v16, 3, v18
	v_mul_f32_e32 v18, v33, v35
	v_mul_f32_e32 v19, v25, v36
	v_fmaak_f32 v18, v163, v18, 0x43000000
	v_mul_f32_e32 v20, v21, v37
	v_cvt_pk_u8_f32 v18, v18, 0, 0
	v_fmaak_f32 v19, v163, v19, 0x43000000
	v_mul_f32_e32 v17, v17, v38
	v_cvt_pk_u8_f32 v18, v19, 1, v18
	v_fmaak_f32 v19, v163, v20, 0x43000000
	v_cvt_pk_u8_f32 v18, v19, 2, v18
	v_fmaak_f32 v17, v163, v17, 0x43000000
	v_cvt_pk_u8_f32 v17, v17, 3, v18
	ds_bpermute_b32 v18, v144, v158
	ds_bpermute_b32 v19, v145, v158
	ds_bpermute_b32 v20, v146, v158
	ds_bpermute_b32 v21, v147, v158
	v_xor_b32_e32 v14, 0x80808080, v14
	s_waitcnt lgkmcnt(3)
; #define LAS __attribute__((address_space(3)))
; __host__ __device__ __forceinline__ size_t blk8_off(int r, int k, int KT8_) { return ((size_t)((r >> 8) * KT8_ + (k >> 7)) * 256 + (size_t)(r & 255)) * 128 + (size_t)(k & 127); }
; #define LDS_WAIT() asm volatile("s_waitcnt lgkmcnt(0)" ::: "memory")
; template <bool STRIP, int ROT>
; __device__ __forceinline__ void gu_finish_t(f32x4 (&v)[16], float gA, float gB, const GUDesc& d, LAS unsigned* T, int lane, const float (&sinv)[4]) {
;     ...
;     for (int jq = 0; jq < 4; ++jq) {
;         float g[4];
; #pragma unroll
;         for (int e2 = 0; e2 < 4; ++e2) g[e2] = jq < 2 ? __shfl(gA, 32 * jq + 4 * kr + e2) : __shfl(gB, 32 * (jq - 2) + 4 * kr + e2);
; #pragma unroll
;         for (int e = 0; e < 4; ++e)
;             T[(4 * nq + e) * 33 + 8 * jq + kr] = pack4_i8(v[4 * jq + 0][e] * g[0] * inv[e], v[4 * jq + 1][e] * g[1] * inv[e], v[4 * jq + 2][e] * g[2] * inv[e], v[4 * jq + 3][e] * g[3] * inv[e]);
;     }
;     LDS_WAIT(); asm volatile("" ::: "memory");
;     const int nl = lane >> 3, c = lane & 7;
; #pragma unroll
;     for (int g4 = 0; g4 < 4; ++g4) {
;         const int nloc = 8 * g4 + nl, dr = d.il ? gu_dest(d.n0 + nloc, d.bj) : d.n0 + nloc;
;         const LAS unsigned* t = T + nloc * 33 + 4 * c;
;         u32x4 o; o.x = t[0]; o.y = t[1]; o.z = t[2]; o.w = t[3];
;         *(u32x4*)(d.WQ + blk8_off(dr, d.k0 + 16 * c, d.kt8)) = o;
;         if (!STRIP) if (d.k0 == 0 && c == 0) d.sb[dr] = __uint_as_float(d.cmax[dr]) * (1.0f / 127.0f);
	v_mul_f32_e32 v10, v10, v18
	s_waitcnt lgkmcnt(2)
	v_mul_f32_e32 v6, v6, v19
	v_fmaak_f32 v10, v130, v10, 0x43000000
	s_waitcnt lgkmcnt(1)
	v_mul_f32_e32 v2, v2, v20
	v_cvt_pk_u8_f32 v10, v10, 0, 0
	v_fmaak_f32 v6, v130, v6, 0x43000000
	s_waitcnt lgkmcnt(0)
	v_mul_f32_e32 v22, v26, v21
	v_cvt_pk_u8_f32 v6, v6, 1, v10
	v_fmaak_f32 v2, v130, v2, 0x43000000
	v_cvt_pk_u8_f32 v2, v2, 2, v6
	v_fmaak_f32 v6, v130, v22, 0x43000000
	v_cvt_pk_u8_f32 v2, v6, 3, v2
	v_xor_b32_e32 v2, 0x80808080, v2
	ds_write2_b32 v151, v14, v2 offset0:16 offset1:24
	v_mul_f32_e32 v2, v11, v18
	v_mul_f32_e32 v6, v7, v19
	v_fmaak_f32 v2, v135, v2, 0x43000000
	v_mul_f32_e32 v3, v3, v20
	v_cvt_pk_u8_f32 v2, v2, 0, 0
	v_fmaak_f32 v6, v135, v6, 0x43000000
	v_mul_f32_e32 v7, v27, v21
	v_cvt_pk_u8_f32 v2, v6, 1, v2
	v_fmaak_f32 v3, v135, v3, 0x43000000
	v_cvt_pk_u8_f32 v2, v3, 2, v2
	v_fmaak_f32 v3, v135, v7, 0x43000000
	v_cvt_pk_u8_f32 v2, v3, 3, v2
	v_xor_b32_e32 v15, 0x80808080, v15
	v_xor_b32_e32 v2, 0x80808080, v2
	ds_write2_b32 v151, v15, v2 offset0:49 offset1:57
	v_mul_f32_e32 v2, v12, v18
	v_mul_f32_e32 v3, v8, v19
	v_fmaak_f32 v2, v162, v2, 0x43000000
	v_mul_f32_e32 v4, v4, v20
	v_cvt_pk_u8_f32 v2, v2, 0, 0
	v_fmaak_f32 v3, v162, v3, 0x43000000
	v_mul_f32_e32 v6, v28, v21
	v_cvt_pk_u8_f32 v2, v3, 1, v2
	v_fmaak_f32 v3, v162, v4, 0x43000000
	v_cvt_pk_u8_f32 v2, v3, 2, v2
	v_fmaak_f32 v3, v162, v6, 0x43000000
	v_cvt_pk_u8_f32 v2, v3, 3, v2
	v_xor_b32_e32 v16, 0x80808080, v16
	v_xor_b32_e32 v2, 0x80808080, v2
	ds_write2_b32 v151, v16, v2 offset0:82 offset1:90
	v_mul_f32_e32 v2, v13, v18
	v_mul_f32_e32 v3, v9, v19
	v_fmaak_f32 v2, v163, v2, 0x43000000
	v_mul_f32_e32 v4, v5, v20
	v_cvt_pk_u8_f32 v2, v2, 0, 0
	v_fmaak_f32 v3, v163, v3, 0x43000000
	v_mul_f32_e32 v5, v29, v21
	v_cvt_pk_u8_f32 v2, v3, 1, v2
	v_fmaak_f32 v3, v163, v4, 0x43000000
	v_cvt_pk_u8_f32 v2, v3, 2, v2
	v_fmaak_f32 v3, v163, v5, 0x43000000
	v_cvt_pk_u8_f32 v2, v3, 3, v2
	v_xor_b32_e32 v17, 0x80808080, v17
	v_xor_b32_e32 v2, 0x80808080, v2
	ds_write2_b32 v151, v17, v2 offset0:115 offset1:123
	v_add_u32_e32 v2, s12, v137
	v_lshlrev_b32_e32 v3, 1, v2
	v_and_b32_e32 v3, 0xffffff00, v3
	v_add_u32_e32 v3, s13, v3
	v_xor_b32_e32 v34, 0x80808080, v34
	v_and_or_b32 v3, v2, s51, v3
	ds_write2_b32 v151, v53, v34 offset0:99 offset1:107
	v_cndmask_b32_e64 v2, v3, v2, s[4:5]
	v_add_u32_e32 v3, s40, v132
	s_waitcnt lgkmcnt(0)
	v_lshrrev_b32_e32 v5, 8, v2
	v_ashrrev_i32_e32 v4, 7, v3
	v_mad_i32_i24 v10, v5, s54, v4
	ds_read2_b32 v[6:7], v152 offset1:1
	ds_read2_b32 v[8:9], v152 offset0:2 offset1:3
	v_ashrrev_i32_e32 v11, 31, v10
	v_lshlrev_b64 v[10:11], 15, v[10:11]
	v_lshlrev_b32_e32 v5, 7, v2
	v_and_b32_e32 v12, 0x7f80, v5
	v_mov_b32_e32 v13, v131
	v_lshl_add_u64 v[10:11], s[28:29], 0, v[10:11]
	v_and_b32_e32 v130, 0x7f, v3
	v_lshl_add_u64 v[10:11], v[10:11], 0, v[12:13]
	v_or_b32_e32 v3, s40, v138
	v_lshl_add_u64 v[10:11], v[10:11], 0, v[130:131]
	v_cmp_eq_u32_e32 vcc, 0, v3
	s_waitcnt lgkmcnt(0)
	global_store_dwordx4 v[10:11], v[6:9], off
	s_and_saveexec_b64 s[0:1], vcc
	s_cbranch_execz .LBB0_2542
	v_ashrrev_i32_e32 v3, 31, v2
	v_lshlrev_b64 v[2:3], 2, v[2:3]
	v_lshl_add_u64 v[6:7], s[10:11], 0, v[2:3]
	global_load_dword v5, v[6:7], off
	v_lshl_add_u64 v[2:3], s[20:21], 0, v[2:3]
	s_waitcnt vmcnt(0)
	v_mul_f32_e32 v5, 0x3c010204, v5
	global_store_dword v[2:3], v5, off

; __device__ __forceinline__ void gu_load(f32x4 (&v)[16], float& gA, float& gB, const GUDesc& d, int lane) {
;     const int kr = lane >> 3, nq = lane & 7;
;     const float* __restrict__ src = d.W + (size_t)(d.k0 + 4 * kr) * d.N + d.n0 + 4 * nq;
;     gA = d.gain ? d.gain[d.k0 + lane] : 1.0f; gB = d.gain ? d.gain[d.k0 + 64 + lane] : 1.0f;
; #pragma unroll
;     for (int i = 0; i < 16; ++i) v[i] = *(const f32x4*)(src + (size_t)(32 * (i >> 2) + (i & 3)) * d.N);
; }
; template <bool STRIP, int ROT>
; __device__ __forceinline__ void gu_finish_t(f32x4 (&v)[16], float gA, float gB, const GUDesc& d, LAS unsigned* T, int lane, const float (&sinv)[4]) {
;     ...
;     const int dq0 = d.il ? gu_dest(d.n0 + 4 * nq, d.bj) : d.n0 + 4 * nq;
;     if (ROT) rot32_tile<ROT>(v, lane);
;     float inv[4];
; #pragma unroll
;     for (int e = 0; e < 4; ++e) { if (STRIP) inv[e] = sinv[e]; else { const float cm = __uint_as_float(d.cmax[dq0 + e]); inv[e] = cm > 0.f ? 127.0f / cm : 0.f; } }
; #pragma unroll
;     for (int jq = 0; jq < 4; ++jq) {
;         float g[4];
; #pragma unroll
;         for (int e2 = 0; e2 < 4; ++e2) g[e2] = jq < 2 ? __shfl(gA, 32 * jq + 4 * kr + e2) : __shfl(gB, 32 * (jq - 2) + 4 * kr + e2);
; #pragma unroll
;         for (int e = 0; e < 4; ++e)
;             T[(4 * nq + e) * 33 + 8 * jq + kr] = pack4_i8(v[4 * jq + 0][e] * g[0] * inv[e], v[4 * jq + 1][e] * g[1] * inv[e], v[4 * jq + 2][e] * g[2] * inv[e], v[4 * jq + 3][e] * g[3] * inv[e]);
.LBB0_2561:
	v_or_b32_e32 v2, s40, v136
	v_mul_hi_i32_i24_e32 v3, s0, v2
	v_mul_i32_i24_e32 v2, s0, v2
	s_ashr_i32 s13, s12, 31
	s_waitcnt lgkmcnt(0)
	v_lshl_add_u64 v[2:3], v[2:3], 2, v[4:5]
	v_lshl_add_u64 v[2:3], s[12:13], 2, v[2:3]
	v_mov_b32_e32 v135, v131
	s_lshl_b32 s8, s0, 2
	v_lshl_add_u64 v[2:3], v[2:3], 0, v[134:135]
	v_lshl_add_u64 v[4:5], v[2:3], 0, s[8:9]
	global_load_dwordx4 v[62:65], v[2:3], off nt
	global_load_dwordx4 v[58:61], v[4:5], off nt
	v_lshl_add_u64 v[2:3], v[4:5], 0, s[8:9]
	v_lshl_add_u64 v[4:5], v[2:3], 0, s[8:9]
	s_mulk_i32 s0, 0x74
	s_mov_b32 s1, s9
	global_load_dwordx4 v[54:57], v[2:3], off nt
	global_load_dwordx4 v[50:53], v[4:5], off nt
	v_lshl_add_u64 v[2:3], v[4:5], 0, s[0:1]
	v_lshl_add_u64 v[4:5], v[2:3], 0, s[8:9]
	global_load_dwordx4 v[46:49], v[2:3], off nt
	global_load_dwordx4 v[42:45], v[4:5], off nt
	v_lshl_add_u64 v[2:3], v[4:5], 0, s[8:9]
	v_lshl_add_u64 v[4:5], v[2:3], 0, s[8:9]
	global_load_dwordx4 v[38:41], v[2:3], off nt
	global_load_dwordx4 v[34:37], v[4:5], off nt
	v_lshl_add_u64 v[2:3], v[4:5], 0, s[0:1]
	global_load_dwordx4 v[30:33], v[2:3], off nt
	v_lshl_add_u64 v[2:3], v[2:3], 0, s[8:9]
	global_load_dwordx4 v[22:25], v[2:3], off nt
	v_lshl_add_u64 v[2:3], v[2:3], 0, s[8:9]
	global_load_dwordx4 v[18:21], v[2:3], off nt
	v_lshl_add_u64 v[2:3], v[2:3], 0, s[8:9]
	global_load_dwordx4 v[14:17], v[2:3], off nt
	v_lshl_add_u64 v[2:3], v[2:3], 0, s[0:1]
	global_load_dwordx4 v[10:13], v[2:3], off nt
	v_lshl_add_u64 v[2:3], v[2:3], 0, s[8:9]
	v_lshl_add_u64 v[26:27], v[2:3], 0, s[8:9]
	global_load_dwordx4 v[6:9], v[2:3], off nt
	s_cmp_ge_i32 s59, s33
	global_load_dwordx4 v[2:5], v[26:27], off nt
	v_lshl_add_u64 v[26:27], v[26:27], 0, s[8:9]
	global_load_dwordx4 v[26:29], v[26:27], off nt
	s_cbranch_scc1 .LBB0_2528
	s_add_u32 s28, s78, s22
	s_addc_u32 s29, s79, s23
	s_add_u32 s22, s38, s26
	s_addc_u32 s23, s39, s27
	s_lshl_b32 s0, s16, 1
	s_and_b32 s8, s0, 0xffffff00
	v_bitop3_b32 v135, s16, v153, v139 bitop3:0xc8
	v_or_b32_e32 v135, s8, v135
	v_or_b32_e32 v130, s16, v139
	v_or_b32_e32 v135, s19, v135
	v_cndmask_b32_e64 v168, v135, v130, s[2:3]
	v_ashrrev_i32_e32 v169, 31, v168
	v_lshl_add_u64 v[168:169], v[168:169], 2, s[14:15]
	global_load_dwordx4 v[168:171], v[168:169], off nt
	ds_bpermute_b32 v130, v140, v161
	ds_bpermute_b32 v135, v141, v161
	ds_bpermute_b32 v172, v142, v161
	ds_bpermute_b32 v173, v143, v161
	s_waitcnt vmcnt(36) lgkmcnt(3)
	v_mul_f32_e32 v115, v115, v130
	v_mul_f32_e32 v114, v114, v130
	s_waitcnt vmcnt(35) lgkmcnt(2)
	v_mul_f32_e32 v119, v119, v135
	v_mul_f32_e32 v116, v116, v130
	v_mul_f32_e32 v118, v118, v135
	v_mul_f32_e32 v120, v120, v135
	s_waitcnt vmcnt(34) lgkmcnt(1)
	v_mul_f32_e32 v124, v124, v172
	v_mul_f32_e32 v117, v117, v130
	v_mul_f32_e32 v122, v122, v172
	s_waitcnt vmcnt(33) lgkmcnt(0)
	v_mul_f32_e32 v126, v126, v173
	v_mul_f32_e32 v123, v123, v172
	v_mul_f32_e32 v127, v127, v173
	s_waitcnt vmcnt(0)
	v_div_scale_f32 v174, s[0:1], v168, v168, s52
	v_div_scale_f32 v176, s[0:1], v169, v169, s52
	v_rcp_f32_e32 v182, v174
	v_rcp_f32_e32 v183, v176
	v_div_scale_f32 v178, s[4:5], v170, v170, s52
	v_rcp_f32_e32 v184, v178
	v_div_scale_f32 v180, s[6:7], v171, v171, s52
	v_fma_f32 v186, -v174, v182, 1.0
	v_div_scale_f32 v175, vcc, s52, v168, s52
	v_rcp_f32_e32 v185, v180
	v_fma_f32 v187, -v176, v183, 1.0
	v_fmac_f32_e32 v182, v186, v182
	v_div_scale_f32 v177, s[0:1], s52, v169, s52
	v_fmac_f32_e32 v183, v187, v183
	v_mul_f32_e32 v186, v175, v182
	v_fma_f32 v188, -v178, v184, 1.0
	v_mul_f32_e32 v187, v177, v183
	v_fma_f32 v190, -v174, v186, v175
	v_div_scale_f32 v179, s[4:5], s52, v170, s52
	v_fmac_f32_e32 v184, v188, v184
	v_fma_f32 v191, -v176, v187, v177
	v_fmac_f32_e32 v186, v190, v182
	v_fma_f32 v189, -v180, v185, 1.0
	v_mul_f32_e32 v188, v179, v184
	v_fmac_f32_e32 v187, v191, v183
	v_fma_f32 v174, -v174, v186, v175
	v_div_scale_f32 v181, s[6:7], s52, v171, s52
	v_fmac_f32_e32 v185, v189, v185
	v_fma_f32 v192, -v178, v188, v179
	v_fma_f32 v175, -v176, v187, v177
	v_div_fmas_f32 v174, v174, v182, v186
	s_mov_b64 vcc, s[0:1]
	v_mul_f32_e32 v189, v181, v185
	v_fmac_f32_e32 v188, v192, v184
	v_div_fixup_f32 v174, v174, v168, s52
	v_div_fmas_f32 v175, v175, v183, v187
	v_cmp_lt_f32_e32 vcc, 0, v168
	v_fma_f32 v193, -v180, v189, v181
	v_fma_f32 v176, -v178, v188, v179
	v_cndmask_b32_e32 v168, 0, v174, vcc
	s_mov_b64 vcc, s[4:5]
	v_fmac_f32_e32 v189, v193, v185
	v_div_fixup_f32 v174, v175, v169, s52
	v_div_fmas_f32 v175, v176, v184, v188
	v_cmp_lt_f32_e32 vcc, 0, v169
	v_fma_f32 v177, -v180, v189, v181
	v_fmaak_f32 v114, v168, v114, 0x43000000
	v_cndmask_b32_e32 v169, 0, v174, vcc
	s_mov_b64 vcc, s[6:7]
	v_div_fixup_f32 v174, v175, v170, s52
	v_div_fmas_f32 v175, v177, v185, v189
	v_cmp_lt_f32_e32 vcc, 0, v170
	v_fmaak_f32 v115, v169, v115, 0x43000000
	v_fmaak_f32 v119, v169, v119, 0x43000000
	v_cndmask_b32_e32 v170, 0, v174, vcc
	v_cvt_pk_u8_f32 v115, v115, 0, 0
	v_fmaak_f32 v116, v170, v116, 0x43000000
	v_fmaak_f32 v118, v168, v118, 0x43000000
	v_cvt_pk_u8_f32 v114, v114, 0, 0
	v_cvt_pk_u8_f32 v115, v119, 1, v115
	v_cvt_pk_u8_f32 v116, v116, 0, 0
	v_fmaak_f32 v119, v170, v120, 0x43000000
	v_div_fixup_f32 v174, v175, v171, s52
	v_cmp_lt_f32_e32 vcc, 0, v171
	v_cvt_pk_u8_f32 v114, v118, 1, v114
	v_mul_f32_e32 v118, v128, v173
	v_cvt_pk_u8_f32 v116, v119, 1, v116
	v_fmaak_f32 v119, v170, v124, 0x43000000
	v_cndmask_b32_e32 v171, 0, v174, vcc
	v_cvt_pk_u8_f32 v116, v119, 2, v116
	v_fmaak_f32 v118, v170, v118, 0x43000000
	v_cvt_pk_u8_f32 v116, v118, 3, v116
	v_mul_f32_e32 v118, v121, v135
	v_fmaak_f32 v117, v171, v117, 0x43000000
	v_mul_f32_e32 v119, v125, v172
	v_cvt_pk_u8_f32 v117, v117, 0, 0
	v_fmaak_f32 v118, v171, v118, 0x43000000
	v_mul_f32_e32 v120, v129, v173
	v_cvt_pk_u8_f32 v117, v118, 1, v117
	v_fmaak_f32 v118, v171, v119, 0x43000000
	v_cvt_pk_u8_f32 v117, v118, 2, v117
	v_fmaak_f32 v118, v171, v120, 0x43000000
	v_cvt_pk_u8_f32 v117, v118, 3, v117
	ds_bpermute_b32 v118, v144, v161
	ds_bpermute_b32 v119, v145, v161
	ds_bpermute_b32 v120, v146, v161
	ds_bpermute_b32 v121, v147, v161
	v_fmaak_f32 v122, v168, v122, 0x43000000
	s_waitcnt lgkmcnt(3)
; template <bool STRIP, int ROT>
; __device__ __forceinline__ void gu_finish_t(f32x4 (&v)[16], float gA, float gB, const GUDesc& d, LAS unsigned* T, int lane, const float (&sinv)[4]) {
;     ...
;     for (int jq = 0; jq < 4; ++jq) {
;         float g[4];
; #pragma unroll
;         for (int e2 = 0; e2 < 4; ++e2) g[e2] = jq < 2 ? __shfl(gA, 32 * jq + 4 * kr + e2) : __shfl(gB, 32 * (jq - 2) + 4 * kr + e2);
; #pragma unroll
;         for (int e = 0; e < 4; ++e)
;             T[(4 * nq + e) * 33 + 8 * jq + kr] = pack4_i8(v[4 * jq + 0][e] * g[0] * inv[e], v[4 * jq + 1][e] * g[1] * inv[e], v[4 * jq + 2][e] * g[2] * inv[e], v[4 * jq + 3][e] * g[3] * inv[e]);
;     }
	v_mul_f32_e32 v98, v98, v118
	s_waitcnt lgkmcnt(2)
	v_mul_f32_e32 v102, v102, v119
	v_fmaak_f32 v98, v168, v98, 0x43000000
	s_waitcnt lgkmcnt(1)
	v_mul_f32_e32 v106, v106, v120
	v_cvt_pk_u8_f32 v98, v98, 0, 0
	v_fmaak_f32 v102, v168, v102, 0x43000000
	s_waitcnt lgkmcnt(0)
	v_mul_f32_e32 v110, v110, v121
	v_cvt_pk_u8_f32 v98, v102, 1, v98
	v_fmaak_f32 v102, v168, v106, 0x43000000
	v_fmaak_f32 v126, v168, v126, 0x43000000
	v_cvt_pk_u8_f32 v114, v122, 2, v114
	v_cvt_pk_u8_f32 v98, v102, 2, v98
	v_fmaak_f32 v102, v168, v110, 0x43000000
	v_cvt_pk_u8_f32 v114, v126, 3, v114
	v_cvt_pk_u8_f32 v98, v102, 3, v98
	v_xor_b32_e32 v114, 0x80808080, v114
	v_xor_b32_e32 v98, 0x80808080, v98
	ds_write2_b32 v151, v114, v98 offset1:8
	v_mul_f32_e32 v98, v99, v118
	v_mul_f32_e32 v99, v103, v119
	v_fmaak_f32 v98, v169, v98, 0x43000000
	v_mul_f32_e32 v102, v107, v120
	v_cvt_pk_u8_f32 v98, v98, 0, 0
	v_fmaak_f32 v99, v169, v99, 0x43000000
	v_fmaak_f32 v123, v169, v123, 0x43000000
	v_mul_f32_e32 v103, v111, v121
	v_cvt_pk_u8_f32 v98, v99, 1, v98
	v_fmaak_f32 v99, v169, v102, 0x43000000
	v_fmaak_f32 v127, v169, v127, 0x43000000
	v_cvt_pk_u8_f32 v115, v123, 2, v115
	v_cvt_pk_u8_f32 v98, v99, 2, v98
	v_fmaak_f32 v99, v169, v103, 0x43000000
	v_cvt_pk_u8_f32 v115, v127, 3, v115
	v_cvt_pk_u8_f32 v98, v99, 3, v98
	v_xor_b32_e32 v115, 0x80808080, v115
	v_xor_b32_e32 v98, 0x80808080, v98
	ds_write2_b32 v151, v115, v98 offset0:33 offset1:41
	v_mul_f32_e32 v98, v100, v118
	v_mul_f32_e32 v99, v104, v119
	v_fmaak_f32 v98, v170, v98, 0x43000000
	v_mul_f32_e32 v100, v108, v120
	v_cvt_pk_u8_f32 v98, v98, 0, 0
	v_fmaak_f32 v99, v170, v99, 0x43000000
	v_mul_f32_e32 v102, v112, v121
	v_cvt_pk_u8_f32 v98, v99, 1, v98
	v_fmaak_f32 v99, v170, v100, 0x43000000
	v_cvt_pk_u8_f32 v98, v99, 2, v98
	v_fmaak_f32 v99, v170, v102, 0x43000000
	v_cvt_pk_u8_f32 v98, v99, 3, v98
	v_xor_b32_e32 v116, 0x80808080, v116
	v_xor_b32_e32 v98, 0x80808080, v98
	ds_write2_b32 v151, v116, v98 offset0:66 offset1:74
	v_mul_f32_e32 v98, v101, v118
	v_mul_f32_e32 v99, v105, v119
	v_fmaak_f32 v98, v171, v98, 0x43000000
	v_mul_f32_e32 v100, v109, v120
	v_cvt_pk_u8_f32 v98, v98, 0, 0
	v_fmaak_f32 v99, v171, v99, 0x43000000
	v_mul_f32_e32 v101, v113, v121
	v_cvt_pk_u8_f32 v98, v99, 1, v98
	v_fmaak_f32 v99, v171, v100, 0x43000000
	v_cvt_pk_u8_f32 v98, v99, 2, v98
	v_fmaak_f32 v99, v171, v101, 0x43000000
	v_cvt_pk_u8_f32 v98, v99, 3, v98
	ds_bpermute_b32 v99, v140, v160
	ds_bpermute_b32 v100, v141, v160
	ds_bpermute_b32 v101, v142, v160
	ds_bpermute_b32 v102, v143, v160
	v_xor_b32_e32 v117, 0x80808080, v117
	s_waitcnt lgkmcnt(3)
	v_mul_f32_e32 v82, v82, v99
	s_waitcnt lgkmcnt(2)
	v_mul_f32_e32 v86, v86, v100
	v_fmaak_f32 v82, v168, v82, 0x43000000
	s_waitcnt lgkmcnt(1)
	v_mul_f32_e32 v90, v90, v101
	v_cvt_pk_u8_f32 v82, v82, 0, 0
	v_fmaak_f32 v86, v168, v86, 0x43000000
	s_waitcnt lgkmcnt(0)
	v_mul_f32_e32 v94, v94, v102
	v_cvt_pk_u8_f32 v82, v86, 1, v82
	v_fmaak_f32 v86, v168, v90, 0x43000000
	v_cvt_pk_u8_f32 v82, v86, 2, v82
	v_fmaak_f32 v86, v168, v94, 0x43000000
	v_mul_f32_e32 v83, v83, v99
	v_cvt_pk_u8_f32 v82, v86, 3, v82
	v_mul_f32_e32 v86, v87, v100
	v_fmaak_f32 v83, v169, v83, 0x43000000
	v_mul_f32_e32 v87, v91, v101
	v_cvt_pk_u8_f32 v83, v83, 0, 0
	v_fmaak_f32 v86, v169, v86, 0x43000000
	v_mul_f32_e32 v90, v95, v102
	v_cvt_pk_u8_f32 v83, v86, 1, v83
	v_fmaak_f32 v86, v169, v87, 0x43000000
	v_cvt_pk_u8_f32 v83, v86, 2, v83
	v_fmaak_f32 v86, v169, v90, 0x43000000
	v_mul_f32_e32 v84, v84, v99
	v_cvt_pk_u8_f32 v83, v86, 3, v83
	v_mul_f32_e32 v86, v88, v100
	v_fmaak_f32 v84, v170, v84, 0x43000000
	v_mul_f32_e32 v87, v92, v101
	v_cvt_pk_u8_f32 v84, v84, 0, 0
	v_fmaak_f32 v86, v170, v86, 0x43000000
	v_mul_f32_e32 v88, v96, v102
	v_cvt_pk_u8_f32 v84, v86, 1, v84
	v_fmaak_f32 v86, v170, v87, 0x43000000
	v_cvt_pk_u8_f32 v84, v86, 2, v84
	v_fmaak_f32 v86, v170, v88, 0x43000000
	v_mul_f32_e32 v85, v85, v99
	v_cvt_pk_u8_f32 v84, v86, 3, v84
	v_mul_f32_e32 v86, v89, v100
	v_fmaak_f32 v85, v171, v85, 0x43000000
	v_mul_f32_e32 v87, v93, v101
	v_cvt_pk_u8_f32 v85, v85, 0, 0
	v_fmaak_f32 v86, v171, v86, 0x43000000
	v_mul_f32_e32 v88, v97, v102
	v_cvt_pk_u8_f32 v85, v86, 1, v85
	v_fmaak_f32 v86, v171, v87, 0x43000000
	v_cvt_pk_u8_f32 v85, v86, 2, v85
	v_fmaak_f32 v86, v171, v88, 0x43000000
	v_cvt_pk_u8_f32 v85, v86, 3, v85
	ds_bpermute_b32 v86, v144, v160
	ds_bpermute_b32 v87, v145, v160
	ds_bpermute_b32 v88, v146, v160
	ds_bpermute_b32 v89, v147, v160
	v_xor_b32_e32 v82, 0x80808080, v82
	s_waitcnt lgkmcnt(3)
; #define LAS __attribute__((address_space(3)))
; __host__ __device__ __forceinline__ size_t blk8_off(int r, int k, int KT8_) { return ((size_t)((r >> 8) * KT8_ + (k >> 7)) * 256 + (size_t)(r & 255)) * 128 + (size_t)(k & 127); }
; #define LDS_WAIT() asm volatile("s_waitcnt lgkmcnt(0)" ::: "memory")
; template <bool STRIP, int ROT>
; __device__ __forceinline__ void gu_finish_t(f32x4 (&v)[16], float gA, float gB, const GUDesc& d, LAS unsigned* T, int lane, const float (&sinv)[4]) {
;     ...
;     for (int jq = 0; jq < 4; ++jq) {
;         float g[4];
; #pragma unroll
;         for (int e2 = 0; e2 < 4; ++e2) g[e2] = jq < 2 ? __shfl(gA, 32 * jq + 4 * kr + e2) : __shfl(gB, 32 * (jq - 2) + 4 * kr + e2);
; #pragma unroll
;         for (int e = 0; e < 4; ++e)
;             T[(4 * nq + e) * 33 + 8 * jq + kr] = pack4_i8(v[4 * jq + 0][e] * g[0] * inv[e], v[4 * jq + 1][e] * g[1] * inv[e], v[4 * jq + 2][e] * g[2] * inv[e], v[4 * jq + 3][e] * g[3] * inv[e]);
;     }
;     LDS_WAIT(); asm volatile("" ::: "memory");
;     const int nl = lane >> 3, c = lane & 7;
; #pragma unroll
;     for (int g4 = 0; g4 < 4; ++g4) {
;         const int nloc = 8 * g4 + nl, dr = d.il ? gu_dest(d.n0 + nloc, d.bj) : d.n0 + nloc;
;         const LAS unsigned* t = T + nloc * 33 + 4 * c;
;         u32x4 o; o.x = t[0]; o.y = t[1]; o.z = t[2]; o.w = t[3];
;         *(u32x4*)(d.WQ + blk8_off(dr, d.k0 + 16 * c, d.kt8)) = o;
;         if (!STRIP) if (d.k0 == 0 && c == 0) d.sb[dr] = __uint_as_float(d.cmax[dr]) * (1.0f / 127.0f);
	v_mul_f32_e32 v66, v66, v86
	s_waitcnt lgkmcnt(2)
	v_mul_f32_e32 v70, v70, v87
	v_fmaak_f32 v66, v168, v66, 0x43000000
	s_waitcnt lgkmcnt(1)
	v_mul_f32_e32 v74, v74, v88
	v_cvt_pk_u8_f32 v66, v66, 0, 0
	v_fmaak_f32 v70, v168, v70, 0x43000000
	s_waitcnt lgkmcnt(0)
	v_mul_f32_e32 v78, v78, v89
	v_cvt_pk_u8_f32 v66, v70, 1, v66
	v_fmaak_f32 v70, v168, v74, 0x43000000
	v_cvt_pk_u8_f32 v66, v70, 2, v66
	v_fmaak_f32 v70, v168, v78, 0x43000000
	v_cvt_pk_u8_f32 v66, v70, 3, v66
	v_xor_b32_e32 v66, 0x80808080, v66
	ds_write2_b32 v151, v82, v66 offset0:16 offset1:24
	v_mul_f32_e32 v66, v67, v86
	v_mul_f32_e32 v67, v71, v87
	v_fmaak_f32 v66, v169, v66, 0x43000000
	v_mul_f32_e32 v70, v75, v88
	v_cvt_pk_u8_f32 v66, v66, 0, 0
	v_fmaak_f32 v67, v169, v67, 0x43000000
	v_mul_f32_e32 v71, v79, v89
	v_cvt_pk_u8_f32 v66, v67, 1, v66
	v_fmaak_f32 v67, v169, v70, 0x43000000
	v_cvt_pk_u8_f32 v66, v67, 2, v66
	v_fmaak_f32 v67, v169, v71, 0x43000000
	v_cvt_pk_u8_f32 v66, v67, 3, v66
	v_xor_b32_e32 v83, 0x80808080, v83
	v_xor_b32_e32 v66, 0x80808080, v66
	ds_write2_b32 v151, v83, v66 offset0:49 offset1:57
	v_mul_f32_e32 v66, v68, v86
	v_mul_f32_e32 v67, v72, v87
	v_fmaak_f32 v66, v170, v66, 0x43000000
	v_mul_f32_e32 v68, v76, v88
	v_cvt_pk_u8_f32 v66, v66, 0, 0
	v_fmaak_f32 v67, v170, v67, 0x43000000
	v_mul_f32_e32 v70, v80, v89
	v_cvt_pk_u8_f32 v66, v67, 1, v66
	v_fmaak_f32 v67, v170, v68, 0x43000000
	v_cvt_pk_u8_f32 v66, v67, 2, v66
	v_fmaak_f32 v67, v170, v70, 0x43000000
	v_cvt_pk_u8_f32 v66, v67, 3, v66
	v_xor_b32_e32 v84, 0x80808080, v84
	v_xor_b32_e32 v66, 0x80808080, v66
	ds_write2_b32 v151, v84, v66 offset0:82 offset1:90
	v_mul_f32_e32 v66, v69, v86
	v_mul_f32_e32 v67, v73, v87
	v_fmaak_f32 v66, v171, v66, 0x43000000
	v_mul_f32_e32 v68, v77, v88
	v_cvt_pk_u8_f32 v66, v66, 0, 0
	v_fmaak_f32 v67, v171, v67, 0x43000000
	v_mul_f32_e32 v69, v81, v89
	v_cvt_pk_u8_f32 v66, v67, 1, v66
	v_fmaak_f32 v67, v171, v68, 0x43000000
	v_cvt_pk_u8_f32 v66, v67, 2, v66
	v_fmaak_f32 v67, v171, v69, 0x43000000
	v_cvt_pk_u8_f32 v66, v67, 3, v66
	v_bitop3_b32 v67, s16, v154, v137 bitop3:0xc8
	v_xor_b32_e32 v85, 0x80808080, v85
	v_xor_b32_e32 v66, 0x80808080, v66
	v_or_b32_e32 v67, s8, v67
	v_xor_b32_e32 v98, 0x80808080, v98
	ds_write2_b32 v151, v85, v66 offset0:115 offset1:123
	v_or_b32_e32 v66, s16, v137
	v_or_b32_e32 v67, s19, v67
	ds_write2_b32 v151, v117, v98 offset0:99 offset1:107
	v_cndmask_b32_e64 v66, v67, v66, s[2:3]
	s_ashr_i32 s4, s56, 7
	s_waitcnt lgkmcnt(0)
	v_lshrrev_b32_e32 v67, 8, v66
	v_mov_b32_e32 v72, s4
	v_mad_i32_i24 v72, v67, s55, v72
	ds_read2_b32 v[68:69], v152 offset1:1
	ds_read2_b32 v[70:71], v152 offset0:2 offset1:3
	v_ashrrev_i32_e32 v73, 31, v72
	v_lshlrev_b64 v[72:73], 15, v[72:73]
	v_lshlrev_b32_e32 v67, 7, v66
	v_and_b32_e32 v130, 0x7380, v67
	v_lshl_add_u64 v[72:73], s[28:29], 0, v[72:73]
	v_lshl_add_u64 v[72:73], v[72:73], 0, v[130:131]
	v_or_b32_e32 v67, s56, v138
	v_lshl_add_u64 v[72:73], v[72:73], 0, v[132:133]
	v_cmp_eq_u32_e32 vcc, 0, v67
	s_waitcnt lgkmcnt(0)
	global_store_dwordx4 v[72:73], v[68:71], off
	s_and_saveexec_b64 s[0:1], vcc
	s_cbranch_execz .LBB0_2564
	v_ashrrev_i32_e32 v67, 31, v66
	v_lshlrev_b64 v[66:67], 2, v[66:67]
	v_lshl_add_u64 v[68:69], s[14:15], 0, v[66:67]
	global_load_dword v68, v[68:69], off
	v_lshl_add_u64 v[66:67], s[22:23], 0, v[66:67]
	s_waitcnt vmcnt(0)
	v_mul_f32_e32 v68, 0x3c010204, v68
	global_store_dword v[66:67], v68, off

; #define LAS __attribute__((address_space(3)))
; __device__ __forceinline__ float bfly8(float x, bool up) { const float p = __uint_as_float(__builtin_amdgcn_update_dpp(0u, __float_as_uint(x), 0x128, 0xf, 0xf, false)); return up ? p - x : x + p; }
; __device__ __forceinline__ void gu_load(f32x4 (&v)[16], float& gA, float& gB, const GUDesc& d, int lane) {
;     const int kr = lane >> 3, nq = lane & 7;
;     const float* __restrict__ src = d.W + (size_t)(d.k0 + 4 * kr) * d.N + d.n0 + 4 * nq;
;     gA = d.gain ? d.gain[d.k0 + lane] : 1.0f; gB = d.gain ? d.gain[d.k0 + 64 + lane] : 1.0f;
; #pragma unroll
;     for (int i = 0; i < 16; ++i) v[i] = *(const f32x4*)(src + (size_t)(32 * (i >> 2) + (i & 3)) * d.N);
; }
; template <int ROT>
; __device__ __forceinline__ void rot32_tile(f32x4 (&v)[16], int lane) {
; #pragma unroll
;     for (int jq = 0; jq < 4; ++jq) {
;         const f32x4 a = v[4 * jq], b = v[4 * jq + 1], c = v[4 * jq + 2], d = v[4 * jq + 3];
;         const f32x4 a1 = a + b, b1 = a - b, c1 = c + d, d1 = c - d;
;         if (ROT >= 2) { v[4 * jq] = a1 + c1; v[4 * jq + 2] = a1 - c1; v[4 * jq + 1] = b1 + d1; v[4 * jq + 3] = b1 - d1; }
;         else { v[4 * jq] = a1; v[4 * jq + 1] = b1; v[4 * jq + 2] = c1; v[4 * jq + 3] = d1; }
;     }
;     { const bool s8 = (lane & 8) != 0, s16 = (lane & 16) != 0, s32 = (lane & 32) != 0;
; #pragma unroll
;       for (int i = 0; i < 16; ++i)
; #pragma unroll
;           for (int e = 0; e < 4; ++e) { float x = v[i][e]; if (ROT >= 3) x = bfly8(x, s8); if (ROT >= 4) x = bfly16(x, s16); if (ROT >= 5) x = bfly32(x, s32); v[i][e] = x; } }
; #pragma unroll
;     for (int i = 0; i < 16; ++i) v[i] *= (ROT == 1 ? 0.70710678118654752f : ROT == 2 ? 0.5f : ROT == 3 ? 0.35355339059327373f : ROT == 4 ? 0.25f : 0.17677669529663687f);
; }
; template <bool STRIP, int ROT>
; __device__ __forceinline__ void gu_finish_t(f32x4 (&v)[16], float gA, float gB, const GUDesc& d, LAS unsigned* T, int lane, const float (&sinv)[4]) {
;     const int kr = lane >> 3, nq = lane & 7;
;     const int dq0 = d.il ? gu_dest(d.n0 + 4 * nq, d.bj) : d.n0 + 4 * nq;
;     if (ROT) rot32_tile<ROT>(v, lane);
;     float inv[4];
; #pragma unroll
;     for (int e = 0; e < 4; ++e) { if (STRIP) inv[e] = sinv[e]; else { const float cm = __uint_as_float(d.cmax[dq0 + e]); inv[e] = cm > 0.f ? 127.0f / cm : 0.f; } }
.LBB0_3967:
	v_or_b32_e32 v2, s37, v49
	s_add_u32 s14, s20, s14
	v_mul_hi_i32_i24_e32 v3, s16, v2
	v_mul_i32_i24_e32 v2, s16, v2
	s_addc_u32 s15, s21, s15
	s_waitcnt lgkmcnt(0)
	v_lshl_add_u64 v[2:3], v[2:3], 2, v[4:5]
	s_ashr_i32 s13, s12, 31
	v_lshl_add_u64 v[2:3], s[12:13], 2, v[2:3]
	v_lshl_add_u64 v[2:3], v[2:3], 0, v[38:39]
	s_lshl_b32 s0, s16, 2
	v_lshl_add_u64 v[4:5], v[2:3], 0, s[0:1]
	global_load_dwordx4 v[40:43], v[2:3], off nt
	global_load_dwordx4 v[44:47], v[4:5], off nt
	v_lshl_add_u64 v[2:3], v[4:5], 0, s[0:1]
	v_lshl_add_u64 v[4:5], v[2:3], 0, s[0:1]
	s_mulk_i32 s16, 0x74
	s_mov_b32 s17, s1
	global_load_dwordx4 v[72:75], v[2:3], off nt
	global_load_dwordx4 v[76:79], v[4:5], off nt
	v_lshl_add_u64 v[2:3], v[4:5], 0, s[16:17]
	v_lshl_add_u64 v[4:5], v[2:3], 0, s[0:1]
	global_load_dwordx4 v[80:83], v[2:3], off nt
	global_load_dwordx4 v[84:87], v[4:5], off nt
	v_lshl_add_u64 v[2:3], v[4:5], 0, s[0:1]
	v_lshl_add_u64 v[4:5], v[2:3], 0, s[0:1]
	global_load_dwordx4 v[88:91], v[2:3], off nt
	global_load_dwordx4 v[92:95], v[4:5], off nt
	v_lshl_add_u64 v[2:3], v[4:5], 0, s[16:17]
	global_load_dwordx4 v[10:13], v[2:3], off nt
	v_lshl_add_u64 v[2:3], v[2:3], 0, s[0:1]
	v_lshl_add_u64 v[6:7], v[2:3], 0, s[0:1]
	global_load_dwordx4 v[26:29], v[2:3], off nt
	s_lshl_b32 s13, s12, 1
	global_load_dwordx4 v[2:5], v[6:7], off nt
	v_lshl_add_u64 v[6:7], v[6:7], 0, s[0:1]
	global_load_dwordx4 v[14:17], v[6:7], off nt
	s_waitcnt vmcnt(12)
	v_bitop3_b32 v9, s12, v64, v52 bitop3:0xc8
	s_and_b32 s13, s13, 0xffffff00
	v_lshl_add_u64 v[6:7], v[6:7], 0, s[16:17]
	v_or_b32_e32 v9, s13, v9
	global_load_dwordx4 v[18:21], v[6:7], off nt
	v_lshl_add_u64 v[6:7], v[6:7], 0, s[0:1]
	v_or_b32_e32 v8, s12, v52
	v_or_b32_e32 v9, s35, v9
	v_lshl_add_u64 v[22:23], v[6:7], 0, s[0:1]
	v_cndmask_b32_e64 v96, v9, v8, s[2:3]
	global_load_dwordx4 v[30:33], v[6:7], off nt
	v_ashrrev_i32_e32 v97, 31, v96
	global_load_dwordx4 v[6:9], v[22:23], off nt
	v_lshl_add_u64 v[22:23], v[22:23], 0, s[0:1]
	global_load_dwordx4 v[22:25], v[22:23], off nt
	s_ashr_i32 s0, s37, 7
	s_waitcnt vmcnt(14)
	v_pk_add_f32 v[98:99], v[42:43], v[46:47]
	v_pk_add_f32 v[100:101], v[40:41], v[44:45]
	v_sub_f32_e32 v103, v43, v47
	v_sub_f32_e32 v102, v42, v46
	v_sub_f32_e32 v105, v41, v45
	v_sub_f32_e32 v104, v40, v44
	s_waitcnt vmcnt(12)
	v_pk_add_f32 v[40:41], v[74:75], v[78:79]
	v_pk_add_f32 v[42:43], v[72:73], v[76:77]
	v_sub_f32_e32 v75, v75, v79
	v_sub_f32_e32 v74, v74, v78
	v_sub_f32_e32 v73, v73, v77
	v_sub_f32_e32 v72, v72, v76
	v_pk_add_f32 v[44:45], v[98:99], v[40:41]
	v_pk_add_f32 v[46:47], v[100:101], v[42:43]
	v_sub_f32_e32 v41, v99, v41
	v_sub_f32_e32 v40, v98, v40
	v_sub_f32_e32 v43, v101, v43
	v_sub_f32_e32 v42, v100, v42
	v_pk_add_f32 v[76:77], v[104:105], v[72:73]
	v_pk_add_f32 v[78:79], v[102:103], v[74:75]
	v_sub_f32_e32 v99, v105, v73
	v_sub_f32_e32 v98, v104, v72
	v_sub_f32_e32 v101, v103, v75
	v_sub_f32_e32 v100, v102, v74
	s_waitcnt vmcnt(10)
	v_pk_add_f32 v[72:73], v[82:83], v[86:87]
	v_pk_add_f32 v[74:75], v[80:81], v[84:85]
	v_sub_f32_e32 v81, v81, v85
	v_sub_f32_e32 v80, v80, v84
	s_waitcnt vmcnt(8)
	v_pk_add_f32 v[84:85], v[90:91], v[94:95]
	v_sub_f32_e32 v83, v83, v87
	v_sub_f32_e32 v82, v82, v86
	v_pk_add_f32 v[86:87], v[88:89], v[92:93]
	v_sub_f32_e32 v89, v89, v93
	v_sub_f32_e32 v88, v88, v92
	v_pk_add_f32 v[92:93], v[72:73], v[84:85]
	v_sub_f32_e32 v85, v73, v85
	v_sub_f32_e32 v84, v72, v84
	v_lshl_add_u64 v[72:73], v[96:97], 2, s[8:9]
	v_sub_f32_e32 v91, v91, v95
	v_sub_f32_e32 v90, v90, v94
	v_pk_add_f32 v[94:95], v[74:75], v[86:87]
	v_sub_f32_e32 v87, v75, v87
	v_sub_f32_e32 v86, v74, v86
	global_load_dwordx4 v[72:75], v[72:73], off nt
	v_pk_add_f32 v[102:103], v[80:81], v[88:89]
	v_pk_add_f32 v[104:105], v[82:83], v[90:91]
	v_sub_f32_e32 v81, v81, v89
	v_sub_f32_e32 v80, v80, v88
	v_sub_f32_e32 v83, v83, v91
	v_sub_f32_e32 v82, v82, v90
	s_waitcnt vmcnt(7)
	v_pk_add_f32 v[88:89], v[12:13], v[28:29]
	v_pk_add_f32 v[90:91], v[10:11], v[26:27]
	v_sub_f32_e32 v13, v13, v29
	v_sub_f32_e32 v12, v12, v28
	v_sub_f32_e32 v11, v11, v27
	v_sub_f32_e32 v10, v10, v26
	s_waitcnt vmcnt(5)
	v_pk_add_f32 v[26:27], v[4:5], v[16:17]
	v_pk_add_f32 v[28:29], v[2:3], v[14:15]
	v_sub_f32_e32 v5, v5, v17
	v_sub_f32_e32 v4, v4, v16
	v_sub_f32_e32 v3, v3, v15
	v_sub_f32_e32 v2, v2, v14
	v_pk_add_f32 v[14:15], v[88:89], v[26:27]
	v_pk_add_f32 v[16:17], v[90:91], v[28:29]
	v_sub_f32_e32 v27, v89, v27
	v_sub_f32_e32 v26, v88, v26
	v_sub_f32_e32 v29, v91, v29
	v_sub_f32_e32 v28, v90, v28
	v_pk_add_f32 v[88:89], v[10:11], v[2:3]
	v_pk_add_f32 v[90:91], v[12:13], v[4:5]
	v_sub_f32_e32 v3, v11, v3
	v_sub_f32_e32 v2, v10, v2
	v_sub_f32_e32 v5, v13, v5
	v_sub_f32_e32 v4, v12, v4
	s_waitcnt vmcnt(3)
	v_pk_add_f32 v[10:11], v[20:21], v[32:33]
	v_pk_add_f32 v[12:13], v[18:19], v[30:31]
	v_sub_f32_e32 v19, v19, v31
	v_sub_f32_e32 v18, v18, v30
	s_waitcnt vmcnt(1)
; #define LAS __attribute__((address_space(3)))
; __device__ __forceinline__ float bfly8(float x, bool up) { const float p = __uint_as_float(__builtin_amdgcn_update_dpp(0u, __float_as_uint(x), 0x128, 0xf, 0xf, false)); return up ? p - x : x + p; }
; template <int ROT>
; __device__ __forceinline__ void rot32_tile(f32x4 (&v)[16], int lane) {
; #pragma unroll
;     for (int jq = 0; jq < 4; ++jq) {
;         const f32x4 a = v[4 * jq], b = v[4 * jq + 1], c = v[4 * jq + 2], d = v[4 * jq + 3];
;         const f32x4 a1 = a + b, b1 = a - b, c1 = c + d, d1 = c - d;
;         if (ROT >= 2) { v[4 * jq] = a1 + c1; v[4 * jq + 2] = a1 - c1; v[4 * jq + 1] = b1 + d1; v[4 * jq + 3] = b1 - d1; }
;         else { v[4 * jq] = a1; v[4 * jq + 1] = b1; v[4 * jq + 2] = c1; v[4 * jq + 3] = d1; }
;     }
;     { const bool s8 = (lane & 8) != 0, s16 = (lane & 16) != 0, s32 = (lane & 32) != 0;
; #pragma unroll
;       for (int i = 0; i < 16; ++i)
; #pragma unroll
;           for (int e = 0; e < 4; ++e) { float x = v[i][e]; if (ROT >= 3) x = bfly8(x, s8); if (ROT >= 4) x = bfly16(x, s16); if (ROT >= 5) x = bfly32(x, s32); v[i][e] = x; } }
; #pragma unroll
;     for (int i = 0; i < 16; ++i) v[i] *= (ROT == 1 ? 0.70710678118654752f : ROT == 2 ? 0.5f : ROT == 3 ? 0.35355339059327373f : ROT == 4 ? 0.25f : 0.17677669529663687f);
; }
; template <bool STRIP, int ROT>
; __device__ __forceinline__ void gu_finish_t(f32x4 (&v)[16], float gA, float gB, const GUDesc& d, LAS unsigned* T, int lane, const float (&sinv)[4]) {
;     const int kr = lane >> 3, nq = lane & 7;
;     const int dq0 = d.il ? gu_dest(d.n0 + 4 * nq, d.bj) : d.n0 + 4 * nq;
;     if (ROT) rot32_tile<ROT>(v, lane);
;     float inv[4];
; #pragma unroll
;     for (int e = 0; e < 4; ++e) { if (STRIP) inv[e] = sinv[e]; else { const float cm = __uint_as_float(d.cmax[dq0 + e]); inv[e] = cm > 0.f ? 127.0f / cm : 0.f; } }
; #pragma unroll
;     for (int jq = 0; jq < 4; ++jq) {
;         float g[4];
; #pragma unroll
;         for (int e2 = 0; e2 < 4; ++e2) g[e2] = jq < 2 ? __shfl(gA, 32 * jq + 4 * kr + e2) : __shfl(gB, 32 * (jq - 2) + 4 * kr + e2);
; #pragma unroll
;         for (int e = 0; e < 4; ++e)
;             T[(4 * nq + e) * 33 + 8 * jq + kr] = pack4_i8(v[4 * jq + 0][e] * g[0] * inv[e], v[4 * jq + 1][e] * g[1] * inv[e], v[4 * jq + 2][e] * g[2] * inv[e], v[4 * jq + 3][e] * g[3] * inv[e]);
;     }
	v_pk_add_f32 v[30:31], v[8:9], v[24:25]
	v_sub_f32_e32 v21, v21, v33
	v_sub_f32_e32 v20, v20, v32
	v_pk_add_f32 v[32:33], v[6:7], v[22:23]
	v_sub_f32_e32 v7, v7, v23
	v_sub_f32_e32 v6, v6, v22
	v_pk_add_f32 v[22:23], v[10:11], v[30:31]
	v_pk_mul_f32 v[110:111], v[2:3], 0.5 op_sel_hi:[1,0]
	v_pk_mul_f32 v[2:3], v[22:23], 0.5 op_sel_hi:[1,0]
	v_sub_f32_e32 v9, v9, v25
	v_sub_f32_e32 v8, v8, v24
	v_pk_add_f32 v[24:25], v[12:13], v[32:33]
	v_sub_f32_e32 v33, v13, v33
	v_sub_f32_e32 v32, v12, v32
	v_pk_add_f32 v[12:13], v[18:19], v[6:7]
	v_sub_f32_e32 v19, v19, v7
	v_sub_f32_e32 v18, v18, v6
	v_pk_mul_f32 v[106:107], v[16:17], 0.5 op_sel_hi:[1,0]
	v_pk_mul_f32 v[16:17], v[18:19], 0.5 op_sel_hi:[1,0]
	v_sub_f32_e32 v31, v11, v31
	v_sub_f32_e32 v30, v10, v30
	v_pk_mul_f32 v[10:11], v[24:25], 0.5 op_sel_hi:[1,0]
	v_pk_mul_f32 v[6:7], v[30:31], 0.5 op_sel_hi:[1,0]
	v_pk_add_f32 v[96:97], v[20:21], v[8:9]
	v_sub_f32_e32 v9, v21, v9
	v_sub_f32_e32 v8, v20, v8
	v_pk_mul_f32 v[20:21], v[44:45], 0.5 op_sel_hi:[1,0]
	v_pk_mul_f32 v[44:45], v[46:47], 0.5 op_sel_hi:[1,0]
	v_pk_mul_f32 v[46:47], v[78:79], 0.5 op_sel_hi:[1,0]
	v_pk_mul_f32 v[76:77], v[76:77], 0.5 op_sel_hi:[1,0]
	v_pk_mul_f32 v[78:79], v[100:101], 0.5 op_sel_hi:[1,0]
	v_pk_mul_f32 v[100:101], v[104:105], 0.5 op_sel_hi:[1,0]
	v_pk_mul_f32 v[104:105], v[14:15], 0.5 op_sel_hi:[1,0]
	v_pk_mul_f32 v[14:15], v[32:33], 0.5 op_sel_hi:[1,0]
	v_pk_mul_f32 v[42:43], v[42:43], 0.5 op_sel_hi:[1,0]
	v_pk_mul_f32 v[98:99], v[98:99], 0.5 op_sel_hi:[1,0]
	v_pk_mul_f32 v[40:41], v[40:41], 0.5 op_sel_hi:[1,0]
	v_pk_mul_f32 v[94:95], v[94:95], 0.5 op_sel_hi:[1,0]
	v_pk_mul_f32 v[102:103], v[102:103], 0.5 op_sel_hi:[1,0]
	v_pk_mul_f32 v[86:87], v[86:87], 0.5 op_sel_hi:[1,0]
	v_pk_mul_f32 v[80:81], v[80:81], 0.5 op_sel_hi:[1,0]
	v_pk_mul_f32 v[92:93], v[92:93], 0.5 op_sel_hi:[1,0]
	v_pk_mul_f32 v[84:85], v[84:85], 0.5 op_sel_hi:[1,0]
	v_pk_mul_f32 v[82:83], v[82:83], 0.5 op_sel_hi:[1,0]
	v_pk_mul_f32 v[88:89], v[88:89], 0.5 op_sel_hi:[1,0]
	s_waitcnt vmcnt(0)
	v_div_scale_f32 v22, s[16:17], v72, v72, s34
	v_rcp_f32_e32 v23, v22
	v_pk_mul_f32 v[28:29], v[28:29], 0.5 op_sel_hi:[1,0]
	v_pk_mul_f32 v[90:91], v[90:91], 0.5 op_sel_hi:[1,0]
	v_pk_mul_f32 v[26:27], v[26:27], 0.5 op_sel_hi:[1,0]
	v_fma_f32 v18, -v22, v23, 1.0
	v_fmac_f32_e32 v23, v18, v23
	v_div_scale_f32 v18, vcc, s34, v72, s34
	v_mul_f32_e32 v19, v18, v23
	v_fma_f32 v24, -v22, v19, v18
	v_fmac_f32_e32 v19, v24, v23
	v_fma_f32 v18, -v22, v19, v18
	v_div_fmas_f32 v18, v18, v23, v19
	v_div_scale_f32 v19, s[16:17], v73, v73, s34
	v_rcp_f32_e32 v22, v19
	v_div_fixup_f32 v18, v18, v72, s34
	v_cmp_lt_f32_e32 vcc, 0, v72
	v_pk_mul_f32 v[108:109], v[4:5], 0.5 op_sel_hi:[1,0]
	v_fma_f32 v23, -v19, v22, 1.0
	v_cndmask_b32_e32 v18, 0, v18, vcc
	v_fmac_f32_e32 v22, v23, v22
	v_div_scale_f32 v23, vcc, s34, v73, s34
	v_mul_f32_e32 v24, v23, v22
	v_fma_f32 v25, -v19, v24, v23
	v_fmac_f32_e32 v24, v25, v22
	v_fma_f32 v19, -v19, v24, v23
	v_div_fmas_f32 v19, v19, v22, v24
	v_div_scale_f32 v22, s[16:17], v74, v74, s34
	v_rcp_f32_e32 v23, v22
	v_div_fixup_f32 v19, v19, v73, s34
	v_cmp_lt_f32_e32 vcc, 0, v73
	v_pk_mul_f32 v[4:5], v[96:97], 0.5 op_sel_hi:[1,0]
	v_fma_f32 v24, -v22, v23, 1.0
	v_cndmask_b32_e32 v19, 0, v19, vcc
	v_fmac_f32_e32 v23, v24, v23
	v_div_scale_f32 v24, vcc, s34, v74, s34
	v_mul_f32_e32 v25, v24, v23
	v_fma_f32 v30, -v22, v25, v24
	v_fmac_f32_e32 v25, v30, v23
	v_fma_f32 v22, -v22, v25, v24
	v_div_fmas_f32 v22, v22, v23, v25
	v_div_scale_f32 v23, s[16:17], v75, v75, s34
	v_rcp_f32_e32 v24, v23
	v_div_fixup_f32 v22, v22, v74, s34
	v_cmp_lt_f32_e32 vcc, 0, v74
	v_pk_mul_f32 v[12:13], v[12:13], 0.5 op_sel_hi:[1,0]
	v_fma_f32 v25, -v23, v24, 1.0
	v_cndmask_b32_e32 v22, 0, v22, vcc
	v_fmac_f32_e32 v24, v25, v24
	v_div_scale_f32 v25, vcc, s34, v75, s34
	v_mul_f32_e32 v30, v25, v24
	v_fma_f32 v31, -v23, v30, v25
	v_fmac_f32_e32 v30, v31, v24
	v_fma_f32 v23, -v23, v30, v25
	v_div_fmas_f32 v23, v23, v24, v30
	ds_bpermute_b32 v24, v53, v71
	ds_bpermute_b32 v25, v54, v71
	ds_bpermute_b32 v30, v55, v71
	ds_bpermute_b32 v31, v56, v71
	v_div_fixup_f32 v23, v23, v75, s34
	s_waitcnt lgkmcnt(3)
	v_mul_f32_e32 v32, v44, v24
	s_waitcnt lgkmcnt(2)
	v_mul_f32_e32 v33, v76, v25
	v_fmaak_f32 v32, v18, v32, 0x43000000
	s_waitcnt lgkmcnt(1)
	v_mul_f32_e32 v42, v42, v30
	v_cvt_pk_u8_f32 v32, v32, 0, 0
	v_fmaak_f32 v33, v18, v33, 0x43000000
	s_waitcnt lgkmcnt(0)
	v_mul_f32_e32 v44, v98, v31
	v_cvt_pk_u8_f32 v32, v33, 1, v32
	v_fmaak_f32 v33, v18, v42, 0x43000000
	v_cvt_pk_u8_f32 v32, v33, 2, v32
	v_fmaak_f32 v33, v18, v44, 0x43000000
	v_cvt_pk_u8_f32 v32, v33, 3, v32
	v_mul_f32_e32 v33, v45, v24
	v_mul_f32_e32 v42, v77, v25
	v_fmaak_f32 v33, v19, v33, 0x43000000
	v_cmp_lt_f32_e32 vcc, 0, v75
	v_mul_f32_e32 v43, v43, v30
	v_cvt_pk_u8_f32 v33, v33, 0, 0
	v_fmaak_f32 v42, v19, v42, 0x43000000
	v_cndmask_b32_e32 v23, 0, v23, vcc
	v_mul_f32_e32 v44, v99, v31
	v_cvt_pk_u8_f32 v33, v42, 1, v33
	v_fmaak_f32 v42, v19, v43, 0x43000000
	v_mul_f32_e32 v21, v21, v24
	v_cvt_pk_u8_f32 v33, v42, 2, v33
	v_fmaak_f32 v42, v19, v44, 0x43000000
	v_mul_f32_e32 v20, v20, v24
	v_mul_f32_e32 v24, v47, v25
	v_fmaak_f32 v21, v23, v21, 0x43000000
	v_cvt_pk_u8_f32 v33, v42, 3, v33
	v_mul_f32_e32 v42, v46, v25
	v_mul_f32_e32 v25, v41, v30
	v_cvt_pk_u8_f32 v21, v21, 0, 0
	v_fmaak_f32 v24, v23, v24, 0x43000000
	v_mul_f32_e32 v40, v40, v30
	v_mul_f32_e32 v30, v79, v31
	v_cvt_pk_u8_f32 v21, v24, 1, v21
	v_fmaak_f32 v24, v23, v25, 0x43000000
	v_cvt_pk_u8_f32 v21, v24, 2, v21
	v_fmaak_f32 v24, v23, v30, 0x43000000
	v_cvt_pk_u8_f32 v21, v24, 3, v21
	ds_bpermute_b32 v24, v57, v71
	v_fmaak_f32 v20, v22, v20, 0x43000000
	ds_bpermute_b32 v25, v58, v71
	v_cvt_pk_u8_f32 v20, v20, 0, 0
	v_fmaak_f32 v42, v22, v42, 0x43000000
	ds_bpermute_b32 v30, v59, v71
	v_mul_f32_e32 v43, v78, v31
	v_cvt_pk_u8_f32 v20, v42, 1, v20
	v_fmaak_f32 v40, v22, v40, 0x43000000
	ds_bpermute_b32 v31, v60, v71
	v_cvt_pk_u8_f32 v20, v40, 2, v20
	v_fmaak_f32 v40, v22, v43, 0x43000000
	v_cvt_pk_u8_f32 v20, v40, 3, v20
	s_waitcnt lgkmcnt(3)
; template <bool STRIP, int ROT>
; __device__ __forceinline__ void gu_finish_t(f32x4 (&v)[16], float gA, float gB, const GUDesc& d, LAS unsigned* T, int lane, const float (&sinv)[4]) {
;     ...
;     for (int jq = 0; jq < 4; ++jq) {
;         float g[4];
; #pragma unroll
;         for (int e2 = 0; e2 < 4; ++e2) g[e2] = jq < 2 ? __shfl(gA, 32 * jq + 4 * kr + e2) : __shfl(gB, 32 * (jq - 2) + 4 * kr + e2);
; #pragma unroll
;         for (int e = 0; e < 4; ++e)
;             T[(4 * nq + e) * 33 + 8 * jq + kr] = pack4_i8(v[4 * jq + 0][e] * g[0] * inv[e], v[4 * jq + 1][e] * g[1] * inv[e], v[4 * jq + 2][e] * g[2] * inv[e], v[4 * jq + 3][e] * g[3] * inv[e]);
;     }
	v_mul_f32_e32 v40, v94, v24
	s_waitcnt lgkmcnt(2)
	v_mul_f32_e32 v41, v102, v25
	v_fmaak_f32 v40, v18, v40, 0x43000000
	s_waitcnt lgkmcnt(1)
	v_mul_f32_e32 v42, v86, v30
	v_cvt_pk_u8_f32 v40, v40, 0, 0
	v_fmaak_f32 v41, v18, v41, 0x43000000
	s_waitcnt lgkmcnt(0)
	v_mul_f32_e32 v43, v80, v31
	v_cvt_pk_u8_f32 v40, v41, 1, v40
	v_fmaak_f32 v41, v18, v42, 0x43000000
	v_cvt_pk_u8_f32 v40, v41, 2, v40
	v_fmaak_f32 v41, v18, v43, 0x43000000
	v_cvt_pk_u8_f32 v40, v41, 3, v40
	v_xor_b32_e32 v32, 0x80808080, v32
	v_xor_b32_e32 v40, 0x80808080, v40
	ds_write2_b32 v65, v32, v40 offset1:8
	v_mul_f32_e32 v32, v95, v24
	v_mul_f32_e32 v40, v103, v25
	v_fmaak_f32 v32, v19, v32, 0x43000000
	v_mul_f32_e32 v41, v87, v30
	v_cvt_pk_u8_f32 v32, v32, 0, 0
	v_fmaak_f32 v40, v19, v40, 0x43000000
	v_mul_f32_e32 v42, v81, v31
	v_cvt_pk_u8_f32 v32, v40, 1, v32
	v_fmaak_f32 v40, v19, v41, 0x43000000
	v_cvt_pk_u8_f32 v32, v40, 2, v32
	v_fmaak_f32 v40, v19, v42, 0x43000000
	v_cvt_pk_u8_f32 v32, v40, 3, v32
	v_xor_b32_e32 v33, 0x80808080, v33
	v_xor_b32_e32 v32, 0x80808080, v32
	ds_write2_b32 v65, v33, v32 offset0:33 offset1:41
	v_mul_f32_e32 v32, v92, v24
	v_mul_f32_e32 v33, v100, v25
	v_fmaak_f32 v32, v22, v32, 0x43000000
	v_mul_f32_e32 v40, v84, v30
	v_cvt_pk_u8_f32 v32, v32, 0, 0
	v_fmaak_f32 v33, v22, v33, 0x43000000
	v_mul_f32_e32 v41, v82, v31
	v_cvt_pk_u8_f32 v32, v33, 1, v32
	v_fmaak_f32 v33, v22, v40, 0x43000000
	v_cvt_pk_u8_f32 v32, v33, 2, v32
	v_fmaak_f32 v33, v22, v41, 0x43000000
	v_cvt_pk_u8_f32 v32, v33, 3, v32
	v_xor_b32_e32 v20, 0x80808080, v20
	v_xor_b32_e32 v32, 0x80808080, v32
	ds_write2_b32 v65, v20, v32 offset0:66 offset1:74
	v_mul_f32_e32 v20, v93, v24
	v_mul_f32_e32 v24, v101, v25
	v_fmaak_f32 v20, v23, v20, 0x43000000
	v_mul_f32_e32 v25, v85, v30
	v_cvt_pk_u8_f32 v20, v20, 0, 0
	v_fmaak_f32 v24, v23, v24, 0x43000000
	v_mul_f32_e32 v30, v83, v31
	v_cvt_pk_u8_f32 v20, v24, 1, v20
	v_fmaak_f32 v24, v23, v25, 0x43000000
	v_cvt_pk_u8_f32 v20, v24, 2, v20
	v_fmaak_f32 v24, v23, v30, 0x43000000
	v_cvt_pk_u8_f32 v20, v24, 3, v20
	ds_bpermute_b32 v24, v53, v34
	ds_bpermute_b32 v25, v54, v34
	ds_bpermute_b32 v30, v55, v34
	ds_bpermute_b32 v31, v56, v34
	v_xor_b32_e32 v21, 0x80808080, v21
	v_xor_b32_e32 v20, 0x80808080, v20
	ds_write2_b32 v65, v21, v20 offset0:99 offset1:107
	s_waitcnt lgkmcnt(4)
	v_mul_f32_e32 v20, v106, v24
	s_waitcnt lgkmcnt(3)
	v_mul_f32_e32 v21, v88, v25
	v_fmaak_f32 v20, v18, v20, 0x43000000
	s_waitcnt lgkmcnt(2)
	v_mul_f32_e32 v28, v28, v30
	v_cvt_pk_u8_f32 v20, v20, 0, 0
	v_fmaak_f32 v21, v18, v21, 0x43000000
	s_waitcnt lgkmcnt(1)
	v_mul_f32_e32 v32, v110, v31
	v_cvt_pk_u8_f32 v20, v21, 1, v20
	v_fmaak_f32 v21, v18, v28, 0x43000000
	v_cvt_pk_u8_f32 v20, v21, 2, v20
	v_fmaak_f32 v21, v18, v32, 0x43000000
	v_cvt_pk_u8_f32 v20, v21, 3, v20
	v_mul_f32_e32 v21, v107, v24
	v_mul_f32_e32 v28, v89, v25
	v_fmaak_f32 v21, v19, v21, 0x43000000
	v_mul_f32_e32 v29, v29, v30
	v_cvt_pk_u8_f32 v21, v21, 0, 0
	v_fmaak_f32 v28, v19, v28, 0x43000000
	v_mul_f32_e32 v32, v111, v31
	v_cvt_pk_u8_f32 v21, v28, 1, v21
	v_fmaak_f32 v28, v19, v29, 0x43000000
	v_cvt_pk_u8_f32 v21, v28, 2, v21
	v_fmaak_f32 v28, v19, v32, 0x43000000
	v_cvt_pk_u8_f32 v21, v28, 3, v21
	v_mul_f32_e32 v28, v104, v24
	v_mul_f32_e32 v29, v90, v25
	v_fmaak_f32 v28, v22, v28, 0x43000000
	v_mul_f32_e32 v26, v26, v30
	v_cvt_pk_u8_f32 v28, v28, 0, 0
	v_fmaak_f32 v29, v22, v29, 0x43000000
	v_mul_f32_e32 v24, v105, v24
	v_mul_f32_e32 v32, v108, v31
	v_cvt_pk_u8_f32 v28, v29, 1, v28
	v_fmaak_f32 v26, v22, v26, 0x43000000
	v_mul_f32_e32 v25, v91, v25
	v_fmaak_f32 v24, v23, v24, 0x43000000
	v_cvt_pk_u8_f32 v26, v26, 2, v28
	v_fmaak_f32 v28, v22, v32, 0x43000000
	v_mul_f32_e32 v27, v27, v30
	v_cvt_pk_u8_f32 v24, v24, 0, 0
	v_fmaak_f32 v25, v23, v25, 0x43000000
	v_cvt_pk_u8_f32 v26, v28, 3, v26
	v_mul_f32_e32 v28, v109, v31
	v_cvt_pk_u8_f32 v24, v25, 1, v24
	v_fmaak_f32 v25, v23, v27, 0x43000000
	v_cvt_pk_u8_f32 v24, v25, 2, v24
	v_fmaak_f32 v25, v23, v28, 0x43000000
	v_cvt_pk_u8_f32 v24, v25, 3, v24
	ds_bpermute_b32 v25, v57, v34
	ds_bpermute_b32 v27, v58, v34
	ds_bpermute_b32 v28, v59, v34
	ds_bpermute_b32 v29, v60, v34
	v_pk_mul_f32 v[8:9], v[8:9], 0.5 op_sel_hi:[1,0]
	s_waitcnt lgkmcnt(3)
; #define LAS __attribute__((address_space(3)))
; __host__ __device__ __forceinline__ size_t blk8_off(int r, int k, int KT8_) { return ((size_t)((r >> 8) * KT8_ + (k >> 7)) * 256 + (size_t)(r & 255)) * 128 + (size_t)(k & 127); }
; #define LDS_WAIT() asm volatile("s_waitcnt lgkmcnt(0)" ::: "memory")
; template <bool STRIP, int ROT>
; __device__ __forceinline__ void gu_finish_t(f32x4 (&v)[16], float gA, float gB, const GUDesc& d, LAS unsigned* T, int lane, const float (&sinv)[4]) {
;     ...
;     for (int jq = 0; jq < 4; ++jq) {
;         float g[4];
; #pragma unroll
;         for (int e2 = 0; e2 < 4; ++e2) g[e2] = jq < 2 ? __shfl(gA, 32 * jq + 4 * kr + e2) : __shfl(gB, 32 * (jq - 2) + 4 * kr + e2);
; #pragma unroll
;         for (int e = 0; e < 4; ++e)
;             T[(4 * nq + e) * 33 + 8 * jq + kr] = pack4_i8(v[4 * jq + 0][e] * g[0] * inv[e], v[4 * jq + 1][e] * g[1] * inv[e], v[4 * jq + 2][e] * g[2] * inv[e], v[4 * jq + 3][e] * g[3] * inv[e]);
;     }
;     LDS_WAIT(); asm volatile("" ::: "memory");
;     const int nl = lane >> 3, c = lane & 7;
; #pragma unroll
;     for (int g4 = 0; g4 < 4; ++g4) {
;         const int nloc = 8 * g4 + nl, dr = d.il ? gu_dest(d.n0 + nloc, d.bj) : d.n0 + nloc;
;         const LAS unsigned* t = T + nloc * 33 + 4 * c;
;         u32x4 o; o.x = t[0]; o.y = t[1]; o.z = t[2]; o.w = t[3];
;         *(u32x4*)(d.WQ + blk8_off(dr, d.k0 + 16 * c, d.kt8)) = o;
;         if (!STRIP) if (d.k0 == 0 && c == 0) d.sb[dr] = __uint_as_float(d.cmax[dr]) * (1.0f / 127.0f);
	v_mul_f32_e32 v2, v2, v25
	v_mul_f32_e32 v10, v10, v25
	s_waitcnt lgkmcnt(2)
	v_mul_f32_e32 v4, v4, v27
	v_fmaak_f32 v2, v22, v2, 0x43000000
	v_mul_f32_e32 v12, v12, v27
	v_fmaak_f32 v10, v18, v10, 0x43000000
	s_waitcnt lgkmcnt(1)
	v_mul_f32_e32 v6, v6, v28
	v_cvt_pk_u8_f32 v2, v2, 0, 0
	v_fmaak_f32 v4, v22, v4, 0x43000000
	v_mul_f32_e32 v14, v14, v28
	v_cvt_pk_u8_f32 v10, v10, 0, 0
	v_fmaak_f32 v12, v18, v12, 0x43000000
	s_waitcnt lgkmcnt(0)
	v_mul_f32_e32 v8, v8, v29
	v_cvt_pk_u8_f32 v2, v4, 1, v2
	v_fmaak_f32 v4, v22, v6, 0x43000000
	v_mul_f32_e32 v16, v16, v29
	v_cvt_pk_u8_f32 v10, v12, 1, v10
	v_fmaak_f32 v12, v18, v14, 0x43000000
	v_cvt_pk_u8_f32 v2, v4, 2, v2
	v_fmaak_f32 v4, v22, v8, 0x43000000
	v_cvt_pk_u8_f32 v10, v12, 2, v10
	v_fmaak_f32 v12, v18, v16, 0x43000000
	v_cvt_pk_u8_f32 v2, v4, 3, v2
	v_xor_b32_e32 v26, 0x80808080, v26
	v_cvt_pk_u8_f32 v10, v12, 3, v10
	v_xor_b32_e32 v2, 0x80808080, v2
	v_xor_b32_e32 v20, 0x80808080, v20
	v_xor_b32_e32 v10, 0x80808080, v10
	ds_write2_b32 v65, v26, v2 offset0:82 offset1:90
	v_mul_f32_e32 v2, v3, v25
	ds_write2_b32 v65, v20, v10 offset0:16 offset1:24
	v_mul_f32_e32 v10, v11, v25
	v_mul_f32_e32 v3, v5, v27
	v_fmaak_f32 v2, v23, v2, 0x43000000
	v_mul_f32_e32 v11, v13, v27
	v_fmaak_f32 v10, v19, v10, 0x43000000
	v_mul_f32_e32 v4, v7, v28
	v_cvt_pk_u8_f32 v2, v2, 0, 0
	v_fmaak_f32 v3, v23, v3, 0x43000000
	v_mul_f32_e32 v12, v15, v28
	v_cvt_pk_u8_f32 v10, v10, 0, 0
	v_fmaak_f32 v11, v19, v11, 0x43000000
	v_mul_f32_e32 v5, v9, v29
	v_cvt_pk_u8_f32 v2, v3, 1, v2
	v_fmaak_f32 v3, v23, v4, 0x43000000
	v_mul_f32_e32 v13, v17, v29
	v_cvt_pk_u8_f32 v10, v11, 1, v10
	v_fmaak_f32 v11, v19, v12, 0x43000000
	v_cvt_pk_u8_f32 v2, v3, 2, v2
	v_fmaak_f32 v3, v23, v5, 0x43000000
	v_cvt_pk_u8_f32 v10, v11, 2, v10
	v_fmaak_f32 v11, v19, v13, 0x43000000
	v_cvt_pk_u8_f32 v2, v3, 3, v2
	v_bitop3_b32 v3, s12, v66, v50 bitop3:0xc8
	v_xor_b32_e32 v24, 0x80808080, v24
	v_cvt_pk_u8_f32 v10, v11, 3, v10
	v_xor_b32_e32 v2, 0x80808080, v2
	v_or_b32_e32 v3, s13, v3
	v_xor_b32_e32 v21, 0x80808080, v21
	v_xor_b32_e32 v10, 0x80808080, v10
	ds_write2_b32 v65, v24, v2 offset0:115 offset1:123
	v_or_b32_e32 v2, s12, v50
	v_or_b32_e32 v3, s35, v3
	ds_write2_b32 v65, v21, v10 offset0:49 offset1:57
	v_cndmask_b32_e64 v2, v3, v2, s[2:3]
	s_waitcnt lgkmcnt(0)
	v_lshrrev_b32_e32 v3, 8, v2
	v_mov_b32_e32 v8, s0
	v_mad_i32_i24 v8, v3, s36, v8
	ds_read2_b32 v[4:5], v67 offset1:1
	ds_read2_b32 v[6:7], v67 offset0:2 offset1:3
	v_ashrrev_i32_e32 v9, 31, v8
	v_lshlrev_b64 v[8:9], 15, v[8:9]
	v_lshlrev_b32_e32 v3, 7, v2
	v_and_b32_e32 v34, 0x7380, v3
	v_lshl_add_u64 v[8:9], s[10:11], 0, v[8:9]
	v_lshl_add_u64 v[8:9], v[8:9], 0, v[34:35]
	v_or_b32_e32 v3, s37, v51
	v_lshl_add_u64 v[8:9], v[8:9], 0, v[36:37]
	v_cmp_eq_u32_e32 vcc, 0, v3
	s_waitcnt lgkmcnt(0)
	global_store_dwordx4 v[8:9], v[4:7], off
	s_and_saveexec_b64 s[16:17], vcc
	s_cbranch_execz .LBB0_3969
	v_ashrrev_i32_e32 v3, 31, v2
	v_lshlrev_b64 v[2:3], 2, v[2:3]
	v_lshl_add_u64 v[4:5], s[8:9], 0, v[2:3]
	global_load_dword v4, v[4:5], off
	v_lshl_add_u64 v[2:3], s[14:15], 0, v[2:3]
	s_waitcnt vmcnt(0)
	v_mul_f32_e32 v4, 0x3c010204, v4
	global_store_dword v[2:3], v4, off

; #define LAS __attribute__((address_space(3)))
; __device__ __forceinline__ float bfly8(float x, bool up) { const float p = __uint_as_float(__builtin_amdgcn_update_dpp(0u, __float_as_uint(x), 0x128, 0xf, 0xf, false)); return up ? p - x : x + p; }
; __device__ __forceinline__ void gu_load(f32x4 (&v)[16], float& gA, float& gB, const GUDesc& d, int lane) {
;     const int kr = lane >> 3, nq = lane & 7;
;     const float* __restrict__ src = d.W + (size_t)(d.k0 + 4 * kr) * d.N + d.n0 + 4 * nq;
;     gA = d.gain ? d.gain[d.k0 + lane] : 1.0f; gB = d.gain ? d.gain[d.k0 + 64 + lane] : 1.0f;
; #pragma unroll
;     for (int i = 0; i < 16; ++i) v[i] = *(const f32x4*)(src + (size_t)(32 * (i >> 2) + (i & 3)) * d.N);
; }
; template <int ROT>
; __device__ __forceinline__ void rot32_tile(f32x4 (&v)[16], int lane) {
; #pragma unroll
;     for (int jq = 0; jq < 4; ++jq) {
;         const f32x4 a = v[4 * jq], b = v[4 * jq + 1], c = v[4 * jq + 2], d = v[4 * jq + 3];
;         const f32x4 a1 = a + b, b1 = a - b, c1 = c + d, d1 = c - d;
;         if (ROT >= 2) { v[4 * jq] = a1 + c1; v[4 * jq + 2] = a1 - c1; v[4 * jq + 1] = b1 + d1; v[4 * jq + 3] = b1 - d1; }
;         else { v[4 * jq] = a1; v[4 * jq + 1] = b1; v[4 * jq + 2] = c1; v[4 * jq + 3] = d1; }
;     }
;     { const bool s8 = (lane & 8) != 0, s16 = (lane & 16) != 0, s32 = (lane & 32) != 0;
; #pragma unroll
;       for (int i = 0; i < 16; ++i)
; #pragma unroll
;           for (int e = 0; e < 4; ++e) { float x = v[i][e]; if (ROT >= 3) x = bfly8(x, s8); if (ROT >= 4) x = bfly16(x, s16); if (ROT >= 5) x = bfly32(x, s32); v[i][e] = x; } }
; #pragma unroll
;     for (int i = 0; i < 16; ++i) v[i] *= (ROT == 1 ? 0.70710678118654752f : ROT == 2 ? 0.5f : ROT == 3 ? 0.35355339059327373f : ROT == 4 ? 0.25f : 0.17677669529663687f);
; }
; template <bool STRIP, int ROT>
; __device__ __forceinline__ void gu_finish_t(f32x4 (&v)[16], float gA, float gB, const GUDesc& d, LAS unsigned* T, int lane, const float (&sinv)[4]) {
;     const int kr = lane >> 3, nq = lane & 7;
;     const int dq0 = d.il ? gu_dest(d.n0 + 4 * nq, d.bj) : d.n0 + 4 * nq;
;     if (ROT) rot32_tile<ROT>(v, lane);
;     float inv[4];
; #pragma unroll
;     for (int e = 0; e < 4; ++e) { if (STRIP) inv[e] = sinv[e]; else { const float cm = __uint_as_float(d.cmax[dq0 + e]); inv[e] = cm > 0.f ? 127.0f / cm : 0.f; } }
.LBB0_4001:
	v_or_b32_e32 v34, s52, v137
	s_add_u32 s22, s29, s4
	v_mul_hi_i32_i24_e32 v35, s24, v34
	v_mul_i32_i24_e32 v34, s24, v34
	s_addc_u32 s23, s30, s5
	s_waitcnt lgkmcnt(0)
	v_lshl_add_u64 v[34:35], v[34:35], 2, v[36:37]
	s_ashr_i32 s13, s12, 31
	v_lshl_add_u64 v[34:35], s[12:13], 2, v[34:35]
	v_mov_b32_e32 v135, v131
	v_lshl_add_u64 v[34:35], v[34:35], 0, v[134:135]
	s_lshl_b32 s8, s24, 2
	v_lshl_add_u64 v[36:37], v[34:35], 0, s[8:9]
	global_load_dwordx4 v[122:125], v[34:35], off nt
	global_load_dwordx4 v[126:129], v[36:37], off nt
	v_lshl_add_u64 v[34:35], v[36:37], 0, s[8:9]
	v_lshl_add_u64 v[36:37], v[34:35], 0, s[8:9]
	s_mul_i32 s4, s24, 0x74
	s_mov_b32 s5, s9
	global_load_dwordx4 v[114:117], v[34:35], off nt
	global_load_dwordx4 v[118:121], v[36:37], off nt
	v_lshl_add_u64 v[34:35], v[36:37], 0, s[4:5]
	v_lshl_add_u64 v[36:37], v[34:35], 0, s[8:9]
	global_load_dwordx4 v[106:109], v[34:35], off nt
	global_load_dwordx4 v[110:113], v[36:37], off nt
	v_lshl_add_u64 v[34:35], v[36:37], 0, s[8:9]
	v_lshl_add_u64 v[36:37], v[34:35], 0, s[8:9]
	global_load_dwordx4 v[98:101], v[34:35], off nt
	global_load_dwordx4 v[102:105], v[36:37], off nt
	v_lshl_add_u64 v[34:35], v[36:37], 0, s[4:5]
	global_load_dwordx4 v[54:57], v[34:35], off nt
	v_lshl_add_u64 v[34:35], v[34:35], 0, s[8:9]
	global_load_dwordx4 v[62:65], v[34:35], off nt
	v_lshl_add_u64 v[34:35], v[34:35], 0, s[8:9]
	v_add_u32_e32 v130, s0, v139
	global_load_dwordx4 v[50:53], v[34:35], off nt
	v_lshl_add_u64 v[34:35], v[34:35], 0, s[8:9]
	s_cmp_eq_u32 s54, 0
	v_lshlrev_b32_e32 v135, 1, v130
	global_load_dwordx4 v[58:61], v[34:35], off nt
	v_lshl_add_u64 v[34:35], v[34:35], 0, s[4:5]
	s_cselect_b64 s[4:5], -1, 0
	v_and_b32_e32 v135, 0xffffff00, v135
	s_lshl_b32 s1, s53, 7
	v_add_u32_e32 v135, s1, v135
	v_and_or_b32 v135, v130, s48, v135
	v_cndmask_b32_e64 v162, v135, v130, s[4:5]
	s_waitcnt vmcnt(12)
	v_pk_add_f32 v[164:165], v[96:97], v[92:93]
	v_pk_add_f32 v[166:167], v[94:95], v[90:91]
	v_sub_f32_e32 v93, v97, v93
	v_sub_f32_e32 v92, v96, v92
	v_sub_f32_e32 v91, v95, v91
	v_sub_f32_e32 v90, v94, v90
	v_pk_add_f32 v[94:95], v[88:89], v[84:85]
	v_pk_add_f32 v[96:97], v[86:87], v[82:83]
	v_sub_f32_e32 v169, v89, v85
	v_sub_f32_e32 v168, v88, v84
	v_sub_f32_e32 v171, v87, v83
	v_sub_f32_e32 v170, v86, v82
	v_pk_add_f32 v[86:87], v[164:165], v[94:95]
	v_pk_add_f32 v[88:89], v[166:167], v[96:97]
	v_sub_f32_e32 v83, v165, v95
	v_sub_f32_e32 v82, v164, v94
	v_sub_f32_e32 v85, v167, v97
	v_sub_f32_e32 v84, v166, v96
	v_pk_add_f32 v[164:165], v[80:81], v[76:77]
	v_pk_add_f32 v[166:167], v[78:79], v[74:75]
	v_sub_f32_e32 v77, v81, v77
	v_sub_f32_e32 v76, v80, v76
	v_sub_f32_e32 v75, v79, v75
	v_sub_f32_e32 v74, v78, v74
	v_pk_add_f32 v[78:79], v[72:73], v[68:69]
	v_pk_add_f32 v[80:81], v[70:71], v[66:67]
	v_sub_f32_e32 v67, v71, v67
	v_sub_f32_e32 v66, v70, v66
	v_ashrrev_i32_e32 v163, 31, v162
	v_pk_add_f32 v[70:71], v[164:165], v[78:79]
	v_sub_f32_e32 v79, v165, v79
	v_sub_f32_e32 v78, v164, v78
	v_pk_add_f32 v[164:165], v[74:75], v[66:67]
	v_sub_f32_e32 v75, v75, v67
	v_sub_f32_e32 v74, v74, v66
	v_lshl_add_u64 v[66:67], v[162:163], 2, s[6:7]
	v_sub_f32_e32 v73, v73, v69
	v_sub_f32_e32 v72, v72, v68
	global_load_dwordx4 v[66:69], v[66:67], off nt
	v_pk_add_f32 v[96:97], v[92:93], v[168:169]
	v_sub_f32_e32 v93, v93, v169
	v_sub_f32_e32 v92, v92, v168
	v_pk_add_f32 v[168:169], v[166:167], v[80:81]
	v_sub_f32_e32 v81, v167, v81
	v_sub_f32_e32 v80, v166, v80
	v_pk_add_f32 v[166:167], v[76:77], v[72:73]
	v_sub_f32_e32 v73, v77, v73
	v_sub_f32_e32 v72, v76, v72
	v_pk_add_f32 v[76:77], v[32:33], v[28:29]
	v_pk_add_f32 v[162:163], v[30:31], v[26:27]
	v_sub_f32_e32 v29, v33, v29
	v_sub_f32_e32 v28, v32, v28
	v_sub_f32_e32 v27, v31, v27
	v_sub_f32_e32 v26, v30, v26
	v_pk_add_f32 v[30:31], v[20:21], v[16:17]
	v_pk_add_f32 v[32:33], v[18:19], v[14:15]
	v_sub_f32_e32 v17, v21, v17
	v_sub_f32_e32 v16, v20, v16
	v_sub_f32_e32 v15, v19, v15
	v_sub_f32_e32 v14, v18, v14
	v_pk_add_f32 v[18:19], v[76:77], v[30:31]
	v_pk_add_f32 v[20:21], v[162:163], v[32:33]
	v_sub_f32_e32 v31, v77, v31
	v_sub_f32_e32 v30, v76, v30
	v_sub_f32_e32 v33, v163, v33
	v_sub_f32_e32 v32, v162, v32
	v_pk_add_f32 v[76:77], v[26:27], v[14:15]
	v_pk_add_f32 v[162:163], v[28:29], v[16:17]
	v_sub_f32_e32 v15, v27, v15
	v_sub_f32_e32 v14, v26, v14
	v_sub_f32_e32 v17, v29, v17
	v_sub_f32_e32 v16, v28, v16
	v_pk_add_f32 v[26:27], v[8:9], v[12:13]
	v_pk_add_f32 v[28:29], v[6:7], v[10:11]
	v_sub_f32_e32 v7, v11, v7
	v_sub_f32_e32 v6, v10, v6
	v_pk_add_f32 v[10:11], v[24:25], v[4:5]
	v_sub_f32_e32 v9, v13, v9
	v_sub_f32_e32 v8, v12, v8
	v_pk_add_f32 v[12:13], v[22:23], v[2:3]
	v_sub_f32_e32 v3, v3, v23
	v_sub_f32_e32 v2, v2, v22
	v_pk_add_f32 v[22:23], v[10:11], v[26:27]
	v_sub_f32_e32 v5, v5, v25
	v_sub_f32_e32 v4, v4, v24
	v_pk_add_f32 v[24:25], v[12:13], v[28:29]
	v_sub_f32_e32 v29, v29, v13
	v_sub_f32_e32 v28, v28, v12
	v_pk_add_f32 v[12:13], v[2:3], v[6:7]
	v_sub_f32_e32 v173, v7, v3
	v_sub_f32_e32 v172, v6, v2
	v_pk_mul_f32 v[2:3], v[22:23], 0.5 op_sel_hi:[1,0]
	v_sub_f32_e32 v27, v27, v11
	v_sub_f32_e32 v26, v26, v10
	v_pk_mul_f32 v[10:11], v[24:25], 0.5 op_sel_hi:[1,0]
	v_pk_mul_f32 v[6:7], v[26:27], 0.5 op_sel_hi:[1,0]
	v_pk_mul_f32 v[176:177], v[14:15], 0.5 op_sel_hi:[1,0]
	v_pk_mul_f32 v[14:15], v[28:29], 0.5 op_sel_hi:[1,0]
	v_pk_add_f32 v[94:95], v[90:91], v[170:171]
	v_pk_mul_f32 v[88:89], v[88:89], 0.5 op_sel_hi:[1,0]
	v_pk_mul_f32 v[94:95], v[94:95], 0.5 op_sel_hi:[1,0]
	v_sub_f32_e32 v91, v91, v171
	v_sub_f32_e32 v90, v90, v170
	v_pk_mul_f32 v[84:85], v[84:85], 0.5 op_sel_hi:[1,0]
	v_pk_mul_f32 v[90:91], v[90:91], 0.5 op_sel_hi:[1,0]
	v_pk_mul_f32 v[86:87], v[86:87], 0.5 op_sel_hi:[1,0]
	v_pk_mul_f32 v[96:97], v[96:97], 0.5 op_sel_hi:[1,0]
	v_pk_mul_f32 v[82:83], v[82:83], 0.5 op_sel_hi:[1,0]
	v_pk_mul_f32 v[92:93], v[92:93], 0.5 op_sel_hi:[1,0]
	global_load_dwordx4 v[38:41], v[34:35], off nt
	v_lshl_add_u64 v[34:35], v[34:35], 0, s[8:9]
	v_lshl_add_u64 v[42:43], v[34:35], 0, s[8:9]
	global_load_dwordx4 v[46:49], v[34:35], off nt
	v_pk_mul_f32 v[168:169], v[168:169], 0.5 op_sel_hi:[1,0]
	global_load_dwordx4 v[34:37], v[42:43], off nt
	v_lshl_add_u64 v[42:43], v[42:43], 0, s[8:9]
	global_load_dwordx4 v[42:45], v[42:43], off nt
	v_pk_mul_f32 v[164:165], v[164:165], 0.5 op_sel_hi:[1,0]
	s_waitcnt vmcnt(4)
; #define LAS __attribute__((address_space(3)))
; template <int ROT>
; __device__ __forceinline__ void rot32_tile(f32x4 (&v)[16], int lane) {
;     ...
; #pragma unroll
;     for (int i = 0; i < 16; ++i) v[i] *= (ROT == 1 ? 0.70710678118654752f : ROT == 2 ? 0.5f : ROT == 3 ? 0.35355339059327373f : ROT == 4 ? 0.25f : 0.17677669529663687f);
; }
; template <bool STRIP, int ROT>
; __device__ __forceinline__ void gu_finish_t(f32x4 (&v)[16], float gA, float gB, const GUDesc& d, LAS unsigned* T, int lane, const float (&sinv)[4]) {
;     const int kr = lane >> 3, nq = lane & 7;
;     const int dq0 = d.il ? gu_dest(d.n0 + 4 * nq, d.bj) : d.n0 + 4 * nq;
;     if (ROT) rot32_tile<ROT>(v, lane);
;     float inv[4];
; #pragma unroll
;     for (int e = 0; e < 4; ++e) { if (STRIP) inv[e] = sinv[e]; else { const float cm = __uint_as_float(d.cmax[dq0 + e]); inv[e] = cm > 0.f ? 127.0f / cm : 0.f; } }
; #pragma unroll
;     for (int jq = 0; jq < 4; ++jq) {
;         float g[4];
; #pragma unroll
;         for (int e2 = 0; e2 < 4; ++e2) g[e2] = jq < 2 ? __shfl(gA, 32 * jq + 4 * kr + e2) : __shfl(gB, 32 * (jq - 2) + 4 * kr + e2);
; #pragma unroll
;         for (int e = 0; e < 4; ++e)
;             T[(4 * nq + e) * 33 + 8 * jq + kr] = pack4_i8(v[4 * jq + 0][e] * g[0] * inv[e], v[4 * jq + 1][e] * g[1] * inv[e], v[4 * jq + 2][e] * g[2] * inv[e], v[4 * jq + 3][e] * g[3] * inv[e]);
;     }
	v_div_scale_f32 v22, s[24:25], v66, v66, s49
	v_rcp_f32_e32 v23, v22
	v_pk_mul_f32 v[80:81], v[80:81], 0.5 op_sel_hi:[1,0]
	v_pk_mul_f32 v[74:75], v[74:75], 0.5 op_sel_hi:[1,0]
	v_pk_mul_f32 v[70:71], v[70:71], 0.5 op_sel_hi:[1,0]
	v_fma_f32 v24, -v22, v23, 1.0
	v_fmac_f32_e32 v23, v24, v23
	v_div_scale_f32 v24, vcc, s49, v66, s49
	v_mul_f32_e32 v25, v24, v23
	v_fma_f32 v26, -v22, v25, v24
	v_fmac_f32_e32 v25, v26, v23
	v_fma_f32 v22, -v22, v25, v24
	v_div_fmas_f32 v22, v22, v23, v25
	v_div_scale_f32 v23, s[24:25], v67, v67, s49
	v_rcp_f32_e32 v24, v23
	v_div_fixup_f32 v22, v22, v66, s49
	v_cmp_lt_f32_e32 vcc, 0, v66
	v_pk_mul_f32 v[166:167], v[166:167], 0.5 op_sel_hi:[1,0]
	v_fma_f32 v25, -v23, v24, 1.0
	v_cndmask_b32_e32 v22, 0, v22, vcc
	v_fmac_f32_e32 v24, v25, v24
	v_div_scale_f32 v25, vcc, s49, v67, s49
	v_mul_f32_e32 v26, v25, v24
	v_fma_f32 v27, -v23, v26, v25
	v_fmac_f32_e32 v26, v27, v24
	v_fma_f32 v23, -v23, v26, v25
	v_div_fmas_f32 v23, v23, v24, v26
	v_div_scale_f32 v24, s[24:25], v68, v68, s49
	v_rcp_f32_e32 v25, v24
	v_div_fixup_f32 v23, v23, v67, s49
	v_cmp_lt_f32_e32 vcc, 0, v67
	v_pk_mul_f32 v[78:79], v[78:79], 0.5 op_sel_hi:[1,0]
	v_fma_f32 v26, -v24, v25, 1.0
	v_cndmask_b32_e32 v23, 0, v23, vcc
	v_fmac_f32_e32 v25, v26, v25
	v_div_scale_f32 v26, vcc, s49, v68, s49
	v_mul_f32_e32 v27, v26, v25
	v_fma_f32 v28, -v24, v27, v26
	v_fmac_f32_e32 v27, v28, v25
	v_fma_f32 v24, -v24, v27, v26
	v_div_fmas_f32 v24, v24, v25, v27
	v_div_scale_f32 v25, s[24:25], v69, v69, s49
	v_rcp_f32_e32 v26, v25
	v_div_fixup_f32 v24, v24, v68, s49
	v_cmp_lt_f32_e32 vcc, 0, v68
	v_pk_mul_f32 v[72:73], v[72:73], 0.5 op_sel_hi:[1,0]
	v_fma_f32 v27, -v25, v26, 1.0
	v_cndmask_b32_e32 v24, 0, v24, vcc
	v_fmac_f32_e32 v26, v27, v26
	v_div_scale_f32 v27, vcc, s49, v69, s49
	v_mul_f32_e32 v28, v27, v26
	v_fma_f32 v29, -v25, v28, v27
	v_fmac_f32_e32 v28, v29, v26
	v_fma_f32 v25, -v25, v28, v27
	v_div_fmas_f32 v25, v25, v26, v28
	ds_bpermute_b32 v26, v140, v159
	ds_bpermute_b32 v27, v141, v159
	ds_bpermute_b32 v28, v142, v159
	ds_bpermute_b32 v29, v143, v159
	v_div_fixup_f32 v25, v25, v69, s49
	s_waitcnt lgkmcnt(3)
	v_mul_f32_e32 v66, v88, v26
	s_waitcnt lgkmcnt(2)
	v_mul_f32_e32 v67, v94, v27
	v_fmaak_f32 v66, v22, v66, 0x43000000
	s_waitcnt lgkmcnt(1)
	v_mul_f32_e32 v68, v84, v28
	v_cvt_pk_u8_f32 v66, v66, 0, 0
	v_fmaak_f32 v67, v22, v67, 0x43000000
	v_cmp_lt_f32_e32 vcc, 0, v69
	s_waitcnt lgkmcnt(0)
	v_mul_f32_e32 v69, v90, v29
	v_cvt_pk_u8_f32 v66, v67, 1, v66
	v_fmaak_f32 v67, v22, v68, 0x43000000
	v_cvt_pk_u8_f32 v66, v67, 2, v66
	v_fmaak_f32 v67, v22, v69, 0x43000000
	v_cvt_pk_u8_f32 v66, v67, 3, v66
	v_mul_f32_e32 v67, v89, v26
	v_mul_f32_e32 v68, v95, v27
	v_fmaak_f32 v67, v23, v67, 0x43000000
	v_mul_f32_e32 v69, v85, v28
	v_cvt_pk_u8_f32 v67, v67, 0, 0
	v_fmaak_f32 v68, v23, v68, 0x43000000
	v_mul_f32_e32 v84, v91, v29
	v_cvt_pk_u8_f32 v67, v68, 1, v67
	v_fmaak_f32 v68, v23, v69, 0x43000000
	v_cvt_pk_u8_f32 v67, v68, 2, v67
	v_fmaak_f32 v68, v23, v84, 0x43000000
	v_cndmask_b32_e32 v25, 0, v25, vcc
	v_cvt_pk_u8_f32 v67, v68, 3, v67
	v_mul_f32_e32 v68, v86, v26
	v_mul_f32_e32 v26, v87, v26
	v_mul_f32_e32 v69, v96, v27
	v_mul_f32_e32 v27, v97, v27
	v_fmaak_f32 v26, v25, v26, 0x43000000
	v_mul_f32_e32 v82, v82, v28
	v_mul_f32_e32 v28, v83, v28
	v_cvt_pk_u8_f32 v26, v26, 0, 0
	v_fmaak_f32 v27, v25, v27, 0x43000000
	v_mul_f32_e32 v84, v92, v29
	v_mul_f32_e32 v29, v93, v29
	v_cvt_pk_u8_f32 v26, v27, 1, v26
	v_fmaak_f32 v27, v25, v28, 0x43000000
	v_fmaak_f32 v68, v24, v68, 0x43000000
	v_cvt_pk_u8_f32 v26, v27, 2, v26
	v_fmaak_f32 v27, v25, v29, 0x43000000
	v_cvt_pk_u8_f32 v68, v68, 0, 0
	v_fmaak_f32 v69, v24, v69, 0x43000000
	v_cvt_pk_u8_f32 v26, v27, 3, v26
	ds_bpermute_b32 v27, v144, v159
	v_cvt_pk_u8_f32 v68, v69, 1, v68
	v_fmaak_f32 v69, v24, v82, 0x43000000
	ds_bpermute_b32 v28, v145, v159
	v_cvt_pk_u8_f32 v68, v69, 2, v68
	v_fmaak_f32 v69, v24, v84, 0x43000000
	ds_bpermute_b32 v29, v146, v159
	v_cvt_pk_u8_f32 v68, v69, 3, v68
	ds_bpermute_b32 v69, v147, v159
	s_waitcnt lgkmcnt(3)
	v_mul_f32_e32 v82, v168, v27
	s_waitcnt lgkmcnt(2)
	v_mul_f32_e32 v83, v164, v28
	v_fmaak_f32 v82, v22, v82, 0x43000000
	s_waitcnt lgkmcnt(1)
	v_mul_f32_e32 v80, v80, v29
	v_cvt_pk_u8_f32 v82, v82, 0, 0
	v_fmaak_f32 v83, v22, v83, 0x43000000
	s_waitcnt lgkmcnt(0)
	v_mul_f32_e32 v74, v74, v69
	v_cvt_pk_u8_f32 v82, v83, 1, v82
	v_fmaak_f32 v80, v22, v80, 0x43000000
	v_cvt_pk_u8_f32 v80, v80, 2, v82
	v_fmaak_f32 v74, v22, v74, 0x43000000
	v_cvt_pk_u8_f32 v74, v74, 3, v80
	v_xor_b32_e32 v66, 0x80808080, v66
	v_xor_b32_e32 v74, 0x80808080, v74
	ds_write2_b32 v151, v66, v74 offset1:8
	v_mul_f32_e32 v66, v169, v27
	v_mul_f32_e32 v74, v165, v28
	v_fmaak_f32 v66, v23, v66, 0x43000000
	v_mul_f32_e32 v80, v81, v29
	v_cvt_pk_u8_f32 v66, v66, 0, 0
	v_fmaak_f32 v74, v23, v74, 0x43000000
	v_mul_f32_e32 v75, v75, v69
	v_cvt_pk_u8_f32 v66, v74, 1, v66
	v_fmaak_f32 v74, v23, v80, 0x43000000
	v_cvt_pk_u8_f32 v66, v74, 2, v66
	v_fmaak_f32 v74, v23, v75, 0x43000000
	v_cvt_pk_u8_f32 v66, v74, 3, v66
	v_xor_b32_e32 v67, 0x80808080, v67
	v_xor_b32_e32 v66, 0x80808080, v66
	ds_write2_b32 v151, v67, v66 offset0:33 offset1:41
	v_mul_f32_e32 v66, v70, v27
	v_mul_f32_e32 v67, v166, v28
	v_fmaak_f32 v66, v24, v66, 0x43000000
	v_mul_f32_e32 v70, v78, v29
	v_cvt_pk_u8_f32 v66, v66, 0, 0
	v_fmaak_f32 v67, v24, v67, 0x43000000
	v_mul_f32_e32 v72, v72, v69
	v_cvt_pk_u8_f32 v66, v67, 1, v66
	v_fmaak_f32 v67, v24, v70, 0x43000000
	v_cvt_pk_u8_f32 v66, v67, 2, v66
	v_fmaak_f32 v67, v24, v72, 0x43000000
	v_mul_f32_e32 v27, v71, v27
	v_cvt_pk_u8_f32 v66, v67, 3, v66
	v_mul_f32_e32 v28, v167, v28
	v_fmaak_f32 v27, v25, v27, 0x43000000
	v_xor_b32_e32 v68, 0x80808080, v68
	v_xor_b32_e32 v66, 0x80808080, v66
	v_mul_f32_e32 v29, v79, v29
	v_cvt_pk_u8_f32 v27, v27, 0, 0
	v_fmaak_f32 v28, v25, v28, 0x43000000
	ds_write2_b32 v151, v68, v66 offset0:66 offset1:74
	v_mul_f32_e32 v66, v73, v69
	v_cvt_pk_u8_f32 v27, v28, 1, v27
	v_fmaak_f32 v28, v25, v29, 0x43000000
	v_cvt_pk_u8_f32 v27, v28, 2, v27
	v_fmaak_f32 v28, v25, v66, 0x43000000
	v_cvt_pk_u8_f32 v27, v28, 3, v27
	ds_bpermute_b32 v28, v140, v158
	ds_bpermute_b32 v29, v141, v158
	ds_bpermute_b32 v66, v142, v158
	ds_bpermute_b32 v67, v143, v158
	v_pk_mul_f32 v[20:21], v[20:21], 0.5 op_sel_hi:[1,0]
	v_pk_mul_f32 v[76:77], v[76:77], 0.5 op_sel_hi:[1,0]
	v_xor_b32_e32 v26, 0x80808080, v26
	v_xor_b32_e32 v27, 0x80808080, v27
	s_waitcnt lgkmcnt(3)
; #define LAS __attribute__((address_space(3)))
; __host__ __device__ __forceinline__ size_t blk8_off(int r, int k, int KT8_) { return ((size_t)((r >> 8) * KT8_ + (k >> 7)) * 256 + (size_t)(r & 255)) * 128 + (size_t)(k & 127); }
; #define LDS_WAIT() asm volatile("s_waitcnt lgkmcnt(0)" ::: "memory")
; template <bool STRIP, int ROT>
; __device__ __forceinline__ void gu_finish_t(f32x4 (&v)[16], float gA, float gB, const GUDesc& d, LAS unsigned* T, int lane, const float (&sinv)[4]) {
;     ...
;     for (int jq = 0; jq < 4; ++jq) {
;         float g[4];
; #pragma unroll
;         for (int e2 = 0; e2 < 4; ++e2) g[e2] = jq < 2 ? __shfl(gA, 32 * jq + 4 * kr + e2) : __shfl(gB, 32 * (jq - 2) + 4 * kr + e2);
; #pragma unroll
;         for (int e = 0; e < 4; ++e)
;             T[(4 * nq + e) * 33 + 8 * jq + kr] = pack4_i8(v[4 * jq + 0][e] * g[0] * inv[e], v[4 * jq + 1][e] * g[1] * inv[e], v[4 * jq + 2][e] * g[2] * inv[e], v[4 * jq + 3][e] * g[3] * inv[e]);
;     }
;     LDS_WAIT(); asm volatile("" ::: "memory");
;     const int nl = lane >> 3, c = lane & 7;
; #pragma unroll
;     for (int g4 = 0; g4 < 4; ++g4) {
;         const int nloc = 8 * g4 + nl, dr = d.il ? gu_dest(d.n0 + nloc, d.bj) : d.n0 + nloc;
;         const LAS unsigned* t = T + nloc * 33 + 4 * c;
;         u32x4 o; o.x = t[0]; o.y = t[1]; o.z = t[2]; o.w = t[3];
;         *(u32x4*)(d.WQ + blk8_off(dr, d.k0 + 16 * c, d.kt8)) = o;
;         if (!STRIP) if (d.k0 == 0 && c == 0) d.sb[dr] = __uint_as_float(d.cmax[dr]) * (1.0f / 127.0f);
	v_mul_f32_e32 v20, v20, v28
	v_pk_mul_f32 v[32:33], v[32:33], 0.5 op_sel_hi:[1,0]
	ds_write2_b32 v151, v26, v27 offset0:99 offset1:107
	s_waitcnt lgkmcnt(3)
	v_mul_f32_e32 v26, v76, v29
	v_fmaak_f32 v20, v22, v20, 0x43000000
	s_waitcnt lgkmcnt(2)
	v_mul_f32_e32 v27, v32, v66
	v_cvt_pk_u8_f32 v20, v20, 0, 0
	v_fmaak_f32 v26, v22, v26, 0x43000000
	s_waitcnt lgkmcnt(1)
	v_mul_f32_e32 v32, v176, v67
	v_cvt_pk_u8_f32 v20, v26, 1, v20
	v_fmaak_f32 v26, v22, v27, 0x43000000
	v_cvt_pk_u8_f32 v20, v26, 2, v20
	v_fmaak_f32 v26, v22, v32, 0x43000000
	v_mul_f32_e32 v21, v21, v28
	v_cvt_pk_u8_f32 v20, v26, 3, v20
	v_mul_f32_e32 v26, v77, v29
	v_fmaak_f32 v21, v23, v21, 0x43000000
	v_mul_f32_e32 v27, v33, v66
	v_cvt_pk_u8_f32 v21, v21, 0, 0
	v_fmaak_f32 v26, v23, v26, 0x43000000
	v_pk_mul_f32 v[18:19], v[18:19], 0.5 op_sel_hi:[1,0]
	v_mul_f32_e32 v32, v177, v67
	v_cvt_pk_u8_f32 v21, v26, 1, v21
	v_fmaak_f32 v26, v23, v27, 0x43000000
	v_pk_mul_f32 v[162:163], v[162:163], 0.5 op_sel_hi:[1,0]
	v_cvt_pk_u8_f32 v21, v26, 2, v21
	v_fmaak_f32 v26, v23, v32, 0x43000000
	v_mul_f32_e32 v18, v18, v28
	v_pk_mul_f32 v[30:31], v[30:31], 0.5 op_sel_hi:[1,0]
	v_cvt_pk_u8_f32 v21, v26, 3, v21
	v_mul_f32_e32 v26, v162, v29
	v_fmaak_f32 v18, v24, v18, 0x43000000
	v_pk_mul_f32 v[174:175], v[16:17], 0.5 op_sel_hi:[1,0]
	v_mul_f32_e32 v27, v30, v66
	v_cvt_pk_u8_f32 v18, v18, 0, 0
	v_fmaak_f32 v26, v24, v26, 0x43000000
	v_mul_f32_e32 v30, v174, v67
	v_cvt_pk_u8_f32 v18, v26, 1, v18
	v_fmaak_f32 v26, v24, v27, 0x43000000
	v_cvt_pk_u8_f32 v18, v26, 2, v18
	v_fmaak_f32 v26, v24, v30, 0x43000000
	v_mul_f32_e32 v19, v19, v28
	v_cvt_pk_u8_f32 v18, v26, 3, v18
	v_mul_f32_e32 v26, v163, v29
	v_fmaak_f32 v19, v25, v19, 0x43000000
	v_mul_f32_e32 v27, v31, v66
	v_cvt_pk_u8_f32 v19, v19, 0, 0
	v_fmaak_f32 v26, v25, v26, 0x43000000
	v_mul_f32_e32 v28, v175, v67
	v_cvt_pk_u8_f32 v19, v26, 1, v19
	v_fmaak_f32 v26, v25, v27, 0x43000000
	v_cvt_pk_u8_f32 v19, v26, 2, v19
	v_fmaak_f32 v26, v25, v28, 0x43000000
	v_cvt_pk_u8_f32 v19, v26, 3, v19
	ds_bpermute_b32 v26, v144, v158
	ds_bpermute_b32 v27, v145, v158
	ds_bpermute_b32 v28, v146, v158
	ds_bpermute_b32 v29, v147, v158
	v_pk_add_f32 v[170:171], v[4:5], v[8:9]
	v_sub_f32_e32 v9, v9, v5
	v_sub_f32_e32 v8, v8, v4
	v_pk_mul_f32 v[4:5], v[170:171], 0.5 op_sel_hi:[1,0]
	s_waitcnt lgkmcnt(3)
	v_mul_f32_e32 v2, v2, v26
	s_waitcnt lgkmcnt(2)
	v_mul_f32_e32 v4, v4, v27
	v_fmaak_f32 v2, v24, v2, 0x43000000
	v_pk_mul_f32 v[8:9], v[8:9], 0.5 op_sel_hi:[1,0]
	s_waitcnt lgkmcnt(1)
	v_mul_f32_e32 v6, v6, v28
	v_cvt_pk_u8_f32 v2, v2, 0, 0
	v_fmaak_f32 v4, v24, v4, 0x43000000
	s_waitcnt lgkmcnt(0)
	v_mul_f32_e32 v8, v8, v29
	v_cvt_pk_u8_f32 v2, v4, 1, v2
	v_fmaak_f32 v4, v24, v6, 0x43000000
	v_cvt_pk_u8_f32 v2, v4, 2, v2
	v_fmaak_f32 v4, v24, v8, 0x43000000
	v_pk_mul_f32 v[12:13], v[12:13], 0.5 op_sel_hi:[1,0]
	v_mul_f32_e32 v10, v10, v26
	v_cvt_pk_u8_f32 v2, v4, 3, v2
	v_xor_b32_e32 v18, 0x80808080, v18
	v_mul_f32_e32 v12, v12, v27
	v_fmaak_f32 v10, v22, v10, 0x43000000
	v_xor_b32_e32 v2, 0x80808080, v2
	v_pk_mul_f32 v[16:17], v[172:173], 0.5 op_sel_hi:[1,0]
	v_mul_f32_e32 v14, v14, v28
	v_cvt_pk_u8_f32 v10, v10, 0, 0
	v_fmaak_f32 v12, v22, v12, 0x43000000
	ds_write2_b32 v151, v18, v2 offset0:82 offset1:90
	v_mul_f32_e32 v2, v3, v26
	v_mul_f32_e32 v16, v16, v29
	v_cvt_pk_u8_f32 v10, v12, 1, v10
	v_fmaak_f32 v12, v22, v14, 0x43000000
	v_mul_f32_e32 v3, v5, v27
	v_fmaak_f32 v2, v25, v2, 0x43000000
	v_cvt_pk_u8_f32 v10, v12, 2, v10
	v_fmaak_f32 v12, v22, v16, 0x43000000
	v_mul_f32_e32 v4, v7, v28
	v_cvt_pk_u8_f32 v2, v2, 0, 0
	v_fmaak_f32 v3, v25, v3, 0x43000000
	v_cvt_pk_u8_f32 v10, v12, 3, v10
	v_mul_f32_e32 v5, v9, v29
	v_cvt_pk_u8_f32 v2, v3, 1, v2
	v_fmaak_f32 v3, v25, v4, 0x43000000
	v_xor_b32_e32 v20, 0x80808080, v20
	v_xor_b32_e32 v10, 0x80808080, v10
	v_cvt_pk_u8_f32 v2, v3, 2, v2
	v_fmaak_f32 v3, v25, v5, 0x43000000
	ds_write2_b32 v151, v20, v10 offset0:16 offset1:24
	v_mul_f32_e32 v10, v11, v26
	v_cvt_pk_u8_f32 v2, v3, 3, v2
	v_xor_b32_e32 v19, 0x80808080, v19
	v_mul_f32_e32 v11, v13, v27
	v_fmaak_f32 v10, v23, v10, 0x43000000
	v_xor_b32_e32 v2, 0x80808080, v2
	v_mul_f32_e32 v12, v15, v28
	v_cvt_pk_u8_f32 v10, v10, 0, 0
	v_fmaak_f32 v11, v23, v11, 0x43000000
	ds_write2_b32 v151, v19, v2 offset0:115 offset1:123
	v_add_u32_e32 v2, s0, v1
	v_mul_f32_e32 v13, v17, v29
	v_cvt_pk_u8_f32 v10, v11, 1, v10
	v_fmaak_f32 v11, v23, v12, 0x43000000
	v_lshlrev_b32_e32 v3, 1, v2
	v_cvt_pk_u8_f32 v10, v11, 2, v10
	v_fmaak_f32 v11, v23, v13, 0x43000000
	v_and_b32_e32 v3, 0xffffff00, v3
	v_cvt_pk_u8_f32 v10, v11, 3, v10
	v_add_u32_e32 v3, s1, v3
	v_xor_b32_e32 v21, 0x80808080, v21
	v_xor_b32_e32 v10, 0x80808080, v10
	v_and_or_b32 v3, v2, s48, v3
	ds_write2_b32 v151, v21, v10 offset0:49 offset1:57
	v_cndmask_b32_e64 v2, v3, v2, s[4:5]
	v_add_u32_e32 v3, s31, v132
	s_waitcnt lgkmcnt(0)
	v_lshrrev_b32_e32 v5, 8, v2
	v_ashrrev_i32_e32 v4, 7, v3
	v_mad_i32_i24 v10, v5, s34, v4
	ds_read2_b32 v[6:7], v152 offset1:1
	ds_read2_b32 v[8:9], v152 offset0:2 offset1:3
	v_ashrrev_i32_e32 v11, 31, v10
	v_lshlrev_b64 v[10:11], 15, v[10:11]
	v_lshlrev_b32_e32 v5, 7, v2
	v_and_b32_e32 v12, 0x7f80, v5
	v_mov_b32_e32 v13, v131
	v_lshl_add_u64 v[10:11], s[16:17], 0, v[10:11]
	v_and_b32_e32 v130, 0x7f, v3
	v_lshl_add_u64 v[10:11], v[10:11], 0, v[12:13]
	v_or_b32_e32 v3, s31, v138
	v_lshl_add_u64 v[10:11], v[10:11], 0, v[130:131]
	v_cmp_eq_u32_e32 vcc, 0, v3
	s_waitcnt lgkmcnt(0)
	global_store_dwordx4 v[10:11], v[6:9], off
	s_and_saveexec_b64 s[24:25], vcc
	s_cbranch_execz .LBB0_4003
	v_ashrrev_i32_e32 v3, 31, v2
	v_lshlrev_b64 v[2:3], 2, v[2:3]
	v_lshl_add_u64 v[6:7], s[6:7], 0, v[2:3]
	global_load_dword v5, v[6:7], off
	v_lshl_add_u64 v[2:3], s[22:23], 0, v[2:3]
	s_waitcnt vmcnt(0)
	v_mul_f32_e32 v5, 0x3c010204, v5
	global_store_dword v[2:3], v5, off
